# v27 + closing barrier moved up 4 MFMAs (two chain pairs), prio 2
# speedup vs baseline: 1.0160x; 1.0009x over previous
.LBB0_379:
	v_add_u32_e32 v14, s56, v140
	v_add_u32_e32 v30, s57, v140
	ds_read_b128 v[2:5], v14
	ds_read_b128 v[6:9], v14 offset:1024
	ds_read_b128 v[10:13], v14 offset:2048
	ds_read_b128 v[14:17], v14 offset:3072
	ds_read_b128 v[18:21], v30
	ds_read_b128 v[22:25], v30 offset:1024
	ds_read_b128 v[26:29], v30 offset:2048
	ds_read_b128 v[30:33], v30 offset:3072
	v_add_u32_e32 v141, 0, v1
	ds_read_b128 v[34:37], v141
	ds_read_b128 v[38:41], v141 offset:1024
	ds_read_b128 v[42:45], v141 offset:2048
	ds_read_b128 v[46:49], v141 offset:3072
	ds_read_b128 v[50:53], v141 offset:4096
	ds_read_b128 v[54:57], v141 offset:5120
	ds_read_b128 v[58:61], v141 offset:6144
	ds_read_b128 v[62:65], v141 offset:7168
	s_waitcnt vmcnt(8)
	s_waitcnt lgkmcnt(0)
	s_barrier
	s_setprio 1
	s_waitcnt lgkmcnt(0)
	v_mfma_f32_16x16x32_bf16 v[66:69], v[2:5], v[34:37], 0
	v_mfma_f32_16x16x32_bf16 v[66:69], v[6:9], v[38:41], v[66:69]
	v_mfma_f32_16x16x32_bf16 v[70:73], v[10:13], v[34:37], 0
	v_mfma_f32_16x16x32_bf16 v[70:73], v[14:17], v[38:41], v[70:73]
	v_mfma_f32_16x16x32_bf16 v[78:81], v[10:13], v[42:45], 0
	v_mfma_f32_16x16x32_bf16 v[78:81], v[14:17], v[46:49], v[78:81]
	v_mfma_f32_16x16x32_bf16 v[74:77], v[2:5], v[42:45], 0
	v_mfma_f32_16x16x32_bf16 v[74:77], v[6:9], v[46:49], v[74:77]
	v_mfma_f32_16x16x32_bf16 v[82:85], v[2:5], v[50:53], 0
	v_mfma_f32_16x16x32_bf16 v[82:85], v[6:9], v[54:57], v[82:85]
	v_mfma_f32_16x16x32_bf16 v[86:89], v[10:13], v[50:53], 0
	v_mfma_f32_16x16x32_bf16 v[86:89], v[14:17], v[54:57], v[86:89]
	v_mfma_f32_16x16x32_bf16 v[94:97], v[10:13], v[58:61], 0
	v_mfma_f32_16x16x32_bf16 v[94:97], v[14:17], v[62:65], v[94:97]
	v_mfma_f32_16x16x32_bf16 v[90:93], v[2:5], v[58:61], 0
	v_mfma_f32_16x16x32_bf16 v[90:93], v[6:9], v[62:65], v[90:93]
	s_setprio 0
	s_setprio 1
	v_mfma_f32_16x16x32_bf16 v[98:101], v[18:21], v[34:37], 0
	v_mfma_f32_16x16x32_bf16 v[34:37], v[26:29], v[34:37], 0
	v_mfma_f32_16x16x32_bf16 v[102:105], v[18:21], v[42:45], 0
	v_mfma_f32_16x16x32_bf16 v[42:45], v[26:29], v[42:45], 0
	v_mfma_f32_16x16x32_bf16 v[106:109], v[18:21], v[50:53], 0
	v_mfma_f32_16x16x32_bf16 v[50:53], v[26:29], v[50:53], 0
	v_mfma_f32_16x16x32_bf16 v[110:113], v[18:21], v[58:61], 0
	v_mfma_f32_16x16x32_bf16 v[58:61], v[26:29], v[58:61], 0
	v_mfma_f32_16x16x32_bf16 v[98:101], v[22:25], v[38:41], v[98:101]
	v_mfma_f32_16x16x32_bf16 v[38:41], v[30:33], v[38:41], v[34:37]
	v_mfma_f32_16x16x32_bf16 v[102:105], v[22:25], v[46:49], v[102:105]
	v_mfma_f32_16x16x32_bf16 v[46:49], v[30:33], v[46:49], v[42:45]
	s_setprio 2
	s_barrier
	v_mfma_f32_16x16x32_bf16 v[106:109], v[22:25], v[54:57], v[106:109]
	v_mfma_f32_16x16x32_bf16 v[54:57], v[30:33], v[54:57], v[50:53]
	v_mfma_f32_16x16x32_bf16 v[110:113], v[22:25], v[62:65], v[110:113]
	v_mfma_f32_16x16x32_bf16 v[62:65], v[30:33], v[62:65], v[58:61]
	s_setprio 0
	v_lshl_add_u64 v[136:137], s[38:39], 0, v[130:131]
	s_add_i32 s60, s56, s21
	v_mov_b32_e32 v135, v131
	v_lshl_add_u64 v[142:143], v[136:137], 0, s[10:11]
	s_mov_b32 m0, s60
	v_lshl_add_u64 v[244:245], s[38:39], 0, v[134:135]
	ds_read_b128 v[34:37], v141 offset:16384
	ds_read_b128 v[42:45], v141 offset:17408
	ds_read_b128 v[50:53], v141 offset:18432
	ds_read_b128 v[58:61], v141 offset:19456
	ds_read_b128 v[114:117], v141 offset:20480
	ds_read_b128 v[118:121], v141 offset:21504
	ds_read_b128 v[122:125], v141 offset:22528
	ds_read_b128 v[126:129], v141 offset:23552
	global_load_lds_dwordx4 v[142:143], off
	v_lshl_add_u64 v[142:143], v[244:245], 0, s[10:11]
	s_add_i32 m0, s60, 0x2000
	s_add_i32 s60, s57, s21
	global_load_lds_dwordx4 v[142:143], off
	s_mov_b32 m0, s60
	v_mov_b32_e32 v139, v131
	global_load_lds_dwordx4 v130, s[40:41]
	s_add_i32 m0, s60, 0x2000
	v_lshl_add_u64 v[246:247], s[36:37], 0, v[138:139]
	v_mov_b32_e32 v133, v131
	global_load_lds_dwordx4 v134, s[40:41]
	v_lshl_add_u64 v[142:143], v[246:247], 0, s[10:11]
	s_mov_b32 m0, s33
	v_lshl_add_u64 v[248:249], s[36:37], 0, v[132:133]
	global_load_lds_dwordx4 v[142:143], off
	v_lshl_add_u64 v[142:143], v[248:249], 0, s[10:11]
	s_mov_b32 m0, s46
	s_nop 0
	global_load_lds_dwordx4 v[142:143], off
	s_waitcnt vmcnt(8)
	s_waitcnt lgkmcnt(0)
	s_barrier
	s_setprio 1
	s_waitcnt lgkmcnt(0)
	v_mfma_f32_16x16x32_bf16 v[142:145], v[2:5], v[34:37], 0
	v_mfma_f32_16x16x32_bf16 v[148:151], v[10:13], v[34:37], 0
	v_mfma_f32_16x16x32_bf16 v[152:155], v[2:5], v[50:53], 0
	v_mfma_f32_16x16x32_bf16 v[156:159], v[10:13], v[50:53], 0
	v_mfma_f32_16x16x32_bf16 v[160:163], v[2:5], v[114:117], 0
	v_mfma_f32_16x16x32_bf16 v[164:167], v[10:13], v[114:117], 0
	v_mfma_f32_16x16x32_bf16 v[2:5], v[2:5], v[122:125], 0
	v_mfma_f32_16x16x32_bf16 v[10:13], v[10:13], v[122:125], 0
	v_mfma_f32_16x16x32_bf16 v[142:145], v[6:9], v[42:45], v[142:145]
	v_mfma_f32_16x16x32_bf16 v[148:151], v[14:17], v[42:45], v[148:151]
	v_mfma_f32_16x16x32_bf16 v[152:155], v[6:9], v[58:61], v[152:155]
	v_mfma_f32_16x16x32_bf16 v[156:159], v[14:17], v[58:61], v[156:159]
	v_mfma_f32_16x16x32_bf16 v[160:163], v[6:9], v[118:121], v[160:163]
	v_mfma_f32_16x16x32_bf16 v[164:167], v[14:17], v[118:121], v[164:167]
	v_mfma_f32_16x16x32_bf16 v[168:171], v[6:9], v[126:129], v[2:5]
	v_mfma_f32_16x16x32_bf16 v[172:175], v[14:17], v[126:129], v[10:13]
	s_setprio 0
	s_setprio 1
	v_mfma_f32_16x16x32_bf16 v[2:5], v[18:21], v[34:37], 0
	v_mfma_f32_16x16x32_bf16 v[6:9], v[26:29], v[34:37], 0
	v_mfma_f32_16x16x32_bf16 v[10:13], v[18:21], v[50:53], 0
	v_mfma_f32_16x16x32_bf16 v[14:17], v[26:29], v[50:53], 0
	v_mfma_f32_16x16x32_bf16 v[34:37], v[18:21], v[114:117], 0
	v_mfma_f32_16x16x32_bf16 v[50:53], v[26:29], v[114:117], 0
	v_mfma_f32_16x16x32_bf16 v[18:21], v[18:21], v[122:125], 0
	v_mfma_f32_16x16x32_bf16 v[26:29], v[26:29], v[122:125], 0
	v_mfma_f32_16x16x32_bf16 v[114:117], v[22:25], v[42:45], v[2:5]
	v_mfma_f32_16x16x32_bf16 v[188:191], v[22:25], v[118:121], v[34:37]
	v_mfma_f32_16x16x32_bf16 v[118:121], v[30:33], v[118:121], v[50:53]
	v_mfma_f32_16x16x32_bf16 v[176:179], v[30:33], v[42:45], v[6:9]
	s_setprio 2
	s_barrier
	v_mfma_f32_16x16x32_bf16 v[180:183], v[22:25], v[58:61], v[10:13]
	v_mfma_f32_16x16x32_bf16 v[184:187], v[30:33], v[58:61], v[14:17]
	v_mfma_f32_16x16x32_bf16 v[192:195], v[22:25], v[126:129], v[18:21]
	v_mfma_f32_16x16x32_bf16 v[196:199], v[30:33], v[126:129], v[26:29]
	s_setprio 0
	s_add_i32 s60, 0, 0x18000
	v_add_u32_e32 v2, s60, v140
	s_add_i32 s61, 0, 0x1c000
	ds_read_b128 v[200:203], v2
	ds_read_b128 v[204:207], v2 offset:1024
	ds_read_b128 v[208:211], v2 offset:2048
	ds_read_b128 v[212:215], v2 offset:3072
	v_add_u32_e32 v2, s61, v140
	ds_read_b128 v[216:219], v2
	ds_read_b128 v[220:223], v2 offset:1024
	ds_read_b128 v[224:227], v2 offset:2048
	ds_read_b128 v[228:231], v2 offset:3072
	s_mov_b32 m0, s47
	ds_read_b128 v[42:45], v141 offset:32768
	ds_read_b128 v[50:53], v141 offset:33792
	ds_read_b128 v[58:61], v141 offset:34816
	ds_read_b128 v[122:125], v141 offset:35840
	ds_read_b128 v[126:129], v141 offset:36864
	ds_read_b128 v[232:235], v141 offset:37888
	ds_read_b128 v[236:239], v141 offset:38912
	ds_read_b128 v[240:243], v141 offset:39936
	global_load_lds_dwordx4 v138, s[42:43]
	s_mov_b32 m0, s48
	s_nop 0
	global_load_lds_dwordx4 v132, s[42:43]
	s_waitcnt vmcnt(8)
	s_waitcnt lgkmcnt(0)
	s_barrier
	s_setprio 1
	s_waitcnt lgkmcnt(0)
	v_mfma_f32_16x16x32_bf16 v[2:5], v[200:203], v[42:45], v[66:69]
	v_mfma_f32_16x16x32_bf16 v[6:9], v[208:211], v[42:45], v[70:73]
	v_mfma_f32_16x16x32_bf16 v[10:13], v[200:203], v[58:61], v[74:77]
	v_mfma_f32_16x16x32_bf16 v[14:17], v[208:211], v[58:61], v[78:81]
	v_mfma_f32_16x16x32_bf16 v[18:21], v[200:203], v[126:129], v[82:85]
	v_mfma_f32_16x16x32_bf16 v[22:25], v[208:211], v[126:129], v[86:89]
	v_mfma_f32_16x16x32_bf16 v[26:29], v[200:203], v[236:239], v[90:93]
	v_mfma_f32_16x16x32_bf16 v[30:33], v[208:211], v[236:239], v[94:97]
	v_mfma_f32_16x16x32_bf16 v[2:5], v[204:207], v[50:53], v[2:5]
	v_mfma_f32_16x16x32_bf16 v[6:9], v[212:215], v[50:53], v[6:9]
	v_mfma_f32_16x16x32_bf16 v[10:13], v[204:207], v[122:125], v[10:13]
	v_mfma_f32_16x16x32_bf16 v[14:17], v[212:215], v[122:125], v[14:17]
	v_mfma_f32_16x16x32_bf16 v[18:21], v[204:207], v[232:235], v[18:21]
	v_mfma_f32_16x16x32_bf16 v[22:25], v[212:215], v[232:235], v[22:25]
	v_mfma_f32_16x16x32_bf16 v[26:29], v[204:207], v[240:243], v[26:29]
	v_mfma_f32_16x16x32_bf16 v[30:33], v[212:215], v[240:243], v[30:33]
	s_setprio 0
	s_setprio 1
	v_mfma_f32_16x16x32_bf16 v[34:37], v[216:219], v[42:45], v[98:101]
	v_mfma_f32_16x16x32_bf16 v[38:41], v[224:227], v[42:45], v[38:41]
	v_mfma_f32_16x16x32_bf16 v[34:37], v[220:223], v[50:53], v[34:37]
	v_mfma_f32_16x16x32_bf16 v[38:41], v[228:231], v[50:53], v[38:41]
	v_mfma_f32_16x16x32_bf16 v[42:45], v[216:219], v[58:61], v[102:105]
	v_mfma_f32_16x16x32_bf16 v[46:49], v[224:227], v[58:61], v[46:49]
	v_mfma_f32_16x16x32_bf16 v[50:53], v[216:219], v[126:129], v[106:109]
	v_mfma_f32_16x16x32_bf16 v[54:57], v[224:227], v[126:129], v[54:57]
	v_mfma_f32_16x16x32_bf16 v[58:61], v[216:219], v[236:239], v[110:113]
	v_mfma_f32_16x16x32_bf16 v[62:65], v[224:227], v[236:239], v[62:65]
	v_mfma_f32_16x16x32_bf16 v[42:45], v[220:223], v[122:125], v[42:45]
	v_mfma_f32_16x16x32_bf16 v[46:49], v[228:231], v[122:125], v[46:49]
	s_setprio 2
	s_barrier
	v_mfma_f32_16x16x32_bf16 v[50:53], v[220:223], v[232:235], v[50:53]
	v_mfma_f32_16x16x32_bf16 v[54:57], v[228:231], v[232:235], v[54:57]
	v_mfma_f32_16x16x32_bf16 v[58:61], v[220:223], v[240:243], v[58:61]
	v_mfma_f32_16x16x32_bf16 v[62:65], v[228:231], v[240:243], v[62:65]
	s_setprio 0
	s_add_i32 s60, s60, s21
	v_lshl_add_u64 v[66:67], v[136:137], 0, s[12:13]
	s_mov_b32 m0, s60
	ds_read_b128 v[94:97], v141 offset:49152
	ds_read_b128 v[98:101], v141 offset:50176
	ds_read_b128 v[102:105], v141 offset:51200
	ds_read_b128 v[106:109], v141 offset:52224
	ds_read_b128 v[110:113], v141 offset:53248
	ds_read_b128 v[232:235], v141 offset:54272
	ds_read_b128 v[236:239], v141 offset:55296
	ds_read_b128 v[240:243], v141 offset:56320
	global_load_lds_dwordx4 v[66:67], off
	v_lshl_add_u64 v[66:67], v[244:245], 0, s[12:13]
	s_add_i32 m0, s60, 0x2000
	s_add_i32 s60, s61, s21
	global_load_lds_dwordx4 v[66:67], off
	s_mov_b32 m0, s60
	v_lshl_add_u64 v[66:67], v[246:247], 0, s[12:13]
	global_load_lds_dwordx4 v130, s[44:45]
	s_add_i32 m0, s60, 0x2000
	s_nop 0
	global_load_lds_dwordx4 v134, s[44:45]
	s_mov_b32 m0, s52
	s_nop 0
	global_load_lds_dwordx4 v[66:67], off
	v_lshl_add_u64 v[66:67], v[248:249], 0, s[12:13]
	s_mov_b32 m0, s53
	s_nop 0
	global_load_lds_dwordx4 v[66:67], off
	s_waitcnt vmcnt(8)
	s_waitcnt lgkmcnt(0)
	s_barrier
	s_setprio 1
	s_waitcnt lgkmcnt(0)
	v_mfma_f32_16x16x32_bf16 v[66:69], v[200:203], v[94:97], v[142:145]
	v_mfma_f32_16x16x32_bf16 v[122:125], v[204:207], v[98:101], v[66:69]
	v_mfma_f32_16x16x32_bf16 v[66:69], v[208:211], v[94:97], v[148:151]
	v_mfma_f32_16x16x32_bf16 v[126:129], v[212:215], v[98:101], v[66:69]
	v_mfma_f32_16x16x32_bf16 v[66:69], v[200:203], v[102:105], v[152:155]
	v_mfma_f32_16x16x32_bf16 v[70:73], v[208:211], v[102:105], v[156:159]
	v_mfma_f32_16x16x32_bf16 v[74:77], v[200:203], v[110:113], v[160:163]
	v_mfma_f32_16x16x32_bf16 v[78:81], v[208:211], v[110:113], v[164:167]
	v_mfma_f32_16x16x32_bf16 v[82:85], v[200:203], v[236:239], v[168:171]
	v_mfma_f32_16x16x32_bf16 v[86:89], v[208:211], v[236:239], v[172:175]
	v_mfma_f32_16x16x32_bf16 v[66:69], v[204:207], v[106:109], v[66:69]
	v_mfma_f32_16x16x32_bf16 v[70:73], v[212:215], v[106:109], v[70:73]
	v_mfma_f32_16x16x32_bf16 v[74:77], v[204:207], v[232:235], v[74:77]
	v_mfma_f32_16x16x32_bf16 v[78:81], v[212:215], v[232:235], v[78:81]
	v_mfma_f32_16x16x32_bf16 v[82:85], v[204:207], v[240:243], v[82:85]
	v_mfma_f32_16x16x32_bf16 v[86:89], v[212:215], v[240:243], v[86:89]
	s_setprio 0
	s_setprio 1
	v_mfma_f32_16x16x32_bf16 v[90:93], v[216:219], v[94:97], v[114:117]
	v_mfma_f32_16x16x32_bf16 v[94:97], v[224:227], v[94:97], v[176:179]
	v_mfma_f32_16x16x32_bf16 v[90:93], v[220:223], v[98:101], v[90:93]
	v_mfma_f32_16x16x32_bf16 v[94:97], v[228:231], v[98:101], v[94:97]
	v_mfma_f32_16x16x32_bf16 v[98:101], v[216:219], v[102:105], v[180:183]
	v_mfma_f32_16x16x32_bf16 v[102:105], v[224:227], v[102:105], v[184:187]
	v_mfma_f32_16x16x32_bf16 v[98:101], v[220:223], v[106:109], v[98:101]
	v_mfma_f32_16x16x32_bf16 v[102:105], v[228:231], v[106:109], v[102:105]
	v_mfma_f32_16x16x32_bf16 v[106:109], v[216:219], v[110:113], v[188:191]
	v_mfma_f32_16x16x32_bf16 v[110:113], v[224:227], v[110:113], v[118:121]
	v_mfma_f32_16x16x32_bf16 v[114:117], v[216:219], v[236:239], v[192:195]
	v_mfma_f32_16x16x32_bf16 v[118:121], v[224:227], v[236:239], v[196:199]
	s_setprio 2
	s_barrier
	v_mfma_f32_16x16x32_bf16 v[106:109], v[220:223], v[232:235], v[106:109]
	v_mfma_f32_16x16x32_bf16 v[110:113], v[228:231], v[232:235], v[110:113]
	v_mfma_f32_16x16x32_bf16 v[114:117], v[220:223], v[240:243], v[114:117]
	v_mfma_f32_16x16x32_bf16 v[118:121], v[228:231], v[240:243], v[118:121]
	s_setprio 0
	s_add_i32 s59, s59, 2
	s_cmp_ge_i32 s59, s15
	s_cbranch_scc0 .LBB0_379
	v_mov_b32_e32 v136, v130
	s_branch .LBB0_382

.LBB0_383:
	v_add_u32_e32 v133, s56, v140
	ds_read_b128 v[142:145], v133
	ds_read_b128 v[148:151], v133 offset:1024
	ds_read_b128 v[152:155], v133 offset:2048
	ds_read_b128 v[156:159], v133 offset:3072
	v_add_u32_e32 v133, s57, v140
	ds_read_b128 v[160:163], v133
	ds_read_b128 v[164:167], v133 offset:1024
	ds_read_b128 v[168:171], v133 offset:2048
	ds_read_b128 v[172:175], v133 offset:3072
	s_add_u32 s38, s36, 0xfff80080
	s_addc_u32 s39, s37, -1
	s_cmp_eq_u32 s43, 28
	s_cselect_b32 s41, s31, s39
	s_cselect_b32 s40, s30, s38
	s_cselect_b32 s39, s35, s42
	s_cselect_b32 s38, s34, s15
	s_mov_b32 m0, s54
	v_add_u32_e32 v141, 0, v1
	ds_read_b128 v[176:179], v141
	ds_read_b128 v[180:183], v141 offset:1024
	ds_read_b128 v[184:187], v141 offset:2048
	ds_read_b128 v[188:191], v141 offset:3072
	ds_read_b128 v[192:195], v141 offset:4096
	ds_read_b128 v[196:199], v141 offset:5120
	ds_read_b128 v[200:203], v141 offset:6144
	ds_read_b128 v[204:207], v141 offset:7168
	global_load_lds_dwordx4 v130, s[36:37]
	s_mov_b32 m0, s55
	v_mov_b32_e32 v133, v131
	global_load_lds_dwordx4 v132, s[36:37]
	s_waitcnt vmcnt(8)
	s_waitcnt lgkmcnt(0)
	s_barrier
	s_setprio 1
	s_waitcnt lgkmcnt(0)
	v_mfma_f32_16x16x32_bf16 v[2:5], v[142:145], v[176:179], v[2:5]
	v_mfma_f32_16x16x32_bf16 v[2:5], v[148:151], v[180:183], v[2:5]
	v_mfma_f32_16x16x32_bf16 v[6:9], v[156:159], v[180:183], v[6:9]
	v_mfma_f32_16x16x32_bf16 v[6:9], v[152:155], v[176:179], v[6:9]
	v_mfma_f32_16x16x32_bf16 v[14:17], v[152:155], v[184:187], v[14:17]
	v_mfma_f32_16x16x32_bf16 v[14:17], v[156:159], v[188:191], v[14:17]
	v_mfma_f32_16x16x32_bf16 v[10:13], v[148:151], v[188:191], v[10:13]
	v_mfma_f32_16x16x32_bf16 v[10:13], v[142:145], v[184:187], v[10:13]
	v_mfma_f32_16x16x32_bf16 v[18:21], v[142:145], v[192:195], v[18:21]
	v_mfma_f32_16x16x32_bf16 v[18:21], v[148:151], v[196:199], v[18:21]
	v_mfma_f32_16x16x32_bf16 v[22:25], v[156:159], v[196:199], v[22:25]
	v_mfma_f32_16x16x32_bf16 v[22:25], v[152:155], v[192:195], v[22:25]
	v_mfma_f32_16x16x32_bf16 v[30:33], v[152:155], v[200:203], v[30:33]
	v_mfma_f32_16x16x32_bf16 v[30:33], v[156:159], v[204:207], v[30:33]
	v_mfma_f32_16x16x32_bf16 v[26:29], v[148:151], v[204:207], v[26:29]
	v_mfma_f32_16x16x32_bf16 v[26:29], v[142:145], v[200:203], v[26:29]
	s_setprio 0
	s_setprio 1
	v_mfma_f32_16x16x32_bf16 v[34:37], v[160:163], v[176:179], v[34:37]
	v_mfma_f32_16x16x32_bf16 v[34:37], v[164:167], v[180:183], v[34:37]
	v_mfma_f32_16x16x32_bf16 v[38:41], v[172:175], v[180:183], v[38:41]
	v_mfma_f32_16x16x32_bf16 v[38:41], v[168:171], v[176:179], v[38:41]
	v_mfma_f32_16x16x32_bf16 v[46:49], v[168:171], v[184:187], v[46:49]
	v_mfma_f32_16x16x32_bf16 v[46:49], v[172:175], v[188:191], v[46:49]
	v_mfma_f32_16x16x32_bf16 v[42:45], v[164:167], v[188:191], v[42:45]
	v_mfma_f32_16x16x32_bf16 v[42:45], v[160:163], v[184:187], v[42:45]
	v_mfma_f32_16x16x32_bf16 v[50:53], v[160:163], v[192:195], v[50:53]
	v_mfma_f32_16x16x32_bf16 v[50:53], v[164:167], v[196:199], v[50:53]
	v_mfma_f32_16x16x32_bf16 v[54:57], v[172:175], v[196:199], v[54:57]
	v_mfma_f32_16x16x32_bf16 v[54:57], v[168:171], v[192:195], v[54:57]
	s_setprio 2
	s_barrier
	v_mfma_f32_16x16x32_bf16 v[62:65], v[168:171], v[200:203], v[62:65]
	v_mfma_f32_16x16x32_bf16 v[62:65], v[172:175], v[204:207], v[62:65]
	v_mfma_f32_16x16x32_bf16 v[58:61], v[164:167], v[204:207], v[58:61]
	v_mfma_f32_16x16x32_bf16 v[58:61], v[160:163], v[200:203], v[58:61]
	s_setprio 0
	s_add_i32 s44, s56, s21
	s_mov_b32 m0, s44
	ds_read_b128 v[176:179], v141 offset:16384
	ds_read_b128 v[180:183], v141 offset:17408
	ds_read_b128 v[184:187], v141 offset:18432
	ds_read_b128 v[188:191], v141 offset:19456
	ds_read_b128 v[192:195], v141 offset:20480
	ds_read_b128 v[196:199], v141 offset:21504
	ds_read_b128 v[200:203], v141 offset:22528
	ds_read_b128 v[204:207], v141 offset:23552
	global_load_lds_dwordx4 v136, s[38:39]
	s_add_i32 m0, s44, 0x2000
	s_add_u32 s44, s38, 0x80000
	s_addc_u32 s45, s39, 0
	s_add_i32 s59, s57, s21
	global_load_lds_dwordx4 v134, s[38:39]
	s_mov_b32 m0, s59
	v_mov_b32_e32 v137, v131
	global_load_lds_dwordx4 v136, s[44:45]
	s_add_i32 m0, s59, 0x2000
	v_mov_b32_e32 v135, v131
	global_load_lds_dwordx4 v134, s[44:45]
	s_mov_b32 m0, s33
	v_lshl_add_u64 v[138:139], s[38:39], 0, v[136:137]
	global_load_lds_dwordx4 v130, s[40:41]
	s_mov_b32 m0, s46
	v_lshl_add_u64 v[208:209], s[38:39], 0, v[134:135]
	global_load_lds_dwordx4 v132, s[40:41]
	s_waitcnt vmcnt(8)
	s_waitcnt lgkmcnt(0)
	v_lshl_add_u64 v[210:211], s[40:41], 0, v[130:131]
	v_lshl_add_u64 v[212:213], s[40:41], 0, v[132:133]
	s_barrier
	s_setprio 1
	s_waitcnt lgkmcnt(0)
	v_mfma_f32_16x16x32_bf16 v[122:125], v[142:145], v[176:179], v[122:125]
	v_mfma_f32_16x16x32_bf16 v[122:125], v[148:151], v[180:183], v[122:125]
	v_mfma_f32_16x16x32_bf16 v[126:129], v[156:159], v[180:183], v[126:129]
	v_mfma_f32_16x16x32_bf16 v[126:129], v[152:155], v[176:179], v[126:129]
	v_mfma_f32_16x16x32_bf16 v[70:73], v[152:155], v[184:187], v[70:73]
	v_mfma_f32_16x16x32_bf16 v[70:73], v[156:159], v[188:191], v[70:73]
	v_mfma_f32_16x16x32_bf16 v[66:69], v[148:151], v[188:191], v[66:69]
	v_mfma_f32_16x16x32_bf16 v[66:69], v[142:145], v[184:187], v[66:69]
	v_mfma_f32_16x16x32_bf16 v[74:77], v[142:145], v[192:195], v[74:77]
	v_mfma_f32_16x16x32_bf16 v[74:77], v[148:151], v[196:199], v[74:77]
	v_mfma_f32_16x16x32_bf16 v[78:81], v[156:159], v[196:199], v[78:81]
	v_mfma_f32_16x16x32_bf16 v[78:81], v[152:155], v[192:195], v[78:81]
	v_mfma_f32_16x16x32_bf16 v[86:89], v[152:155], v[200:203], v[86:89]
	v_mfma_f32_16x16x32_bf16 v[86:89], v[156:159], v[204:207], v[86:89]
	v_mfma_f32_16x16x32_bf16 v[82:85], v[148:151], v[204:207], v[82:85]
	v_mfma_f32_16x16x32_bf16 v[82:85], v[142:145], v[200:203], v[82:85]
	s_setprio 0
	s_setprio 1
	v_mfma_f32_16x16x32_bf16 v[90:93], v[160:163], v[176:179], v[90:93]
	v_mfma_f32_16x16x32_bf16 v[90:93], v[164:167], v[180:183], v[90:93]
	v_mfma_f32_16x16x32_bf16 v[94:97], v[172:175], v[180:183], v[94:97]
	v_mfma_f32_16x16x32_bf16 v[94:97], v[168:171], v[176:179], v[94:97]
	v_mfma_f32_16x16x32_bf16 v[102:105], v[168:171], v[184:187], v[102:105]
	v_mfma_f32_16x16x32_bf16 v[102:105], v[172:175], v[188:191], v[102:105]
	v_mfma_f32_16x16x32_bf16 v[98:101], v[164:167], v[188:191], v[98:101]
	v_mfma_f32_16x16x32_bf16 v[98:101], v[160:163], v[184:187], v[98:101]
	v_mfma_f32_16x16x32_bf16 v[106:109], v[160:163], v[192:195], v[106:109]
	v_mfma_f32_16x16x32_bf16 v[106:109], v[164:167], v[196:199], v[106:109]
	v_mfma_f32_16x16x32_bf16 v[110:113], v[172:175], v[196:199], v[110:113]
	v_mfma_f32_16x16x32_bf16 v[110:113], v[168:171], v[192:195], v[110:113]
	s_setprio 2
	s_barrier
	v_mfma_f32_16x16x32_bf16 v[118:121], v[168:171], v[200:203], v[118:121]
	v_mfma_f32_16x16x32_bf16 v[118:121], v[172:175], v[204:207], v[118:121]
	v_mfma_f32_16x16x32_bf16 v[114:117], v[164:167], v[204:207], v[114:117]
	v_mfma_f32_16x16x32_bf16 v[114:117], v[160:163], v[200:203], v[114:117]
	s_setprio 0
	s_add_i32 s44, 0, 0x18000
	v_add_u32_e32 v135, s44, v140
	s_add_i32 s45, 0, 0x1c000
	ds_read_b128 v[142:145], v135
	ds_read_b128 v[148:151], v135 offset:1024
	ds_read_b128 v[152:155], v135 offset:2048
	ds_read_b128 v[156:159], v135 offset:3072
	v_add_u32_e32 v135, s45, v140
	ds_read_b128 v[160:163], v135
	ds_read_b128 v[164:167], v135 offset:1024
	ds_read_b128 v[168:171], v135 offset:2048
	ds_read_b128 v[172:175], v135 offset:3072
	s_add_u32 s40, s40, 0x80000
	s_addc_u32 s41, s41, 0
	s_mov_b32 m0, s47
	ds_read_b128 v[176:179], v141 offset:32768
	ds_read_b128 v[180:183], v141 offset:33792
	ds_read_b128 v[184:187], v141 offset:34816
	ds_read_b128 v[188:191], v141 offset:35840
	ds_read_b128 v[192:195], v141 offset:36864
	ds_read_b128 v[196:199], v141 offset:37888
	ds_read_b128 v[200:203], v141 offset:38912
	ds_read_b128 v[204:207], v141 offset:39936
	global_load_lds_dwordx4 v130, s[40:41]
	s_mov_b32 m0, s48
	s_nop 0
	global_load_lds_dwordx4 v132, s[40:41]
	s_waitcnt vmcnt(8)
	s_waitcnt lgkmcnt(0)
	s_barrier
	s_setprio 1
	s_waitcnt lgkmcnt(0)
	v_mfma_f32_16x16x32_bf16 v[2:5], v[142:145], v[176:179], v[2:5]
	v_mfma_f32_16x16x32_bf16 v[2:5], v[148:151], v[180:183], v[2:5]
	v_mfma_f32_16x16x32_bf16 v[6:9], v[156:159], v[180:183], v[6:9]
	v_mfma_f32_16x16x32_bf16 v[6:9], v[152:155], v[176:179], v[6:9]
	v_mfma_f32_16x16x32_bf16 v[14:17], v[152:155], v[184:187], v[14:17]
	v_mfma_f32_16x16x32_bf16 v[14:17], v[156:159], v[188:191], v[14:17]
	v_mfma_f32_16x16x32_bf16 v[10:13], v[148:151], v[188:191], v[10:13]
	v_mfma_f32_16x16x32_bf16 v[10:13], v[142:145], v[184:187], v[10:13]
	v_mfma_f32_16x16x32_bf16 v[18:21], v[142:145], v[192:195], v[18:21]
	v_mfma_f32_16x16x32_bf16 v[18:21], v[148:151], v[196:199], v[18:21]
	v_mfma_f32_16x16x32_bf16 v[22:25], v[156:159], v[196:199], v[22:25]
	v_mfma_f32_16x16x32_bf16 v[22:25], v[152:155], v[192:195], v[22:25]
	v_mfma_f32_16x16x32_bf16 v[30:33], v[152:155], v[200:203], v[30:33]
	v_mfma_f32_16x16x32_bf16 v[30:33], v[156:159], v[204:207], v[30:33]
	v_mfma_f32_16x16x32_bf16 v[26:29], v[148:151], v[204:207], v[26:29]
	v_mfma_f32_16x16x32_bf16 v[26:29], v[142:145], v[200:203], v[26:29]
	s_setprio 0
	s_setprio 1
	v_mfma_f32_16x16x32_bf16 v[34:37], v[160:163], v[176:179], v[34:37]
	v_mfma_f32_16x16x32_bf16 v[34:37], v[164:167], v[180:183], v[34:37]
	v_mfma_f32_16x16x32_bf16 v[38:41], v[172:175], v[180:183], v[38:41]
	v_mfma_f32_16x16x32_bf16 v[38:41], v[168:171], v[176:179], v[38:41]
	v_mfma_f32_16x16x32_bf16 v[46:49], v[168:171], v[184:187], v[46:49]
	v_mfma_f32_16x16x32_bf16 v[46:49], v[172:175], v[188:191], v[46:49]
	v_mfma_f32_16x16x32_bf16 v[42:45], v[164:167], v[188:191], v[42:45]
	v_mfma_f32_16x16x32_bf16 v[42:45], v[160:163], v[184:187], v[42:45]
	v_mfma_f32_16x16x32_bf16 v[50:53], v[160:163], v[192:195], v[50:53]
	v_mfma_f32_16x16x32_bf16 v[50:53], v[164:167], v[196:199], v[50:53]
	v_mfma_f32_16x16x32_bf16 v[54:57], v[172:175], v[196:199], v[54:57]
	v_mfma_f32_16x16x32_bf16 v[54:57], v[168:171], v[192:195], v[54:57]
	s_setprio 2
	s_barrier
	v_mfma_f32_16x16x32_bf16 v[62:65], v[168:171], v[200:203], v[62:65]
	v_mfma_f32_16x16x32_bf16 v[62:65], v[172:175], v[204:207], v[62:65]
	v_mfma_f32_16x16x32_bf16 v[58:61], v[164:167], v[204:207], v[58:61]
	v_mfma_f32_16x16x32_bf16 v[58:61], v[160:163], v[200:203], v[58:61]
	s_setprio 0
	s_add_i32 s40, s44, s21
	v_lshl_add_u64 v[138:139], v[138:139], 0, s[6:7]
	s_mov_b32 m0, s40
	ds_read_b128 v[176:179], v141 offset:49152
	ds_read_b128 v[180:183], v141 offset:50176
	ds_read_b128 v[184:187], v141 offset:51200
	ds_read_b128 v[188:191], v141 offset:52224
	ds_read_b128 v[192:195], v141 offset:53248
	ds_read_b128 v[196:199], v141 offset:54272
	ds_read_b128 v[200:203], v141 offset:55296
	ds_read_b128 v[204:207], v141 offset:56320
	global_load_lds_dwordx4 v[138:139], off
	s_add_i32 m0, s40, 0x2000
	s_add_u32 s38, s38, 0x80080
	v_lshl_add_u64 v[138:139], v[208:209], 0, s[6:7]
	s_addc_u32 s39, s39, 0
	s_add_i32 s40, s45, s21
	global_load_lds_dwordx4 v[138:139], off
	s_mov_b32 m0, s40
	v_lshl_add_u64 v[138:139], v[210:211], 0, s[6:7]
	global_load_lds_dwordx4 v136, s[38:39]
	s_add_i32 m0, s40, 0x2000
	s_nop 0
	global_load_lds_dwordx4 v134, s[38:39]
	s_mov_b32 m0, s52
	s_nop 0
	global_load_lds_dwordx4 v[138:139], off
	v_lshl_add_u64 v[138:139], v[212:213], 0, s[6:7]
	s_mov_b32 m0, s53
	s_nop 0
	global_load_lds_dwordx4 v[138:139], off
	s_waitcnt vmcnt(8)
	s_waitcnt lgkmcnt(0)
	s_barrier
	s_setprio 1
	s_waitcnt lgkmcnt(0)
	v_mfma_f32_16x16x32_bf16 v[122:125], v[142:145], v[176:179], v[122:125]
	v_mfma_f32_16x16x32_bf16 v[122:125], v[148:151], v[180:183], v[122:125]
	v_mfma_f32_16x16x32_bf16 v[126:129], v[156:159], v[180:183], v[126:129]
	v_mfma_f32_16x16x32_bf16 v[126:129], v[152:155], v[176:179], v[126:129]
	v_mfma_f32_16x16x32_bf16 v[70:73], v[152:155], v[184:187], v[70:73]
	v_mfma_f32_16x16x32_bf16 v[70:73], v[156:159], v[188:191], v[70:73]
	v_mfma_f32_16x16x32_bf16 v[66:69], v[148:151], v[188:191], v[66:69]
	v_mfma_f32_16x16x32_bf16 v[66:69], v[142:145], v[184:187], v[66:69]
	v_mfma_f32_16x16x32_bf16 v[74:77], v[142:145], v[192:195], v[74:77]
	v_mfma_f32_16x16x32_bf16 v[74:77], v[148:151], v[196:199], v[74:77]
	v_mfma_f32_16x16x32_bf16 v[78:81], v[156:159], v[196:199], v[78:81]
	v_mfma_f32_16x16x32_bf16 v[78:81], v[152:155], v[192:195], v[78:81]
	v_mfma_f32_16x16x32_bf16 v[86:89], v[152:155], v[200:203], v[86:89]
	v_mfma_f32_16x16x32_bf16 v[86:89], v[156:159], v[204:207], v[86:89]
	v_mfma_f32_16x16x32_bf16 v[82:85], v[148:151], v[204:207], v[82:85]
	v_mfma_f32_16x16x32_bf16 v[82:85], v[142:145], v[200:203], v[82:85]
	s_setprio 0
	s_setprio 1
	v_mfma_f32_16x16x32_bf16 v[90:93], v[160:163], v[176:179], v[90:93]
	v_mfma_f32_16x16x32_bf16 v[90:93], v[164:167], v[180:183], v[90:93]
	v_mfma_f32_16x16x32_bf16 v[94:97], v[172:175], v[180:183], v[94:97]
	v_mfma_f32_16x16x32_bf16 v[94:97], v[168:171], v[176:179], v[94:97]
	v_mfma_f32_16x16x32_bf16 v[102:105], v[168:171], v[184:187], v[102:105]
	v_mfma_f32_16x16x32_bf16 v[102:105], v[172:175], v[188:191], v[102:105]
	v_mfma_f32_16x16x32_bf16 v[98:101], v[164:167], v[188:191], v[98:101]
	v_mfma_f32_16x16x32_bf16 v[98:101], v[160:163], v[184:187], v[98:101]
	v_mfma_f32_16x16x32_bf16 v[106:109], v[160:163], v[192:195], v[106:109]
	v_mfma_f32_16x16x32_bf16 v[106:109], v[164:167], v[196:199], v[106:109]
	v_mfma_f32_16x16x32_bf16 v[110:113], v[172:175], v[196:199], v[110:113]
	v_mfma_f32_16x16x32_bf16 v[110:113], v[168:171], v[192:195], v[110:113]
	s_setprio 2
	s_barrier
	v_mfma_f32_16x16x32_bf16 v[118:121], v[168:171], v[200:203], v[118:121]
	v_mfma_f32_16x16x32_bf16 v[118:121], v[172:175], v[204:207], v[118:121]
	v_mfma_f32_16x16x32_bf16 v[114:117], v[164:167], v[204:207], v[114:117]
	v_mfma_f32_16x16x32_bf16 v[114:117], v[160:163], v[200:203], v[114:117]
	s_setprio 0
	s_add_i32 s43, s43, 2
	s_add_u32 s36, s36, 0x100
	s_addc_u32 s37, s37, 0
	s_add_u32 s15, s15, 0x100
	s_addc_u32 s42, s42, 0
	s_cmp_gt_u32 s43, 29
	s_cbranch_scc0 .LBB0_383
	s_and_b64 vcc, exec, s[8:9]
	s_cbranch_vccz .LBB0_386
	s_barrier

.LBB0_462:
	v_add_u32_e32 v14, s54, v140
	v_add_u32_e32 v30, s55, v140
	ds_read_b128 v[2:5], v14
	ds_read_b128 v[6:9], v14 offset:1024
	ds_read_b128 v[10:13], v14 offset:2048
	ds_read_b128 v[14:17], v14 offset:3072
	ds_read_b128 v[18:21], v30
	ds_read_b128 v[22:25], v30 offset:1024
	ds_read_b128 v[26:29], v30 offset:2048
	ds_read_b128 v[30:33], v30 offset:3072
	v_add_u32_e32 v141, 0, v1
	ds_read_b128 v[34:37], v141
	ds_read_b128 v[38:41], v141 offset:1024
	ds_read_b128 v[42:45], v141 offset:2048
	ds_read_b128 v[46:49], v141 offset:3072
	ds_read_b128 v[50:53], v141 offset:4096
	ds_read_b128 v[54:57], v141 offset:5120
	ds_read_b128 v[58:61], v141 offset:6144
	ds_read_b128 v[62:65], v141 offset:7168
	s_waitcnt vmcnt(8)
	s_waitcnt lgkmcnt(0)
	s_barrier
	s_setprio 1
	s_waitcnt lgkmcnt(0)
	v_mfma_f32_16x16x32_bf16 v[66:69], v[2:5], v[34:37], 0
	v_mfma_f32_16x16x32_bf16 v[66:69], v[6:9], v[38:41], v[66:69]
	v_mfma_f32_16x16x32_bf16 v[70:73], v[10:13], v[34:37], 0
	v_mfma_f32_16x16x32_bf16 v[70:73], v[14:17], v[38:41], v[70:73]
	v_mfma_f32_16x16x32_bf16 v[78:81], v[10:13], v[42:45], 0
	v_mfma_f32_16x16x32_bf16 v[78:81], v[14:17], v[46:49], v[78:81]
	v_mfma_f32_16x16x32_bf16 v[74:77], v[2:5], v[42:45], 0
	v_mfma_f32_16x16x32_bf16 v[74:77], v[6:9], v[46:49], v[74:77]
	v_mfma_f32_16x16x32_bf16 v[82:85], v[2:5], v[50:53], 0
	v_mfma_f32_16x16x32_bf16 v[82:85], v[6:9], v[54:57], v[82:85]
	v_mfma_f32_16x16x32_bf16 v[86:89], v[10:13], v[50:53], 0
	v_mfma_f32_16x16x32_bf16 v[86:89], v[14:17], v[54:57], v[86:89]
	v_mfma_f32_16x16x32_bf16 v[94:97], v[10:13], v[58:61], 0
	v_mfma_f32_16x16x32_bf16 v[94:97], v[14:17], v[62:65], v[94:97]
	v_mfma_f32_16x16x32_bf16 v[90:93], v[2:5], v[58:61], 0
	v_mfma_f32_16x16x32_bf16 v[90:93], v[6:9], v[62:65], v[90:93]
	s_setprio 0
	s_setprio 1
	v_mfma_f32_16x16x32_bf16 v[98:101], v[18:21], v[34:37], 0
	v_mfma_f32_16x16x32_bf16 v[34:37], v[26:29], v[34:37], 0
	v_mfma_f32_16x16x32_bf16 v[102:105], v[18:21], v[42:45], 0
	v_mfma_f32_16x16x32_bf16 v[42:45], v[26:29], v[42:45], 0
	v_mfma_f32_16x16x32_bf16 v[106:109], v[18:21], v[50:53], 0
	v_mfma_f32_16x16x32_bf16 v[50:53], v[26:29], v[50:53], 0
	v_mfma_f32_16x16x32_bf16 v[110:113], v[18:21], v[58:61], 0
	v_mfma_f32_16x16x32_bf16 v[58:61], v[26:29], v[58:61], 0
	v_mfma_f32_16x16x32_bf16 v[98:101], v[22:25], v[38:41], v[98:101]
	v_mfma_f32_16x16x32_bf16 v[38:41], v[30:33], v[38:41], v[34:37]
	v_mfma_f32_16x16x32_bf16 v[102:105], v[22:25], v[46:49], v[102:105]
	v_mfma_f32_16x16x32_bf16 v[46:49], v[30:33], v[46:49], v[42:45]
	s_setprio 2
	s_barrier
	v_mfma_f32_16x16x32_bf16 v[106:109], v[22:25], v[54:57], v[106:109]
	v_mfma_f32_16x16x32_bf16 v[54:57], v[30:33], v[54:57], v[50:53]
	v_mfma_f32_16x16x32_bf16 v[110:113], v[22:25], v[62:65], v[110:113]
	v_mfma_f32_16x16x32_bf16 v[62:65], v[30:33], v[62:65], v[58:61]
	s_setprio 0
	v_lshl_add_u64 v[136:137], s[36:37], 0, v[130:131]
	s_add_i32 s62, s54, s21
	v_mov_b32_e32 v135, v131
	v_lshl_add_u64 v[142:143], v[136:137], 0, s[12:13]
	s_mov_b32 m0, s62
	v_lshl_add_u64 v[244:245], s[36:37], 0, v[134:135]
	ds_read_b128 v[34:37], v141 offset:16384
	ds_read_b128 v[42:45], v141 offset:17408
	ds_read_b128 v[50:53], v141 offset:18432
	ds_read_b128 v[58:61], v141 offset:19456
	ds_read_b128 v[114:117], v141 offset:20480
	ds_read_b128 v[118:121], v141 offset:21504
	ds_read_b128 v[122:125], v141 offset:22528
	ds_read_b128 v[126:129], v141 offset:23552
	global_load_lds_dwordx4 v[142:143], off
	v_lshl_add_u64 v[142:143], v[244:245], 0, s[12:13]
	s_add_i32 m0, s62, 0x2000
	s_add_i32 s62, s55, s21
	global_load_lds_dwordx4 v[142:143], off
	s_mov_b32 m0, s62
	v_mov_b32_e32 v139, v131
	global_load_lds_dwordx4 v130, s[38:39]
	s_add_i32 m0, s62, 0x2000
	v_lshl_add_u64 v[246:247], s[34:35], 0, v[138:139]
	v_mov_b32_e32 v133, v131
	global_load_lds_dwordx4 v134, s[38:39]
	v_lshl_add_u64 v[142:143], v[246:247], 0, s[12:13]
	s_mov_b32 m0, s33
	v_lshl_add_u64 v[248:249], s[34:35], 0, v[132:133]
	global_load_lds_dwordx4 v[142:143], off
	v_lshl_add_u64 v[142:143], v[248:249], 0, s[12:13]
	s_mov_b32 m0, s44
	s_nop 0
	global_load_lds_dwordx4 v[142:143], off
	s_waitcnt vmcnt(8)
	s_waitcnt lgkmcnt(0)
	s_barrier
	s_setprio 1
	s_waitcnt lgkmcnt(0)
	v_mfma_f32_16x16x32_bf16 v[142:145], v[2:5], v[34:37], 0
	v_mfma_f32_16x16x32_bf16 v[148:151], v[10:13], v[34:37], 0
	v_mfma_f32_16x16x32_bf16 v[152:155], v[2:5], v[50:53], 0
	v_mfma_f32_16x16x32_bf16 v[156:159], v[10:13], v[50:53], 0
	v_mfma_f32_16x16x32_bf16 v[160:163], v[2:5], v[114:117], 0
	v_mfma_f32_16x16x32_bf16 v[164:167], v[10:13], v[114:117], 0
	v_mfma_f32_16x16x32_bf16 v[2:5], v[2:5], v[122:125], 0
	v_mfma_f32_16x16x32_bf16 v[10:13], v[10:13], v[122:125], 0
	v_mfma_f32_16x16x32_bf16 v[142:145], v[6:9], v[42:45], v[142:145]
	v_mfma_f32_16x16x32_bf16 v[148:151], v[14:17], v[42:45], v[148:151]
	v_mfma_f32_16x16x32_bf16 v[152:155], v[6:9], v[58:61], v[152:155]
	v_mfma_f32_16x16x32_bf16 v[156:159], v[14:17], v[58:61], v[156:159]
	v_mfma_f32_16x16x32_bf16 v[160:163], v[6:9], v[118:121], v[160:163]
	v_mfma_f32_16x16x32_bf16 v[164:167], v[14:17], v[118:121], v[164:167]
	v_mfma_f32_16x16x32_bf16 v[168:171], v[6:9], v[126:129], v[2:5]
	v_mfma_f32_16x16x32_bf16 v[172:175], v[14:17], v[126:129], v[10:13]
	s_setprio 0
	s_setprio 1
	v_mfma_f32_16x16x32_bf16 v[2:5], v[18:21], v[34:37], 0
	v_mfma_f32_16x16x32_bf16 v[6:9], v[26:29], v[34:37], 0
	v_mfma_f32_16x16x32_bf16 v[10:13], v[18:21], v[50:53], 0
	v_mfma_f32_16x16x32_bf16 v[14:17], v[26:29], v[50:53], 0
	v_mfma_f32_16x16x32_bf16 v[34:37], v[18:21], v[114:117], 0
	v_mfma_f32_16x16x32_bf16 v[50:53], v[26:29], v[114:117], 0
	v_mfma_f32_16x16x32_bf16 v[18:21], v[18:21], v[122:125], 0
	v_mfma_f32_16x16x32_bf16 v[26:29], v[26:29], v[122:125], 0
	v_mfma_f32_16x16x32_bf16 v[114:117], v[22:25], v[42:45], v[2:5]
	v_mfma_f32_16x16x32_bf16 v[122:125], v[30:33], v[42:45], v[6:9]
	v_mfma_f32_16x16x32_bf16 v[184:187], v[22:25], v[118:121], v[34:37]
	v_mfma_f32_16x16x32_bf16 v[118:121], v[30:33], v[118:121], v[50:53]
	s_setprio 2
	s_barrier
	v_mfma_f32_16x16x32_bf16 v[188:191], v[22:25], v[126:129], v[18:21]
	v_mfma_f32_16x16x32_bf16 v[126:129], v[30:33], v[126:129], v[26:29]
	v_mfma_f32_16x16x32_bf16 v[176:179], v[22:25], v[58:61], v[10:13]
	v_mfma_f32_16x16x32_bf16 v[180:183], v[30:33], v[58:61], v[14:17]
	s_setprio 0
	s_add_i32 s62, 0, 0x18000
	v_add_u32_e32 v2, s62, v140
	s_add_i32 s63, 0, 0x1c000
	ds_read_b128 v[192:195], v2
	ds_read_b128 v[196:199], v2 offset:1024
	ds_read_b128 v[200:203], v2 offset:2048
	ds_read_b128 v[204:207], v2 offset:3072
	v_add_u32_e32 v2, s63, v140
	ds_read_b128 v[208:211], v2
	ds_read_b128 v[212:215], v2 offset:1024
	ds_read_b128 v[216:219], v2 offset:2048
	ds_read_b128 v[220:223], v2 offset:3072
	s_mov_b32 m0, s45
	ds_read_b128 v[42:45], v141 offset:32768
	ds_read_b128 v[50:53], v141 offset:33792
	ds_read_b128 v[58:61], v141 offset:34816
	ds_read_b128 v[224:227], v141 offset:35840
	ds_read_b128 v[228:231], v141 offset:36864
	ds_read_b128 v[232:235], v141 offset:37888
	ds_read_b128 v[236:239], v141 offset:38912
	ds_read_b128 v[240:243], v141 offset:39936
	global_load_lds_dwordx4 v138, s[40:41]
	s_mov_b32 m0, s46
	s_nop 0
	global_load_lds_dwordx4 v132, s[40:41]
	s_waitcnt vmcnt(8)
	s_waitcnt lgkmcnt(0)
	s_barrier
	s_setprio 1
	s_waitcnt lgkmcnt(0)
	v_mfma_f32_16x16x32_bf16 v[2:5], v[192:195], v[42:45], v[66:69]
	v_mfma_f32_16x16x32_bf16 v[6:9], v[200:203], v[42:45], v[70:73]
	v_mfma_f32_16x16x32_bf16 v[10:13], v[192:195], v[58:61], v[74:77]
	v_mfma_f32_16x16x32_bf16 v[14:17], v[200:203], v[58:61], v[78:81]
	v_mfma_f32_16x16x32_bf16 v[18:21], v[192:195], v[228:231], v[82:85]
	v_mfma_f32_16x16x32_bf16 v[22:25], v[200:203], v[228:231], v[86:89]
	v_mfma_f32_16x16x32_bf16 v[26:29], v[192:195], v[236:239], v[90:93]
	v_mfma_f32_16x16x32_bf16 v[30:33], v[200:203], v[236:239], v[94:97]
	v_mfma_f32_16x16x32_bf16 v[2:5], v[196:199], v[50:53], v[2:5]
	v_mfma_f32_16x16x32_bf16 v[6:9], v[204:207], v[50:53], v[6:9]
	v_mfma_f32_16x16x32_bf16 v[10:13], v[196:199], v[224:227], v[10:13]
	v_mfma_f32_16x16x32_bf16 v[14:17], v[204:207], v[224:227], v[14:17]
	v_mfma_f32_16x16x32_bf16 v[18:21], v[196:199], v[232:235], v[18:21]
	v_mfma_f32_16x16x32_bf16 v[22:25], v[204:207], v[232:235], v[22:25]
	v_mfma_f32_16x16x32_bf16 v[26:29], v[196:199], v[240:243], v[26:29]
	v_mfma_f32_16x16x32_bf16 v[30:33], v[204:207], v[240:243], v[30:33]
	s_setprio 0
	s_setprio 1
	v_mfma_f32_16x16x32_bf16 v[34:37], v[208:211], v[42:45], v[98:101]
	v_mfma_f32_16x16x32_bf16 v[38:41], v[216:219], v[42:45], v[38:41]
	v_mfma_f32_16x16x32_bf16 v[34:37], v[212:215], v[50:53], v[34:37]
	v_mfma_f32_16x16x32_bf16 v[38:41], v[220:223], v[50:53], v[38:41]
	v_mfma_f32_16x16x32_bf16 v[42:45], v[208:211], v[58:61], v[102:105]
	v_mfma_f32_16x16x32_bf16 v[46:49], v[216:219], v[58:61], v[46:49]
	v_mfma_f32_16x16x32_bf16 v[50:53], v[208:211], v[228:231], v[106:109]
	v_mfma_f32_16x16x32_bf16 v[54:57], v[216:219], v[228:231], v[54:57]
	v_mfma_f32_16x16x32_bf16 v[58:61], v[208:211], v[236:239], v[110:113]
	v_mfma_f32_16x16x32_bf16 v[62:65], v[216:219], v[236:239], v[62:65]
	v_mfma_f32_16x16x32_bf16 v[42:45], v[212:215], v[224:227], v[42:45]
	v_mfma_f32_16x16x32_bf16 v[46:49], v[220:223], v[224:227], v[46:49]
	s_setprio 2
	s_barrier
	v_mfma_f32_16x16x32_bf16 v[50:53], v[212:215], v[232:235], v[50:53]
	v_mfma_f32_16x16x32_bf16 v[54:57], v[220:223], v[232:235], v[54:57]
	v_mfma_f32_16x16x32_bf16 v[58:61], v[212:215], v[240:243], v[58:61]
	v_mfma_f32_16x16x32_bf16 v[62:65], v[220:223], v[240:243], v[62:65]
	s_setprio 0
	s_add_i32 s62, s62, s21
	v_lshl_add_u64 v[66:67], v[136:137], 0, s[14:15]
	s_mov_b32 m0, s62
	ds_read_b128 v[102:105], v141 offset:49152
	ds_read_b128 v[106:109], v141 offset:50176
	ds_read_b128 v[110:113], v141 offset:51200
	ds_read_b128 v[224:227], v141 offset:52224
	ds_read_b128 v[228:231], v141 offset:53248
	ds_read_b128 v[232:235], v141 offset:54272
	ds_read_b128 v[236:239], v141 offset:55296
	ds_read_b128 v[240:243], v141 offset:56320
	global_load_lds_dwordx4 v[66:67], off
	v_lshl_add_u64 v[66:67], v[244:245], 0, s[14:15]
	s_add_i32 m0, s62, 0x2000
	s_add_i32 s62, s63, s21
	global_load_lds_dwordx4 v[66:67], off
	s_mov_b32 m0, s62
	v_lshl_add_u64 v[66:67], v[246:247], 0, s[14:15]
	global_load_lds_dwordx4 v130, s[42:43]
	s_add_i32 m0, s62, 0x2000
	s_nop 0
	global_load_lds_dwordx4 v134, s[42:43]
	s_mov_b32 m0, s50
	s_nop 0
	global_load_lds_dwordx4 v[66:67], off
	v_lshl_add_u64 v[66:67], v[248:249], 0, s[14:15]
	s_mov_b32 m0, s51
	s_nop 0
	global_load_lds_dwordx4 v[66:67], off
	s_waitcnt vmcnt(8)
	s_waitcnt lgkmcnt(0)
	s_barrier
	s_setprio 1
	s_waitcnt lgkmcnt(0)
	v_mfma_f32_16x16x32_bf16 v[66:69], v[192:195], v[102:105], v[142:145]
	v_mfma_f32_16x16x32_bf16 v[70:73], v[200:203], v[102:105], v[148:151]
	v_mfma_f32_16x16x32_bf16 v[74:77], v[192:195], v[110:113], v[152:155]
	v_mfma_f32_16x16x32_bf16 v[78:81], v[200:203], v[110:113], v[156:159]
	v_mfma_f32_16x16x32_bf16 v[82:85], v[192:195], v[228:231], v[160:163]
	v_mfma_f32_16x16x32_bf16 v[86:89], v[200:203], v[228:231], v[164:167]
	v_mfma_f32_16x16x32_bf16 v[90:93], v[192:195], v[236:239], v[168:171]
	v_mfma_f32_16x16x32_bf16 v[94:97], v[200:203], v[236:239], v[172:175]
	v_mfma_f32_16x16x32_bf16 v[66:69], v[196:199], v[106:109], v[66:69]
	v_mfma_f32_16x16x32_bf16 v[70:73], v[204:207], v[106:109], v[70:73]
	v_mfma_f32_16x16x32_bf16 v[74:77], v[196:199], v[224:227], v[74:77]
	v_mfma_f32_16x16x32_bf16 v[78:81], v[204:207], v[224:227], v[78:81]
	v_mfma_f32_16x16x32_bf16 v[82:85], v[196:199], v[232:235], v[82:85]
	v_mfma_f32_16x16x32_bf16 v[86:89], v[204:207], v[232:235], v[86:89]
	v_mfma_f32_16x16x32_bf16 v[90:93], v[196:199], v[240:243], v[90:93]
	v_mfma_f32_16x16x32_bf16 v[94:97], v[204:207], v[240:243], v[94:97]
	s_setprio 0
	s_setprio 1
	v_mfma_f32_16x16x32_bf16 v[98:101], v[208:211], v[102:105], v[114:117]
	v_mfma_f32_16x16x32_bf16 v[102:105], v[216:219], v[102:105], v[122:125]
	v_mfma_f32_16x16x32_bf16 v[98:101], v[212:215], v[106:109], v[98:101]
	v_mfma_f32_16x16x32_bf16 v[102:105], v[220:223], v[106:109], v[102:105]
	v_mfma_f32_16x16x32_bf16 v[106:109], v[208:211], v[110:113], v[176:179]
	v_mfma_f32_16x16x32_bf16 v[110:113], v[216:219], v[110:113], v[180:183]
	v_mfma_f32_16x16x32_bf16 v[114:117], v[208:211], v[228:231], v[184:187]
	v_mfma_f32_16x16x32_bf16 v[118:121], v[216:219], v[228:231], v[118:121]
	v_mfma_f32_16x16x32_bf16 v[122:125], v[208:211], v[236:239], v[188:191]
	v_mfma_f32_16x16x32_bf16 v[126:129], v[216:219], v[236:239], v[126:129]
	v_mfma_f32_16x16x32_bf16 v[106:109], v[212:215], v[224:227], v[106:109]
	v_mfma_f32_16x16x32_bf16 v[110:113], v[220:223], v[224:227], v[110:113]
	s_setprio 2
	s_barrier
	v_mfma_f32_16x16x32_bf16 v[114:117], v[212:215], v[232:235], v[114:117]
	v_mfma_f32_16x16x32_bf16 v[118:121], v[220:223], v[232:235], v[118:121]
	v_mfma_f32_16x16x32_bf16 v[122:125], v[212:215], v[240:243], v[122:125]
	v_mfma_f32_16x16x32_bf16 v[126:129], v[220:223], v[240:243], v[126:129]
	s_setprio 0
	s_add_i32 s61, s61, 2
	s_cmp_ge_i32 s61, s60
	s_cbranch_scc0 .LBB0_462
	v_mov_b32_e32 v136, v130
	s_branch .LBB0_465

.LBB0_466:
	v_add_u32_e32 v133, s54, v140
	ds_read_b128 v[142:145], v133
	ds_read_b128 v[148:151], v133 offset:1024
	ds_read_b128 v[152:155], v133 offset:2048
	ds_read_b128 v[156:159], v133 offset:3072
	v_add_u32_e32 v133, s55, v140
	ds_read_b128 v[160:163], v133
	ds_read_b128 v[164:167], v133 offset:1024
	ds_read_b128 v[168:171], v133 offset:2048
	ds_read_b128 v[172:175], v133 offset:3072
	s_add_u32 s36, s34, 0xffc00080
	s_addc_u32 s37, s35, -1
	s_cmp_eq_u32 s42, 4
	s_cselect_b32 s39, s29, s37
	s_cselect_b32 s38, s28, s36
	s_cselect_b32 s37, s31, s41
	s_cselect_b32 s36, s30, s40
	s_mov_b32 m0, s52
	v_add_u32_e32 v141, 0, v1
	ds_read_b128 v[176:179], v141
	ds_read_b128 v[180:183], v141 offset:1024
	ds_read_b128 v[184:187], v141 offset:2048
	ds_read_b128 v[188:191], v141 offset:3072
	ds_read_b128 v[192:195], v141 offset:4096
	ds_read_b128 v[196:199], v141 offset:5120
	ds_read_b128 v[200:203], v141 offset:6144
	ds_read_b128 v[204:207], v141 offset:7168
	global_load_lds_dwordx4 v130, s[34:35]
	s_mov_b32 m0, s53
	v_mov_b32_e32 v133, v131
	global_load_lds_dwordx4 v132, s[34:35]
	s_waitcnt vmcnt(8)
	s_waitcnt lgkmcnt(0)
	s_barrier
	s_setprio 1
	s_waitcnt lgkmcnt(0)
	v_mfma_f32_16x16x32_bf16 v[2:5], v[142:145], v[176:179], v[2:5]
	v_mfma_f32_16x16x32_bf16 v[2:5], v[148:151], v[180:183], v[2:5]
	v_mfma_f32_16x16x32_bf16 v[6:9], v[156:159], v[180:183], v[6:9]
	v_mfma_f32_16x16x32_bf16 v[6:9], v[152:155], v[176:179], v[6:9]
	v_mfma_f32_16x16x32_bf16 v[14:17], v[152:155], v[184:187], v[14:17]
	v_mfma_f32_16x16x32_bf16 v[14:17], v[156:159], v[188:191], v[14:17]
	v_mfma_f32_16x16x32_bf16 v[10:13], v[148:151], v[188:191], v[10:13]
	v_mfma_f32_16x16x32_bf16 v[10:13], v[142:145], v[184:187], v[10:13]
	v_mfma_f32_16x16x32_bf16 v[18:21], v[142:145], v[192:195], v[18:21]
	v_mfma_f32_16x16x32_bf16 v[18:21], v[148:151], v[196:199], v[18:21]
	v_mfma_f32_16x16x32_bf16 v[22:25], v[156:159], v[196:199], v[22:25]
	v_mfma_f32_16x16x32_bf16 v[22:25], v[152:155], v[192:195], v[22:25]
	v_mfma_f32_16x16x32_bf16 v[30:33], v[152:155], v[200:203], v[30:33]
	v_mfma_f32_16x16x32_bf16 v[30:33], v[156:159], v[204:207], v[30:33]
	v_mfma_f32_16x16x32_bf16 v[26:29], v[148:151], v[204:207], v[26:29]
	v_mfma_f32_16x16x32_bf16 v[26:29], v[142:145], v[200:203], v[26:29]
	s_setprio 0
	s_setprio 1
	v_mfma_f32_16x16x32_bf16 v[34:37], v[160:163], v[176:179], v[34:37]
	v_mfma_f32_16x16x32_bf16 v[34:37], v[164:167], v[180:183], v[34:37]
	v_mfma_f32_16x16x32_bf16 v[38:41], v[172:175], v[180:183], v[38:41]
	v_mfma_f32_16x16x32_bf16 v[38:41], v[168:171], v[176:179], v[38:41]
	v_mfma_f32_16x16x32_bf16 v[46:49], v[168:171], v[184:187], v[46:49]
	v_mfma_f32_16x16x32_bf16 v[46:49], v[172:175], v[188:191], v[46:49]
	v_mfma_f32_16x16x32_bf16 v[42:45], v[164:167], v[188:191], v[42:45]
	v_mfma_f32_16x16x32_bf16 v[42:45], v[160:163], v[184:187], v[42:45]
	v_mfma_f32_16x16x32_bf16 v[50:53], v[160:163], v[192:195], v[50:53]
	v_mfma_f32_16x16x32_bf16 v[50:53], v[164:167], v[196:199], v[50:53]
	v_mfma_f32_16x16x32_bf16 v[54:57], v[172:175], v[196:199], v[54:57]
	v_mfma_f32_16x16x32_bf16 v[54:57], v[168:171], v[192:195], v[54:57]
	s_setprio 2
	s_barrier
	v_mfma_f32_16x16x32_bf16 v[62:65], v[168:171], v[200:203], v[62:65]
	v_mfma_f32_16x16x32_bf16 v[62:65], v[172:175], v[204:207], v[62:65]
	v_mfma_f32_16x16x32_bf16 v[58:61], v[164:167], v[204:207], v[58:61]
	v_mfma_f32_16x16x32_bf16 v[58:61], v[160:163], v[200:203], v[58:61]
	s_setprio 0
	s_add_i32 s43, s54, s21
	s_mov_b32 m0, s43
	ds_read_b128 v[176:179], v141 offset:16384
	ds_read_b128 v[180:183], v141 offset:17408
	ds_read_b128 v[184:187], v141 offset:18432
	ds_read_b128 v[188:191], v141 offset:19456
	ds_read_b128 v[192:195], v141 offset:20480
	ds_read_b128 v[196:199], v141 offset:21504
	ds_read_b128 v[200:203], v141 offset:22528
	ds_read_b128 v[204:207], v141 offset:23552
	global_load_lds_dwordx4 v136, s[36:37]
	s_add_i32 m0, s43, 0x2000
	s_add_u32 s60, s36, 0x80000
	s_addc_u32 s61, s37, 0
	s_add_i32 s43, s55, s21
	global_load_lds_dwordx4 v134, s[36:37]
	s_mov_b32 m0, s43
	v_mov_b32_e32 v137, v131
	global_load_lds_dwordx4 v136, s[60:61]
	s_add_i32 m0, s43, 0x2000
	v_mov_b32_e32 v135, v131
	global_load_lds_dwordx4 v134, s[60:61]
	s_mov_b32 m0, s33
	v_lshl_add_u64 v[138:139], s[36:37], 0, v[136:137]
	global_load_lds_dwordx4 v130, s[38:39]
	s_mov_b32 m0, s44
	v_lshl_add_u64 v[208:209], s[36:37], 0, v[134:135]
	global_load_lds_dwordx4 v132, s[38:39]
	s_waitcnt vmcnt(8)
	s_waitcnt lgkmcnt(0)
	v_lshl_add_u64 v[210:211], s[38:39], 0, v[130:131]
	v_lshl_add_u64 v[212:213], s[38:39], 0, v[132:133]
	s_barrier
	s_setprio 1
	s_waitcnt lgkmcnt(0)
	v_mfma_f32_16x16x32_bf16 v[66:69], v[142:145], v[176:179], v[66:69]
	v_mfma_f32_16x16x32_bf16 v[66:69], v[148:151], v[180:183], v[66:69]
	v_mfma_f32_16x16x32_bf16 v[70:73], v[156:159], v[180:183], v[70:73]
	v_mfma_f32_16x16x32_bf16 v[70:73], v[152:155], v[176:179], v[70:73]
	v_mfma_f32_16x16x32_bf16 v[78:81], v[152:155], v[184:187], v[78:81]
	v_mfma_f32_16x16x32_bf16 v[78:81], v[156:159], v[188:191], v[78:81]
	v_mfma_f32_16x16x32_bf16 v[74:77], v[148:151], v[188:191], v[74:77]
	v_mfma_f32_16x16x32_bf16 v[74:77], v[142:145], v[184:187], v[74:77]
	v_mfma_f32_16x16x32_bf16 v[82:85], v[142:145], v[192:195], v[82:85]
	v_mfma_f32_16x16x32_bf16 v[82:85], v[148:151], v[196:199], v[82:85]
	v_mfma_f32_16x16x32_bf16 v[86:89], v[156:159], v[196:199], v[86:89]
	v_mfma_f32_16x16x32_bf16 v[86:89], v[152:155], v[192:195], v[86:89]
	v_mfma_f32_16x16x32_bf16 v[94:97], v[152:155], v[200:203], v[94:97]
	v_mfma_f32_16x16x32_bf16 v[94:97], v[156:159], v[204:207], v[94:97]
	v_mfma_f32_16x16x32_bf16 v[90:93], v[148:151], v[204:207], v[90:93]
	v_mfma_f32_16x16x32_bf16 v[90:93], v[142:145], v[200:203], v[90:93]
	s_setprio 0
	s_setprio 1
	v_mfma_f32_16x16x32_bf16 v[98:101], v[160:163], v[176:179], v[98:101]
	v_mfma_f32_16x16x32_bf16 v[98:101], v[164:167], v[180:183], v[98:101]
	v_mfma_f32_16x16x32_bf16 v[102:105], v[172:175], v[180:183], v[102:105]
	v_mfma_f32_16x16x32_bf16 v[102:105], v[168:171], v[176:179], v[102:105]
	v_mfma_f32_16x16x32_bf16 v[110:113], v[168:171], v[184:187], v[110:113]
	v_mfma_f32_16x16x32_bf16 v[110:113], v[172:175], v[188:191], v[110:113]
	v_mfma_f32_16x16x32_bf16 v[106:109], v[164:167], v[188:191], v[106:109]
	v_mfma_f32_16x16x32_bf16 v[106:109], v[160:163], v[184:187], v[106:109]
	v_mfma_f32_16x16x32_bf16 v[114:117], v[160:163], v[192:195], v[114:117]
	v_mfma_f32_16x16x32_bf16 v[114:117], v[164:167], v[196:199], v[114:117]
	v_mfma_f32_16x16x32_bf16 v[118:121], v[172:175], v[196:199], v[118:121]
	v_mfma_f32_16x16x32_bf16 v[118:121], v[168:171], v[192:195], v[118:121]
	s_setprio 2
	s_barrier
	v_mfma_f32_16x16x32_bf16 v[126:129], v[168:171], v[200:203], v[126:129]
	v_mfma_f32_16x16x32_bf16 v[126:129], v[172:175], v[204:207], v[126:129]
	v_mfma_f32_16x16x32_bf16 v[122:125], v[164:167], v[204:207], v[122:125]
	v_mfma_f32_16x16x32_bf16 v[122:125], v[160:163], v[200:203], v[122:125]
	s_setprio 0
	s_add_i32 s43, 0, 0x18000
	v_add_u32_e32 v135, s43, v140
	s_add_i32 s60, 0, 0x1c000
	ds_read_b128 v[142:145], v135
	ds_read_b128 v[148:151], v135 offset:1024
	ds_read_b128 v[152:155], v135 offset:2048
	ds_read_b128 v[156:159], v135 offset:3072
	v_add_u32_e32 v135, s60, v140
	ds_read_b128 v[160:163], v135
	ds_read_b128 v[164:167], v135 offset:1024
	ds_read_b128 v[168:171], v135 offset:2048
	ds_read_b128 v[172:175], v135 offset:3072
	s_add_u32 s38, s38, 0x400000
	s_addc_u32 s39, s39, 0
	s_mov_b32 m0, s45
	ds_read_b128 v[176:179], v141 offset:32768
	ds_read_b128 v[180:183], v141 offset:33792
	ds_read_b128 v[184:187], v141 offset:34816
	ds_read_b128 v[188:191], v141 offset:35840
	ds_read_b128 v[192:195], v141 offset:36864
	ds_read_b128 v[196:199], v141 offset:37888
	ds_read_b128 v[200:203], v141 offset:38912
	ds_read_b128 v[204:207], v141 offset:39936
	global_load_lds_dwordx4 v130, s[38:39]
	s_mov_b32 m0, s46
	s_nop 0
	global_load_lds_dwordx4 v132, s[38:39]
	s_waitcnt vmcnt(8)
	s_waitcnt lgkmcnt(0)
	s_barrier
	s_setprio 1
	s_waitcnt lgkmcnt(0)
	v_mfma_f32_16x16x32_bf16 v[2:5], v[142:145], v[176:179], v[2:5]
	v_mfma_f32_16x16x32_bf16 v[2:5], v[148:151], v[180:183], v[2:5]
	v_mfma_f32_16x16x32_bf16 v[6:9], v[156:159], v[180:183], v[6:9]
	v_mfma_f32_16x16x32_bf16 v[6:9], v[152:155], v[176:179], v[6:9]
	v_mfma_f32_16x16x32_bf16 v[14:17], v[152:155], v[184:187], v[14:17]
	v_mfma_f32_16x16x32_bf16 v[14:17], v[156:159], v[188:191], v[14:17]
	v_mfma_f32_16x16x32_bf16 v[10:13], v[148:151], v[188:191], v[10:13]
	v_mfma_f32_16x16x32_bf16 v[10:13], v[142:145], v[184:187], v[10:13]
	v_mfma_f32_16x16x32_bf16 v[18:21], v[142:145], v[192:195], v[18:21]
	v_mfma_f32_16x16x32_bf16 v[18:21], v[148:151], v[196:199], v[18:21]
	v_mfma_f32_16x16x32_bf16 v[22:25], v[156:159], v[196:199], v[22:25]
	v_mfma_f32_16x16x32_bf16 v[22:25], v[152:155], v[192:195], v[22:25]
	v_mfma_f32_16x16x32_bf16 v[30:33], v[152:155], v[200:203], v[30:33]
	v_mfma_f32_16x16x32_bf16 v[30:33], v[156:159], v[204:207], v[30:33]
	v_mfma_f32_16x16x32_bf16 v[26:29], v[148:151], v[204:207], v[26:29]
	v_mfma_f32_16x16x32_bf16 v[26:29], v[142:145], v[200:203], v[26:29]
	s_setprio 0
	s_setprio 1
	v_mfma_f32_16x16x32_bf16 v[34:37], v[160:163], v[176:179], v[34:37]
	v_mfma_f32_16x16x32_bf16 v[34:37], v[164:167], v[180:183], v[34:37]
	v_mfma_f32_16x16x32_bf16 v[38:41], v[172:175], v[180:183], v[38:41]
	v_mfma_f32_16x16x32_bf16 v[38:41], v[168:171], v[176:179], v[38:41]
	v_mfma_f32_16x16x32_bf16 v[46:49], v[168:171], v[184:187], v[46:49]
	v_mfma_f32_16x16x32_bf16 v[46:49], v[172:175], v[188:191], v[46:49]
	v_mfma_f32_16x16x32_bf16 v[42:45], v[164:167], v[188:191], v[42:45]
	v_mfma_f32_16x16x32_bf16 v[42:45], v[160:163], v[184:187], v[42:45]
	v_mfma_f32_16x16x32_bf16 v[50:53], v[160:163], v[192:195], v[50:53]
	v_mfma_f32_16x16x32_bf16 v[50:53], v[164:167], v[196:199], v[50:53]
	v_mfma_f32_16x16x32_bf16 v[54:57], v[172:175], v[196:199], v[54:57]
	v_mfma_f32_16x16x32_bf16 v[54:57], v[168:171], v[192:195], v[54:57]
	s_setprio 2
	s_barrier
	v_mfma_f32_16x16x32_bf16 v[62:65], v[168:171], v[200:203], v[62:65]
	v_mfma_f32_16x16x32_bf16 v[62:65], v[172:175], v[204:207], v[62:65]
	v_mfma_f32_16x16x32_bf16 v[58:61], v[164:167], v[204:207], v[58:61]
	v_mfma_f32_16x16x32_bf16 v[58:61], v[160:163], v[200:203], v[58:61]
	s_setprio 0
	s_add_i32 s38, s43, s21
	v_lshl_add_u64 v[138:139], v[138:139], 0, s[8:9]
	s_mov_b32 m0, s38
	ds_read_b128 v[176:179], v141 offset:49152
	ds_read_b128 v[180:183], v141 offset:50176
	ds_read_b128 v[184:187], v141 offset:51200
	ds_read_b128 v[188:191], v141 offset:52224
	ds_read_b128 v[192:195], v141 offset:53248
	ds_read_b128 v[196:199], v141 offset:54272
	ds_read_b128 v[200:203], v141 offset:55296
	ds_read_b128 v[204:207], v141 offset:56320
	global_load_lds_dwordx4 v[138:139], off
	s_add_i32 m0, s38, 0x2000
	s_add_u32 s36, s36, 0x80080
	v_lshl_add_u64 v[138:139], v[208:209], 0, s[8:9]
	s_addc_u32 s37, s37, 0
	s_add_i32 s38, s60, s21
	global_load_lds_dwordx4 v[138:139], off
	s_mov_b32 m0, s38
	v_lshl_add_u64 v[138:139], v[210:211], 0, s[8:9]
	global_load_lds_dwordx4 v136, s[36:37]
	s_add_i32 m0, s38, 0x2000
	s_nop 0
	global_load_lds_dwordx4 v134, s[36:37]
	s_mov_b32 m0, s50
	s_nop 0
	global_load_lds_dwordx4 v[138:139], off
	v_lshl_add_u64 v[138:139], v[212:213], 0, s[8:9]
	s_mov_b32 m0, s51
	s_nop 0
	global_load_lds_dwordx4 v[138:139], off
	s_waitcnt vmcnt(8)
	s_waitcnt lgkmcnt(0)
	s_barrier
	s_setprio 1
	s_waitcnt lgkmcnt(0)
	v_mfma_f32_16x16x32_bf16 v[66:69], v[142:145], v[176:179], v[66:69]
	v_mfma_f32_16x16x32_bf16 v[66:69], v[148:151], v[180:183], v[66:69]
	v_mfma_f32_16x16x32_bf16 v[70:73], v[156:159], v[180:183], v[70:73]
	v_mfma_f32_16x16x32_bf16 v[70:73], v[152:155], v[176:179], v[70:73]
	v_mfma_f32_16x16x32_bf16 v[78:81], v[152:155], v[184:187], v[78:81]
	v_mfma_f32_16x16x32_bf16 v[78:81], v[156:159], v[188:191], v[78:81]
	v_mfma_f32_16x16x32_bf16 v[74:77], v[148:151], v[188:191], v[74:77]
	v_mfma_f32_16x16x32_bf16 v[74:77], v[142:145], v[184:187], v[74:77]
	v_mfma_f32_16x16x32_bf16 v[82:85], v[142:145], v[192:195], v[82:85]
	v_mfma_f32_16x16x32_bf16 v[82:85], v[148:151], v[196:199], v[82:85]
	v_mfma_f32_16x16x32_bf16 v[86:89], v[156:159], v[196:199], v[86:89]
	v_mfma_f32_16x16x32_bf16 v[86:89], v[152:155], v[192:195], v[86:89]
	v_mfma_f32_16x16x32_bf16 v[94:97], v[152:155], v[200:203], v[94:97]
	v_mfma_f32_16x16x32_bf16 v[94:97], v[156:159], v[204:207], v[94:97]
	v_mfma_f32_16x16x32_bf16 v[90:93], v[148:151], v[204:207], v[90:93]
	v_mfma_f32_16x16x32_bf16 v[90:93], v[142:145], v[200:203], v[90:93]
	s_setprio 0
	s_setprio 1
	v_mfma_f32_16x16x32_bf16 v[98:101], v[160:163], v[176:179], v[98:101]
	v_mfma_f32_16x16x32_bf16 v[98:101], v[164:167], v[180:183], v[98:101]
	v_mfma_f32_16x16x32_bf16 v[102:105], v[172:175], v[180:183], v[102:105]
	v_mfma_f32_16x16x32_bf16 v[102:105], v[168:171], v[176:179], v[102:105]
	v_mfma_f32_16x16x32_bf16 v[110:113], v[168:171], v[184:187], v[110:113]
	v_mfma_f32_16x16x32_bf16 v[110:113], v[172:175], v[188:191], v[110:113]
	v_mfma_f32_16x16x32_bf16 v[106:109], v[164:167], v[188:191], v[106:109]
	v_mfma_f32_16x16x32_bf16 v[106:109], v[160:163], v[184:187], v[106:109]
	v_mfma_f32_16x16x32_bf16 v[114:117], v[160:163], v[192:195], v[114:117]
	v_mfma_f32_16x16x32_bf16 v[114:117], v[164:167], v[196:199], v[114:117]
	v_mfma_f32_16x16x32_bf16 v[118:121], v[172:175], v[196:199], v[118:121]
	v_mfma_f32_16x16x32_bf16 v[118:121], v[168:171], v[192:195], v[118:121]
	s_setprio 2
	s_barrier
	v_mfma_f32_16x16x32_bf16 v[126:129], v[168:171], v[200:203], v[126:129]
	v_mfma_f32_16x16x32_bf16 v[126:129], v[172:175], v[204:207], v[126:129]
	v_mfma_f32_16x16x32_bf16 v[122:125], v[164:167], v[204:207], v[122:125]
	v_mfma_f32_16x16x32_bf16 v[122:125], v[160:163], v[200:203], v[122:125]
	s_setprio 0
	s_add_i32 s42, s42, 2
	s_add_u32 s34, s34, 0x100
	s_addc_u32 s35, s35, 0
	s_add_u32 s40, s40, 0x100
	s_addc_u32 s41, s41, 0
	s_cmp_gt_u32 s42, 5
	s_cbranch_scc0 .LBB0_466
	s_and_b64 vcc, exec, s[10:11]
	s_cbranch_vccz .LBB0_469
	s_barrier

.LBB0_495:
	v_add_u32_e32 v14, s58, v140
	v_add_u32_e32 v30, s59, v140
	ds_read_b128 v[2:5], v14
	ds_read_b128 v[6:9], v14 offset:1024
	ds_read_b128 v[10:13], v14 offset:2048
	ds_read_b128 v[14:17], v14 offset:3072
	ds_read_b128 v[18:21], v30
	ds_read_b128 v[22:25], v30 offset:1024
	ds_read_b128 v[26:29], v30 offset:2048
	ds_read_b128 v[30:33], v30 offset:3072
	v_add_u32_e32 v141, 0, v1
	ds_read_b128 v[34:37], v141
	ds_read_b128 v[38:41], v141 offset:1024
	ds_read_b128 v[42:45], v141 offset:2048
	ds_read_b128 v[46:49], v141 offset:3072
	ds_read_b128 v[50:53], v141 offset:4096
	ds_read_b128 v[54:57], v141 offset:5120
	ds_read_b128 v[58:61], v141 offset:6144
	ds_read_b128 v[62:65], v141 offset:7168
	s_waitcnt vmcnt(8)
	s_waitcnt lgkmcnt(0)
	s_barrier
	s_setprio 1
	s_waitcnt lgkmcnt(0)
	v_mfma_f32_16x16x32_bf16 v[66:69], v[2:5], v[34:37], 0
	v_mfma_f32_16x16x32_bf16 v[66:69], v[6:9], v[38:41], v[66:69]
	v_mfma_f32_16x16x32_bf16 v[70:73], v[10:13], v[34:37], 0
	v_mfma_f32_16x16x32_bf16 v[70:73], v[14:17], v[38:41], v[70:73]
	v_mfma_f32_16x16x32_bf16 v[78:81], v[10:13], v[42:45], 0
	v_mfma_f32_16x16x32_bf16 v[78:81], v[14:17], v[46:49], v[78:81]
	v_mfma_f32_16x16x32_bf16 v[74:77], v[2:5], v[42:45], 0
	v_mfma_f32_16x16x32_bf16 v[74:77], v[6:9], v[46:49], v[74:77]
	v_mfma_f32_16x16x32_bf16 v[82:85], v[2:5], v[50:53], 0
	v_mfma_f32_16x16x32_bf16 v[82:85], v[6:9], v[54:57], v[82:85]
	v_mfma_f32_16x16x32_bf16 v[86:89], v[10:13], v[50:53], 0
	v_mfma_f32_16x16x32_bf16 v[86:89], v[14:17], v[54:57], v[86:89]
	v_mfma_f32_16x16x32_bf16 v[94:97], v[10:13], v[58:61], 0
	v_mfma_f32_16x16x32_bf16 v[94:97], v[14:17], v[62:65], v[94:97]
	v_mfma_f32_16x16x32_bf16 v[90:93], v[2:5], v[58:61], 0
	v_mfma_f32_16x16x32_bf16 v[90:93], v[6:9], v[62:65], v[90:93]
	s_setprio 0
	s_setprio 1
	v_mfma_f32_16x16x32_bf16 v[98:101], v[18:21], v[34:37], 0
	v_mfma_f32_16x16x32_bf16 v[34:37], v[26:29], v[34:37], 0
	v_mfma_f32_16x16x32_bf16 v[102:105], v[18:21], v[42:45], 0
	v_mfma_f32_16x16x32_bf16 v[42:45], v[26:29], v[42:45], 0
	v_mfma_f32_16x16x32_bf16 v[106:109], v[18:21], v[50:53], 0
	v_mfma_f32_16x16x32_bf16 v[50:53], v[26:29], v[50:53], 0
	v_mfma_f32_16x16x32_bf16 v[110:113], v[18:21], v[58:61], 0
	v_mfma_f32_16x16x32_bf16 v[58:61], v[26:29], v[58:61], 0
	v_mfma_f32_16x16x32_bf16 v[98:101], v[22:25], v[38:41], v[98:101]
	v_mfma_f32_16x16x32_bf16 v[38:41], v[30:33], v[38:41], v[34:37]
	v_mfma_f32_16x16x32_bf16 v[102:105], v[22:25], v[46:49], v[102:105]
	v_mfma_f32_16x16x32_bf16 v[46:49], v[30:33], v[46:49], v[42:45]
	s_setprio 2
	s_barrier
	v_mfma_f32_16x16x32_bf16 v[106:109], v[22:25], v[54:57], v[106:109]
	v_mfma_f32_16x16x32_bf16 v[54:57], v[30:33], v[54:57], v[50:53]
	v_mfma_f32_16x16x32_bf16 v[110:113], v[22:25], v[62:65], v[110:113]
	v_mfma_f32_16x16x32_bf16 v[62:65], v[30:33], v[62:65], v[58:61]
	s_setprio 0
	v_lshl_add_u64 v[136:137], s[38:39], 0, v[130:131]
	s_add_i32 s62, s58, s46
	v_mov_b32_e32 v135, v131
	v_lshl_add_u64 v[142:143], v[136:137], 0, s[10:11]
	s_mov_b32 m0, s62
	v_lshl_add_u64 v[244:245], s[38:39], 0, v[134:135]
	ds_read_b128 v[34:37], v141 offset:16384
	ds_read_b128 v[42:45], v141 offset:17408
	ds_read_b128 v[50:53], v141 offset:18432
	ds_read_b128 v[58:61], v141 offset:19456
	ds_read_b128 v[114:117], v141 offset:20480
	ds_read_b128 v[118:121], v141 offset:21504
	ds_read_b128 v[122:125], v141 offset:22528
	ds_read_b128 v[126:129], v141 offset:23552
	global_load_lds_dwordx4 v[142:143], off
	v_lshl_add_u64 v[142:143], v[244:245], 0, s[10:11]
	s_add_i32 m0, s62, 0x2000
	s_add_i32 s62, s59, s46
	global_load_lds_dwordx4 v[142:143], off
	s_mov_b32 m0, s62
	v_mov_b32_e32 v139, v131
	global_load_lds_dwordx4 v130, s[40:41]
	s_add_i32 m0, s62, 0x2000
	v_lshl_add_u64 v[246:247], s[36:37], 0, v[138:139]
	v_mov_b32_e32 v133, v131
	global_load_lds_dwordx4 v134, s[40:41]
	v_lshl_add_u64 v[142:143], v[246:247], 0, s[10:11]
	s_mov_b32 m0, s47
	v_lshl_add_u64 v[248:249], s[36:37], 0, v[132:133]
	global_load_lds_dwordx4 v[142:143], off
	v_lshl_add_u64 v[142:143], v[248:249], 0, s[10:11]
	s_mov_b32 m0, s48
	s_nop 0
	global_load_lds_dwordx4 v[142:143], off
	s_waitcnt vmcnt(8)
	s_waitcnt lgkmcnt(0)
	s_barrier
	s_setprio 1
	s_waitcnt lgkmcnt(0)
	v_mfma_f32_16x16x32_bf16 v[142:145], v[2:5], v[34:37], 0
	v_mfma_f32_16x16x32_bf16 v[148:151], v[10:13], v[34:37], 0
	v_mfma_f32_16x16x32_bf16 v[152:155], v[2:5], v[50:53], 0
	v_mfma_f32_16x16x32_bf16 v[156:159], v[10:13], v[50:53], 0
	v_mfma_f32_16x16x32_bf16 v[160:163], v[2:5], v[114:117], 0
	v_mfma_f32_16x16x32_bf16 v[164:167], v[10:13], v[114:117], 0
	v_mfma_f32_16x16x32_bf16 v[2:5], v[2:5], v[122:125], 0
	v_mfma_f32_16x16x32_bf16 v[10:13], v[10:13], v[122:125], 0
	v_mfma_f32_16x16x32_bf16 v[142:145], v[6:9], v[42:45], v[142:145]
	v_mfma_f32_16x16x32_bf16 v[148:151], v[14:17], v[42:45], v[148:151]
	v_mfma_f32_16x16x32_bf16 v[152:155], v[6:9], v[58:61], v[152:155]
	v_mfma_f32_16x16x32_bf16 v[156:159], v[14:17], v[58:61], v[156:159]
	v_mfma_f32_16x16x32_bf16 v[160:163], v[6:9], v[118:121], v[160:163]
	v_mfma_f32_16x16x32_bf16 v[164:167], v[14:17], v[118:121], v[164:167]
	v_mfma_f32_16x16x32_bf16 v[168:171], v[6:9], v[126:129], v[2:5]
	v_mfma_f32_16x16x32_bf16 v[172:175], v[14:17], v[126:129], v[10:13]
	s_setprio 0
	s_setprio 1
	v_mfma_f32_16x16x32_bf16 v[2:5], v[18:21], v[34:37], 0
	v_mfma_f32_16x16x32_bf16 v[6:9], v[26:29], v[34:37], 0
	v_mfma_f32_16x16x32_bf16 v[10:13], v[18:21], v[50:53], 0
	v_mfma_f32_16x16x32_bf16 v[14:17], v[26:29], v[50:53], 0
	v_mfma_f32_16x16x32_bf16 v[34:37], v[18:21], v[114:117], 0
	v_mfma_f32_16x16x32_bf16 v[50:53], v[26:29], v[114:117], 0
	v_mfma_f32_16x16x32_bf16 v[18:21], v[18:21], v[122:125], 0
	v_mfma_f32_16x16x32_bf16 v[26:29], v[26:29], v[122:125], 0
	v_mfma_f32_16x16x32_bf16 v[114:117], v[22:25], v[42:45], v[2:5]
	v_mfma_f32_16x16x32_bf16 v[122:125], v[30:33], v[42:45], v[6:9]
	v_mfma_f32_16x16x32_bf16 v[184:187], v[22:25], v[118:121], v[34:37]
	v_mfma_f32_16x16x32_bf16 v[118:121], v[30:33], v[118:121], v[50:53]
	s_setprio 2
	s_barrier
	v_mfma_f32_16x16x32_bf16 v[188:191], v[22:25], v[126:129], v[18:21]
	v_mfma_f32_16x16x32_bf16 v[126:129], v[30:33], v[126:129], v[26:29]
	v_mfma_f32_16x16x32_bf16 v[176:179], v[22:25], v[58:61], v[10:13]
	v_mfma_f32_16x16x32_bf16 v[180:183], v[30:33], v[58:61], v[14:17]
	s_setprio 0
	s_add_i32 s62, 0, 0x18000
	v_add_u32_e32 v2, s62, v140
	s_add_i32 s63, 0, 0x1c000
	ds_read_b128 v[192:195], v2
	ds_read_b128 v[196:199], v2 offset:1024
	ds_read_b128 v[200:203], v2 offset:2048
	ds_read_b128 v[204:207], v2 offset:3072
	v_add_u32_e32 v2, s63, v140
	ds_read_b128 v[208:211], v2
	ds_read_b128 v[212:215], v2 offset:1024
	ds_read_b128 v[216:219], v2 offset:2048
	ds_read_b128 v[220:223], v2 offset:3072
	s_mov_b32 m0, s49
	ds_read_b128 v[42:45], v141 offset:32768
	ds_read_b128 v[50:53], v141 offset:33792
	ds_read_b128 v[58:61], v141 offset:34816
	ds_read_b128 v[224:227], v141 offset:35840
	ds_read_b128 v[228:231], v141 offset:36864
	ds_read_b128 v[232:235], v141 offset:37888
	ds_read_b128 v[236:239], v141 offset:38912
	ds_read_b128 v[240:243], v141 offset:39936
	global_load_lds_dwordx4 v138, s[42:43]
	s_mov_b32 m0, s50
	s_nop 0
	global_load_lds_dwordx4 v132, s[42:43]
	s_waitcnt vmcnt(8)
	s_waitcnt lgkmcnt(0)
	s_barrier
	s_setprio 1
	s_waitcnt lgkmcnt(0)
	v_mfma_f32_16x16x32_bf16 v[2:5], v[192:195], v[42:45], v[66:69]
	v_mfma_f32_16x16x32_bf16 v[6:9], v[200:203], v[42:45], v[70:73]
	v_mfma_f32_16x16x32_bf16 v[10:13], v[192:195], v[58:61], v[74:77]
	v_mfma_f32_16x16x32_bf16 v[14:17], v[200:203], v[58:61], v[78:81]
	v_mfma_f32_16x16x32_bf16 v[18:21], v[192:195], v[228:231], v[82:85]
	v_mfma_f32_16x16x32_bf16 v[22:25], v[200:203], v[228:231], v[86:89]
	v_mfma_f32_16x16x32_bf16 v[26:29], v[192:195], v[236:239], v[90:93]
	v_mfma_f32_16x16x32_bf16 v[30:33], v[200:203], v[236:239], v[94:97]
	v_mfma_f32_16x16x32_bf16 v[2:5], v[196:199], v[50:53], v[2:5]
	v_mfma_f32_16x16x32_bf16 v[6:9], v[204:207], v[50:53], v[6:9]
	v_mfma_f32_16x16x32_bf16 v[10:13], v[196:199], v[224:227], v[10:13]
	v_mfma_f32_16x16x32_bf16 v[14:17], v[204:207], v[224:227], v[14:17]
	v_mfma_f32_16x16x32_bf16 v[18:21], v[196:199], v[232:235], v[18:21]
	v_mfma_f32_16x16x32_bf16 v[22:25], v[204:207], v[232:235], v[22:25]
	v_mfma_f32_16x16x32_bf16 v[26:29], v[196:199], v[240:243], v[26:29]
	v_mfma_f32_16x16x32_bf16 v[30:33], v[204:207], v[240:243], v[30:33]
	s_setprio 0
	s_setprio 1
	v_mfma_f32_16x16x32_bf16 v[34:37], v[208:211], v[42:45], v[98:101]
	v_mfma_f32_16x16x32_bf16 v[38:41], v[216:219], v[42:45], v[38:41]
	v_mfma_f32_16x16x32_bf16 v[34:37], v[212:215], v[50:53], v[34:37]
	v_mfma_f32_16x16x32_bf16 v[38:41], v[220:223], v[50:53], v[38:41]
	v_mfma_f32_16x16x32_bf16 v[42:45], v[208:211], v[58:61], v[102:105]
	v_mfma_f32_16x16x32_bf16 v[46:49], v[216:219], v[58:61], v[46:49]
	v_mfma_f32_16x16x32_bf16 v[50:53], v[208:211], v[228:231], v[106:109]
	v_mfma_f32_16x16x32_bf16 v[54:57], v[216:219], v[228:231], v[54:57]
	v_mfma_f32_16x16x32_bf16 v[58:61], v[208:211], v[236:239], v[110:113]
	v_mfma_f32_16x16x32_bf16 v[62:65], v[216:219], v[236:239], v[62:65]
	v_mfma_f32_16x16x32_bf16 v[42:45], v[212:215], v[224:227], v[42:45]
	v_mfma_f32_16x16x32_bf16 v[46:49], v[220:223], v[224:227], v[46:49]
	s_setprio 2
	s_barrier
	v_mfma_f32_16x16x32_bf16 v[50:53], v[212:215], v[232:235], v[50:53]
	v_mfma_f32_16x16x32_bf16 v[54:57], v[220:223], v[232:235], v[54:57]
	v_mfma_f32_16x16x32_bf16 v[58:61], v[212:215], v[240:243], v[58:61]
	v_mfma_f32_16x16x32_bf16 v[62:65], v[220:223], v[240:243], v[62:65]
	s_setprio 0
	s_add_i32 s62, s62, s46
	v_lshl_add_u64 v[66:67], v[136:137], 0, s[12:13]
	s_mov_b32 m0, s62
	ds_read_b128 v[102:105], v141 offset:49152
	ds_read_b128 v[106:109], v141 offset:50176
	ds_read_b128 v[110:113], v141 offset:51200
	ds_read_b128 v[224:227], v141 offset:52224
	ds_read_b128 v[228:231], v141 offset:53248
	ds_read_b128 v[232:235], v141 offset:54272
	ds_read_b128 v[236:239], v141 offset:55296
	ds_read_b128 v[240:243], v141 offset:56320
	global_load_lds_dwordx4 v[66:67], off
	v_lshl_add_u64 v[66:67], v[244:245], 0, s[12:13]
	s_add_i32 m0, s62, 0x2000
	s_add_i32 s62, s63, s46
	global_load_lds_dwordx4 v[66:67], off
	s_mov_b32 m0, s62
	v_lshl_add_u64 v[66:67], v[246:247], 0, s[12:13]
	global_load_lds_dwordx4 v130, s[44:45]
	s_add_i32 m0, s62, 0x2000
	s_nop 0
	global_load_lds_dwordx4 v134, s[44:45]
	s_mov_b32 m0, s54
	s_nop 0
	global_load_lds_dwordx4 v[66:67], off
	v_lshl_add_u64 v[66:67], v[248:249], 0, s[12:13]
	s_mov_b32 m0, s55
	s_nop 0
	global_load_lds_dwordx4 v[66:67], off
	s_waitcnt vmcnt(8)
	s_waitcnt lgkmcnt(0)
	s_barrier
	s_setprio 1
	s_waitcnt lgkmcnt(0)
	v_mfma_f32_16x16x32_bf16 v[66:69], v[192:195], v[102:105], v[142:145]
	v_mfma_f32_16x16x32_bf16 v[70:73], v[200:203], v[102:105], v[148:151]
	v_mfma_f32_16x16x32_bf16 v[74:77], v[192:195], v[110:113], v[152:155]
	v_mfma_f32_16x16x32_bf16 v[78:81], v[200:203], v[110:113], v[156:159]
	v_mfma_f32_16x16x32_bf16 v[82:85], v[192:195], v[228:231], v[160:163]
	v_mfma_f32_16x16x32_bf16 v[86:89], v[200:203], v[228:231], v[164:167]
	v_mfma_f32_16x16x32_bf16 v[90:93], v[192:195], v[236:239], v[168:171]
	v_mfma_f32_16x16x32_bf16 v[94:97], v[200:203], v[236:239], v[172:175]
	v_mfma_f32_16x16x32_bf16 v[66:69], v[196:199], v[106:109], v[66:69]
	v_mfma_f32_16x16x32_bf16 v[70:73], v[204:207], v[106:109], v[70:73]
	v_mfma_f32_16x16x32_bf16 v[74:77], v[196:199], v[224:227], v[74:77]
	v_mfma_f32_16x16x32_bf16 v[78:81], v[204:207], v[224:227], v[78:81]
	v_mfma_f32_16x16x32_bf16 v[82:85], v[196:199], v[232:235], v[82:85]
	v_mfma_f32_16x16x32_bf16 v[86:89], v[204:207], v[232:235], v[86:89]
	v_mfma_f32_16x16x32_bf16 v[90:93], v[196:199], v[240:243], v[90:93]
	v_mfma_f32_16x16x32_bf16 v[94:97], v[204:207], v[240:243], v[94:97]
	s_setprio 0
	s_setprio 1
	v_mfma_f32_16x16x32_bf16 v[98:101], v[208:211], v[102:105], v[114:117]
	v_mfma_f32_16x16x32_bf16 v[102:105], v[216:219], v[102:105], v[122:125]
	v_mfma_f32_16x16x32_bf16 v[98:101], v[212:215], v[106:109], v[98:101]
	v_mfma_f32_16x16x32_bf16 v[102:105], v[220:223], v[106:109], v[102:105]
	v_mfma_f32_16x16x32_bf16 v[106:109], v[208:211], v[110:113], v[176:179]
	v_mfma_f32_16x16x32_bf16 v[110:113], v[216:219], v[110:113], v[180:183]
	v_mfma_f32_16x16x32_bf16 v[114:117], v[208:211], v[228:231], v[184:187]
	v_mfma_f32_16x16x32_bf16 v[118:121], v[216:219], v[228:231], v[118:121]
	v_mfma_f32_16x16x32_bf16 v[122:125], v[208:211], v[236:239], v[188:191]
	v_mfma_f32_16x16x32_bf16 v[126:129], v[216:219], v[236:239], v[126:129]
	v_mfma_f32_16x16x32_bf16 v[106:109], v[212:215], v[224:227], v[106:109]
	v_mfma_f32_16x16x32_bf16 v[110:113], v[220:223], v[224:227], v[110:113]
	s_setprio 2
	s_barrier
	v_mfma_f32_16x16x32_bf16 v[114:117], v[212:215], v[232:235], v[114:117]
	v_mfma_f32_16x16x32_bf16 v[118:121], v[220:223], v[232:235], v[118:121]
	v_mfma_f32_16x16x32_bf16 v[122:125], v[212:215], v[240:243], v[122:125]
	v_mfma_f32_16x16x32_bf16 v[126:129], v[220:223], v[240:243], v[126:129]
	s_setprio 0
	s_add_i32 s27, s27, 2
	s_cmp_ge_i32 s27, s15
	s_cbranch_scc0 .LBB0_495
	v_mov_b32_e32 v136, v130
	s_branch .LBB0_498

.LBB0_499:
	v_add_u32_e32 v133, s58, v140
	ds_read_b128 v[142:145], v133
	ds_read_b128 v[148:151], v133 offset:1024
	ds_read_b128 v[152:155], v133 offset:2048
	ds_read_b128 v[156:159], v133 offset:3072
	v_add_u32_e32 v133, s59, v140
	ds_read_b128 v[160:163], v133
	ds_read_b128 v[164:167], v133 offset:1024
	ds_read_b128 v[168:171], v133 offset:2048
	ds_read_b128 v[172:175], v133 offset:3072
	s_add_u32 s38, s36, 0xfff80080
	s_addc_u32 s39, s37, -1
	s_cmp_eq_u32 s42, 4
	s_cselect_b32 s41, s31, s39
	s_cselect_b32 s40, s30, s38
	s_cselect_b32 s39, s35, s27
	s_cselect_b32 s38, s34, s15
	s_mov_b32 m0, s56
	v_add_u32_e32 v141, 0, v1
	ds_read_b128 v[176:179], v141
	ds_read_b128 v[180:183], v141 offset:1024
	ds_read_b128 v[184:187], v141 offset:2048
	ds_read_b128 v[188:191], v141 offset:3072
	ds_read_b128 v[192:195], v141 offset:4096
	ds_read_b128 v[196:199], v141 offset:5120
	ds_read_b128 v[200:203], v141 offset:6144
	ds_read_b128 v[204:207], v141 offset:7168
	global_load_lds_dwordx4 v130, s[36:37]
	s_mov_b32 m0, s57
	v_mov_b32_e32 v133, v131
	global_load_lds_dwordx4 v132, s[36:37]
	s_waitcnt vmcnt(8)
	s_waitcnt lgkmcnt(0)
	s_barrier
	s_setprio 1
	s_waitcnt lgkmcnt(0)
	v_mfma_f32_16x16x32_bf16 v[2:5], v[142:145], v[176:179], v[2:5]
	v_mfma_f32_16x16x32_bf16 v[2:5], v[148:151], v[180:183], v[2:5]
	v_mfma_f32_16x16x32_bf16 v[6:9], v[156:159], v[180:183], v[6:9]
	v_mfma_f32_16x16x32_bf16 v[6:9], v[152:155], v[176:179], v[6:9]
	v_mfma_f32_16x16x32_bf16 v[14:17], v[152:155], v[184:187], v[14:17]
	v_mfma_f32_16x16x32_bf16 v[14:17], v[156:159], v[188:191], v[14:17]
	v_mfma_f32_16x16x32_bf16 v[10:13], v[148:151], v[188:191], v[10:13]
	v_mfma_f32_16x16x32_bf16 v[10:13], v[142:145], v[184:187], v[10:13]
	v_mfma_f32_16x16x32_bf16 v[18:21], v[142:145], v[192:195], v[18:21]
	v_mfma_f32_16x16x32_bf16 v[18:21], v[148:151], v[196:199], v[18:21]
	v_mfma_f32_16x16x32_bf16 v[22:25], v[156:159], v[196:199], v[22:25]
	v_mfma_f32_16x16x32_bf16 v[22:25], v[152:155], v[192:195], v[22:25]
	v_mfma_f32_16x16x32_bf16 v[30:33], v[152:155], v[200:203], v[30:33]
	v_mfma_f32_16x16x32_bf16 v[30:33], v[156:159], v[204:207], v[30:33]
	v_mfma_f32_16x16x32_bf16 v[26:29], v[148:151], v[204:207], v[26:29]
	v_mfma_f32_16x16x32_bf16 v[26:29], v[142:145], v[200:203], v[26:29]
	s_setprio 0
	s_setprio 1
	v_mfma_f32_16x16x32_bf16 v[34:37], v[160:163], v[176:179], v[34:37]
	v_mfma_f32_16x16x32_bf16 v[34:37], v[164:167], v[180:183], v[34:37]
	v_mfma_f32_16x16x32_bf16 v[38:41], v[172:175], v[180:183], v[38:41]
	v_mfma_f32_16x16x32_bf16 v[38:41], v[168:171], v[176:179], v[38:41]
	v_mfma_f32_16x16x32_bf16 v[46:49], v[168:171], v[184:187], v[46:49]
	v_mfma_f32_16x16x32_bf16 v[46:49], v[172:175], v[188:191], v[46:49]
	v_mfma_f32_16x16x32_bf16 v[42:45], v[164:167], v[188:191], v[42:45]
	v_mfma_f32_16x16x32_bf16 v[42:45], v[160:163], v[184:187], v[42:45]
	v_mfma_f32_16x16x32_bf16 v[50:53], v[160:163], v[192:195], v[50:53]
	v_mfma_f32_16x16x32_bf16 v[50:53], v[164:167], v[196:199], v[50:53]
	v_mfma_f32_16x16x32_bf16 v[54:57], v[172:175], v[196:199], v[54:57]
	v_mfma_f32_16x16x32_bf16 v[54:57], v[168:171], v[192:195], v[54:57]
	s_setprio 2
	s_barrier
	v_mfma_f32_16x16x32_bf16 v[62:65], v[168:171], v[200:203], v[62:65]
	v_mfma_f32_16x16x32_bf16 v[62:65], v[172:175], v[204:207], v[62:65]
	v_mfma_f32_16x16x32_bf16 v[58:61], v[164:167], v[204:207], v[58:61]
	v_mfma_f32_16x16x32_bf16 v[58:61], v[160:163], v[200:203], v[58:61]
	s_setprio 0
	s_add_i32 s43, s58, s46
	s_mov_b32 m0, s43
	ds_read_b128 v[176:179], v141 offset:16384
	ds_read_b128 v[180:183], v141 offset:17408
	ds_read_b128 v[184:187], v141 offset:18432
	ds_read_b128 v[188:191], v141 offset:19456
	ds_read_b128 v[192:195], v141 offset:20480
	ds_read_b128 v[196:199], v141 offset:21504
	ds_read_b128 v[200:203], v141 offset:22528
	ds_read_b128 v[204:207], v141 offset:23552
	global_load_lds_dwordx4 v136, s[38:39]
	s_add_i32 m0, s43, 0x2000
	s_add_u32 s44, s38, 0x400000
	s_addc_u32 s45, s39, 0
	s_add_i32 s43, s59, s46
	global_load_lds_dwordx4 v134, s[38:39]
	s_mov_b32 m0, s43
	v_mov_b32_e32 v137, v131
	global_load_lds_dwordx4 v136, s[44:45]
	s_add_i32 m0, s43, 0x2000
	v_mov_b32_e32 v135, v131
	global_load_lds_dwordx4 v134, s[44:45]
	s_mov_b32 m0, s47
	v_lshl_add_u64 v[138:139], s[38:39], 0, v[136:137]
	global_load_lds_dwordx4 v130, s[40:41]
	s_mov_b32 m0, s48
	v_lshl_add_u64 v[208:209], s[38:39], 0, v[134:135]
	global_load_lds_dwordx4 v132, s[40:41]
	s_waitcnt vmcnt(8)
	s_waitcnt lgkmcnt(0)
	v_lshl_add_u64 v[210:211], s[40:41], 0, v[130:131]
	v_lshl_add_u64 v[212:213], s[40:41], 0, v[132:133]
	s_barrier
	s_setprio 1
	s_waitcnt lgkmcnt(0)
	v_mfma_f32_16x16x32_bf16 v[66:69], v[142:145], v[176:179], v[66:69]
	v_mfma_f32_16x16x32_bf16 v[66:69], v[148:151], v[180:183], v[66:69]
	v_mfma_f32_16x16x32_bf16 v[70:73], v[156:159], v[180:183], v[70:73]
	v_mfma_f32_16x16x32_bf16 v[70:73], v[152:155], v[176:179], v[70:73]
	v_mfma_f32_16x16x32_bf16 v[78:81], v[152:155], v[184:187], v[78:81]
	v_mfma_f32_16x16x32_bf16 v[78:81], v[156:159], v[188:191], v[78:81]
	v_mfma_f32_16x16x32_bf16 v[74:77], v[148:151], v[188:191], v[74:77]
	v_mfma_f32_16x16x32_bf16 v[74:77], v[142:145], v[184:187], v[74:77]
	v_mfma_f32_16x16x32_bf16 v[82:85], v[142:145], v[192:195], v[82:85]
	v_mfma_f32_16x16x32_bf16 v[82:85], v[148:151], v[196:199], v[82:85]
	v_mfma_f32_16x16x32_bf16 v[86:89], v[156:159], v[196:199], v[86:89]
	v_mfma_f32_16x16x32_bf16 v[86:89], v[152:155], v[192:195], v[86:89]
	v_mfma_f32_16x16x32_bf16 v[94:97], v[152:155], v[200:203], v[94:97]
	v_mfma_f32_16x16x32_bf16 v[94:97], v[156:159], v[204:207], v[94:97]
	v_mfma_f32_16x16x32_bf16 v[90:93], v[148:151], v[204:207], v[90:93]
	v_mfma_f32_16x16x32_bf16 v[90:93], v[142:145], v[200:203], v[90:93]
	s_setprio 0
	s_setprio 1
	v_mfma_f32_16x16x32_bf16 v[98:101], v[160:163], v[176:179], v[98:101]
	v_mfma_f32_16x16x32_bf16 v[98:101], v[164:167], v[180:183], v[98:101]
	v_mfma_f32_16x16x32_bf16 v[102:105], v[172:175], v[180:183], v[102:105]
	v_mfma_f32_16x16x32_bf16 v[102:105], v[168:171], v[176:179], v[102:105]
	v_mfma_f32_16x16x32_bf16 v[110:113], v[168:171], v[184:187], v[110:113]
	v_mfma_f32_16x16x32_bf16 v[110:113], v[172:175], v[188:191], v[110:113]
	v_mfma_f32_16x16x32_bf16 v[106:109], v[164:167], v[188:191], v[106:109]
	v_mfma_f32_16x16x32_bf16 v[106:109], v[160:163], v[184:187], v[106:109]
	v_mfma_f32_16x16x32_bf16 v[114:117], v[160:163], v[192:195], v[114:117]
	v_mfma_f32_16x16x32_bf16 v[114:117], v[164:167], v[196:199], v[114:117]
	v_mfma_f32_16x16x32_bf16 v[118:121], v[172:175], v[196:199], v[118:121]
	v_mfma_f32_16x16x32_bf16 v[118:121], v[168:171], v[192:195], v[118:121]
	s_setprio 2
	s_barrier
	v_mfma_f32_16x16x32_bf16 v[126:129], v[168:171], v[200:203], v[126:129]
	v_mfma_f32_16x16x32_bf16 v[126:129], v[172:175], v[204:207], v[126:129]
	v_mfma_f32_16x16x32_bf16 v[122:125], v[164:167], v[204:207], v[122:125]
	v_mfma_f32_16x16x32_bf16 v[122:125], v[160:163], v[200:203], v[122:125]
	s_setprio 0
	s_add_i32 s43, 0, 0x18000
	v_add_u32_e32 v135, s43, v140
	s_add_i32 s44, 0, 0x1c000
	ds_read_b128 v[142:145], v135
	ds_read_b128 v[148:151], v135 offset:1024
	ds_read_b128 v[152:155], v135 offset:2048
	ds_read_b128 v[156:159], v135 offset:3072
	v_add_u32_e32 v135, s44, v140
	ds_read_b128 v[160:163], v135
	ds_read_b128 v[164:167], v135 offset:1024
	ds_read_b128 v[168:171], v135 offset:2048
	ds_read_b128 v[172:175], v135 offset:3072
	s_add_u32 s40, s40, 0x80000
	s_addc_u32 s41, s41, 0
	s_mov_b32 m0, s49
	ds_read_b128 v[176:179], v141 offset:32768
	ds_read_b128 v[180:183], v141 offset:33792
	ds_read_b128 v[184:187], v141 offset:34816
	ds_read_b128 v[188:191], v141 offset:35840
	ds_read_b128 v[192:195], v141 offset:36864
	ds_read_b128 v[196:199], v141 offset:37888
	ds_read_b128 v[200:203], v141 offset:38912
	ds_read_b128 v[204:207], v141 offset:39936
	global_load_lds_dwordx4 v130, s[40:41]
	s_mov_b32 m0, s50
	s_nop 0
	global_load_lds_dwordx4 v132, s[40:41]
	s_waitcnt vmcnt(8)
	s_waitcnt lgkmcnt(0)
	s_barrier
	s_setprio 1
	s_waitcnt lgkmcnt(0)
	v_mfma_f32_16x16x32_bf16 v[2:5], v[142:145], v[176:179], v[2:5]
	v_mfma_f32_16x16x32_bf16 v[2:5], v[148:151], v[180:183], v[2:5]
	v_mfma_f32_16x16x32_bf16 v[6:9], v[156:159], v[180:183], v[6:9]
	v_mfma_f32_16x16x32_bf16 v[6:9], v[152:155], v[176:179], v[6:9]
	v_mfma_f32_16x16x32_bf16 v[14:17], v[152:155], v[184:187], v[14:17]
	v_mfma_f32_16x16x32_bf16 v[14:17], v[156:159], v[188:191], v[14:17]
	v_mfma_f32_16x16x32_bf16 v[10:13], v[148:151], v[188:191], v[10:13]
	v_mfma_f32_16x16x32_bf16 v[10:13], v[142:145], v[184:187], v[10:13]
	v_mfma_f32_16x16x32_bf16 v[18:21], v[142:145], v[192:195], v[18:21]
	v_mfma_f32_16x16x32_bf16 v[18:21], v[148:151], v[196:199], v[18:21]
	v_mfma_f32_16x16x32_bf16 v[22:25], v[156:159], v[196:199], v[22:25]
	v_mfma_f32_16x16x32_bf16 v[22:25], v[152:155], v[192:195], v[22:25]
	v_mfma_f32_16x16x32_bf16 v[30:33], v[152:155], v[200:203], v[30:33]
	v_mfma_f32_16x16x32_bf16 v[30:33], v[156:159], v[204:207], v[30:33]
	v_mfma_f32_16x16x32_bf16 v[26:29], v[148:151], v[204:207], v[26:29]
	v_mfma_f32_16x16x32_bf16 v[26:29], v[142:145], v[200:203], v[26:29]
	s_setprio 0
	s_setprio 1
	v_mfma_f32_16x16x32_bf16 v[34:37], v[160:163], v[176:179], v[34:37]
	v_mfma_f32_16x16x32_bf16 v[34:37], v[164:167], v[180:183], v[34:37]
	v_mfma_f32_16x16x32_bf16 v[38:41], v[172:175], v[180:183], v[38:41]
	v_mfma_f32_16x16x32_bf16 v[38:41], v[168:171], v[176:179], v[38:41]
	v_mfma_f32_16x16x32_bf16 v[46:49], v[168:171], v[184:187], v[46:49]
	v_mfma_f32_16x16x32_bf16 v[46:49], v[172:175], v[188:191], v[46:49]
	v_mfma_f32_16x16x32_bf16 v[42:45], v[164:167], v[188:191], v[42:45]
	v_mfma_f32_16x16x32_bf16 v[42:45], v[160:163], v[184:187], v[42:45]
	v_mfma_f32_16x16x32_bf16 v[50:53], v[160:163], v[192:195], v[50:53]
	v_mfma_f32_16x16x32_bf16 v[50:53], v[164:167], v[196:199], v[50:53]
	v_mfma_f32_16x16x32_bf16 v[54:57], v[172:175], v[196:199], v[54:57]
	v_mfma_f32_16x16x32_bf16 v[54:57], v[168:171], v[192:195], v[54:57]
	s_setprio 2
	s_barrier
	v_mfma_f32_16x16x32_bf16 v[62:65], v[168:171], v[200:203], v[62:65]
	v_mfma_f32_16x16x32_bf16 v[62:65], v[172:175], v[204:207], v[62:65]
	v_mfma_f32_16x16x32_bf16 v[58:61], v[164:167], v[204:207], v[58:61]
	v_mfma_f32_16x16x32_bf16 v[58:61], v[160:163], v[200:203], v[58:61]
	s_setprio 0
	s_add_i32 s40, s43, s46
	v_lshl_add_u64 v[138:139], v[138:139], 0, s[6:7]
	s_mov_b32 m0, s40
	ds_read_b128 v[176:179], v141 offset:49152
	ds_read_b128 v[180:183], v141 offset:50176
	ds_read_b128 v[184:187], v141 offset:51200
	ds_read_b128 v[188:191], v141 offset:52224
	ds_read_b128 v[192:195], v141 offset:53248
	ds_read_b128 v[196:199], v141 offset:54272
	ds_read_b128 v[200:203], v141 offset:55296
	ds_read_b128 v[204:207], v141 offset:56320
	global_load_lds_dwordx4 v[138:139], off
	s_add_i32 m0, s40, 0x2000
	s_add_u32 s38, s38, 0x400080
	v_lshl_add_u64 v[138:139], v[208:209], 0, s[6:7]
	s_addc_u32 s39, s39, 0
	s_add_i32 s40, s44, s46
	global_load_lds_dwordx4 v[138:139], off
	s_mov_b32 m0, s40
	v_lshl_add_u64 v[138:139], v[210:211], 0, s[6:7]
	global_load_lds_dwordx4 v136, s[38:39]
	s_add_i32 m0, s40, 0x2000
	s_nop 0
	global_load_lds_dwordx4 v134, s[38:39]
	s_mov_b32 m0, s54
	s_nop 0
	global_load_lds_dwordx4 v[138:139], off
	v_lshl_add_u64 v[138:139], v[212:213], 0, s[6:7]
	s_mov_b32 m0, s55
	s_nop 0
	global_load_lds_dwordx4 v[138:139], off
	s_waitcnt vmcnt(8)
	s_waitcnt lgkmcnt(0)
	s_barrier
	s_setprio 1
	s_waitcnt lgkmcnt(0)
	v_mfma_f32_16x16x32_bf16 v[66:69], v[142:145], v[176:179], v[66:69]
	v_mfma_f32_16x16x32_bf16 v[66:69], v[148:151], v[180:183], v[66:69]
	v_mfma_f32_16x16x32_bf16 v[70:73], v[156:159], v[180:183], v[70:73]
	v_mfma_f32_16x16x32_bf16 v[70:73], v[152:155], v[176:179], v[70:73]
	v_mfma_f32_16x16x32_bf16 v[78:81], v[152:155], v[184:187], v[78:81]
	v_mfma_f32_16x16x32_bf16 v[78:81], v[156:159], v[188:191], v[78:81]
	v_mfma_f32_16x16x32_bf16 v[74:77], v[148:151], v[188:191], v[74:77]
	v_mfma_f32_16x16x32_bf16 v[74:77], v[142:145], v[184:187], v[74:77]
	v_mfma_f32_16x16x32_bf16 v[82:85], v[142:145], v[192:195], v[82:85]
	v_mfma_f32_16x16x32_bf16 v[82:85], v[148:151], v[196:199], v[82:85]
	v_mfma_f32_16x16x32_bf16 v[86:89], v[156:159], v[196:199], v[86:89]
	v_mfma_f32_16x16x32_bf16 v[86:89], v[152:155], v[192:195], v[86:89]
	v_mfma_f32_16x16x32_bf16 v[94:97], v[152:155], v[200:203], v[94:97]
	v_mfma_f32_16x16x32_bf16 v[94:97], v[156:159], v[204:207], v[94:97]
	v_mfma_f32_16x16x32_bf16 v[90:93], v[148:151], v[204:207], v[90:93]
	v_mfma_f32_16x16x32_bf16 v[90:93], v[142:145], v[200:203], v[90:93]
	s_setprio 0
	s_setprio 1
	v_mfma_f32_16x16x32_bf16 v[98:101], v[160:163], v[176:179], v[98:101]
	v_mfma_f32_16x16x32_bf16 v[98:101], v[164:167], v[180:183], v[98:101]
	v_mfma_f32_16x16x32_bf16 v[102:105], v[172:175], v[180:183], v[102:105]
	v_mfma_f32_16x16x32_bf16 v[102:105], v[168:171], v[176:179], v[102:105]
	v_mfma_f32_16x16x32_bf16 v[110:113], v[168:171], v[184:187], v[110:113]
	v_mfma_f32_16x16x32_bf16 v[110:113], v[172:175], v[188:191], v[110:113]
	v_mfma_f32_16x16x32_bf16 v[106:109], v[164:167], v[188:191], v[106:109]
	v_mfma_f32_16x16x32_bf16 v[106:109], v[160:163], v[184:187], v[106:109]
	v_mfma_f32_16x16x32_bf16 v[114:117], v[160:163], v[192:195], v[114:117]
	v_mfma_f32_16x16x32_bf16 v[114:117], v[164:167], v[196:199], v[114:117]
	v_mfma_f32_16x16x32_bf16 v[118:121], v[172:175], v[196:199], v[118:121]
	v_mfma_f32_16x16x32_bf16 v[118:121], v[168:171], v[192:195], v[118:121]
	s_setprio 2
	s_barrier
	v_mfma_f32_16x16x32_bf16 v[126:129], v[168:171], v[200:203], v[126:129]
	v_mfma_f32_16x16x32_bf16 v[126:129], v[172:175], v[204:207], v[126:129]
	v_mfma_f32_16x16x32_bf16 v[122:125], v[164:167], v[204:207], v[122:125]
	v_mfma_f32_16x16x32_bf16 v[122:125], v[160:163], v[200:203], v[122:125]
	s_setprio 0
	s_add_i32 s42, s42, 2
	s_add_u32 s36, s36, 0x100
	s_addc_u32 s37, s37, 0
	s_add_u32 s15, s15, 0x100
	s_addc_u32 s27, s27, 0
	s_cmp_gt_u32 s42, 5
	s_cbranch_scc0 .LBB0_499
	s_and_b64 vcc, exec, s[8:9]
	s_cbranch_vccz .LBB0_502
	s_barrier

.LBB0_528:
	s_add_i32 s53, 0, 0x10000
	s_add_i32 s72, 0, 0x14000
	v_add_u32_e32 v16, s53, v147
	v_add_u32_e32 v32, s72, v147
	ds_read_b128 v[4:7], v16
	ds_read_b128 v[8:11], v16 offset:1024
	ds_read_b128 v[12:15], v16 offset:2048
	ds_read_b128 v[16:19], v16 offset:3072
	ds_read_b128 v[20:23], v32
	ds_read_b128 v[24:27], v32 offset:1024
	ds_read_b128 v[28:31], v32 offset:2048
	ds_read_b128 v[32:35], v32 offset:3072
	v_add_u32_e32 v231, 0, v146
	ds_read_b128 v[36:39], v231
	ds_read_b128 v[40:43], v231 offset:1024
	ds_read_b128 v[44:47], v231 offset:2048
	ds_read_b128 v[48:51], v231 offset:3072
	ds_read_b128 v[52:55], v231 offset:4096
	ds_read_b128 v[56:59], v231 offset:5120
	ds_read_b128 v[60:63], v231 offset:6144
	ds_read_b128 v[64:67], v231 offset:7168
	s_waitcnt vmcnt(8)
	s_waitcnt lgkmcnt(0)
	s_barrier
	s_setprio 1
	s_waitcnt lgkmcnt(0)
	v_mfma_f32_16x16x32_f16 v[68:71], v[4:7], v[36:39], 0
	v_mfma_f32_16x16x32_f16 v[68:71], v[8:11], v[40:43], v[68:71]
	v_mfma_f32_16x16x32_f16 v[72:75], v[12:15], v[36:39], 0
	v_mfma_f32_16x16x32_f16 v[72:75], v[16:19], v[40:43], v[72:75]
	v_mfma_f32_16x16x32_f16 v[80:83], v[12:15], v[44:47], 0
	v_mfma_f32_16x16x32_f16 v[80:83], v[16:19], v[48:51], v[80:83]
	v_mfma_f32_16x16x32_f16 v[76:79], v[4:7], v[44:47], 0
	v_mfma_f32_16x16x32_f16 v[76:79], v[8:11], v[48:51], v[76:79]
	v_mfma_f32_16x16x32_f16 v[84:87], v[4:7], v[52:55], 0
	v_mfma_f32_16x16x32_f16 v[84:87], v[8:11], v[56:59], v[84:87]
	v_mfma_f32_16x16x32_f16 v[88:91], v[12:15], v[52:55], 0
	v_mfma_f32_16x16x32_f16 v[88:91], v[16:19], v[56:59], v[88:91]
	v_mfma_f32_16x16x32_f16 v[96:99], v[12:15], v[60:63], 0
	v_mfma_f32_16x16x32_f16 v[96:99], v[16:19], v[64:67], v[96:99]
	v_mfma_f32_16x16x32_f16 v[92:95], v[4:7], v[60:63], 0
	v_mfma_f32_16x16x32_f16 v[92:95], v[8:11], v[64:67], v[92:95]
	s_setprio 0
	s_setprio 1
	v_mfma_f32_16x16x32_f16 v[100:103], v[20:23], v[36:39], 0
	v_mfma_f32_16x16x32_f16 v[36:39], v[28:31], v[36:39], 0
	v_mfma_f32_16x16x32_f16 v[104:107], v[20:23], v[44:47], 0
	v_mfma_f32_16x16x32_f16 v[44:47], v[28:31], v[44:47], 0
	v_mfma_f32_16x16x32_f16 v[108:111], v[20:23], v[52:55], 0
	v_mfma_f32_16x16x32_f16 v[52:55], v[28:31], v[52:55], 0
	v_mfma_f32_16x16x32_f16 v[112:115], v[20:23], v[60:63], 0
	v_mfma_f32_16x16x32_f16 v[60:63], v[28:31], v[60:63], 0
	v_mfma_f32_16x16x32_f16 v[100:103], v[24:27], v[40:43], v[100:103]
	v_mfma_f32_16x16x32_f16 v[40:43], v[32:35], v[40:43], v[36:39]
	v_mfma_f32_16x16x32_f16 v[104:107], v[24:27], v[48:51], v[104:107]
	v_mfma_f32_16x16x32_f16 v[48:51], v[32:35], v[48:51], v[44:47]
	s_setprio 2
	s_barrier
	v_mfma_f32_16x16x32_f16 v[108:111], v[24:27], v[56:59], v[108:111]
	v_mfma_f32_16x16x32_f16 v[56:59], v[32:35], v[56:59], v[52:55]
	v_mfma_f32_16x16x32_f16 v[112:115], v[24:27], v[64:67], v[112:115]
	v_mfma_f32_16x16x32_f16 v[64:67], v[32:35], v[64:67], v[60:63]
	s_setprio 0
	v_lshl_add_u64 v[136:137], s[6:7], 0, v[2:3]
	s_add_i32 s53, s53, s38
	v_mov_b32_e32 v135, v3
	v_lshl_add_u64 v[140:141], v[136:137], 0, s[74:75]
	s_mov_b32 m0, s53
	v_lshl_add_u64 v[144:145], s[6:7], 0, v[134:135]
	ds_read_b128 v[36:39], v231 offset:16384
	ds_read_b128 v[44:47], v231 offset:17408
	ds_read_b128 v[52:55], v231 offset:18432
	ds_read_b128 v[60:63], v231 offset:19456
	ds_read_b128 v[116:119], v231 offset:20480
	ds_read_b128 v[120:123], v231 offset:21504
	ds_read_b128 v[124:127], v231 offset:22528
	ds_read_b128 v[128:131], v231 offset:23552
	global_load_lds_dwordx4 v[140:141], off
	v_lshl_add_u64 v[140:141], v[144:145], 0, s[74:75]
	s_add_i32 m0, s53, 0x2000
	s_add_i32 s53, s72, s38
	global_load_lds_dwordx4 v[140:141], off
	s_mov_b32 m0, s53
	v_mov_b32_e32 v139, v3
	global_load_lds_dwordx4 v2, s[16:17]
	s_add_i32 m0, s53, 0x2000
	v_lshl_add_u64 v[248:249], s[8:9], 0, v[138:139]
	v_mov_b32_e32 v133, v3
	global_load_lds_dwordx4 v134, s[16:17]
	v_lshl_add_u64 v[140:141], v[248:249], 0, s[74:75]
	s_mov_b32 m0, s58
	v_lshl_add_u64 v[250:251], s[8:9], 0, v[132:133]
	global_load_lds_dwordx4 v[140:141], off
	v_lshl_add_u64 v[140:141], v[250:251], 0, s[74:75]
	s_mov_b32 m0, s59
	s_nop 0
	global_load_lds_dwordx4 v[140:141], off
	s_waitcnt vmcnt(8)
	s_waitcnt lgkmcnt(0)
	s_barrier
	s_setprio 1
	s_waitcnt lgkmcnt(0)
	v_mfma_f32_16x16x32_f16 v[140:143], v[4:7], v[36:39], 0
	v_mfma_f32_16x16x32_f16 v[148:151], v[12:15], v[36:39], 0
	v_mfma_f32_16x16x32_f16 v[152:155], v[4:7], v[52:55], 0
	v_mfma_f32_16x16x32_f16 v[156:159], v[12:15], v[52:55], 0
	v_mfma_f32_16x16x32_f16 v[160:163], v[4:7], v[116:119], 0
	v_mfma_f32_16x16x32_f16 v[164:167], v[12:15], v[116:119], 0
	v_mfma_f32_16x16x32_f16 v[4:7], v[4:7], v[124:127], 0
	v_mfma_f32_16x16x32_f16 v[12:15], v[12:15], v[124:127], 0
	v_mfma_f32_16x16x32_f16 v[140:143], v[8:11], v[44:47], v[140:143]
	v_mfma_f32_16x16x32_f16 v[148:151], v[16:19], v[44:47], v[148:151]
	v_mfma_f32_16x16x32_f16 v[152:155], v[8:11], v[60:63], v[152:155]
	v_mfma_f32_16x16x32_f16 v[156:159], v[16:19], v[60:63], v[156:159]
	v_mfma_f32_16x16x32_f16 v[160:163], v[8:11], v[120:123], v[160:163]
	v_mfma_f32_16x16x32_f16 v[164:167], v[16:19], v[120:123], v[164:167]
	v_mfma_f32_16x16x32_f16 v[168:171], v[8:11], v[128:131], v[4:7]
	v_mfma_f32_16x16x32_f16 v[172:175], v[16:19], v[128:131], v[12:15]
	s_setprio 0
	s_setprio 1
	v_mfma_f32_16x16x32_f16 v[4:7], v[20:23], v[36:39], 0
	v_mfma_f32_16x16x32_f16 v[8:11], v[28:31], v[36:39], 0
	v_mfma_f32_16x16x32_f16 v[12:15], v[20:23], v[52:55], 0
	v_mfma_f32_16x16x32_f16 v[16:19], v[28:31], v[52:55], 0
	v_mfma_f32_16x16x32_f16 v[36:39], v[20:23], v[116:119], 0
	v_mfma_f32_16x16x32_f16 v[52:55], v[28:31], v[116:119], 0
	v_mfma_f32_16x16x32_f16 v[20:23], v[20:23], v[124:127], 0
	v_mfma_f32_16x16x32_f16 v[28:31], v[28:31], v[124:127], 0
	v_mfma_f32_16x16x32_f16 v[116:119], v[24:27], v[44:47], v[4:7]
	v_mfma_f32_16x16x32_f16 v[124:127], v[32:35], v[44:47], v[8:11]
	v_mfma_f32_16x16x32_f16 v[184:187], v[24:27], v[120:123], v[36:39]
	v_mfma_f32_16x16x32_f16 v[120:123], v[32:35], v[120:123], v[52:55]
	s_setprio 2
	s_barrier
	v_mfma_f32_16x16x32_f16 v[188:191], v[24:27], v[128:131], v[20:23]
	v_mfma_f32_16x16x32_f16 v[128:131], v[32:35], v[128:131], v[28:31]
	v_mfma_f32_16x16x32_f16 v[176:179], v[24:27], v[60:63], v[12:15]
	v_mfma_f32_16x16x32_f16 v[180:183], v[32:35], v[60:63], v[16:19]
	s_setprio 0
	s_add_i32 s53, 0, 0x18000
	v_add_u32_e32 v4, s53, v147
	s_add_i32 s72, 0, 0x1c000
	ds_read_b128 v[192:195], v4
	ds_read_b128 v[196:199], v4 offset:1024
	ds_read_b128 v[200:203], v4 offset:2048
	ds_read_b128 v[204:207], v4 offset:3072
	v_add_u32_e32 v4, s72, v147
	ds_read_b128 v[208:211], v4
	ds_read_b128 v[212:215], v4 offset:1024
	ds_read_b128 v[216:219], v4 offset:2048
	ds_read_b128 v[220:223], v4 offset:3072
	s_mov_b32 m0, s60
	ds_read_b128 v[44:47], v231 offset:32768
	ds_read_b128 v[52:55], v231 offset:33792
	ds_read_b128 v[60:63], v231 offset:34816
	ds_read_b128 v[224:227], v231 offset:35840
	ds_read_b128 v[232:235], v231 offset:36864
	ds_read_b128 v[236:239], v231 offset:37888
	ds_read_b128 v[240:243], v231 offset:38912
	ds_read_b128 v[244:247], v231 offset:39936
	global_load_lds_dwordx4 v138, s[26:27]
	s_mov_b32 m0, s61
	s_nop 0
	global_load_lds_dwordx4 v132, s[26:27]
	s_waitcnt vmcnt(8)
	s_waitcnt lgkmcnt(0)
	s_barrier
	s_setprio 1
	s_waitcnt lgkmcnt(0)
	v_mfma_f32_16x16x32_f16 v[4:7], v[192:195], v[44:47], v[68:71]
	v_mfma_f32_16x16x32_f16 v[8:11], v[200:203], v[44:47], v[72:75]
	v_mfma_f32_16x16x32_f16 v[12:15], v[192:195], v[60:63], v[76:79]
	v_mfma_f32_16x16x32_f16 v[16:19], v[200:203], v[60:63], v[80:83]
	v_mfma_f32_16x16x32_f16 v[20:23], v[192:195], v[232:235], v[84:87]
	v_mfma_f32_16x16x32_f16 v[24:27], v[200:203], v[232:235], v[88:91]
	v_mfma_f32_16x16x32_f16 v[28:31], v[192:195], v[240:243], v[92:95]
	v_mfma_f32_16x16x32_f16 v[32:35], v[200:203], v[240:243], v[96:99]
	v_mfma_f32_16x16x32_f16 v[4:7], v[196:199], v[52:55], v[4:7]
	v_mfma_f32_16x16x32_f16 v[8:11], v[204:207], v[52:55], v[8:11]
	v_mfma_f32_16x16x32_f16 v[12:15], v[196:199], v[224:227], v[12:15]
	v_mfma_f32_16x16x32_f16 v[16:19], v[204:207], v[224:227], v[16:19]
	v_mfma_f32_16x16x32_f16 v[20:23], v[196:199], v[236:239], v[20:23]
	v_mfma_f32_16x16x32_f16 v[24:27], v[204:207], v[236:239], v[24:27]
	v_mfma_f32_16x16x32_f16 v[28:31], v[196:199], v[244:247], v[28:31]
	v_mfma_f32_16x16x32_f16 v[32:35], v[204:207], v[244:247], v[32:35]
	s_setprio 0
	s_setprio 1
	v_mfma_f32_16x16x32_f16 v[36:39], v[208:211], v[44:47], v[100:103]
	v_mfma_f32_16x16x32_f16 v[40:43], v[216:219], v[44:47], v[40:43]
	v_mfma_f32_16x16x32_f16 v[36:39], v[212:215], v[52:55], v[36:39]
	v_mfma_f32_16x16x32_f16 v[40:43], v[220:223], v[52:55], v[40:43]
	v_mfma_f32_16x16x32_f16 v[44:47], v[208:211], v[60:63], v[104:107]
	v_mfma_f32_16x16x32_f16 v[48:51], v[216:219], v[60:63], v[48:51]
	v_mfma_f32_16x16x32_f16 v[52:55], v[208:211], v[232:235], v[108:111]
	v_mfma_f32_16x16x32_f16 v[56:59], v[216:219], v[232:235], v[56:59]
	v_mfma_f32_16x16x32_f16 v[60:63], v[208:211], v[240:243], v[112:115]
	v_mfma_f32_16x16x32_f16 v[64:67], v[216:219], v[240:243], v[64:67]
	v_mfma_f32_16x16x32_f16 v[44:47], v[212:215], v[224:227], v[44:47]
	v_mfma_f32_16x16x32_f16 v[48:51], v[220:223], v[224:227], v[48:51]
	s_setprio 2
	s_barrier
	v_mfma_f32_16x16x32_f16 v[52:55], v[212:215], v[236:239], v[52:55]
	v_mfma_f32_16x16x32_f16 v[56:59], v[220:223], v[236:239], v[56:59]
	v_mfma_f32_16x16x32_f16 v[60:63], v[212:215], v[244:247], v[60:63]
	v_mfma_f32_16x16x32_f16 v[64:67], v[220:223], v[244:247], v[64:67]
	s_setprio 0
	s_add_i32 s53, s53, s38
	v_lshl_add_u64 v[68:69], v[136:137], 0, s[24:25]
	s_mov_b32 m0, s53
	ds_read_b128 v[104:107], v231 offset:49152
	ds_read_b128 v[108:111], v231 offset:50176
	ds_read_b128 v[112:115], v231 offset:51200
	ds_read_b128 v[224:227], v231 offset:52224
	ds_read_b128 v[232:235], v231 offset:53248
	ds_read_b128 v[236:239], v231 offset:54272
	ds_read_b128 v[240:243], v231 offset:55296
	ds_read_b128 v[244:247], v231 offset:56320
	global_load_lds_dwordx4 v[68:69], off
	v_lshl_add_u64 v[68:69], v[144:145], 0, s[24:25]
	s_add_i32 m0, s53, 0x2000
	s_add_i32 s53, s72, s38
	global_load_lds_dwordx4 v[68:69], off
	s_mov_b32 m0, s53
	v_lshl_add_u64 v[68:69], v[248:249], 0, s[24:25]
	global_load_lds_dwordx4 v2, s[28:29]
	s_add_i32 m0, s53, 0x2000
	s_nop 0
	global_load_lds_dwordx4 v134, s[28:29]
	s_mov_b32 m0, s64
	s_nop 0
	global_load_lds_dwordx4 v[68:69], off
	v_lshl_add_u64 v[68:69], v[250:251], 0, s[24:25]
	s_mov_b32 m0, s65
	s_nop 0
	global_load_lds_dwordx4 v[68:69], off
	s_waitcnt vmcnt(8)
	s_waitcnt lgkmcnt(0)
	s_barrier
	s_setprio 1
	s_waitcnt lgkmcnt(0)
	v_mfma_f32_16x16x32_f16 v[68:71], v[192:195], v[104:107], v[140:143]
	v_mfma_f32_16x16x32_f16 v[72:75], v[200:203], v[104:107], v[148:151]
	v_mfma_f32_16x16x32_f16 v[76:79], v[192:195], v[112:115], v[152:155]
	v_mfma_f32_16x16x32_f16 v[80:83], v[200:203], v[112:115], v[156:159]
	v_mfma_f32_16x16x32_f16 v[84:87], v[192:195], v[232:235], v[160:163]
	v_mfma_f32_16x16x32_f16 v[88:91], v[200:203], v[232:235], v[164:167]
	v_mfma_f32_16x16x32_f16 v[92:95], v[192:195], v[240:243], v[168:171]
	v_mfma_f32_16x16x32_f16 v[96:99], v[200:203], v[240:243], v[172:175]
	v_mfma_f32_16x16x32_f16 v[68:71], v[196:199], v[108:111], v[68:71]
	v_mfma_f32_16x16x32_f16 v[72:75], v[204:207], v[108:111], v[72:75]
	v_mfma_f32_16x16x32_f16 v[76:79], v[196:199], v[224:227], v[76:79]
	v_mfma_f32_16x16x32_f16 v[80:83], v[204:207], v[224:227], v[80:83]
	v_mfma_f32_16x16x32_f16 v[84:87], v[196:199], v[236:239], v[84:87]
	v_mfma_f32_16x16x32_f16 v[88:91], v[204:207], v[236:239], v[88:91]
	v_mfma_f32_16x16x32_f16 v[92:95], v[196:199], v[244:247], v[92:95]
	v_mfma_f32_16x16x32_f16 v[96:99], v[204:207], v[244:247], v[96:99]
	s_setprio 0
	s_setprio 1
	v_mfma_f32_16x16x32_f16 v[100:103], v[208:211], v[104:107], v[116:119]
	v_mfma_f32_16x16x32_f16 v[104:107], v[216:219], v[104:107], v[124:127]
	v_mfma_f32_16x16x32_f16 v[100:103], v[212:215], v[108:111], v[100:103]
	v_mfma_f32_16x16x32_f16 v[104:107], v[220:223], v[108:111], v[104:107]
	v_mfma_f32_16x16x32_f16 v[108:111], v[208:211], v[112:115], v[176:179]
	v_mfma_f32_16x16x32_f16 v[112:115], v[216:219], v[112:115], v[180:183]
	v_mfma_f32_16x16x32_f16 v[116:119], v[208:211], v[232:235], v[184:187]
	v_mfma_f32_16x16x32_f16 v[120:123], v[216:219], v[232:235], v[120:123]
	v_mfma_f32_16x16x32_f16 v[124:127], v[208:211], v[240:243], v[188:191]
	v_mfma_f32_16x16x32_f16 v[128:131], v[216:219], v[240:243], v[128:131]
	v_mfma_f32_16x16x32_f16 v[108:111], v[212:215], v[224:227], v[108:111]
	v_mfma_f32_16x16x32_f16 v[112:115], v[220:223], v[224:227], v[112:115]
	s_setprio 2
	s_barrier
	v_mfma_f32_16x16x32_f16 v[116:119], v[212:215], v[236:239], v[116:119]
	v_mfma_f32_16x16x32_f16 v[120:123], v[220:223], v[236:239], v[120:123]
	v_mfma_f32_16x16x32_f16 v[124:127], v[212:215], v[244:247], v[124:127]
	v_mfma_f32_16x16x32_f16 v[128:131], v[220:223], v[244:247], v[128:131]
	s_setprio 0
	s_add_i32 s41, s41, 2
	s_cmp_ge_i32 s41, s40
	s_cbranch_scc0 .LBB0_528
	v_mov_b32_e32 v136, v2
	s_branch .LBB0_531

.LBB0_532:
	s_add_u32 s6, s8, 0xfff80080
	s_addc_u32 s7, s9, -1
	s_add_i32 s29, 0, 0x10000
	s_cmp_eq_u32 s28, 28
	s_cselect_b32 s17, s13, s7
	s_cselect_b32 s16, s12, s6
	v_add_u32_e32 v133, s29, v147
	s_cselect_b32 s7, s15, s27
	s_cselect_b32 s6, s14, s26
	s_add_i32 s53, 0, 0x14000
	ds_read_b128 v[138:141], v133
	ds_read_b128 v[142:145], v133 offset:1024
	ds_read_b128 v[148:151], v133 offset:2048
	ds_read_b128 v[152:155], v133 offset:3072
	v_add_u32_e32 v133, s53, v147
	ds_read_b128 v[156:159], v133
	ds_read_b128 v[160:163], v133 offset:1024
	ds_read_b128 v[164:167], v133 offset:2048
	ds_read_b128 v[168:171], v133 offset:3072
	s_mov_b32 m0, s66
	v_add_u32_e32 v212, 0, v146
	ds_read_b128 v[172:175], v212
	ds_read_b128 v[176:179], v212 offset:1024
	ds_read_b128 v[180:183], v212 offset:2048
	ds_read_b128 v[184:187], v212 offset:3072
	ds_read_b128 v[188:191], v212 offset:4096
	ds_read_b128 v[192:195], v212 offset:5120
	ds_read_b128 v[196:199], v212 offset:6144
	ds_read_b128 v[200:203], v212 offset:7168
	global_load_lds_dwordx4 v2, s[8:9]
	s_mov_b32 m0, s67
	v_mov_b32_e32 v133, v3
	global_load_lds_dwordx4 v132, s[8:9]
	s_waitcnt vmcnt(8)
	s_waitcnt lgkmcnt(0)
	s_barrier
	s_setprio 1
	s_waitcnt lgkmcnt(0)
	v_mfma_f32_16x16x32_f16 v[4:7], v[138:141], v[172:175], v[4:7]
	v_mfma_f32_16x16x32_f16 v[4:7], v[142:145], v[176:179], v[4:7]
	v_mfma_f32_16x16x32_f16 v[8:11], v[152:155], v[176:179], v[8:11]
	v_mfma_f32_16x16x32_f16 v[8:11], v[148:151], v[172:175], v[8:11]
	v_mfma_f32_16x16x32_f16 v[16:19], v[148:151], v[180:183], v[16:19]
	v_mfma_f32_16x16x32_f16 v[16:19], v[152:155], v[184:187], v[16:19]
	v_mfma_f32_16x16x32_f16 v[12:15], v[142:145], v[184:187], v[12:15]
	v_mfma_f32_16x16x32_f16 v[12:15], v[138:141], v[180:183], v[12:15]
	v_mfma_f32_16x16x32_f16 v[20:23], v[138:141], v[188:191], v[20:23]
	v_mfma_f32_16x16x32_f16 v[20:23], v[142:145], v[192:195], v[20:23]
	v_mfma_f32_16x16x32_f16 v[24:27], v[152:155], v[192:195], v[24:27]
	v_mfma_f32_16x16x32_f16 v[24:27], v[148:151], v[188:191], v[24:27]
	v_mfma_f32_16x16x32_f16 v[32:35], v[148:151], v[196:199], v[32:35]
	v_mfma_f32_16x16x32_f16 v[32:35], v[152:155], v[200:203], v[32:35]
	v_mfma_f32_16x16x32_f16 v[28:31], v[142:145], v[200:203], v[28:31]
	v_mfma_f32_16x16x32_f16 v[28:31], v[138:141], v[196:199], v[28:31]
	s_setprio 0
	s_setprio 1
	v_mfma_f32_16x16x32_f16 v[36:39], v[156:159], v[172:175], v[36:39]
	v_mfma_f32_16x16x32_f16 v[36:39], v[160:163], v[176:179], v[36:39]
	v_mfma_f32_16x16x32_f16 v[40:43], v[168:171], v[176:179], v[40:43]
	v_mfma_f32_16x16x32_f16 v[40:43], v[164:167], v[172:175], v[40:43]
	v_mfma_f32_16x16x32_f16 v[48:51], v[164:167], v[180:183], v[48:51]
	v_mfma_f32_16x16x32_f16 v[48:51], v[168:171], v[184:187], v[48:51]
	v_mfma_f32_16x16x32_f16 v[44:47], v[160:163], v[184:187], v[44:47]
	v_mfma_f32_16x16x32_f16 v[44:47], v[156:159], v[180:183], v[44:47]
	v_mfma_f32_16x16x32_f16 v[52:55], v[156:159], v[188:191], v[52:55]
	v_mfma_f32_16x16x32_f16 v[52:55], v[160:163], v[192:195], v[52:55]
	v_mfma_f32_16x16x32_f16 v[56:59], v[168:171], v[192:195], v[56:59]
	v_mfma_f32_16x16x32_f16 v[56:59], v[164:167], v[188:191], v[56:59]
	s_setprio 2
	s_barrier
	v_mfma_f32_16x16x32_f16 v[64:67], v[164:167], v[196:199], v[64:67]
	v_mfma_f32_16x16x32_f16 v[64:67], v[168:171], v[200:203], v[64:67]
	v_mfma_f32_16x16x32_f16 v[60:63], v[160:163], v[200:203], v[60:63]
	v_mfma_f32_16x16x32_f16 v[60:63], v[156:159], v[196:199], v[60:63]
	s_setprio 0
	s_add_i32 s29, s29, s38
	s_mov_b32 m0, s29
	ds_read_b128 v[172:175], v212 offset:16384
	ds_read_b128 v[176:179], v212 offset:17408
	ds_read_b128 v[180:183], v212 offset:18432
	ds_read_b128 v[184:187], v212 offset:19456
	ds_read_b128 v[188:191], v212 offset:20480
	ds_read_b128 v[192:195], v212 offset:21504
	ds_read_b128 v[196:199], v212 offset:22528
	ds_read_b128 v[200:203], v212 offset:23552
	global_load_lds_dwordx4 v136, s[6:7]
	s_add_i32 m0, s29, 0x2000
	s_add_u32 s40, s6, 0x80000
	s_addc_u32 s41, s7, 0
	s_add_i32 s29, s53, s38
	global_load_lds_dwordx4 v134, s[6:7]
	s_mov_b32 m0, s29
	v_mov_b32_e32 v137, v3
	global_load_lds_dwordx4 v136, s[40:41]
	s_add_i32 m0, s29, 0x2000
	v_mov_b32_e32 v135, v3
	global_load_lds_dwordx4 v134, s[40:41]
	s_mov_b32 m0, s58
	v_lshl_add_u64 v[204:205], s[6:7], 0, v[136:137]
	global_load_lds_dwordx4 v2, s[16:17]
	s_mov_b32 m0, s59
	v_lshl_add_u64 v[206:207], s[6:7], 0, v[134:135]
	global_load_lds_dwordx4 v132, s[16:17]
	s_waitcnt vmcnt(8)
	s_waitcnt lgkmcnt(0)
	v_lshl_add_u64 v[208:209], s[16:17], 0, v[2:3]
	v_lshl_add_u64 v[210:211], s[16:17], 0, v[132:133]
	s_barrier
	s_setprio 1
	s_waitcnt lgkmcnt(0)
	v_mfma_f32_16x16x32_f16 v[68:71], v[138:141], v[172:175], v[68:71]
	v_mfma_f32_16x16x32_f16 v[68:71], v[142:145], v[176:179], v[68:71]
	v_mfma_f32_16x16x32_f16 v[72:75], v[152:155], v[176:179], v[72:75]
	v_mfma_f32_16x16x32_f16 v[72:75], v[148:151], v[172:175], v[72:75]
	v_mfma_f32_16x16x32_f16 v[80:83], v[148:151], v[180:183], v[80:83]
	v_mfma_f32_16x16x32_f16 v[80:83], v[152:155], v[184:187], v[80:83]
	v_mfma_f32_16x16x32_f16 v[76:79], v[142:145], v[184:187], v[76:79]
	v_mfma_f32_16x16x32_f16 v[76:79], v[138:141], v[180:183], v[76:79]
	v_mfma_f32_16x16x32_f16 v[84:87], v[138:141], v[188:191], v[84:87]
	v_mfma_f32_16x16x32_f16 v[84:87], v[142:145], v[192:195], v[84:87]
	v_mfma_f32_16x16x32_f16 v[88:91], v[152:155], v[192:195], v[88:91]
	v_mfma_f32_16x16x32_f16 v[88:91], v[148:151], v[188:191], v[88:91]
	v_mfma_f32_16x16x32_f16 v[96:99], v[148:151], v[196:199], v[96:99]
	v_mfma_f32_16x16x32_f16 v[96:99], v[152:155], v[200:203], v[96:99]
	v_mfma_f32_16x16x32_f16 v[92:95], v[142:145], v[200:203], v[92:95]
	v_mfma_f32_16x16x32_f16 v[92:95], v[138:141], v[196:199], v[92:95]
	s_setprio 0
	s_setprio 1
	v_mfma_f32_16x16x32_f16 v[100:103], v[156:159], v[172:175], v[100:103]
	v_mfma_f32_16x16x32_f16 v[100:103], v[160:163], v[176:179], v[100:103]
	v_mfma_f32_16x16x32_f16 v[104:107], v[168:171], v[176:179], v[104:107]
	v_mfma_f32_16x16x32_f16 v[104:107], v[164:167], v[172:175], v[104:107]
	v_mfma_f32_16x16x32_f16 v[112:115], v[164:167], v[180:183], v[112:115]
	v_mfma_f32_16x16x32_f16 v[112:115], v[168:171], v[184:187], v[112:115]
	v_mfma_f32_16x16x32_f16 v[108:111], v[160:163], v[184:187], v[108:111]
	v_mfma_f32_16x16x32_f16 v[108:111], v[156:159], v[180:183], v[108:111]
	v_mfma_f32_16x16x32_f16 v[116:119], v[156:159], v[188:191], v[116:119]
	v_mfma_f32_16x16x32_f16 v[116:119], v[160:163], v[192:195], v[116:119]
	v_mfma_f32_16x16x32_f16 v[120:123], v[168:171], v[192:195], v[120:123]
	v_mfma_f32_16x16x32_f16 v[120:123], v[164:167], v[188:191], v[120:123]
	s_setprio 2
	s_barrier
	v_mfma_f32_16x16x32_f16 v[128:131], v[164:167], v[196:199], v[128:131]
	v_mfma_f32_16x16x32_f16 v[128:131], v[168:171], v[200:203], v[128:131]
	v_mfma_f32_16x16x32_f16 v[124:127], v[160:163], v[200:203], v[124:127]
	v_mfma_f32_16x16x32_f16 v[124:127], v[156:159], v[196:199], v[124:127]
	s_setprio 0
	s_add_i32 s29, 0, 0x18000
	v_add_u32_e32 v135, s29, v147
	s_add_i32 s40, 0, 0x1c000
	ds_read_b128 v[138:141], v135
	ds_read_b128 v[142:145], v135 offset:1024
	ds_read_b128 v[148:151], v135 offset:2048
	ds_read_b128 v[152:155], v135 offset:3072
	v_add_u32_e32 v135, s40, v147
	ds_read_b128 v[156:159], v135
	ds_read_b128 v[160:163], v135 offset:1024
	ds_read_b128 v[164:167], v135 offset:2048
	ds_read_b128 v[168:171], v135 offset:3072
	s_add_u32 s16, s16, 0x80000
	s_addc_u32 s17, s17, 0
	s_mov_b32 m0, s60
	ds_read_b128 v[172:175], v212 offset:32768
	ds_read_b128 v[176:179], v212 offset:33792
	ds_read_b128 v[180:183], v212 offset:34816
	ds_read_b128 v[184:187], v212 offset:35840
	ds_read_b128 v[188:191], v212 offset:36864
	ds_read_b128 v[192:195], v212 offset:37888
	ds_read_b128 v[196:199], v212 offset:38912
	ds_read_b128 v[200:203], v212 offset:39936
	global_load_lds_dwordx4 v2, s[16:17]
	s_mov_b32 m0, s61
	s_nop 0
	global_load_lds_dwordx4 v132, s[16:17]
	s_waitcnt vmcnt(8)
	s_waitcnt lgkmcnt(0)
	s_barrier
	s_setprio 1
	s_waitcnt lgkmcnt(0)
	v_mfma_f32_16x16x32_f16 v[4:7], v[138:141], v[172:175], v[4:7]
	v_mfma_f32_16x16x32_f16 v[4:7], v[142:145], v[176:179], v[4:7]
	v_mfma_f32_16x16x32_f16 v[8:11], v[152:155], v[176:179], v[8:11]
	v_mfma_f32_16x16x32_f16 v[8:11], v[148:151], v[172:175], v[8:11]
	v_mfma_f32_16x16x32_f16 v[16:19], v[148:151], v[180:183], v[16:19]
	v_mfma_f32_16x16x32_f16 v[16:19], v[152:155], v[184:187], v[16:19]
	v_mfma_f32_16x16x32_f16 v[12:15], v[142:145], v[184:187], v[12:15]
	v_mfma_f32_16x16x32_f16 v[12:15], v[138:141], v[180:183], v[12:15]
	v_mfma_f32_16x16x32_f16 v[20:23], v[138:141], v[188:191], v[20:23]
	v_mfma_f32_16x16x32_f16 v[20:23], v[142:145], v[192:195], v[20:23]
	v_mfma_f32_16x16x32_f16 v[24:27], v[152:155], v[192:195], v[24:27]
	v_mfma_f32_16x16x32_f16 v[24:27], v[148:151], v[188:191], v[24:27]
	v_mfma_f32_16x16x32_f16 v[32:35], v[148:151], v[196:199], v[32:35]
	v_mfma_f32_16x16x32_f16 v[32:35], v[152:155], v[200:203], v[32:35]
	v_mfma_f32_16x16x32_f16 v[28:31], v[142:145], v[200:203], v[28:31]
	v_mfma_f32_16x16x32_f16 v[28:31], v[138:141], v[196:199], v[28:31]
	s_setprio 0
	s_setprio 1
	v_mfma_f32_16x16x32_f16 v[36:39], v[156:159], v[172:175], v[36:39]
	v_mfma_f32_16x16x32_f16 v[36:39], v[160:163], v[176:179], v[36:39]
	v_mfma_f32_16x16x32_f16 v[40:43], v[168:171], v[176:179], v[40:43]
	v_mfma_f32_16x16x32_f16 v[40:43], v[164:167], v[172:175], v[40:43]
	v_mfma_f32_16x16x32_f16 v[48:51], v[164:167], v[180:183], v[48:51]
	v_mfma_f32_16x16x32_f16 v[48:51], v[168:171], v[184:187], v[48:51]
	v_mfma_f32_16x16x32_f16 v[44:47], v[160:163], v[184:187], v[44:47]
	v_mfma_f32_16x16x32_f16 v[44:47], v[156:159], v[180:183], v[44:47]
	v_mfma_f32_16x16x32_f16 v[52:55], v[156:159], v[188:191], v[52:55]
	v_mfma_f32_16x16x32_f16 v[52:55], v[160:163], v[192:195], v[52:55]
	v_mfma_f32_16x16x32_f16 v[56:59], v[168:171], v[192:195], v[56:59]
	v_mfma_f32_16x16x32_f16 v[56:59], v[164:167], v[188:191], v[56:59]
	s_setprio 2
	s_barrier
	v_mfma_f32_16x16x32_f16 v[64:67], v[164:167], v[196:199], v[64:67]
	v_mfma_f32_16x16x32_f16 v[64:67], v[168:171], v[200:203], v[64:67]
	v_mfma_f32_16x16x32_f16 v[60:63], v[160:163], v[200:203], v[60:63]
	v_mfma_f32_16x16x32_f16 v[60:63], v[156:159], v[196:199], v[60:63]
	s_setprio 0
	s_add_i32 s16, s29, s38
	v_lshl_add_u64 v[204:205], v[204:205], 0, s[86:87]
	s_mov_b32 m0, s16
	ds_read_b128 v[172:175], v212 offset:49152
	ds_read_b128 v[176:179], v212 offset:50176
	ds_read_b128 v[180:183], v212 offset:51200
	ds_read_b128 v[184:187], v212 offset:52224
	ds_read_b128 v[188:191], v212 offset:53248
	ds_read_b128 v[192:195], v212 offset:54272
	ds_read_b128 v[196:199], v212 offset:55296
	ds_read_b128 v[200:203], v212 offset:56320
	global_load_lds_dwordx4 v[204:205], off
	s_add_i32 m0, s16, 0x2000
	s_add_u32 s6, s6, 0x80080
	v_lshl_add_u64 v[204:205], v[206:207], 0, s[86:87]
	s_addc_u32 s7, s7, 0
	s_add_i32 s16, s40, s38
	global_load_lds_dwordx4 v[204:205], off
	s_mov_b32 m0, s16
	v_lshl_add_u64 v[204:205], v[208:209], 0, s[86:87]
	global_load_lds_dwordx4 v136, s[6:7]
	s_add_i32 m0, s16, 0x2000
	s_nop 0
	global_load_lds_dwordx4 v134, s[6:7]
	s_mov_b32 m0, s64
	s_nop 0
	global_load_lds_dwordx4 v[204:205], off
	v_lshl_add_u64 v[204:205], v[210:211], 0, s[86:87]
	s_mov_b32 m0, s65
	s_nop 0
	global_load_lds_dwordx4 v[204:205], off
	s_waitcnt vmcnt(8)
	s_waitcnt lgkmcnt(0)
	s_barrier
	s_setprio 1
	s_waitcnt lgkmcnt(0)
	v_mfma_f32_16x16x32_f16 v[68:71], v[138:141], v[172:175], v[68:71]
	v_mfma_f32_16x16x32_f16 v[68:71], v[142:145], v[176:179], v[68:71]
	v_mfma_f32_16x16x32_f16 v[72:75], v[152:155], v[176:179], v[72:75]
	v_mfma_f32_16x16x32_f16 v[72:75], v[148:151], v[172:175], v[72:75]
	v_mfma_f32_16x16x32_f16 v[80:83], v[148:151], v[180:183], v[80:83]
	v_mfma_f32_16x16x32_f16 v[80:83], v[152:155], v[184:187], v[80:83]
	v_mfma_f32_16x16x32_f16 v[76:79], v[142:145], v[184:187], v[76:79]
	v_mfma_f32_16x16x32_f16 v[76:79], v[138:141], v[180:183], v[76:79]
	v_mfma_f32_16x16x32_f16 v[84:87], v[138:141], v[188:191], v[84:87]
	v_mfma_f32_16x16x32_f16 v[84:87], v[142:145], v[192:195], v[84:87]
	v_mfma_f32_16x16x32_f16 v[88:91], v[152:155], v[192:195], v[88:91]
	v_mfma_f32_16x16x32_f16 v[88:91], v[148:151], v[188:191], v[88:91]
	v_mfma_f32_16x16x32_f16 v[96:99], v[148:151], v[196:199], v[96:99]
	v_mfma_f32_16x16x32_f16 v[96:99], v[152:155], v[200:203], v[96:99]
	v_mfma_f32_16x16x32_f16 v[92:95], v[142:145], v[200:203], v[92:95]
	v_mfma_f32_16x16x32_f16 v[92:95], v[138:141], v[196:199], v[92:95]
	s_setprio 0
	s_setprio 1
	v_mfma_f32_16x16x32_f16 v[100:103], v[156:159], v[172:175], v[100:103]
	v_mfma_f32_16x16x32_f16 v[100:103], v[160:163], v[176:179], v[100:103]
	v_mfma_f32_16x16x32_f16 v[104:107], v[168:171], v[176:179], v[104:107]
	v_mfma_f32_16x16x32_f16 v[104:107], v[164:167], v[172:175], v[104:107]
	v_mfma_f32_16x16x32_f16 v[112:115], v[164:167], v[180:183], v[112:115]
	v_mfma_f32_16x16x32_f16 v[112:115], v[168:171], v[184:187], v[112:115]
	v_mfma_f32_16x16x32_f16 v[108:111], v[160:163], v[184:187], v[108:111]
	v_mfma_f32_16x16x32_f16 v[108:111], v[156:159], v[180:183], v[108:111]
	v_mfma_f32_16x16x32_f16 v[116:119], v[156:159], v[188:191], v[116:119]
	v_mfma_f32_16x16x32_f16 v[116:119], v[160:163], v[192:195], v[116:119]
	v_mfma_f32_16x16x32_f16 v[120:123], v[168:171], v[192:195], v[120:123]
	v_mfma_f32_16x16x32_f16 v[120:123], v[164:167], v[188:191], v[120:123]
	s_setprio 2
	s_barrier
	v_mfma_f32_16x16x32_f16 v[128:131], v[164:167], v[196:199], v[128:131]
	v_mfma_f32_16x16x32_f16 v[128:131], v[168:171], v[200:203], v[128:131]
	v_mfma_f32_16x16x32_f16 v[124:127], v[160:163], v[200:203], v[124:127]
	v_mfma_f32_16x16x32_f16 v[124:127], v[156:159], v[196:199], v[124:127]
	s_setprio 0
	s_add_i32 s28, s28, 2
	s_add_u32 s8, s8, 0x100
	s_addc_u32 s9, s9, 0
	s_add_u32 s26, s26, 0x100
	s_addc_u32 s27, s27, 0
	s_cmp_gt_u32 s28, 29
	s_cbranch_scc0 .LBB0_532
	s_and_b64 vcc, exec, s[50:51]
	s_cbranch_vccz .LBB0_535
	s_barrier

.LBB0_641:
	s_add_i32 s43, 0, 0x10000
	s_add_i32 s71, 0, 0x14000
	v_add_u32_e32 v16, s43, v232
	v_add_u32_e32 v32, s71, v232
	ds_read_b128 v[4:7], v16
	ds_read_b128 v[8:11], v16 offset:1024
	ds_read_b128 v[12:15], v16 offset:2048
	ds_read_b128 v[16:19], v16 offset:3072
	ds_read_b128 v[20:23], v32
	ds_read_b128 v[24:27], v32 offset:1024
	ds_read_b128 v[28:31], v32 offset:2048
	ds_read_b128 v[32:35], v32 offset:3072
	v_add_u32_e32 v233, 0, v231
	ds_read_b128 v[36:39], v233
	ds_read_b128 v[40:43], v233 offset:1024
	ds_read_b128 v[44:47], v233 offset:2048
	ds_read_b128 v[48:51], v233 offset:3072
	ds_read_b128 v[52:55], v233 offset:4096
	ds_read_b128 v[56:59], v233 offset:5120
	ds_read_b128 v[60:63], v233 offset:6144
	ds_read_b128 v[64:67], v233 offset:7168
	s_waitcnt vmcnt(8)
	s_waitcnt lgkmcnt(0)
	s_barrier
	s_setprio 1
	s_waitcnt lgkmcnt(0)
	v_mfma_f32_16x16x32_bf16 v[68:71], v[4:7], v[36:39], 0
	v_mfma_f32_16x16x32_bf16 v[68:71], v[8:11], v[40:43], v[68:71]
	v_mfma_f32_16x16x32_bf16 v[72:75], v[12:15], v[36:39], 0
	v_mfma_f32_16x16x32_bf16 v[72:75], v[16:19], v[40:43], v[72:75]
	v_mfma_f32_16x16x32_bf16 v[80:83], v[12:15], v[44:47], 0
	v_mfma_f32_16x16x32_bf16 v[80:83], v[16:19], v[48:51], v[80:83]
	v_mfma_f32_16x16x32_bf16 v[76:79], v[4:7], v[44:47], 0
	v_mfma_f32_16x16x32_bf16 v[76:79], v[8:11], v[48:51], v[76:79]
	v_mfma_f32_16x16x32_bf16 v[84:87], v[4:7], v[52:55], 0
	v_mfma_f32_16x16x32_bf16 v[84:87], v[8:11], v[56:59], v[84:87]
	v_mfma_f32_16x16x32_bf16 v[88:91], v[12:15], v[52:55], 0
	v_mfma_f32_16x16x32_bf16 v[88:91], v[16:19], v[56:59], v[88:91]
	v_mfma_f32_16x16x32_bf16 v[96:99], v[12:15], v[60:63], 0
	v_mfma_f32_16x16x32_bf16 v[96:99], v[16:19], v[64:67], v[96:99]
	v_mfma_f32_16x16x32_bf16 v[92:95], v[4:7], v[60:63], 0
	v_mfma_f32_16x16x32_bf16 v[92:95], v[8:11], v[64:67], v[92:95]
	s_setprio 0
	s_setprio 1
	v_mfma_f32_16x16x32_bf16 v[100:103], v[20:23], v[36:39], 0
	v_mfma_f32_16x16x32_bf16 v[36:39], v[28:31], v[36:39], 0
	v_mfma_f32_16x16x32_bf16 v[104:107], v[20:23], v[44:47], 0
	v_mfma_f32_16x16x32_bf16 v[44:47], v[28:31], v[44:47], 0
	v_mfma_f32_16x16x32_bf16 v[108:111], v[20:23], v[52:55], 0
	v_mfma_f32_16x16x32_bf16 v[52:55], v[28:31], v[52:55], 0
	v_mfma_f32_16x16x32_bf16 v[112:115], v[20:23], v[60:63], 0
	v_mfma_f32_16x16x32_bf16 v[60:63], v[28:31], v[60:63], 0
	v_mfma_f32_16x16x32_bf16 v[100:103], v[24:27], v[40:43], v[100:103]
	v_mfma_f32_16x16x32_bf16 v[40:43], v[32:35], v[40:43], v[36:39]
	v_mfma_f32_16x16x32_bf16 v[104:107], v[24:27], v[48:51], v[104:107]
	v_mfma_f32_16x16x32_bf16 v[48:51], v[32:35], v[48:51], v[44:47]
	s_setprio 2
	s_barrier
	v_mfma_f32_16x16x32_bf16 v[108:111], v[24:27], v[56:59], v[108:111]
	v_mfma_f32_16x16x32_bf16 v[56:59], v[32:35], v[56:59], v[52:55]
	v_mfma_f32_16x16x32_bf16 v[112:115], v[24:27], v[64:67], v[112:115]
	v_mfma_f32_16x16x32_bf16 v[64:67], v[32:35], v[64:67], v[60:63]
	s_setprio 0
	v_lshl_add_u64 v[186:187], s[8:9], 0, v[2:3]
	s_add_i32 s43, s43, s54
	v_mov_b32_e32 v191, v3
	v_lshl_add_u64 v[134:135], v[186:187], 0, s[80:81]
	s_mov_b32 m0, s43
	v_lshl_add_u64 v[246:247], s[8:9], 0, v[190:191]
	ds_read_b128 v[36:39], v233 offset:16384
	ds_read_b128 v[44:47], v233 offset:17408
	ds_read_b128 v[52:55], v233 offset:18432
	ds_read_b128 v[60:63], v233 offset:19456
	ds_read_b128 v[116:119], v233 offset:20480
	ds_read_b128 v[120:123], v233 offset:21504
	ds_read_b128 v[124:127], v233 offset:22528
	ds_read_b128 v[128:131], v233 offset:23552
	global_load_lds_dwordx4 v[134:135], off
	v_lshl_add_u64 v[134:135], v[246:247], 0, s[80:81]
	s_add_i32 m0, s43, 0x2000
	s_add_i32 s43, s71, s54
	global_load_lds_dwordx4 v[134:135], off
	s_mov_b32 m0, s43
	v_mov_b32_e32 v133, v3
	global_load_lds_dwordx4 v2, s[16:17]
	s_add_i32 m0, s43, 0x2000
	v_lshl_add_u64 v[248:249], s[6:7], 0, v[132:133]
	v_mov_b32_e32 v189, v3
	global_load_lds_dwordx4 v190, s[16:17]
	v_lshl_add_u64 v[134:135], v[248:249], 0, s[80:81]
	s_mov_b32 m0, s55
	v_lshl_add_u64 v[250:251], s[6:7], 0, v[188:189]
	global_load_lds_dwordx4 v[134:135], off
	v_lshl_add_u64 v[134:135], v[250:251], 0, s[80:81]
	s_mov_b32 m0, s56
	s_nop 0
	global_load_lds_dwordx4 v[134:135], off
	s_waitcnt vmcnt(8)
	s_waitcnt lgkmcnt(0)
	s_barrier
	s_setprio 1
	s_waitcnt lgkmcnt(0)
	v_mfma_f32_16x16x32_bf16 v[134:137], v[4:7], v[36:39], 0
	v_mfma_f32_16x16x32_bf16 v[138:141], v[12:15], v[36:39], 0
	v_mfma_f32_16x16x32_bf16 v[142:145], v[4:7], v[52:55], 0
	v_mfma_f32_16x16x32_bf16 v[146:149], v[12:15], v[52:55], 0
	v_mfma_f32_16x16x32_bf16 v[150:153], v[4:7], v[116:119], 0
	v_mfma_f32_16x16x32_bf16 v[154:157], v[12:15], v[116:119], 0
	v_mfma_f32_16x16x32_bf16 v[4:7], v[4:7], v[124:127], 0
	v_mfma_f32_16x16x32_bf16 v[12:15], v[12:15], v[124:127], 0
	v_mfma_f32_16x16x32_bf16 v[134:137], v[8:11], v[44:47], v[134:137]
	v_mfma_f32_16x16x32_bf16 v[138:141], v[16:19], v[44:47], v[138:141]
	v_mfma_f32_16x16x32_bf16 v[142:145], v[8:11], v[60:63], v[142:145]
	v_mfma_f32_16x16x32_bf16 v[146:149], v[16:19], v[60:63], v[146:149]
	v_mfma_f32_16x16x32_bf16 v[150:153], v[8:11], v[120:123], v[150:153]
	v_mfma_f32_16x16x32_bf16 v[154:157], v[16:19], v[120:123], v[154:157]
	v_mfma_f32_16x16x32_bf16 v[158:161], v[8:11], v[128:131], v[4:7]
	v_mfma_f32_16x16x32_bf16 v[162:165], v[16:19], v[128:131], v[12:15]
	s_setprio 0
	s_setprio 1
	v_mfma_f32_16x16x32_bf16 v[4:7], v[20:23], v[36:39], 0
	v_mfma_f32_16x16x32_bf16 v[8:11], v[28:31], v[36:39], 0
	v_mfma_f32_16x16x32_bf16 v[12:15], v[20:23], v[52:55], 0
	v_mfma_f32_16x16x32_bf16 v[16:19], v[28:31], v[52:55], 0
	v_mfma_f32_16x16x32_bf16 v[36:39], v[20:23], v[116:119], 0
	v_mfma_f32_16x16x32_bf16 v[52:55], v[28:31], v[116:119], 0
	v_mfma_f32_16x16x32_bf16 v[20:23], v[20:23], v[124:127], 0
	v_mfma_f32_16x16x32_bf16 v[28:31], v[28:31], v[124:127], 0
	v_mfma_f32_16x16x32_bf16 v[116:119], v[24:27], v[44:47], v[4:7]
	v_mfma_f32_16x16x32_bf16 v[124:127], v[32:35], v[44:47], v[8:11]
	v_mfma_f32_16x16x32_bf16 v[174:177], v[24:27], v[120:123], v[36:39]
	v_mfma_f32_16x16x32_bf16 v[120:123], v[32:35], v[120:123], v[52:55]
	s_setprio 2
	s_barrier
	v_mfma_f32_16x16x32_bf16 v[178:181], v[24:27], v[128:131], v[20:23]
	v_mfma_f32_16x16x32_bf16 v[128:131], v[32:35], v[128:131], v[28:31]
	v_mfma_f32_16x16x32_bf16 v[166:169], v[24:27], v[60:63], v[12:15]
	v_mfma_f32_16x16x32_bf16 v[170:173], v[32:35], v[60:63], v[16:19]
	s_setprio 0
	s_add_i32 s43, 0, 0x18000
	v_add_u32_e32 v4, s43, v232
	s_add_i32 s71, 0, 0x1c000
	ds_read_b128 v[182:185], v4
	ds_read_b128 v[192:195], v4 offset:1024
	ds_read_b128 v[196:199], v4 offset:2048
	ds_read_b128 v[200:203], v4 offset:3072
	v_add_u32_e32 v4, s71, v232
	ds_read_b128 v[204:207], v4
	ds_read_b128 v[208:211], v4 offset:1024
	ds_read_b128 v[212:215], v4 offset:2048
	ds_read_b128 v[216:219], v4 offset:3072
	s_mov_b32 m0, s57
	ds_read_b128 v[44:47], v233 offset:32768
	ds_read_b128 v[52:55], v233 offset:33792
	ds_read_b128 v[60:63], v233 offset:34816
	ds_read_b128 v[220:223], v233 offset:35840
	ds_read_b128 v[224:227], v233 offset:36864
	ds_read_b128 v[234:237], v233 offset:37888
	ds_read_b128 v[238:241], v233 offset:38912
	ds_read_b128 v[242:245], v233 offset:39936
	global_load_lds_dwordx4 v132, s[26:27]
	s_mov_b32 m0, s58
	s_nop 0
	global_load_lds_dwordx4 v188, s[26:27]
	s_waitcnt vmcnt(8)
	s_waitcnt lgkmcnt(0)
	s_barrier
	s_setprio 1
	s_waitcnt lgkmcnt(0)
	v_mfma_f32_16x16x32_bf16 v[4:7], v[182:185], v[44:47], v[68:71]
	v_mfma_f32_16x16x32_bf16 v[8:11], v[196:199], v[44:47], v[72:75]
	v_mfma_f32_16x16x32_bf16 v[12:15], v[182:185], v[60:63], v[76:79]
	v_mfma_f32_16x16x32_bf16 v[16:19], v[196:199], v[60:63], v[80:83]
	v_mfma_f32_16x16x32_bf16 v[20:23], v[182:185], v[224:227], v[84:87]
	v_mfma_f32_16x16x32_bf16 v[24:27], v[196:199], v[224:227], v[88:91]
	v_mfma_f32_16x16x32_bf16 v[28:31], v[182:185], v[238:241], v[92:95]
	v_mfma_f32_16x16x32_bf16 v[32:35], v[196:199], v[238:241], v[96:99]
	v_mfma_f32_16x16x32_bf16 v[4:7], v[192:195], v[52:55], v[4:7]
	v_mfma_f32_16x16x32_bf16 v[8:11], v[200:203], v[52:55], v[8:11]
	v_mfma_f32_16x16x32_bf16 v[12:15], v[192:195], v[220:223], v[12:15]
	v_mfma_f32_16x16x32_bf16 v[16:19], v[200:203], v[220:223], v[16:19]
	v_mfma_f32_16x16x32_bf16 v[20:23], v[192:195], v[234:237], v[20:23]
	v_mfma_f32_16x16x32_bf16 v[24:27], v[200:203], v[234:237], v[24:27]
	v_mfma_f32_16x16x32_bf16 v[28:31], v[192:195], v[242:245], v[28:31]
	v_mfma_f32_16x16x32_bf16 v[32:35], v[200:203], v[242:245], v[32:35]
	s_setprio 0
	s_setprio 1
	v_mfma_f32_16x16x32_bf16 v[36:39], v[204:207], v[44:47], v[100:103]
	v_mfma_f32_16x16x32_bf16 v[40:43], v[212:215], v[44:47], v[40:43]
	v_mfma_f32_16x16x32_bf16 v[36:39], v[208:211], v[52:55], v[36:39]
	v_mfma_f32_16x16x32_bf16 v[40:43], v[216:219], v[52:55], v[40:43]
	v_mfma_f32_16x16x32_bf16 v[44:47], v[204:207], v[60:63], v[104:107]
	v_mfma_f32_16x16x32_bf16 v[48:51], v[212:215], v[60:63], v[48:51]
	v_mfma_f32_16x16x32_bf16 v[52:55], v[204:207], v[224:227], v[108:111]
	v_mfma_f32_16x16x32_bf16 v[56:59], v[212:215], v[224:227], v[56:59]
	v_mfma_f32_16x16x32_bf16 v[60:63], v[204:207], v[238:241], v[112:115]
	v_mfma_f32_16x16x32_bf16 v[64:67], v[212:215], v[238:241], v[64:67]
	v_mfma_f32_16x16x32_bf16 v[44:47], v[208:211], v[220:223], v[44:47]
	v_mfma_f32_16x16x32_bf16 v[48:51], v[216:219], v[220:223], v[48:51]
	s_setprio 2
	s_barrier
	v_mfma_f32_16x16x32_bf16 v[52:55], v[208:211], v[234:237], v[52:55]
	v_mfma_f32_16x16x32_bf16 v[56:59], v[216:219], v[234:237], v[56:59]
	v_mfma_f32_16x16x32_bf16 v[60:63], v[208:211], v[242:245], v[60:63]
	v_mfma_f32_16x16x32_bf16 v[64:67], v[216:219], v[242:245], v[64:67]
	s_setprio 0
	s_add_i32 s43, s43, s54
	v_lshl_add_u64 v[68:69], v[186:187], 0, s[0:1]
	s_mov_b32 m0, s43
	ds_read_b128 v[104:107], v233 offset:49152
	ds_read_b128 v[108:111], v233 offset:50176
	ds_read_b128 v[112:115], v233 offset:51200
	ds_read_b128 v[220:223], v233 offset:52224
	ds_read_b128 v[224:227], v233 offset:53248
	ds_read_b128 v[234:237], v233 offset:54272
	ds_read_b128 v[238:241], v233 offset:55296
	ds_read_b128 v[242:245], v233 offset:56320
	global_load_lds_dwordx4 v[68:69], off
	v_lshl_add_u64 v[68:69], v[246:247], 0, s[0:1]
	s_add_i32 m0, s43, 0x2000
	s_add_i32 s43, s71, s54
	global_load_lds_dwordx4 v[68:69], off
	s_mov_b32 m0, s43
	v_lshl_add_u64 v[68:69], v[248:249], 0, s[0:1]
	global_load_lds_dwordx4 v2, s[28:29]
	s_add_i32 m0, s43, 0x2000
	s_nop 0
	global_load_lds_dwordx4 v190, s[28:29]
	s_mov_b32 m0, s62
	s_nop 0
	global_load_lds_dwordx4 v[68:69], off
	v_lshl_add_u64 v[68:69], v[250:251], 0, s[0:1]
	s_mov_b32 m0, s63
	s_nop 0
	global_load_lds_dwordx4 v[68:69], off
	s_waitcnt vmcnt(8)
	s_waitcnt lgkmcnt(0)
	s_barrier
	s_setprio 1
	s_waitcnt lgkmcnt(0)
	v_mfma_f32_16x16x32_bf16 v[68:71], v[182:185], v[104:107], v[134:137]
	v_mfma_f32_16x16x32_bf16 v[72:75], v[196:199], v[104:107], v[138:141]
	v_mfma_f32_16x16x32_bf16 v[76:79], v[182:185], v[112:115], v[142:145]
	v_mfma_f32_16x16x32_bf16 v[80:83], v[196:199], v[112:115], v[146:149]
	v_mfma_f32_16x16x32_bf16 v[84:87], v[182:185], v[224:227], v[150:153]
	v_mfma_f32_16x16x32_bf16 v[88:91], v[196:199], v[224:227], v[154:157]
	v_mfma_f32_16x16x32_bf16 v[92:95], v[182:185], v[238:241], v[158:161]
	v_mfma_f32_16x16x32_bf16 v[96:99], v[196:199], v[238:241], v[162:165]
	v_mfma_f32_16x16x32_bf16 v[68:71], v[192:195], v[108:111], v[68:71]
	v_mfma_f32_16x16x32_bf16 v[72:75], v[200:203], v[108:111], v[72:75]
	v_mfma_f32_16x16x32_bf16 v[76:79], v[192:195], v[220:223], v[76:79]
	v_mfma_f32_16x16x32_bf16 v[80:83], v[200:203], v[220:223], v[80:83]
	v_mfma_f32_16x16x32_bf16 v[84:87], v[192:195], v[234:237], v[84:87]
	v_mfma_f32_16x16x32_bf16 v[88:91], v[200:203], v[234:237], v[88:91]
	v_mfma_f32_16x16x32_bf16 v[92:95], v[192:195], v[242:245], v[92:95]
	v_mfma_f32_16x16x32_bf16 v[96:99], v[200:203], v[242:245], v[96:99]
	s_setprio 0
	s_setprio 1
	v_mfma_f32_16x16x32_bf16 v[100:103], v[204:207], v[104:107], v[116:119]
	v_mfma_f32_16x16x32_bf16 v[104:107], v[212:215], v[104:107], v[124:127]
	v_mfma_f32_16x16x32_bf16 v[100:103], v[208:211], v[108:111], v[100:103]
	v_mfma_f32_16x16x32_bf16 v[104:107], v[216:219], v[108:111], v[104:107]
	v_mfma_f32_16x16x32_bf16 v[108:111], v[204:207], v[112:115], v[166:169]
	v_mfma_f32_16x16x32_bf16 v[112:115], v[212:215], v[112:115], v[170:173]
	v_mfma_f32_16x16x32_bf16 v[116:119], v[204:207], v[224:227], v[174:177]
	v_mfma_f32_16x16x32_bf16 v[120:123], v[212:215], v[224:227], v[120:123]
	v_mfma_f32_16x16x32_bf16 v[124:127], v[204:207], v[238:241], v[178:181]
	v_mfma_f32_16x16x32_bf16 v[128:131], v[212:215], v[238:241], v[128:131]
	v_mfma_f32_16x16x32_bf16 v[108:111], v[208:211], v[220:223], v[108:111]
	v_mfma_f32_16x16x32_bf16 v[112:115], v[216:219], v[220:223], v[112:115]
	s_setprio 2
	s_barrier
	v_mfma_f32_16x16x32_bf16 v[116:119], v[208:211], v[234:237], v[116:119]
	v_mfma_f32_16x16x32_bf16 v[120:123], v[216:219], v[234:237], v[120:123]
	v_mfma_f32_16x16x32_bf16 v[124:127], v[208:211], v[242:245], v[124:127]
	v_mfma_f32_16x16x32_bf16 v[128:131], v[216:219], v[242:245], v[128:131]
	s_setprio 0
	s_add_i32 s42, s42, 2
	s_cmp_ge_i32 s42, s38
	s_cbranch_scc0 .LBB0_641
	v_mov_b32_e32 v192, v2
	s_branch .LBB0_644

.LBB0_649:
	s_or_b32 s38, s28, 1
	s_lshl_b64 s[42:43], s[38:39], 7
	s_sub_u32 s38, 0, s42
	s_subb_u32 s42, 0, s43
	s_add_u32 s38, s6, s38
	s_addc_u32 s43, s7, s42
	s_add_i32 s71, 0, 0x10000
	s_add_i32 s72, 0, 0x14000
	v_add_u32_e32 v144, s71, v232
	v_add_u32_e32 v160, s72, v232
	s_waitcnt lgkmcnt(0)
	ds_read_b128 v[132:135], v144
	ds_read_b128 v[136:139], v144 offset:1024
	ds_read_b128 v[140:143], v144 offset:2048
	ds_read_b128 v[144:147], v144 offset:3072
	ds_read_b128 v[148:151], v160
	ds_read_b128 v[152:155], v160 offset:1024
	ds_read_b128 v[156:159], v160 offset:2048
	ds_read_b128 v[160:163], v160 offset:3072
	s_add_u32 s42, s38, 0x160000
	s_mov_b32 m0, s64
	v_add_u32_e32 v210, 0, v231
	s_addc_u32 s43, s43, 0
	ds_read_b128 v[164:167], v210
	ds_read_b128 v[168:171], v210 offset:1024
	ds_read_b128 v[172:175], v210 offset:2048
	ds_read_b128 v[176:179], v210 offset:3072
	ds_read_b128 v[180:183], v210 offset:4096
	ds_read_b128 v[184:187], v210 offset:5120
	ds_read_b128 v[194:197], v210 offset:6144
	ds_read_b128 v[198:201], v210 offset:7168
	global_load_lds_dwordx4 v2, s[42:43]
	s_mov_b32 m0, s65
	v_mov_b32_e32 v189, v3
	global_load_lds_dwordx4 v188, s[42:43]
	s_waitcnt vmcnt(8)
	s_waitcnt lgkmcnt(0)
	s_barrier
	s_setprio 1
	s_waitcnt lgkmcnt(0)
	v_mfma_f32_16x16x32_bf16 v[4:7], v[132:135], v[164:167], v[4:7]
	v_mfma_f32_16x16x32_bf16 v[4:7], v[136:139], v[168:171], v[4:7]
	v_mfma_f32_16x16x32_bf16 v[8:11], v[144:147], v[168:171], v[8:11]
	v_mfma_f32_16x16x32_bf16 v[8:11], v[140:143], v[164:167], v[8:11]
	v_mfma_f32_16x16x32_bf16 v[16:19], v[140:143], v[172:175], v[16:19]
	v_mfma_f32_16x16x32_bf16 v[16:19], v[144:147], v[176:179], v[16:19]
	v_mfma_f32_16x16x32_bf16 v[12:15], v[136:139], v[176:179], v[12:15]
	v_mfma_f32_16x16x32_bf16 v[12:15], v[132:135], v[172:175], v[12:15]
	v_mfma_f32_16x16x32_bf16 v[20:23], v[132:135], v[180:183], v[20:23]
	v_mfma_f32_16x16x32_bf16 v[20:23], v[136:139], v[184:187], v[20:23]
	v_mfma_f32_16x16x32_bf16 v[24:27], v[144:147], v[184:187], v[24:27]
	v_mfma_f32_16x16x32_bf16 v[24:27], v[140:143], v[180:183], v[24:27]
	v_mfma_f32_16x16x32_bf16 v[32:35], v[140:143], v[194:197], v[32:35]
	v_mfma_f32_16x16x32_bf16 v[32:35], v[144:147], v[198:201], v[32:35]
	v_mfma_f32_16x16x32_bf16 v[28:31], v[136:139], v[198:201], v[28:31]
	v_mfma_f32_16x16x32_bf16 v[28:31], v[132:135], v[194:197], v[28:31]
	s_setprio 0
	s_setprio 1
	v_mfma_f32_16x16x32_bf16 v[36:39], v[148:151], v[164:167], v[36:39]
	v_mfma_f32_16x16x32_bf16 v[36:39], v[152:155], v[168:171], v[36:39]
	v_mfma_f32_16x16x32_bf16 v[40:43], v[160:163], v[168:171], v[40:43]
	v_mfma_f32_16x16x32_bf16 v[40:43], v[156:159], v[164:167], v[40:43]
	v_mfma_f32_16x16x32_bf16 v[48:51], v[156:159], v[172:175], v[48:51]
	v_mfma_f32_16x16x32_bf16 v[48:51], v[160:163], v[176:179], v[48:51]
	v_mfma_f32_16x16x32_bf16 v[44:47], v[152:155], v[176:179], v[44:47]
	v_mfma_f32_16x16x32_bf16 v[44:47], v[148:151], v[172:175], v[44:47]
	v_mfma_f32_16x16x32_bf16 v[52:55], v[148:151], v[180:183], v[52:55]
	v_mfma_f32_16x16x32_bf16 v[52:55], v[152:155], v[184:187], v[52:55]
	v_mfma_f32_16x16x32_bf16 v[56:59], v[160:163], v[184:187], v[56:59]
	v_mfma_f32_16x16x32_bf16 v[56:59], v[156:159], v[180:183], v[56:59]
	s_setprio 2
	s_barrier
	v_mfma_f32_16x16x32_bf16 v[64:67], v[156:159], v[194:197], v[64:67]
	v_mfma_f32_16x16x32_bf16 v[64:67], v[160:163], v[198:201], v[64:67]
	v_mfma_f32_16x16x32_bf16 v[60:63], v[152:155], v[198:201], v[60:63]
	v_mfma_f32_16x16x32_bf16 v[60:63], v[148:151], v[194:197], v[60:63]
	s_setprio 0
	s_add_i32 s38, s71, s54
	s_mov_b32 m0, s38
	ds_read_b128 v[164:167], v210 offset:16384
	ds_read_b128 v[168:171], v210 offset:17408
	ds_read_b128 v[172:175], v210 offset:18432
	ds_read_b128 v[176:179], v210 offset:19456
	ds_read_b128 v[180:183], v210 offset:20480
	ds_read_b128 v[184:187], v210 offset:21504
	ds_read_b128 v[194:197], v210 offset:22528
	ds_read_b128 v[198:201], v210 offset:23552
	global_load_lds_dwordx4 v192, s[16:17]
	s_add_i32 m0, s38, 0x2000
	s_add_u32 s42, s16, 0x160000
	s_addc_u32 s43, s17, 0
	s_add_i32 s38, s72, s54
	global_load_lds_dwordx4 v190, s[16:17]
	s_mov_b32 m0, s38
	v_mov_b32_e32 v193, v3
	global_load_lds_dwordx4 v192, s[42:43]
	s_add_i32 m0, s38, 0x2000
	v_mov_b32_e32 v191, v3
	global_load_lds_dwordx4 v190, s[42:43]
	s_mov_b32 m0, s55
	v_lshl_add_u64 v[202:203], s[16:17], 0, v[192:193]
	global_load_lds_dwordx4 v2, s[26:27]
	s_mov_b32 m0, s56
	v_lshl_add_u64 v[204:205], s[16:17], 0, v[190:191]
	global_load_lds_dwordx4 v188, s[26:27]
	s_waitcnt vmcnt(8)
	s_waitcnt lgkmcnt(0)
	v_lshl_add_u64 v[206:207], s[26:27], 0, v[2:3]
	v_lshl_add_u64 v[208:209], s[26:27], 0, v[188:189]
	s_barrier
	s_setprio 1
	s_waitcnt lgkmcnt(0)
	v_mfma_f32_16x16x32_bf16 v[68:71], v[132:135], v[164:167], v[68:71]
	v_mfma_f32_16x16x32_bf16 v[68:71], v[136:139], v[168:171], v[68:71]
	v_mfma_f32_16x16x32_bf16 v[72:75], v[144:147], v[168:171], v[72:75]
	v_mfma_f32_16x16x32_bf16 v[72:75], v[140:143], v[164:167], v[72:75]
	v_mfma_f32_16x16x32_bf16 v[80:83], v[140:143], v[172:175], v[80:83]
	v_mfma_f32_16x16x32_bf16 v[80:83], v[144:147], v[176:179], v[80:83]
	v_mfma_f32_16x16x32_bf16 v[76:79], v[136:139], v[176:179], v[76:79]
	v_mfma_f32_16x16x32_bf16 v[76:79], v[132:135], v[172:175], v[76:79]
	v_mfma_f32_16x16x32_bf16 v[84:87], v[132:135], v[180:183], v[84:87]
	v_mfma_f32_16x16x32_bf16 v[84:87], v[136:139], v[184:187], v[84:87]
	v_mfma_f32_16x16x32_bf16 v[88:91], v[144:147], v[184:187], v[88:91]
	v_mfma_f32_16x16x32_bf16 v[88:91], v[140:143], v[180:183], v[88:91]
	v_mfma_f32_16x16x32_bf16 v[96:99], v[140:143], v[194:197], v[96:99]
	v_mfma_f32_16x16x32_bf16 v[96:99], v[144:147], v[198:201], v[96:99]
	v_mfma_f32_16x16x32_bf16 v[92:95], v[136:139], v[198:201], v[92:95]
	v_mfma_f32_16x16x32_bf16 v[92:95], v[132:135], v[194:197], v[92:95]
	s_setprio 0
	s_setprio 1
	v_mfma_f32_16x16x32_bf16 v[100:103], v[148:151], v[164:167], v[100:103]
	v_mfma_f32_16x16x32_bf16 v[100:103], v[152:155], v[168:171], v[100:103]
	v_mfma_f32_16x16x32_bf16 v[104:107], v[160:163], v[168:171], v[104:107]
	v_mfma_f32_16x16x32_bf16 v[104:107], v[156:159], v[164:167], v[104:107]
	v_mfma_f32_16x16x32_bf16 v[112:115], v[156:159], v[172:175], v[112:115]
	v_mfma_f32_16x16x32_bf16 v[112:115], v[160:163], v[176:179], v[112:115]
	v_mfma_f32_16x16x32_bf16 v[108:111], v[152:155], v[176:179], v[108:111]
	v_mfma_f32_16x16x32_bf16 v[108:111], v[148:151], v[172:175], v[108:111]
	v_mfma_f32_16x16x32_bf16 v[116:119], v[148:151], v[180:183], v[116:119]
	v_mfma_f32_16x16x32_bf16 v[116:119], v[152:155], v[184:187], v[116:119]
	v_mfma_f32_16x16x32_bf16 v[120:123], v[160:163], v[184:187], v[120:123]
	v_mfma_f32_16x16x32_bf16 v[120:123], v[156:159], v[180:183], v[120:123]
	s_setprio 2
	s_barrier
	v_mfma_f32_16x16x32_bf16 v[128:131], v[156:159], v[194:197], v[128:131]
	v_mfma_f32_16x16x32_bf16 v[128:131], v[160:163], v[198:201], v[128:131]
	v_mfma_f32_16x16x32_bf16 v[124:127], v[152:155], v[198:201], v[124:127]
	v_mfma_f32_16x16x32_bf16 v[124:127], v[148:151], v[194:197], v[124:127]
	s_setprio 0
	s_add_i32 s38, 0, 0x18000
	s_add_i32 s42, 0, 0x1c000
	v_add_u32_e32 v144, s38, v232
	v_add_u32_e32 v160, s42, v232
	ds_read_b128 v[132:135], v144
	ds_read_b128 v[136:139], v144 offset:1024
	ds_read_b128 v[140:143], v144 offset:2048
	ds_read_b128 v[144:147], v144 offset:3072
	ds_read_b128 v[148:151], v160
	ds_read_b128 v[152:155], v160 offset:1024
	ds_read_b128 v[156:159], v160 offset:2048
	ds_read_b128 v[160:163], v160 offset:3072
	s_add_u32 s26, s26, 0x160000
	s_addc_u32 s27, s27, 0
	s_mov_b32 m0, s57
	ds_read_b128 v[164:167], v210 offset:32768
	ds_read_b128 v[168:171], v210 offset:33792
	ds_read_b128 v[172:175], v210 offset:34816
	ds_read_b128 v[176:179], v210 offset:35840
	ds_read_b128 v[180:183], v210 offset:36864
	ds_read_b128 v[184:187], v210 offset:37888
	ds_read_b128 v[194:197], v210 offset:38912
	ds_read_b128 v[198:201], v210 offset:39936
	global_load_lds_dwordx4 v2, s[26:27]
	s_mov_b32 m0, s58
	s_nop 0
	global_load_lds_dwordx4 v188, s[26:27]
	s_waitcnt vmcnt(8)
	s_waitcnt lgkmcnt(0)
	s_barrier
	s_setprio 1
	s_waitcnt lgkmcnt(0)
	v_mfma_f32_16x16x32_bf16 v[4:7], v[132:135], v[164:167], v[4:7]
	v_mfma_f32_16x16x32_bf16 v[4:7], v[136:139], v[168:171], v[4:7]
	v_mfma_f32_16x16x32_bf16 v[8:11], v[144:147], v[168:171], v[8:11]
	v_mfma_f32_16x16x32_bf16 v[8:11], v[140:143], v[164:167], v[8:11]
	v_mfma_f32_16x16x32_bf16 v[16:19], v[140:143], v[172:175], v[16:19]
	v_mfma_f32_16x16x32_bf16 v[16:19], v[144:147], v[176:179], v[16:19]
	v_mfma_f32_16x16x32_bf16 v[12:15], v[136:139], v[176:179], v[12:15]
	v_mfma_f32_16x16x32_bf16 v[12:15], v[132:135], v[172:175], v[12:15]
	v_mfma_f32_16x16x32_bf16 v[20:23], v[132:135], v[180:183], v[20:23]
	v_mfma_f32_16x16x32_bf16 v[20:23], v[136:139], v[184:187], v[20:23]
	v_mfma_f32_16x16x32_bf16 v[24:27], v[144:147], v[184:187], v[24:27]
	v_mfma_f32_16x16x32_bf16 v[24:27], v[140:143], v[180:183], v[24:27]
	v_mfma_f32_16x16x32_bf16 v[32:35], v[140:143], v[194:197], v[32:35]
	v_mfma_f32_16x16x32_bf16 v[32:35], v[144:147], v[198:201], v[32:35]
	v_mfma_f32_16x16x32_bf16 v[28:31], v[136:139], v[198:201], v[28:31]
	v_mfma_f32_16x16x32_bf16 v[28:31], v[132:135], v[194:197], v[28:31]
	s_setprio 0
	s_setprio 1
	v_mfma_f32_16x16x32_bf16 v[36:39], v[148:151], v[164:167], v[36:39]
	v_mfma_f32_16x16x32_bf16 v[36:39], v[152:155], v[168:171], v[36:39]
	v_mfma_f32_16x16x32_bf16 v[40:43], v[160:163], v[168:171], v[40:43]
	v_mfma_f32_16x16x32_bf16 v[40:43], v[156:159], v[164:167], v[40:43]
	v_mfma_f32_16x16x32_bf16 v[48:51], v[156:159], v[172:175], v[48:51]
	v_mfma_f32_16x16x32_bf16 v[48:51], v[160:163], v[176:179], v[48:51]
	v_mfma_f32_16x16x32_bf16 v[44:47], v[152:155], v[176:179], v[44:47]
	v_mfma_f32_16x16x32_bf16 v[44:47], v[148:151], v[172:175], v[44:47]
	v_mfma_f32_16x16x32_bf16 v[52:55], v[148:151], v[180:183], v[52:55]
	v_mfma_f32_16x16x32_bf16 v[52:55], v[152:155], v[184:187], v[52:55]
	v_mfma_f32_16x16x32_bf16 v[56:59], v[160:163], v[184:187], v[56:59]
	v_mfma_f32_16x16x32_bf16 v[56:59], v[156:159], v[180:183], v[56:59]
	s_setprio 2
	s_barrier
	v_mfma_f32_16x16x32_bf16 v[64:67], v[156:159], v[194:197], v[64:67]
	v_mfma_f32_16x16x32_bf16 v[64:67], v[160:163], v[198:201], v[64:67]
	v_mfma_f32_16x16x32_bf16 v[60:63], v[152:155], v[198:201], v[60:63]
	v_mfma_f32_16x16x32_bf16 v[60:63], v[148:151], v[194:197], v[60:63]
	s_setprio 0
	s_add_i32 s26, s38, s54
	v_lshl_add_u64 v[202:203], v[202:203], 0, s[4:5]
	s_mov_b32 m0, s26
	ds_read_b128 v[164:167], v210 offset:49152
	ds_read_b128 v[168:171], v210 offset:50176
	ds_read_b128 v[172:175], v210 offset:51200
	ds_read_b128 v[176:179], v210 offset:52224
	ds_read_b128 v[180:183], v210 offset:53248
	ds_read_b128 v[184:187], v210 offset:54272
	ds_read_b128 v[194:197], v210 offset:55296
	ds_read_b128 v[198:201], v210 offset:56320
	global_load_lds_dwordx4 v[202:203], off
	s_add_i32 m0, s26, 0x2000
	s_add_u32 s16, s16, 0x15ff80
	v_lshl_add_u64 v[202:203], v[204:205], 0, s[4:5]
	s_addc_u32 s17, s17, 0
	s_add_i32 s26, s42, s54
	global_load_lds_dwordx4 v[202:203], off
	s_mov_b32 m0, s26
	v_lshl_add_u64 v[202:203], v[206:207], 0, s[4:5]
	global_load_lds_dwordx4 v192, s[16:17]
	s_add_i32 m0, s26, 0x2000
	s_nop 0
	global_load_lds_dwordx4 v190, s[16:17]
	s_mov_b32 m0, s62
	s_nop 0
	global_load_lds_dwordx4 v[202:203], off
	v_lshl_add_u64 v[202:203], v[208:209], 0, s[4:5]
	s_mov_b32 m0, s63
	s_nop 0
	global_load_lds_dwordx4 v[202:203], off
	s_waitcnt vmcnt(8)
	s_waitcnt lgkmcnt(0)
	s_barrier
	s_setprio 1
	s_waitcnt lgkmcnt(0)
	v_mfma_f32_16x16x32_bf16 v[68:71], v[132:135], v[164:167], v[68:71]
	v_mfma_f32_16x16x32_bf16 v[68:71], v[136:139], v[168:171], v[68:71]
	v_mfma_f32_16x16x32_bf16 v[72:75], v[144:147], v[168:171], v[72:75]
	v_mfma_f32_16x16x32_bf16 v[72:75], v[140:143], v[164:167], v[72:75]
	v_mfma_f32_16x16x32_bf16 v[80:83], v[140:143], v[172:175], v[80:83]
	v_mfma_f32_16x16x32_bf16 v[80:83], v[144:147], v[176:179], v[80:83]
	v_mfma_f32_16x16x32_bf16 v[76:79], v[136:139], v[176:179], v[76:79]
	v_mfma_f32_16x16x32_bf16 v[76:79], v[132:135], v[172:175], v[76:79]
	v_mfma_f32_16x16x32_bf16 v[84:87], v[132:135], v[180:183], v[84:87]
	v_mfma_f32_16x16x32_bf16 v[84:87], v[136:139], v[184:187], v[84:87]
	v_mfma_f32_16x16x32_bf16 v[88:91], v[144:147], v[184:187], v[88:91]
	v_mfma_f32_16x16x32_bf16 v[88:91], v[140:143], v[180:183], v[88:91]
	v_mfma_f32_16x16x32_bf16 v[96:99], v[140:143], v[194:197], v[96:99]
	v_mfma_f32_16x16x32_bf16 v[96:99], v[144:147], v[198:201], v[96:99]
	v_mfma_f32_16x16x32_bf16 v[92:95], v[136:139], v[198:201], v[92:95]
	v_mfma_f32_16x16x32_bf16 v[92:95], v[132:135], v[194:197], v[92:95]
	s_setprio 0
	s_setprio 1
	v_mfma_f32_16x16x32_bf16 v[100:103], v[148:151], v[164:167], v[100:103]
	v_mfma_f32_16x16x32_bf16 v[100:103], v[152:155], v[168:171], v[100:103]
	v_mfma_f32_16x16x32_bf16 v[104:107], v[160:163], v[168:171], v[104:107]
	v_mfma_f32_16x16x32_bf16 v[104:107], v[156:159], v[164:167], v[104:107]
	v_mfma_f32_16x16x32_bf16 v[112:115], v[156:159], v[172:175], v[112:115]
	v_mfma_f32_16x16x32_bf16 v[112:115], v[160:163], v[176:179], v[112:115]
	v_mfma_f32_16x16x32_bf16 v[108:111], v[152:155], v[176:179], v[108:111]
	v_mfma_f32_16x16x32_bf16 v[108:111], v[148:151], v[172:175], v[108:111]
	v_mfma_f32_16x16x32_bf16 v[116:119], v[148:151], v[180:183], v[116:119]
	v_mfma_f32_16x16x32_bf16 v[116:119], v[152:155], v[184:187], v[116:119]
	v_mfma_f32_16x16x32_bf16 v[120:123], v[160:163], v[184:187], v[120:123]
	v_mfma_f32_16x16x32_bf16 v[120:123], v[156:159], v[180:183], v[120:123]
	s_setprio 2
	s_barrier
	v_mfma_f32_16x16x32_bf16 v[128:131], v[156:159], v[194:197], v[128:131]
	v_mfma_f32_16x16x32_bf16 v[128:131], v[160:163], v[198:201], v[128:131]
	v_mfma_f32_16x16x32_bf16 v[124:127], v[152:155], v[198:201], v[124:127]
	v_mfma_f32_16x16x32_bf16 v[124:127], v[148:151], v[194:197], v[124:127]
	s_setprio 0
	s_cmpk_gt_u32 s28, 0x55
	s_cbranch_scc1 .LBB0_651
	s_mov_b32 s28, s29
	s_branch .LBB0_645

.LBB0_749:
	s_add_i32 s47, 0, 0x10000
	s_add_i32 s49, 0, 0x14000
	v_add_u32_e32 v16, s47, v147
	v_add_u32_e32 v32, s49, v147
	ds_read_b128 v[4:7], v16
	ds_read_b128 v[8:11], v16 offset:1024
	ds_read_b128 v[12:15], v16 offset:2048
	ds_read_b128 v[16:19], v16 offset:3072
	ds_read_b128 v[20:23], v32
	ds_read_b128 v[24:27], v32 offset:1024
	ds_read_b128 v[28:31], v32 offset:2048
	ds_read_b128 v[32:35], v32 offset:3072
	v_add_u32_e32 v231, 0, v146
	ds_read_b128 v[36:39], v231
	ds_read_b128 v[40:43], v231 offset:1024
	ds_read_b128 v[44:47], v231 offset:2048
	ds_read_b128 v[48:51], v231 offset:3072
	ds_read_b128 v[52:55], v231 offset:4096
	ds_read_b128 v[56:59], v231 offset:5120
	ds_read_b128 v[60:63], v231 offset:6144
	ds_read_b128 v[64:67], v231 offset:7168
	s_waitcnt vmcnt(8)
	s_waitcnt lgkmcnt(0)
	s_barrier
	s_setprio 1
	s_waitcnt lgkmcnt(0)
	v_mfma_f32_16x16x32_f16 v[68:71], v[4:7], v[36:39], 0
	v_mfma_f32_16x16x32_f16 v[68:71], v[8:11], v[40:43], v[68:71]
	v_mfma_f32_16x16x32_f16 v[72:75], v[12:15], v[36:39], 0
	v_mfma_f32_16x16x32_f16 v[72:75], v[16:19], v[40:43], v[72:75]
	v_mfma_f32_16x16x32_f16 v[80:83], v[12:15], v[44:47], 0
	v_mfma_f32_16x16x32_f16 v[80:83], v[16:19], v[48:51], v[80:83]
	v_mfma_f32_16x16x32_f16 v[76:79], v[4:7], v[44:47], 0
	v_mfma_f32_16x16x32_f16 v[76:79], v[8:11], v[48:51], v[76:79]
	v_mfma_f32_16x16x32_f16 v[84:87], v[4:7], v[52:55], 0
	v_mfma_f32_16x16x32_f16 v[84:87], v[8:11], v[56:59], v[84:87]
	v_mfma_f32_16x16x32_f16 v[88:91], v[12:15], v[52:55], 0
	v_mfma_f32_16x16x32_f16 v[88:91], v[16:19], v[56:59], v[88:91]
	v_mfma_f32_16x16x32_f16 v[96:99], v[12:15], v[60:63], 0
	v_mfma_f32_16x16x32_f16 v[96:99], v[16:19], v[64:67], v[96:99]
	v_mfma_f32_16x16x32_f16 v[92:95], v[4:7], v[60:63], 0
	v_mfma_f32_16x16x32_f16 v[92:95], v[8:11], v[64:67], v[92:95]
	s_setprio 0
	s_setprio 1
	v_mfma_f32_16x16x32_f16 v[100:103], v[20:23], v[36:39], 0
	v_mfma_f32_16x16x32_f16 v[36:39], v[28:31], v[36:39], 0
	v_mfma_f32_16x16x32_f16 v[104:107], v[20:23], v[44:47], 0
	v_mfma_f32_16x16x32_f16 v[44:47], v[28:31], v[44:47], 0
	v_mfma_f32_16x16x32_f16 v[108:111], v[20:23], v[52:55], 0
	v_mfma_f32_16x16x32_f16 v[52:55], v[28:31], v[52:55], 0
	v_mfma_f32_16x16x32_f16 v[112:115], v[20:23], v[60:63], 0
	v_mfma_f32_16x16x32_f16 v[60:63], v[28:31], v[60:63], 0
	v_mfma_f32_16x16x32_f16 v[100:103], v[24:27], v[40:43], v[100:103]
	v_mfma_f32_16x16x32_f16 v[40:43], v[32:35], v[40:43], v[36:39]
	v_mfma_f32_16x16x32_f16 v[104:107], v[24:27], v[48:51], v[104:107]
	v_mfma_f32_16x16x32_f16 v[48:51], v[32:35], v[48:51], v[44:47]
	s_setprio 2
	s_barrier
	v_mfma_f32_16x16x32_f16 v[108:111], v[24:27], v[56:59], v[108:111]
	v_mfma_f32_16x16x32_f16 v[56:59], v[32:35], v[56:59], v[52:55]
	v_mfma_f32_16x16x32_f16 v[112:115], v[24:27], v[64:67], v[112:115]
	v_mfma_f32_16x16x32_f16 v[64:67], v[32:35], v[64:67], v[60:63]
	s_setprio 0
	v_lshl_add_u64 v[136:137], s[6:7], 0, v[2:3]
	s_add_i32 s47, s47, s62
	v_mov_b32_e32 v135, v3
	v_lshl_add_u64 v[140:141], v[136:137], 0, s[74:75]
	s_mov_b32 m0, s47
	v_lshl_add_u64 v[144:145], s[6:7], 0, v[134:135]
	ds_read_b128 v[36:39], v231 offset:16384
	ds_read_b128 v[44:47], v231 offset:17408
	ds_read_b128 v[52:55], v231 offset:18432
	ds_read_b128 v[60:63], v231 offset:19456
	ds_read_b128 v[116:119], v231 offset:20480
	ds_read_b128 v[120:123], v231 offset:21504
	ds_read_b128 v[124:127], v231 offset:22528
	ds_read_b128 v[128:131], v231 offset:23552
	global_load_lds_dwordx4 v[140:141], off
	v_lshl_add_u64 v[140:141], v[144:145], 0, s[74:75]
	s_add_i32 m0, s47, 0x2000
	s_add_i32 s47, s49, s62
	global_load_lds_dwordx4 v[140:141], off
	s_mov_b32 m0, s47
	v_mov_b32_e32 v139, v3
	global_load_lds_dwordx4 v2, s[16:17]
	s_add_i32 m0, s47, 0x2000
	v_lshl_add_u64 v[248:249], s[8:9], 0, v[138:139]
	v_mov_b32_e32 v133, v3
	global_load_lds_dwordx4 v134, s[16:17]
	v_lshl_add_u64 v[140:141], v[248:249], 0, s[74:75]
	s_mov_b32 m0, s63
	v_lshl_add_u64 v[250:251], s[8:9], 0, v[132:133]
	global_load_lds_dwordx4 v[140:141], off
	v_lshl_add_u64 v[140:141], v[250:251], 0, s[74:75]
	s_mov_b32 m0, s64
	s_nop 0
	global_load_lds_dwordx4 v[140:141], off
	s_waitcnt vmcnt(8)
	s_waitcnt lgkmcnt(0)
	s_barrier
	s_setprio 1
	s_waitcnt lgkmcnt(0)
	v_mfma_f32_16x16x32_f16 v[140:143], v[4:7], v[36:39], 0
	v_mfma_f32_16x16x32_f16 v[148:151], v[12:15], v[36:39], 0
	v_mfma_f32_16x16x32_f16 v[152:155], v[4:7], v[52:55], 0
	v_mfma_f32_16x16x32_f16 v[156:159], v[12:15], v[52:55], 0
	v_mfma_f32_16x16x32_f16 v[160:163], v[4:7], v[116:119], 0
	v_mfma_f32_16x16x32_f16 v[164:167], v[12:15], v[116:119], 0
	v_mfma_f32_16x16x32_f16 v[4:7], v[4:7], v[124:127], 0
	v_mfma_f32_16x16x32_f16 v[12:15], v[12:15], v[124:127], 0
	v_mfma_f32_16x16x32_f16 v[140:143], v[8:11], v[44:47], v[140:143]
	v_mfma_f32_16x16x32_f16 v[148:151], v[16:19], v[44:47], v[148:151]
	v_mfma_f32_16x16x32_f16 v[152:155], v[8:11], v[60:63], v[152:155]
	v_mfma_f32_16x16x32_f16 v[156:159], v[16:19], v[60:63], v[156:159]
	v_mfma_f32_16x16x32_f16 v[160:163], v[8:11], v[120:123], v[160:163]
	v_mfma_f32_16x16x32_f16 v[164:167], v[16:19], v[120:123], v[164:167]
	v_mfma_f32_16x16x32_f16 v[168:171], v[8:11], v[128:131], v[4:7]
	v_mfma_f32_16x16x32_f16 v[172:175], v[16:19], v[128:131], v[12:15]
	s_setprio 0
	s_setprio 1
	v_mfma_f32_16x16x32_f16 v[4:7], v[20:23], v[36:39], 0
	v_mfma_f32_16x16x32_f16 v[8:11], v[28:31], v[36:39], 0
	v_mfma_f32_16x16x32_f16 v[12:15], v[20:23], v[52:55], 0
	v_mfma_f32_16x16x32_f16 v[16:19], v[28:31], v[52:55], 0
	v_mfma_f32_16x16x32_f16 v[36:39], v[20:23], v[116:119], 0
	v_mfma_f32_16x16x32_f16 v[52:55], v[28:31], v[116:119], 0
	v_mfma_f32_16x16x32_f16 v[20:23], v[20:23], v[124:127], 0
	v_mfma_f32_16x16x32_f16 v[28:31], v[28:31], v[124:127], 0
	v_mfma_f32_16x16x32_f16 v[116:119], v[24:27], v[44:47], v[4:7]
	v_mfma_f32_16x16x32_f16 v[124:127], v[32:35], v[44:47], v[8:11]
	v_mfma_f32_16x16x32_f16 v[184:187], v[24:27], v[120:123], v[36:39]
	v_mfma_f32_16x16x32_f16 v[120:123], v[32:35], v[120:123], v[52:55]
	s_setprio 2
	s_barrier
	v_mfma_f32_16x16x32_f16 v[188:191], v[24:27], v[128:131], v[20:23]
	v_mfma_f32_16x16x32_f16 v[128:131], v[32:35], v[128:131], v[28:31]
	v_mfma_f32_16x16x32_f16 v[176:179], v[24:27], v[60:63], v[12:15]
	v_mfma_f32_16x16x32_f16 v[180:183], v[32:35], v[60:63], v[16:19]
	s_setprio 0
	s_add_i32 s47, 0, 0x18000
	v_add_u32_e32 v4, s47, v147
	s_add_i32 s49, 0, 0x1c000
	ds_read_b128 v[192:195], v4
	ds_read_b128 v[196:199], v4 offset:1024
	ds_read_b128 v[200:203], v4 offset:2048
	ds_read_b128 v[204:207], v4 offset:3072
	v_add_u32_e32 v4, s49, v147
	ds_read_b128 v[208:211], v4
	ds_read_b128 v[212:215], v4 offset:1024
	ds_read_b128 v[216:219], v4 offset:2048
	ds_read_b128 v[220:223], v4 offset:3072
	s_mov_b32 m0, s65
	ds_read_b128 v[44:47], v231 offset:32768
	ds_read_b128 v[52:55], v231 offset:33792
	ds_read_b128 v[60:63], v231 offset:34816
	ds_read_b128 v[224:227], v231 offset:35840
	ds_read_b128 v[232:235], v231 offset:36864
	ds_read_b128 v[236:239], v231 offset:37888
	ds_read_b128 v[240:243], v231 offset:38912
	ds_read_b128 v[244:247], v231 offset:39936
	global_load_lds_dwordx4 v138, s[26:27]
	s_mov_b32 m0, s66
	s_nop 0
	global_load_lds_dwordx4 v132, s[26:27]
	s_waitcnt vmcnt(8)
	s_waitcnt lgkmcnt(0)
	s_barrier
	s_setprio 1
	s_waitcnt lgkmcnt(0)
	v_mfma_f32_16x16x32_f16 v[4:7], v[192:195], v[44:47], v[68:71]
	v_mfma_f32_16x16x32_f16 v[8:11], v[200:203], v[44:47], v[72:75]
	v_mfma_f32_16x16x32_f16 v[12:15], v[192:195], v[60:63], v[76:79]
	v_mfma_f32_16x16x32_f16 v[16:19], v[200:203], v[60:63], v[80:83]
	v_mfma_f32_16x16x32_f16 v[20:23], v[192:195], v[232:235], v[84:87]
	v_mfma_f32_16x16x32_f16 v[24:27], v[200:203], v[232:235], v[88:91]
	v_mfma_f32_16x16x32_f16 v[28:31], v[192:195], v[240:243], v[92:95]
	v_mfma_f32_16x16x32_f16 v[32:35], v[200:203], v[240:243], v[96:99]
	v_mfma_f32_16x16x32_f16 v[4:7], v[196:199], v[52:55], v[4:7]
	v_mfma_f32_16x16x32_f16 v[8:11], v[204:207], v[52:55], v[8:11]
	v_mfma_f32_16x16x32_f16 v[12:15], v[196:199], v[224:227], v[12:15]
	v_mfma_f32_16x16x32_f16 v[16:19], v[204:207], v[224:227], v[16:19]
	v_mfma_f32_16x16x32_f16 v[20:23], v[196:199], v[236:239], v[20:23]
	v_mfma_f32_16x16x32_f16 v[24:27], v[204:207], v[236:239], v[24:27]
	v_mfma_f32_16x16x32_f16 v[28:31], v[196:199], v[244:247], v[28:31]
	v_mfma_f32_16x16x32_f16 v[32:35], v[204:207], v[244:247], v[32:35]
	s_setprio 0
	s_setprio 1
	v_mfma_f32_16x16x32_f16 v[36:39], v[208:211], v[44:47], v[100:103]
	v_mfma_f32_16x16x32_f16 v[40:43], v[216:219], v[44:47], v[40:43]
	v_mfma_f32_16x16x32_f16 v[36:39], v[212:215], v[52:55], v[36:39]
	v_mfma_f32_16x16x32_f16 v[40:43], v[220:223], v[52:55], v[40:43]
	v_mfma_f32_16x16x32_f16 v[44:47], v[208:211], v[60:63], v[104:107]
	v_mfma_f32_16x16x32_f16 v[48:51], v[216:219], v[60:63], v[48:51]
	v_mfma_f32_16x16x32_f16 v[52:55], v[208:211], v[232:235], v[108:111]
	v_mfma_f32_16x16x32_f16 v[56:59], v[216:219], v[232:235], v[56:59]
	v_mfma_f32_16x16x32_f16 v[60:63], v[208:211], v[240:243], v[112:115]
	v_mfma_f32_16x16x32_f16 v[64:67], v[216:219], v[240:243], v[64:67]
	v_mfma_f32_16x16x32_f16 v[44:47], v[212:215], v[224:227], v[44:47]
	v_mfma_f32_16x16x32_f16 v[48:51], v[220:223], v[224:227], v[48:51]
	s_setprio 2
	s_barrier
	v_mfma_f32_16x16x32_f16 v[52:55], v[212:215], v[236:239], v[52:55]
	v_mfma_f32_16x16x32_f16 v[56:59], v[220:223], v[236:239], v[56:59]
	v_mfma_f32_16x16x32_f16 v[60:63], v[212:215], v[244:247], v[60:63]
	v_mfma_f32_16x16x32_f16 v[64:67], v[220:223], v[244:247], v[64:67]
	s_setprio 0
	s_add_i32 s47, s47, s62
	v_lshl_add_u64 v[68:69], v[136:137], 0, s[24:25]
	s_mov_b32 m0, s47
	ds_read_b128 v[104:107], v231 offset:49152
	ds_read_b128 v[108:111], v231 offset:50176
	ds_read_b128 v[112:115], v231 offset:51200
	ds_read_b128 v[224:227], v231 offset:52224
	ds_read_b128 v[232:235], v231 offset:53248
	ds_read_b128 v[236:239], v231 offset:54272
	ds_read_b128 v[240:243], v231 offset:55296
	ds_read_b128 v[244:247], v231 offset:56320
	global_load_lds_dwordx4 v[68:69], off
	v_lshl_add_u64 v[68:69], v[144:145], 0, s[24:25]
	s_add_i32 m0, s47, 0x2000
	s_add_i32 s47, s49, s62
	global_load_lds_dwordx4 v[68:69], off
	s_mov_b32 m0, s47
	v_lshl_add_u64 v[68:69], v[248:249], 0, s[24:25]
	global_load_lds_dwordx4 v2, s[28:29]
	s_add_i32 m0, s47, 0x2000
	s_nop 0
	global_load_lds_dwordx4 v134, s[28:29]
	s_mov_b32 m0, s69
	s_nop 0
	global_load_lds_dwordx4 v[68:69], off
	v_lshl_add_u64 v[68:69], v[250:251], 0, s[24:25]
	s_mov_b32 m0, s70
	s_nop 0
	global_load_lds_dwordx4 v[68:69], off
	s_waitcnt vmcnt(8)
	s_waitcnt lgkmcnt(0)
	s_barrier
	s_setprio 1
	s_waitcnt lgkmcnt(0)
	v_mfma_f32_16x16x32_f16 v[68:71], v[192:195], v[104:107], v[140:143]
	v_mfma_f32_16x16x32_f16 v[72:75], v[200:203], v[104:107], v[148:151]
	v_mfma_f32_16x16x32_f16 v[76:79], v[192:195], v[112:115], v[152:155]
	v_mfma_f32_16x16x32_f16 v[80:83], v[200:203], v[112:115], v[156:159]
	v_mfma_f32_16x16x32_f16 v[84:87], v[192:195], v[232:235], v[160:163]
	v_mfma_f32_16x16x32_f16 v[88:91], v[200:203], v[232:235], v[164:167]
	v_mfma_f32_16x16x32_f16 v[92:95], v[192:195], v[240:243], v[168:171]
	v_mfma_f32_16x16x32_f16 v[96:99], v[200:203], v[240:243], v[172:175]
	v_mfma_f32_16x16x32_f16 v[68:71], v[196:199], v[108:111], v[68:71]
	v_mfma_f32_16x16x32_f16 v[72:75], v[204:207], v[108:111], v[72:75]
	v_mfma_f32_16x16x32_f16 v[76:79], v[196:199], v[224:227], v[76:79]
	v_mfma_f32_16x16x32_f16 v[80:83], v[204:207], v[224:227], v[80:83]
	v_mfma_f32_16x16x32_f16 v[84:87], v[196:199], v[236:239], v[84:87]
	v_mfma_f32_16x16x32_f16 v[88:91], v[204:207], v[236:239], v[88:91]
	v_mfma_f32_16x16x32_f16 v[92:95], v[196:199], v[244:247], v[92:95]
	v_mfma_f32_16x16x32_f16 v[96:99], v[204:207], v[244:247], v[96:99]
	s_setprio 0
	s_setprio 1
	v_mfma_f32_16x16x32_f16 v[100:103], v[208:211], v[104:107], v[116:119]
	v_mfma_f32_16x16x32_f16 v[104:107], v[216:219], v[104:107], v[124:127]
	v_mfma_f32_16x16x32_f16 v[100:103], v[212:215], v[108:111], v[100:103]
	v_mfma_f32_16x16x32_f16 v[104:107], v[220:223], v[108:111], v[104:107]
	v_mfma_f32_16x16x32_f16 v[108:111], v[208:211], v[112:115], v[176:179]
	v_mfma_f32_16x16x32_f16 v[112:115], v[216:219], v[112:115], v[180:183]
	v_mfma_f32_16x16x32_f16 v[116:119], v[208:211], v[232:235], v[184:187]
	v_mfma_f32_16x16x32_f16 v[120:123], v[216:219], v[232:235], v[120:123]
	v_mfma_f32_16x16x32_f16 v[124:127], v[208:211], v[240:243], v[188:191]
	v_mfma_f32_16x16x32_f16 v[128:131], v[216:219], v[240:243], v[128:131]
	v_mfma_f32_16x16x32_f16 v[108:111], v[212:215], v[224:227], v[108:111]
	v_mfma_f32_16x16x32_f16 v[112:115], v[220:223], v[224:227], v[112:115]
	s_setprio 2
	s_barrier
	v_mfma_f32_16x16x32_f16 v[116:119], v[212:215], v[236:239], v[116:119]
	v_mfma_f32_16x16x32_f16 v[120:123], v[220:223], v[236:239], v[120:123]
	v_mfma_f32_16x16x32_f16 v[124:127], v[212:215], v[244:247], v[124:127]
	v_mfma_f32_16x16x32_f16 v[128:131], v[220:223], v[244:247], v[128:131]
	s_setprio 0
	s_add_i32 s45, s45, 2
	s_cmp_ge_i32 s45, s44
	s_cbranch_scc0 .LBB0_749
	v_mov_b32_e32 v136, v2
	s_branch .LBB0_752

.LBB0_753:
	s_add_u32 s6, s8, 0xfff80080
	s_addc_u32 s7, s9, -1
	s_add_i32 s29, 0, 0x10000
	s_cmp_eq_u32 s28, 28
	s_cselect_b32 s17, s13, s7
	s_cselect_b32 s16, s12, s6
	v_add_u32_e32 v133, s29, v147
	s_cselect_b32 s7, s15, s27
	s_cselect_b32 s6, s14, s26
	s_add_i32 s47, 0, 0x14000
	ds_read_b128 v[138:141], v133
	ds_read_b128 v[142:145], v133 offset:1024
	ds_read_b128 v[148:151], v133 offset:2048
	ds_read_b128 v[152:155], v133 offset:3072
	v_add_u32_e32 v133, s47, v147
	ds_read_b128 v[156:159], v133
	ds_read_b128 v[160:163], v133 offset:1024
	ds_read_b128 v[164:167], v133 offset:2048
	ds_read_b128 v[168:171], v133 offset:3072
	s_mov_b32 m0, s71
	v_add_u32_e32 v212, 0, v146
	ds_read_b128 v[172:175], v212
	ds_read_b128 v[176:179], v212 offset:1024
	ds_read_b128 v[180:183], v212 offset:2048
	ds_read_b128 v[184:187], v212 offset:3072
	ds_read_b128 v[188:191], v212 offset:4096
	ds_read_b128 v[192:195], v212 offset:5120
	ds_read_b128 v[196:199], v212 offset:6144
	ds_read_b128 v[200:203], v212 offset:7168
	global_load_lds_dwordx4 v2, s[8:9]
	s_mov_b32 m0, s72
	v_mov_b32_e32 v133, v3
	global_load_lds_dwordx4 v132, s[8:9]
	s_waitcnt vmcnt(8)
	s_waitcnt lgkmcnt(0)
	s_barrier
	s_setprio 1
	s_waitcnt lgkmcnt(0)
	v_mfma_f32_16x16x32_f16 v[4:7], v[138:141], v[172:175], v[4:7]
	v_mfma_f32_16x16x32_f16 v[4:7], v[142:145], v[176:179], v[4:7]
	v_mfma_f32_16x16x32_f16 v[8:11], v[152:155], v[176:179], v[8:11]
	v_mfma_f32_16x16x32_f16 v[8:11], v[148:151], v[172:175], v[8:11]
	v_mfma_f32_16x16x32_f16 v[16:19], v[148:151], v[180:183], v[16:19]
	v_mfma_f32_16x16x32_f16 v[16:19], v[152:155], v[184:187], v[16:19]
	v_mfma_f32_16x16x32_f16 v[12:15], v[142:145], v[184:187], v[12:15]
	v_mfma_f32_16x16x32_f16 v[12:15], v[138:141], v[180:183], v[12:15]
	v_mfma_f32_16x16x32_f16 v[20:23], v[138:141], v[188:191], v[20:23]
	v_mfma_f32_16x16x32_f16 v[20:23], v[142:145], v[192:195], v[20:23]
	v_mfma_f32_16x16x32_f16 v[24:27], v[152:155], v[192:195], v[24:27]
	v_mfma_f32_16x16x32_f16 v[24:27], v[148:151], v[188:191], v[24:27]
	v_mfma_f32_16x16x32_f16 v[32:35], v[148:151], v[196:199], v[32:35]
	v_mfma_f32_16x16x32_f16 v[32:35], v[152:155], v[200:203], v[32:35]
	v_mfma_f32_16x16x32_f16 v[28:31], v[142:145], v[200:203], v[28:31]
	v_mfma_f32_16x16x32_f16 v[28:31], v[138:141], v[196:199], v[28:31]
	s_setprio 0
	s_setprio 1
	v_mfma_f32_16x16x32_f16 v[36:39], v[156:159], v[172:175], v[36:39]
	v_mfma_f32_16x16x32_f16 v[36:39], v[160:163], v[176:179], v[36:39]
	v_mfma_f32_16x16x32_f16 v[40:43], v[168:171], v[176:179], v[40:43]
	v_mfma_f32_16x16x32_f16 v[40:43], v[164:167], v[172:175], v[40:43]
	v_mfma_f32_16x16x32_f16 v[48:51], v[164:167], v[180:183], v[48:51]
	v_mfma_f32_16x16x32_f16 v[48:51], v[168:171], v[184:187], v[48:51]
	v_mfma_f32_16x16x32_f16 v[44:47], v[160:163], v[184:187], v[44:47]
	v_mfma_f32_16x16x32_f16 v[44:47], v[156:159], v[180:183], v[44:47]
	v_mfma_f32_16x16x32_f16 v[52:55], v[156:159], v[188:191], v[52:55]
	v_mfma_f32_16x16x32_f16 v[52:55], v[160:163], v[192:195], v[52:55]
	v_mfma_f32_16x16x32_f16 v[56:59], v[168:171], v[192:195], v[56:59]
	v_mfma_f32_16x16x32_f16 v[56:59], v[164:167], v[188:191], v[56:59]
	s_setprio 2
	s_barrier
	v_mfma_f32_16x16x32_f16 v[64:67], v[164:167], v[196:199], v[64:67]
	v_mfma_f32_16x16x32_f16 v[64:67], v[168:171], v[200:203], v[64:67]
	v_mfma_f32_16x16x32_f16 v[60:63], v[160:163], v[200:203], v[60:63]
	v_mfma_f32_16x16x32_f16 v[60:63], v[156:159], v[196:199], v[60:63]
	s_setprio 0
	s_add_i32 s29, s29, s62
	s_mov_b32 m0, s29
	ds_read_b128 v[172:175], v212 offset:16384
	ds_read_b128 v[176:179], v212 offset:17408
	ds_read_b128 v[180:183], v212 offset:18432
	ds_read_b128 v[184:187], v212 offset:19456
	ds_read_b128 v[188:191], v212 offset:20480
	ds_read_b128 v[192:195], v212 offset:21504
	ds_read_b128 v[196:199], v212 offset:22528
	ds_read_b128 v[200:203], v212 offset:23552
	global_load_lds_dwordx4 v136, s[6:7]
	s_add_i32 m0, s29, 0x2000
	s_add_u32 s44, s6, 0x80000
	s_addc_u32 s45, s7, 0
	s_add_i32 s29, s47, s62
	global_load_lds_dwordx4 v134, s[6:7]
	s_mov_b32 m0, s29
	v_mov_b32_e32 v137, v3
	global_load_lds_dwordx4 v136, s[44:45]
	s_add_i32 m0, s29, 0x2000
	v_mov_b32_e32 v135, v3
	global_load_lds_dwordx4 v134, s[44:45]
	s_mov_b32 m0, s63
	v_lshl_add_u64 v[204:205], s[6:7], 0, v[136:137]
	global_load_lds_dwordx4 v2, s[16:17]
	s_mov_b32 m0, s64
	v_lshl_add_u64 v[206:207], s[6:7], 0, v[134:135]
	global_load_lds_dwordx4 v132, s[16:17]
	s_waitcnt vmcnt(8)
	s_waitcnt lgkmcnt(0)
	v_lshl_add_u64 v[208:209], s[16:17], 0, v[2:3]
	v_lshl_add_u64 v[210:211], s[16:17], 0, v[132:133]
	s_barrier
	s_setprio 1
	s_waitcnt lgkmcnt(0)
	v_mfma_f32_16x16x32_f16 v[68:71], v[138:141], v[172:175], v[68:71]
	v_mfma_f32_16x16x32_f16 v[68:71], v[142:145], v[176:179], v[68:71]
	v_mfma_f32_16x16x32_f16 v[72:75], v[152:155], v[176:179], v[72:75]
	v_mfma_f32_16x16x32_f16 v[72:75], v[148:151], v[172:175], v[72:75]
	v_mfma_f32_16x16x32_f16 v[80:83], v[148:151], v[180:183], v[80:83]
	v_mfma_f32_16x16x32_f16 v[80:83], v[152:155], v[184:187], v[80:83]
	v_mfma_f32_16x16x32_f16 v[76:79], v[142:145], v[184:187], v[76:79]
	v_mfma_f32_16x16x32_f16 v[76:79], v[138:141], v[180:183], v[76:79]
	v_mfma_f32_16x16x32_f16 v[84:87], v[138:141], v[188:191], v[84:87]
	v_mfma_f32_16x16x32_f16 v[84:87], v[142:145], v[192:195], v[84:87]
	v_mfma_f32_16x16x32_f16 v[88:91], v[152:155], v[192:195], v[88:91]
	v_mfma_f32_16x16x32_f16 v[88:91], v[148:151], v[188:191], v[88:91]
	v_mfma_f32_16x16x32_f16 v[96:99], v[148:151], v[196:199], v[96:99]
	v_mfma_f32_16x16x32_f16 v[96:99], v[152:155], v[200:203], v[96:99]
	v_mfma_f32_16x16x32_f16 v[92:95], v[142:145], v[200:203], v[92:95]
	v_mfma_f32_16x16x32_f16 v[92:95], v[138:141], v[196:199], v[92:95]
	s_setprio 0
	s_setprio 1
	v_mfma_f32_16x16x32_f16 v[100:103], v[156:159], v[172:175], v[100:103]
	v_mfma_f32_16x16x32_f16 v[100:103], v[160:163], v[176:179], v[100:103]
	v_mfma_f32_16x16x32_f16 v[104:107], v[168:171], v[176:179], v[104:107]
	v_mfma_f32_16x16x32_f16 v[104:107], v[164:167], v[172:175], v[104:107]
	v_mfma_f32_16x16x32_f16 v[112:115], v[164:167], v[180:183], v[112:115]
	v_mfma_f32_16x16x32_f16 v[112:115], v[168:171], v[184:187], v[112:115]
	v_mfma_f32_16x16x32_f16 v[108:111], v[160:163], v[184:187], v[108:111]
	v_mfma_f32_16x16x32_f16 v[108:111], v[156:159], v[180:183], v[108:111]
	v_mfma_f32_16x16x32_f16 v[116:119], v[156:159], v[188:191], v[116:119]
	v_mfma_f32_16x16x32_f16 v[116:119], v[160:163], v[192:195], v[116:119]
	v_mfma_f32_16x16x32_f16 v[120:123], v[168:171], v[192:195], v[120:123]
	v_mfma_f32_16x16x32_f16 v[120:123], v[164:167], v[188:191], v[120:123]
	s_setprio 2
	s_barrier
	v_mfma_f32_16x16x32_f16 v[128:131], v[164:167], v[196:199], v[128:131]
	v_mfma_f32_16x16x32_f16 v[128:131], v[168:171], v[200:203], v[128:131]
	v_mfma_f32_16x16x32_f16 v[124:127], v[160:163], v[200:203], v[124:127]
	v_mfma_f32_16x16x32_f16 v[124:127], v[156:159], v[196:199], v[124:127]
	s_setprio 0
	s_add_i32 s29, 0, 0x18000
	v_add_u32_e32 v135, s29, v147
	s_add_i32 s44, 0, 0x1c000
	ds_read_b128 v[138:141], v135
	ds_read_b128 v[142:145], v135 offset:1024
	ds_read_b128 v[148:151], v135 offset:2048
	ds_read_b128 v[152:155], v135 offset:3072
	v_add_u32_e32 v135, s44, v147
	ds_read_b128 v[156:159], v135
	ds_read_b128 v[160:163], v135 offset:1024
	ds_read_b128 v[164:167], v135 offset:2048
	ds_read_b128 v[168:171], v135 offset:3072
	s_add_u32 s16, s16, 0x80000
	s_addc_u32 s17, s17, 0
	s_mov_b32 m0, s65
	ds_read_b128 v[172:175], v212 offset:32768
	ds_read_b128 v[176:179], v212 offset:33792
	ds_read_b128 v[180:183], v212 offset:34816
	ds_read_b128 v[184:187], v212 offset:35840
	ds_read_b128 v[188:191], v212 offset:36864
	ds_read_b128 v[192:195], v212 offset:37888
	ds_read_b128 v[196:199], v212 offset:38912
	ds_read_b128 v[200:203], v212 offset:39936
	global_load_lds_dwordx4 v2, s[16:17]
	s_mov_b32 m0, s66
	s_nop 0
	global_load_lds_dwordx4 v132, s[16:17]
	s_waitcnt vmcnt(8)
	s_waitcnt lgkmcnt(0)
	s_barrier
	s_setprio 1
	s_waitcnt lgkmcnt(0)
	v_mfma_f32_16x16x32_f16 v[4:7], v[138:141], v[172:175], v[4:7]
	v_mfma_f32_16x16x32_f16 v[4:7], v[142:145], v[176:179], v[4:7]
	v_mfma_f32_16x16x32_f16 v[8:11], v[152:155], v[176:179], v[8:11]
	v_mfma_f32_16x16x32_f16 v[8:11], v[148:151], v[172:175], v[8:11]
	v_mfma_f32_16x16x32_f16 v[16:19], v[148:151], v[180:183], v[16:19]
	v_mfma_f32_16x16x32_f16 v[16:19], v[152:155], v[184:187], v[16:19]
	v_mfma_f32_16x16x32_f16 v[12:15], v[142:145], v[184:187], v[12:15]
	v_mfma_f32_16x16x32_f16 v[12:15], v[138:141], v[180:183], v[12:15]
	v_mfma_f32_16x16x32_f16 v[20:23], v[138:141], v[188:191], v[20:23]
	v_mfma_f32_16x16x32_f16 v[20:23], v[142:145], v[192:195], v[20:23]
	v_mfma_f32_16x16x32_f16 v[24:27], v[152:155], v[192:195], v[24:27]
	v_mfma_f32_16x16x32_f16 v[24:27], v[148:151], v[188:191], v[24:27]
	v_mfma_f32_16x16x32_f16 v[32:35], v[148:151], v[196:199], v[32:35]
	v_mfma_f32_16x16x32_f16 v[32:35], v[152:155], v[200:203], v[32:35]
	v_mfma_f32_16x16x32_f16 v[28:31], v[142:145], v[200:203], v[28:31]
	v_mfma_f32_16x16x32_f16 v[28:31], v[138:141], v[196:199], v[28:31]
	s_setprio 0
	s_setprio 1
	v_mfma_f32_16x16x32_f16 v[36:39], v[156:159], v[172:175], v[36:39]
	v_mfma_f32_16x16x32_f16 v[36:39], v[160:163], v[176:179], v[36:39]
	v_mfma_f32_16x16x32_f16 v[40:43], v[168:171], v[176:179], v[40:43]
	v_mfma_f32_16x16x32_f16 v[40:43], v[164:167], v[172:175], v[40:43]
	v_mfma_f32_16x16x32_f16 v[48:51], v[164:167], v[180:183], v[48:51]
	v_mfma_f32_16x16x32_f16 v[48:51], v[168:171], v[184:187], v[48:51]
	v_mfma_f32_16x16x32_f16 v[44:47], v[160:163], v[184:187], v[44:47]
	v_mfma_f32_16x16x32_f16 v[44:47], v[156:159], v[180:183], v[44:47]
	v_mfma_f32_16x16x32_f16 v[52:55], v[156:159], v[188:191], v[52:55]
	v_mfma_f32_16x16x32_f16 v[52:55], v[160:163], v[192:195], v[52:55]
	v_mfma_f32_16x16x32_f16 v[56:59], v[168:171], v[192:195], v[56:59]
	v_mfma_f32_16x16x32_f16 v[56:59], v[164:167], v[188:191], v[56:59]
	s_setprio 2
	s_barrier
	v_mfma_f32_16x16x32_f16 v[64:67], v[164:167], v[196:199], v[64:67]
	v_mfma_f32_16x16x32_f16 v[64:67], v[168:171], v[200:203], v[64:67]
	v_mfma_f32_16x16x32_f16 v[60:63], v[160:163], v[200:203], v[60:63]
	v_mfma_f32_16x16x32_f16 v[60:63], v[156:159], v[196:199], v[60:63]
	s_setprio 0
	s_add_i32 s16, s29, s62
	v_lshl_add_u64 v[204:205], v[204:205], 0, s[86:87]
	s_mov_b32 m0, s16
	ds_read_b128 v[172:175], v212 offset:49152
	ds_read_b128 v[176:179], v212 offset:50176
	ds_read_b128 v[180:183], v212 offset:51200
	ds_read_b128 v[184:187], v212 offset:52224
	ds_read_b128 v[188:191], v212 offset:53248
	ds_read_b128 v[192:195], v212 offset:54272
	ds_read_b128 v[196:199], v212 offset:55296
	ds_read_b128 v[200:203], v212 offset:56320
	global_load_lds_dwordx4 v[204:205], off
	s_add_i32 m0, s16, 0x2000
	s_add_u32 s6, s6, 0x80080
	v_lshl_add_u64 v[204:205], v[206:207], 0, s[86:87]
	s_addc_u32 s7, s7, 0
	s_add_i32 s16, s44, s62
	global_load_lds_dwordx4 v[204:205], off
	s_mov_b32 m0, s16
	v_lshl_add_u64 v[204:205], v[208:209], 0, s[86:87]
	global_load_lds_dwordx4 v136, s[6:7]
	s_add_i32 m0, s16, 0x2000
	s_nop 0
	global_load_lds_dwordx4 v134, s[6:7]
	s_mov_b32 m0, s69
	s_nop 0
	global_load_lds_dwordx4 v[204:205], off
	v_lshl_add_u64 v[204:205], v[210:211], 0, s[86:87]
	s_mov_b32 m0, s70
	s_nop 0
	global_load_lds_dwordx4 v[204:205], off
	s_waitcnt vmcnt(8)
	s_waitcnt lgkmcnt(0)
	s_barrier
	s_setprio 1
	s_waitcnt lgkmcnt(0)
	v_mfma_f32_16x16x32_f16 v[68:71], v[138:141], v[172:175], v[68:71]
	v_mfma_f32_16x16x32_f16 v[68:71], v[142:145], v[176:179], v[68:71]
	v_mfma_f32_16x16x32_f16 v[72:75], v[152:155], v[176:179], v[72:75]
	v_mfma_f32_16x16x32_f16 v[72:75], v[148:151], v[172:175], v[72:75]
	v_mfma_f32_16x16x32_f16 v[80:83], v[148:151], v[180:183], v[80:83]
	v_mfma_f32_16x16x32_f16 v[80:83], v[152:155], v[184:187], v[80:83]
	v_mfma_f32_16x16x32_f16 v[76:79], v[142:145], v[184:187], v[76:79]
	v_mfma_f32_16x16x32_f16 v[76:79], v[138:141], v[180:183], v[76:79]
	v_mfma_f32_16x16x32_f16 v[84:87], v[138:141], v[188:191], v[84:87]
	v_mfma_f32_16x16x32_f16 v[84:87], v[142:145], v[192:195], v[84:87]
	v_mfma_f32_16x16x32_f16 v[88:91], v[152:155], v[192:195], v[88:91]
	v_mfma_f32_16x16x32_f16 v[88:91], v[148:151], v[188:191], v[88:91]
	v_mfma_f32_16x16x32_f16 v[96:99], v[148:151], v[196:199], v[96:99]
	v_mfma_f32_16x16x32_f16 v[96:99], v[152:155], v[200:203], v[96:99]
	v_mfma_f32_16x16x32_f16 v[92:95], v[142:145], v[200:203], v[92:95]
	v_mfma_f32_16x16x32_f16 v[92:95], v[138:141], v[196:199], v[92:95]
	s_setprio 0
	s_setprio 1
	v_mfma_f32_16x16x32_f16 v[100:103], v[156:159], v[172:175], v[100:103]
	v_mfma_f32_16x16x32_f16 v[100:103], v[160:163], v[176:179], v[100:103]
	v_mfma_f32_16x16x32_f16 v[104:107], v[168:171], v[176:179], v[104:107]
	v_mfma_f32_16x16x32_f16 v[104:107], v[164:167], v[172:175], v[104:107]
	v_mfma_f32_16x16x32_f16 v[112:115], v[164:167], v[180:183], v[112:115]
	v_mfma_f32_16x16x32_f16 v[112:115], v[168:171], v[184:187], v[112:115]
	v_mfma_f32_16x16x32_f16 v[108:111], v[160:163], v[184:187], v[108:111]
	v_mfma_f32_16x16x32_f16 v[108:111], v[156:159], v[180:183], v[108:111]
	v_mfma_f32_16x16x32_f16 v[116:119], v[156:159], v[188:191], v[116:119]
	v_mfma_f32_16x16x32_f16 v[116:119], v[160:163], v[192:195], v[116:119]
	v_mfma_f32_16x16x32_f16 v[120:123], v[168:171], v[192:195], v[120:123]
	v_mfma_f32_16x16x32_f16 v[120:123], v[164:167], v[188:191], v[120:123]
	s_setprio 2
	s_barrier
	v_mfma_f32_16x16x32_f16 v[128:131], v[164:167], v[196:199], v[128:131]
	v_mfma_f32_16x16x32_f16 v[128:131], v[168:171], v[200:203], v[128:131]
	v_mfma_f32_16x16x32_f16 v[124:127], v[160:163], v[200:203], v[124:127]
	v_mfma_f32_16x16x32_f16 v[124:127], v[156:159], v[196:199], v[124:127]
	s_setprio 0
	s_add_i32 s28, s28, 2
	s_add_u32 s8, s8, 0x100
	s_addc_u32 s9, s9, 0
	s_add_u32 s26, s26, 0x100
	s_addc_u32 s27, s27, 0
	s_cmp_gt_u32 s28, 29
	s_cbranch_scc0 .LBB0_753
	s_and_b64 vcc, exec, s[52:53]
	s_cbranch_vccz .LBB0_756
	s_barrier

.LBB0_1175:
	s_add_i32 s61, 0, 0x10000
	s_add_i32 s79, 0, 0x14000
	v_add_u32_e32 v16, s61, v209
	v_add_u32_e32 v32, s79, v209
	ds_read_b128 v[4:7], v16
	ds_read_b128 v[8:11], v16 offset:1024
	ds_read_b128 v[12:15], v16 offset:2048
	ds_read_b128 v[16:19], v16 offset:3072
	ds_read_b128 v[20:23], v32
	ds_read_b128 v[24:27], v32 offset:1024
	ds_read_b128 v[28:31], v32 offset:2048
	ds_read_b128 v[32:35], v32 offset:3072
	v_add_u32_e32 v231, 0, v208
	ds_read_b128 v[36:39], v231
	ds_read_b128 v[40:43], v231 offset:1024
	ds_read_b128 v[44:47], v231 offset:2048
	ds_read_b128 v[48:51], v231 offset:3072
	ds_read_b128 v[52:55], v231 offset:4096
	ds_read_b128 v[56:59], v231 offset:5120
	ds_read_b128 v[60:63], v231 offset:6144
	ds_read_b128 v[64:67], v231 offset:7168
	s_waitcnt vmcnt(8)
	s_waitcnt lgkmcnt(0)
	s_barrier
	s_setprio 1
	s_waitcnt lgkmcnt(0)
	v_mfma_f32_16x16x32_bf16 v[68:71], v[4:7], v[36:39], 0
	v_mfma_f32_16x16x32_bf16 v[68:71], v[8:11], v[40:43], v[68:71]
	v_mfma_f32_16x16x32_bf16 v[72:75], v[12:15], v[36:39], 0
	v_mfma_f32_16x16x32_bf16 v[72:75], v[16:19], v[40:43], v[72:75]
	v_mfma_f32_16x16x32_bf16 v[80:83], v[12:15], v[44:47], 0
	v_mfma_f32_16x16x32_bf16 v[80:83], v[16:19], v[48:51], v[80:83]
	v_mfma_f32_16x16x32_bf16 v[76:79], v[4:7], v[44:47], 0
	v_mfma_f32_16x16x32_bf16 v[76:79], v[8:11], v[48:51], v[76:79]
	v_mfma_f32_16x16x32_bf16 v[84:87], v[4:7], v[52:55], 0
	v_mfma_f32_16x16x32_bf16 v[84:87], v[8:11], v[56:59], v[84:87]
	v_mfma_f32_16x16x32_bf16 v[88:91], v[12:15], v[52:55], 0
	v_mfma_f32_16x16x32_bf16 v[88:91], v[16:19], v[56:59], v[88:91]
	v_mfma_f32_16x16x32_bf16 v[96:99], v[12:15], v[60:63], 0
	v_mfma_f32_16x16x32_bf16 v[96:99], v[16:19], v[64:67], v[96:99]
	v_mfma_f32_16x16x32_bf16 v[92:95], v[4:7], v[60:63], 0
	v_mfma_f32_16x16x32_bf16 v[92:95], v[8:11], v[64:67], v[92:95]
	s_setprio 0
	s_setprio 1
	v_mfma_f32_16x16x32_bf16 v[100:103], v[20:23], v[36:39], 0
	v_mfma_f32_16x16x32_bf16 v[36:39], v[28:31], v[36:39], 0
	v_mfma_f32_16x16x32_bf16 v[104:107], v[20:23], v[44:47], 0
	v_mfma_f32_16x16x32_bf16 v[44:47], v[28:31], v[44:47], 0
	v_mfma_f32_16x16x32_bf16 v[108:111], v[20:23], v[52:55], 0
	v_mfma_f32_16x16x32_bf16 v[52:55], v[28:31], v[52:55], 0
	v_mfma_f32_16x16x32_bf16 v[112:115], v[20:23], v[60:63], 0
	v_mfma_f32_16x16x32_bf16 v[60:63], v[28:31], v[60:63], 0
	v_mfma_f32_16x16x32_bf16 v[100:103], v[24:27], v[40:43], v[100:103]
	v_mfma_f32_16x16x32_bf16 v[40:43], v[32:35], v[40:43], v[36:39]
	v_mfma_f32_16x16x32_bf16 v[104:107], v[24:27], v[48:51], v[104:107]
	v_mfma_f32_16x16x32_bf16 v[48:51], v[32:35], v[48:51], v[44:47]
	s_setprio 2
	s_barrier
	v_mfma_f32_16x16x32_bf16 v[108:111], v[24:27], v[56:59], v[108:111]
	v_mfma_f32_16x16x32_bf16 v[56:59], v[32:35], v[56:59], v[52:55]
	v_mfma_f32_16x16x32_bf16 v[112:115], v[24:27], v[64:67], v[112:115]
	v_mfma_f32_16x16x32_bf16 v[64:67], v[32:35], v[64:67], v[60:63]
	s_setprio 0
	v_lshl_add_u64 v[186:187], s[12:13], 0, v[2:3]
	s_add_i32 s61, s61, s36
	v_mov_b32_e32 v191, v3
	v_lshl_add_u64 v[134:135], v[186:187], 0, s[74:75]
	s_mov_b32 m0, s61
	v_lshl_add_u64 v[226:227], s[12:13], 0, v[190:191]
	ds_read_b128 v[36:39], v231 offset:16384
	ds_read_b128 v[44:47], v231 offset:17408
	ds_read_b128 v[52:55], v231 offset:18432
	ds_read_b128 v[60:63], v231 offset:19456
	ds_read_b128 v[116:119], v231 offset:20480
	ds_read_b128 v[120:123], v231 offset:21504
	ds_read_b128 v[124:127], v231 offset:22528
	ds_read_b128 v[128:131], v231 offset:23552
	global_load_lds_dwordx4 v[134:135], off
	v_lshl_add_u64 v[134:135], v[226:227], 0, s[74:75]
	s_add_i32 m0, s61, 0x2000
	s_add_i32 s61, s79, s36
	global_load_lds_dwordx4 v[134:135], off
	s_mov_b32 m0, s61
	v_mov_b32_e32 v133, v3
	global_load_lds_dwordx4 v2, s[16:17]
	s_add_i32 m0, s61, 0x2000
	v_lshl_add_u64 v[248:249], s[6:7], 0, v[132:133]
	v_mov_b32_e32 v189, v3
	global_load_lds_dwordx4 v190, s[16:17]
	v_lshl_add_u64 v[134:135], v[248:249], 0, s[74:75]
	s_mov_b32 m0, s37
	v_lshl_add_u64 v[250:251], s[6:7], 0, v[188:189]
	global_load_lds_dwordx4 v[134:135], off
	v_lshl_add_u64 v[134:135], v[250:251], 0, s[74:75]
	s_mov_b32 m0, s66
	s_nop 0
	global_load_lds_dwordx4 v[134:135], off
	s_waitcnt vmcnt(8)
	s_waitcnt lgkmcnt(0)
	s_barrier
	s_setprio 1
	s_waitcnt lgkmcnt(0)
	v_mfma_f32_16x16x32_bf16 v[134:137], v[4:7], v[36:39], 0
	v_mfma_f32_16x16x32_bf16 v[138:141], v[12:15], v[36:39], 0
	v_mfma_f32_16x16x32_bf16 v[142:145], v[4:7], v[52:55], 0
	v_mfma_f32_16x16x32_bf16 v[146:149], v[12:15], v[52:55], 0
	v_mfma_f32_16x16x32_bf16 v[150:153], v[4:7], v[116:119], 0
	v_mfma_f32_16x16x32_bf16 v[154:157], v[12:15], v[116:119], 0
	v_mfma_f32_16x16x32_bf16 v[4:7], v[4:7], v[124:127], 0
	v_mfma_f32_16x16x32_bf16 v[12:15], v[12:15], v[124:127], 0
	v_mfma_f32_16x16x32_bf16 v[134:137], v[8:11], v[44:47], v[134:137]
	v_mfma_f32_16x16x32_bf16 v[138:141], v[16:19], v[44:47], v[138:141]
	v_mfma_f32_16x16x32_bf16 v[142:145], v[8:11], v[60:63], v[142:145]
	v_mfma_f32_16x16x32_bf16 v[146:149], v[16:19], v[60:63], v[146:149]
	v_mfma_f32_16x16x32_bf16 v[150:153], v[8:11], v[120:123], v[150:153]
	v_mfma_f32_16x16x32_bf16 v[154:157], v[16:19], v[120:123], v[154:157]
	v_mfma_f32_16x16x32_bf16 v[158:161], v[8:11], v[128:131], v[4:7]
	v_mfma_f32_16x16x32_bf16 v[162:165], v[16:19], v[128:131], v[12:15]
	s_setprio 0
	s_setprio 1
	v_mfma_f32_16x16x32_bf16 v[4:7], v[20:23], v[36:39], 0
	v_mfma_f32_16x16x32_bf16 v[8:11], v[28:31], v[36:39], 0
	v_mfma_f32_16x16x32_bf16 v[12:15], v[20:23], v[52:55], 0
	v_mfma_f32_16x16x32_bf16 v[16:19], v[28:31], v[52:55], 0
	v_mfma_f32_16x16x32_bf16 v[36:39], v[20:23], v[116:119], 0
	v_mfma_f32_16x16x32_bf16 v[52:55], v[28:31], v[116:119], 0
	v_mfma_f32_16x16x32_bf16 v[20:23], v[20:23], v[124:127], 0
	v_mfma_f32_16x16x32_bf16 v[28:31], v[28:31], v[124:127], 0
	v_mfma_f32_16x16x32_bf16 v[116:119], v[24:27], v[44:47], v[4:7]
	v_mfma_f32_16x16x32_bf16 v[124:127], v[32:35], v[44:47], v[8:11]
	v_mfma_f32_16x16x32_bf16 v[174:177], v[24:27], v[120:123], v[36:39]
	v_mfma_f32_16x16x32_bf16 v[120:123], v[32:35], v[120:123], v[52:55]
	s_setprio 2
	s_barrier
	v_mfma_f32_16x16x32_bf16 v[178:181], v[24:27], v[128:131], v[20:23]
	v_mfma_f32_16x16x32_bf16 v[128:131], v[32:35], v[128:131], v[28:31]
	v_mfma_f32_16x16x32_bf16 v[166:169], v[24:27], v[60:63], v[12:15]
	v_mfma_f32_16x16x32_bf16 v[170:173], v[32:35], v[60:63], v[16:19]
	s_setprio 0
	s_add_i32 s61, 0, 0x18000
	v_add_u32_e32 v4, s61, v209
	s_add_i32 s79, 0, 0x1c000
	ds_read_b128 v[182:185], v4
	ds_read_b128 v[192:195], v4 offset:1024
	ds_read_b128 v[196:199], v4 offset:2048
	ds_read_b128 v[200:203], v4 offset:3072
	v_add_u32_e32 v4, s79, v209
	ds_read_b128 v[204:207], v4
	ds_read_b128 v[210:213], v4 offset:1024
	ds_read_b128 v[214:217], v4 offset:2048
	ds_read_b128 v[218:221], v4 offset:3072
	s_mov_b32 m0, s67
	ds_read_b128 v[44:47], v231 offset:32768
	ds_read_b128 v[52:55], v231 offset:33792
	ds_read_b128 v[60:63], v231 offset:34816
	ds_read_b128 v[222:225], v231 offset:35840
	ds_read_b128 v[232:235], v231 offset:36864
	ds_read_b128 v[236:239], v231 offset:37888
	ds_read_b128 v[240:243], v231 offset:38912
	ds_read_b128 v[244:247], v231 offset:39936
	global_load_lds_dwordx4 v132, s[26:27]
	s_mov_b32 m0, s68
	s_nop 0
	global_load_lds_dwordx4 v188, s[26:27]
	s_waitcnt vmcnt(8)
	s_waitcnt lgkmcnt(0)
	s_barrier
	s_setprio 1
	s_waitcnt lgkmcnt(0)
	v_mfma_f32_16x16x32_bf16 v[4:7], v[182:185], v[44:47], v[68:71]
	v_mfma_f32_16x16x32_bf16 v[8:11], v[196:199], v[44:47], v[72:75]
	v_mfma_f32_16x16x32_bf16 v[12:15], v[182:185], v[60:63], v[76:79]
	v_mfma_f32_16x16x32_bf16 v[16:19], v[196:199], v[60:63], v[80:83]
	v_mfma_f32_16x16x32_bf16 v[20:23], v[182:185], v[232:235], v[84:87]
	v_mfma_f32_16x16x32_bf16 v[24:27], v[196:199], v[232:235], v[88:91]
	v_mfma_f32_16x16x32_bf16 v[28:31], v[182:185], v[240:243], v[92:95]
	v_mfma_f32_16x16x32_bf16 v[32:35], v[196:199], v[240:243], v[96:99]
	v_mfma_f32_16x16x32_bf16 v[4:7], v[192:195], v[52:55], v[4:7]
	v_mfma_f32_16x16x32_bf16 v[8:11], v[200:203], v[52:55], v[8:11]
	v_mfma_f32_16x16x32_bf16 v[12:15], v[192:195], v[222:225], v[12:15]
	v_mfma_f32_16x16x32_bf16 v[16:19], v[200:203], v[222:225], v[16:19]
	v_mfma_f32_16x16x32_bf16 v[20:23], v[192:195], v[236:239], v[20:23]
	v_mfma_f32_16x16x32_bf16 v[24:27], v[200:203], v[236:239], v[24:27]
	v_mfma_f32_16x16x32_bf16 v[28:31], v[192:195], v[244:247], v[28:31]
	v_mfma_f32_16x16x32_bf16 v[32:35], v[200:203], v[244:247], v[32:35]
	s_setprio 0
	s_setprio 1
	v_mfma_f32_16x16x32_bf16 v[36:39], v[204:207], v[44:47], v[100:103]
	v_mfma_f32_16x16x32_bf16 v[40:43], v[214:217], v[44:47], v[40:43]
	v_mfma_f32_16x16x32_bf16 v[36:39], v[210:213], v[52:55], v[36:39]
	v_mfma_f32_16x16x32_bf16 v[40:43], v[218:221], v[52:55], v[40:43]
	v_mfma_f32_16x16x32_bf16 v[44:47], v[204:207], v[60:63], v[104:107]
	v_mfma_f32_16x16x32_bf16 v[48:51], v[214:217], v[60:63], v[48:51]
	v_mfma_f32_16x16x32_bf16 v[52:55], v[204:207], v[232:235], v[108:111]
	v_mfma_f32_16x16x32_bf16 v[56:59], v[214:217], v[232:235], v[56:59]
	v_mfma_f32_16x16x32_bf16 v[60:63], v[204:207], v[240:243], v[112:115]
	v_mfma_f32_16x16x32_bf16 v[64:67], v[214:217], v[240:243], v[64:67]
	v_mfma_f32_16x16x32_bf16 v[44:47], v[210:213], v[222:225], v[44:47]
	v_mfma_f32_16x16x32_bf16 v[48:51], v[218:221], v[222:225], v[48:51]
	s_setprio 2
	s_barrier
	v_mfma_f32_16x16x32_bf16 v[52:55], v[210:213], v[236:239], v[52:55]
	v_mfma_f32_16x16x32_bf16 v[56:59], v[218:221], v[236:239], v[56:59]
	v_mfma_f32_16x16x32_bf16 v[60:63], v[210:213], v[244:247], v[60:63]
	v_mfma_f32_16x16x32_bf16 v[64:67], v[218:221], v[244:247], v[64:67]
	s_setprio 0
	s_add_i32 s61, s61, s36
	v_lshl_add_u64 v[68:69], v[186:187], 0, s[24:25]
	s_mov_b32 m0, s61
	ds_read_b128 v[104:107], v231 offset:49152
	ds_read_b128 v[108:111], v231 offset:50176
	ds_read_b128 v[112:115], v231 offset:51200
	ds_read_b128 v[222:225], v231 offset:52224
	ds_read_b128 v[232:235], v231 offset:53248
	ds_read_b128 v[236:239], v231 offset:54272
	ds_read_b128 v[240:243], v231 offset:55296
	ds_read_b128 v[244:247], v231 offset:56320
	global_load_lds_dwordx4 v[68:69], off
	v_lshl_add_u64 v[68:69], v[226:227], 0, s[24:25]
	s_add_i32 m0, s61, 0x2000
	s_add_i32 s61, s79, s36
	global_load_lds_dwordx4 v[68:69], off
	s_mov_b32 m0, s61
	v_lshl_add_u64 v[68:69], v[248:249], 0, s[24:25]
	global_load_lds_dwordx4 v2, s[28:29]
	s_add_i32 m0, s61, 0x2000
	s_nop 0
	global_load_lds_dwordx4 v190, s[28:29]
	s_mov_b32 m0, s71
	s_nop 0
	global_load_lds_dwordx4 v[68:69], off
	v_lshl_add_u64 v[68:69], v[250:251], 0, s[24:25]
	s_mov_b32 m0, s72
	s_nop 0
	global_load_lds_dwordx4 v[68:69], off
	s_waitcnt vmcnt(8)
	s_waitcnt lgkmcnt(0)
	s_barrier
	s_setprio 1
	s_waitcnt lgkmcnt(0)
	v_mfma_f32_16x16x32_bf16 v[68:71], v[182:185], v[104:107], v[134:137]
	v_mfma_f32_16x16x32_bf16 v[72:75], v[196:199], v[104:107], v[138:141]
	v_mfma_f32_16x16x32_bf16 v[76:79], v[182:185], v[112:115], v[142:145]
	v_mfma_f32_16x16x32_bf16 v[80:83], v[196:199], v[112:115], v[146:149]
	v_mfma_f32_16x16x32_bf16 v[84:87], v[182:185], v[232:235], v[150:153]
	v_mfma_f32_16x16x32_bf16 v[88:91], v[196:199], v[232:235], v[154:157]
	v_mfma_f32_16x16x32_bf16 v[92:95], v[182:185], v[240:243], v[158:161]
	v_mfma_f32_16x16x32_bf16 v[96:99], v[196:199], v[240:243], v[162:165]
	v_mfma_f32_16x16x32_bf16 v[68:71], v[192:195], v[108:111], v[68:71]
	v_mfma_f32_16x16x32_bf16 v[72:75], v[200:203], v[108:111], v[72:75]
	v_mfma_f32_16x16x32_bf16 v[76:79], v[192:195], v[222:225], v[76:79]
	v_mfma_f32_16x16x32_bf16 v[80:83], v[200:203], v[222:225], v[80:83]
	v_mfma_f32_16x16x32_bf16 v[84:87], v[192:195], v[236:239], v[84:87]
	v_mfma_f32_16x16x32_bf16 v[88:91], v[200:203], v[236:239], v[88:91]
	v_mfma_f32_16x16x32_bf16 v[92:95], v[192:195], v[244:247], v[92:95]
	v_mfma_f32_16x16x32_bf16 v[96:99], v[200:203], v[244:247], v[96:99]
	s_setprio 0
	s_setprio 1
	v_mfma_f32_16x16x32_bf16 v[100:103], v[204:207], v[104:107], v[116:119]
	v_mfma_f32_16x16x32_bf16 v[104:107], v[214:217], v[104:107], v[124:127]
	v_mfma_f32_16x16x32_bf16 v[100:103], v[210:213], v[108:111], v[100:103]
	v_mfma_f32_16x16x32_bf16 v[104:107], v[218:221], v[108:111], v[104:107]
	v_mfma_f32_16x16x32_bf16 v[108:111], v[204:207], v[112:115], v[166:169]
	v_mfma_f32_16x16x32_bf16 v[112:115], v[214:217], v[112:115], v[170:173]
	v_mfma_f32_16x16x32_bf16 v[116:119], v[204:207], v[232:235], v[174:177]
	v_mfma_f32_16x16x32_bf16 v[120:123], v[214:217], v[232:235], v[120:123]
	v_mfma_f32_16x16x32_bf16 v[124:127], v[204:207], v[240:243], v[178:181]
	v_mfma_f32_16x16x32_bf16 v[128:131], v[214:217], v[240:243], v[128:131]
	v_mfma_f32_16x16x32_bf16 v[108:111], v[210:213], v[222:225], v[108:111]
	v_mfma_f32_16x16x32_bf16 v[112:115], v[218:221], v[222:225], v[112:115]
	s_setprio 2
	s_barrier
	v_mfma_f32_16x16x32_bf16 v[116:119], v[210:213], v[236:239], v[116:119]
	v_mfma_f32_16x16x32_bf16 v[120:123], v[218:221], v[236:239], v[120:123]
	v_mfma_f32_16x16x32_bf16 v[124:127], v[210:213], v[244:247], v[124:127]
	v_mfma_f32_16x16x32_bf16 v[128:131], v[218:221], v[244:247], v[128:131]
	s_setprio 0
	s_add_i32 s43, s43, 2
	s_cmp_ge_i32 s43, s42
	s_cbranch_scc0 .LBB0_1175
.LBB0_1176:
	s_add_i32 s12, 0, 0x10000
	s_add_i32 s13, 0, 0x14000
	v_mov_b32_e32 v192, v2
	v_mov_b32_e32 v2, v132
	v_add_u32_e32 v144, s12, v209
	v_add_u32_e32 v160, s13, v209
	ds_read_b128 v[132:135], v144
	ds_read_b128 v[136:139], v144 offset:1024
	ds_read_b128 v[140:143], v144 offset:2048
	ds_read_b128 v[144:147], v144 offset:3072
	ds_read_b128 v[148:151], v160
	ds_read_b128 v[152:155], v160 offset:1024
	ds_read_b128 v[156:159], v160 offset:2048
	ds_read_b128 v[160:163], v160 offset:3072
	s_add_u32 s6, s6, 0x80180
	s_mov_b32 m0, s73
	v_add_u32_e32 v212, 0, v208
	s_addc_u32 s7, s7, 0
	ds_read_b128 v[164:167], v212
	ds_read_b128 v[168:171], v212 offset:1024
	ds_read_b128 v[172:175], v212 offset:2048
	ds_read_b128 v[176:179], v212 offset:3072
	ds_read_b128 v[180:183], v212 offset:4096
	ds_read_b128 v[184:187], v212 offset:5120
	ds_read_b128 v[194:197], v212 offset:6144
	ds_read_b128 v[198:201], v212 offset:7168
	global_load_lds_dwordx4 v2, s[6:7]
	s_mov_b32 m0, s76
	v_mov_b32_e32 v189, v3
	global_load_lds_dwordx4 v188, s[6:7]
	s_waitcnt vmcnt(8)
	s_waitcnt lgkmcnt(0)
	s_barrier
	s_setprio 1
	s_waitcnt lgkmcnt(0)
	v_mfma_f32_16x16x32_bf16 v[4:7], v[132:135], v[164:167], v[4:7]
	v_mfma_f32_16x16x32_bf16 v[4:7], v[136:139], v[168:171], v[4:7]
	v_mfma_f32_16x16x32_bf16 v[8:11], v[144:147], v[168:171], v[8:11]
	v_mfma_f32_16x16x32_bf16 v[8:11], v[140:143], v[164:167], v[8:11]
	v_mfma_f32_16x16x32_bf16 v[16:19], v[140:143], v[172:175], v[16:19]
	v_mfma_f32_16x16x32_bf16 v[16:19], v[144:147], v[176:179], v[16:19]
	v_mfma_f32_16x16x32_bf16 v[12:15], v[136:139], v[176:179], v[12:15]
	v_mfma_f32_16x16x32_bf16 v[12:15], v[132:135], v[172:175], v[12:15]
	v_mfma_f32_16x16x32_bf16 v[20:23], v[132:135], v[180:183], v[20:23]
	v_mfma_f32_16x16x32_bf16 v[20:23], v[136:139], v[184:187], v[20:23]
	v_mfma_f32_16x16x32_bf16 v[24:27], v[144:147], v[184:187], v[24:27]
	v_mfma_f32_16x16x32_bf16 v[24:27], v[140:143], v[180:183], v[24:27]
	v_mfma_f32_16x16x32_bf16 v[32:35], v[140:143], v[194:197], v[32:35]
	v_mfma_f32_16x16x32_bf16 v[32:35], v[144:147], v[198:201], v[32:35]
	v_mfma_f32_16x16x32_bf16 v[28:31], v[136:139], v[198:201], v[28:31]
	v_mfma_f32_16x16x32_bf16 v[28:31], v[132:135], v[194:197], v[28:31]
	s_setprio 0
	s_setprio 1
	v_mfma_f32_16x16x32_bf16 v[36:39], v[148:151], v[164:167], v[36:39]
	v_mfma_f32_16x16x32_bf16 v[36:39], v[152:155], v[168:171], v[36:39]
	v_mfma_f32_16x16x32_bf16 v[40:43], v[160:163], v[168:171], v[40:43]
	v_mfma_f32_16x16x32_bf16 v[40:43], v[156:159], v[164:167], v[40:43]
	v_mfma_f32_16x16x32_bf16 v[48:51], v[156:159], v[172:175], v[48:51]
	v_mfma_f32_16x16x32_bf16 v[48:51], v[160:163], v[176:179], v[48:51]
	v_mfma_f32_16x16x32_bf16 v[44:47], v[152:155], v[176:179], v[44:47]
	v_mfma_f32_16x16x32_bf16 v[44:47], v[148:151], v[172:175], v[44:47]
	v_mfma_f32_16x16x32_bf16 v[52:55], v[148:151], v[180:183], v[52:55]
	v_mfma_f32_16x16x32_bf16 v[52:55], v[152:155], v[184:187], v[52:55]
	v_mfma_f32_16x16x32_bf16 v[56:59], v[160:163], v[184:187], v[56:59]
	v_mfma_f32_16x16x32_bf16 v[56:59], v[156:159], v[180:183], v[56:59]
	s_setprio 2
	s_barrier
	v_mfma_f32_16x16x32_bf16 v[64:67], v[156:159], v[194:197], v[64:67]
	v_mfma_f32_16x16x32_bf16 v[64:67], v[160:163], v[198:201], v[64:67]
	v_mfma_f32_16x16x32_bf16 v[60:63], v[152:155], v[198:201], v[60:63]
	v_mfma_f32_16x16x32_bf16 v[60:63], v[148:151], v[194:197], v[60:63]
	s_setprio 0
	s_add_i32 s6, s12, s36
	s_mov_b32 m0, s6
	ds_read_b128 v[164:167], v212 offset:16384
	ds_read_b128 v[168:171], v212 offset:17408
	ds_read_b128 v[172:175], v212 offset:18432
	ds_read_b128 v[176:179], v212 offset:19456
	ds_read_b128 v[180:183], v212 offset:20480
	ds_read_b128 v[184:187], v212 offset:21504
	ds_read_b128 v[194:197], v212 offset:22528
	ds_read_b128 v[198:201], v212 offset:23552
	global_load_lds_dwordx4 v192, s[14:15]
	s_add_i32 m0, s6, 0x2000
	s_add_u32 s6, s14, 0x10000
	s_addc_u32 s7, s15, 0
	s_add_i32 s12, s13, s36
	global_load_lds_dwordx4 v190, s[14:15]
	s_mov_b32 m0, s12
	v_mov_b32_e32 v193, v3
	global_load_lds_dwordx4 v192, s[6:7]
	s_add_i32 m0, s12, 0x2000
	v_mov_b32_e32 v191, v3
	global_load_lds_dwordx4 v190, s[6:7]
	s_mov_b32 m0, s37
	v_lshl_add_u64 v[202:203], s[14:15], 0, v[192:193]
	global_load_lds_dwordx4 v2, s[10:11]
	s_mov_b32 m0, s66
	v_lshl_add_u64 v[204:205], s[14:15], 0, v[190:191]
	global_load_lds_dwordx4 v188, s[10:11]
	s_waitcnt vmcnt(8)
	s_waitcnt lgkmcnt(0)
	v_lshl_add_u64 v[206:207], s[10:11], 0, v[2:3]
	v_lshl_add_u64 v[210:211], s[10:11], 0, v[188:189]
	s_barrier
	s_setprio 1
	s_waitcnt lgkmcnt(0)
	v_mfma_f32_16x16x32_bf16 v[68:71], v[132:135], v[164:167], v[68:71]
	v_mfma_f32_16x16x32_bf16 v[68:71], v[136:139], v[168:171], v[68:71]
	v_mfma_f32_16x16x32_bf16 v[72:75], v[144:147], v[168:171], v[72:75]
	v_mfma_f32_16x16x32_bf16 v[72:75], v[140:143], v[164:167], v[72:75]
	v_mfma_f32_16x16x32_bf16 v[80:83], v[140:143], v[172:175], v[80:83]
	v_mfma_f32_16x16x32_bf16 v[80:83], v[144:147], v[176:179], v[80:83]
	v_mfma_f32_16x16x32_bf16 v[76:79], v[136:139], v[176:179], v[76:79]
	v_mfma_f32_16x16x32_bf16 v[76:79], v[132:135], v[172:175], v[76:79]
	v_mfma_f32_16x16x32_bf16 v[84:87], v[132:135], v[180:183], v[84:87]
	v_mfma_f32_16x16x32_bf16 v[84:87], v[136:139], v[184:187], v[84:87]
	v_mfma_f32_16x16x32_bf16 v[88:91], v[144:147], v[184:187], v[88:91]
	v_mfma_f32_16x16x32_bf16 v[88:91], v[140:143], v[180:183], v[88:91]
	v_mfma_f32_16x16x32_bf16 v[96:99], v[140:143], v[194:197], v[96:99]
	v_mfma_f32_16x16x32_bf16 v[96:99], v[144:147], v[198:201], v[96:99]
	v_mfma_f32_16x16x32_bf16 v[92:95], v[136:139], v[198:201], v[92:95]
	v_mfma_f32_16x16x32_bf16 v[92:95], v[132:135], v[194:197], v[92:95]
	s_setprio 0
	s_setprio 1
	v_mfma_f32_16x16x32_bf16 v[100:103], v[148:151], v[164:167], v[100:103]
	v_mfma_f32_16x16x32_bf16 v[100:103], v[152:155], v[168:171], v[100:103]
	v_mfma_f32_16x16x32_bf16 v[104:107], v[160:163], v[168:171], v[104:107]
	v_mfma_f32_16x16x32_bf16 v[104:107], v[156:159], v[164:167], v[104:107]
	v_mfma_f32_16x16x32_bf16 v[112:115], v[156:159], v[172:175], v[112:115]
	v_mfma_f32_16x16x32_bf16 v[112:115], v[160:163], v[176:179], v[112:115]
	v_mfma_f32_16x16x32_bf16 v[108:111], v[152:155], v[176:179], v[108:111]
	v_mfma_f32_16x16x32_bf16 v[108:111], v[148:151], v[172:175], v[108:111]
	v_mfma_f32_16x16x32_bf16 v[116:119], v[148:151], v[180:183], v[116:119]
	v_mfma_f32_16x16x32_bf16 v[116:119], v[152:155], v[184:187], v[116:119]
	v_mfma_f32_16x16x32_bf16 v[120:123], v[160:163], v[184:187], v[120:123]
	v_mfma_f32_16x16x32_bf16 v[120:123], v[156:159], v[180:183], v[120:123]
	s_setprio 2
	s_barrier
	v_mfma_f32_16x16x32_bf16 v[128:131], v[156:159], v[194:197], v[128:131]
	v_mfma_f32_16x16x32_bf16 v[128:131], v[160:163], v[198:201], v[128:131]
	v_mfma_f32_16x16x32_bf16 v[124:127], v[152:155], v[198:201], v[124:127]
	v_mfma_f32_16x16x32_bf16 v[124:127], v[148:151], v[194:197], v[124:127]
	s_setprio 0
	s_add_i32 s12, 0, 0x18000
	s_add_i32 s13, 0, 0x1c000
	v_add_u32_e32 v144, s12, v209
	v_add_u32_e32 v160, s13, v209
	ds_read_b128 v[132:135], v144
	ds_read_b128 v[136:139], v144 offset:1024
	ds_read_b128 v[140:143], v144 offset:2048
	ds_read_b128 v[144:147], v144 offset:3072
	ds_read_b128 v[148:151], v160
	ds_read_b128 v[152:155], v160 offset:1024
	ds_read_b128 v[156:159], v160 offset:2048
	ds_read_b128 v[160:163], v160 offset:3072
	s_add_u32 s6, s10, 0x80000
	s_addc_u32 s7, s11, 0
	s_mov_b32 m0, s67
	ds_read_b128 v[164:167], v212 offset:32768
	ds_read_b128 v[168:171], v212 offset:33792
	ds_read_b128 v[172:175], v212 offset:34816
	ds_read_b128 v[176:179], v212 offset:35840
	ds_read_b128 v[180:183], v212 offset:36864
	ds_read_b128 v[184:187], v212 offset:37888
	ds_read_b128 v[194:197], v212 offset:38912
	ds_read_b128 v[198:201], v212 offset:39936
	global_load_lds_dwordx4 v2, s[6:7]
	s_mov_b32 m0, s68
	s_nop 0
	global_load_lds_dwordx4 v188, s[6:7]
	s_waitcnt vmcnt(8)
	s_waitcnt lgkmcnt(0)
	s_barrier
	s_setprio 1
	s_waitcnt lgkmcnt(0)
	v_mfma_f32_16x16x32_bf16 v[4:7], v[132:135], v[164:167], v[4:7]
	v_mfma_f32_16x16x32_bf16 v[4:7], v[136:139], v[168:171], v[4:7]
	v_mfma_f32_16x16x32_bf16 v[8:11], v[144:147], v[168:171], v[8:11]
	v_mfma_f32_16x16x32_bf16 v[8:11], v[140:143], v[164:167], v[8:11]
	v_mfma_f32_16x16x32_bf16 v[16:19], v[140:143], v[172:175], v[16:19]
	v_mfma_f32_16x16x32_bf16 v[16:19], v[144:147], v[176:179], v[16:19]
	v_mfma_f32_16x16x32_bf16 v[12:15], v[136:139], v[176:179], v[12:15]
	v_mfma_f32_16x16x32_bf16 v[12:15], v[132:135], v[172:175], v[12:15]
	v_mfma_f32_16x16x32_bf16 v[20:23], v[132:135], v[180:183], v[20:23]
	v_mfma_f32_16x16x32_bf16 v[20:23], v[136:139], v[184:187], v[20:23]
	v_mfma_f32_16x16x32_bf16 v[24:27], v[144:147], v[184:187], v[24:27]
	v_mfma_f32_16x16x32_bf16 v[24:27], v[140:143], v[180:183], v[24:27]
	v_mfma_f32_16x16x32_bf16 v[32:35], v[140:143], v[194:197], v[32:35]
	v_mfma_f32_16x16x32_bf16 v[32:35], v[144:147], v[198:201], v[32:35]
	v_mfma_f32_16x16x32_bf16 v[28:31], v[136:139], v[198:201], v[28:31]
	v_mfma_f32_16x16x32_bf16 v[28:31], v[132:135], v[194:197], v[28:31]
	s_setprio 0
	s_setprio 1
	v_mfma_f32_16x16x32_bf16 v[36:39], v[148:151], v[164:167], v[36:39]
	v_mfma_f32_16x16x32_bf16 v[36:39], v[152:155], v[168:171], v[36:39]
	v_mfma_f32_16x16x32_bf16 v[40:43], v[160:163], v[168:171], v[40:43]
	v_mfma_f32_16x16x32_bf16 v[40:43], v[156:159], v[164:167], v[40:43]
	v_mfma_f32_16x16x32_bf16 v[48:51], v[156:159], v[172:175], v[48:51]
	v_mfma_f32_16x16x32_bf16 v[48:51], v[160:163], v[176:179], v[48:51]
	v_mfma_f32_16x16x32_bf16 v[44:47], v[152:155], v[176:179], v[44:47]
	v_mfma_f32_16x16x32_bf16 v[44:47], v[148:151], v[172:175], v[44:47]
	v_mfma_f32_16x16x32_bf16 v[52:55], v[148:151], v[180:183], v[52:55]
	v_mfma_f32_16x16x32_bf16 v[52:55], v[152:155], v[184:187], v[52:55]
	v_mfma_f32_16x16x32_bf16 v[56:59], v[160:163], v[184:187], v[56:59]
	v_mfma_f32_16x16x32_bf16 v[56:59], v[156:159], v[180:183], v[56:59]
	s_setprio 2
	s_barrier
	v_mfma_f32_16x16x32_bf16 v[64:67], v[156:159], v[194:197], v[64:67]
	v_mfma_f32_16x16x32_bf16 v[64:67], v[160:163], v[198:201], v[64:67]
	v_mfma_f32_16x16x32_bf16 v[60:63], v[152:155], v[198:201], v[60:63]
	v_mfma_f32_16x16x32_bf16 v[60:63], v[148:151], v[194:197], v[60:63]
	s_setprio 0
	s_add_i32 s6, s12, s36
	v_lshl_add_u64 v[202:203], v[202:203], 0, s[86:87]
	s_mov_b32 m0, s6
	ds_read_b128 v[164:167], v212 offset:49152
	ds_read_b128 v[168:171], v212 offset:50176
	ds_read_b128 v[172:175], v212 offset:51200
	ds_read_b128 v[176:179], v212 offset:52224
	ds_read_b128 v[180:183], v212 offset:53248
	ds_read_b128 v[184:187], v212 offset:54272
	ds_read_b128 v[194:197], v212 offset:55296
	ds_read_b128 v[198:201], v212 offset:56320
	global_load_lds_dwordx4 v[202:203], off
	s_add_i32 m0, s6, 0x2000
	s_add_u32 s6, s14, 0x10080
	v_lshl_add_u64 v[202:203], v[204:205], 0, s[86:87]
	s_addc_u32 s7, s15, 0
	s_add_i32 s12, s13, s36
	global_load_lds_dwordx4 v[202:203], off
	s_mov_b32 m0, s12
	v_lshl_add_u64 v[202:203], v[206:207], 0, s[86:87]
	global_load_lds_dwordx4 v192, s[6:7]
	s_add_i32 m0, s12, 0x2000
	s_nop 0
	global_load_lds_dwordx4 v190, s[6:7]
	s_mov_b32 m0, s71
	s_nop 0
	global_load_lds_dwordx4 v[202:203], off
	v_lshl_add_u64 v[202:203], v[210:211], 0, s[86:87]
	s_mov_b32 m0, s72
	s_nop 0
	global_load_lds_dwordx4 v[202:203], off
	s_waitcnt vmcnt(8)
	s_waitcnt lgkmcnt(0)
	s_barrier
	s_setprio 1
	s_waitcnt lgkmcnt(0)
	v_mfma_f32_16x16x32_bf16 v[68:71], v[132:135], v[164:167], v[68:71]
	v_mfma_f32_16x16x32_bf16 v[68:71], v[136:139], v[168:171], v[68:71]
	v_mfma_f32_16x16x32_bf16 v[72:75], v[144:147], v[168:171], v[72:75]
	v_mfma_f32_16x16x32_bf16 v[72:75], v[140:143], v[164:167], v[72:75]
	v_mfma_f32_16x16x32_bf16 v[80:83], v[140:143], v[172:175], v[80:83]
	v_mfma_f32_16x16x32_bf16 v[80:83], v[144:147], v[176:179], v[80:83]
	v_mfma_f32_16x16x32_bf16 v[76:79], v[136:139], v[176:179], v[76:79]
	v_mfma_f32_16x16x32_bf16 v[76:79], v[132:135], v[172:175], v[76:79]
	v_mfma_f32_16x16x32_bf16 v[84:87], v[132:135], v[180:183], v[84:87]
	v_mfma_f32_16x16x32_bf16 v[84:87], v[136:139], v[184:187], v[84:87]
	v_mfma_f32_16x16x32_bf16 v[88:91], v[144:147], v[184:187], v[88:91]
	v_mfma_f32_16x16x32_bf16 v[88:91], v[140:143], v[180:183], v[88:91]
	v_mfma_f32_16x16x32_bf16 v[96:99], v[140:143], v[194:197], v[96:99]
	v_mfma_f32_16x16x32_bf16 v[96:99], v[144:147], v[198:201], v[96:99]
	v_mfma_f32_16x16x32_bf16 v[92:95], v[136:139], v[198:201], v[92:95]
	v_mfma_f32_16x16x32_bf16 v[92:95], v[132:135], v[194:197], v[92:95]
	s_setprio 0
	s_setprio 1
	v_mfma_f32_16x16x32_bf16 v[100:103], v[148:151], v[164:167], v[100:103]
	v_mfma_f32_16x16x32_bf16 v[100:103], v[152:155], v[168:171], v[100:103]
	v_mfma_f32_16x16x32_bf16 v[104:107], v[160:163], v[168:171], v[104:107]
	v_mfma_f32_16x16x32_bf16 v[104:107], v[156:159], v[164:167], v[104:107]
	v_mfma_f32_16x16x32_bf16 v[112:115], v[156:159], v[172:175], v[112:115]
	v_mfma_f32_16x16x32_bf16 v[112:115], v[160:163], v[176:179], v[112:115]
	v_mfma_f32_16x16x32_bf16 v[108:111], v[152:155], v[176:179], v[108:111]
	v_mfma_f32_16x16x32_bf16 v[108:111], v[148:151], v[172:175], v[108:111]
	v_mfma_f32_16x16x32_bf16 v[116:119], v[148:151], v[180:183], v[116:119]
	v_mfma_f32_16x16x32_bf16 v[116:119], v[152:155], v[184:187], v[116:119]
	v_mfma_f32_16x16x32_bf16 v[120:123], v[160:163], v[184:187], v[120:123]
	v_mfma_f32_16x16x32_bf16 v[120:123], v[156:159], v[180:183], v[120:123]
	s_setprio 2
	s_barrier
	v_mfma_f32_16x16x32_bf16 v[128:131], v[156:159], v[194:197], v[128:131]
	v_mfma_f32_16x16x32_bf16 v[128:131], v[160:163], v[198:201], v[128:131]
	v_mfma_f32_16x16x32_bf16 v[124:127], v[152:155], v[198:201], v[124:127]
	v_mfma_f32_16x16x32_bf16 v[124:127], v[148:151], v[194:197], v[124:127]
	s_setprio 0
	s_and_b64 vcc, exec, s[58:59]
	s_cbranch_vccz .LBB0_1178
	s_barrier

.LBB0_1625:
	s_add_i32 s51, 0, 0x10000
	s_add_i32 s72, 0, 0x14000
	v_add_u32_e32 v16, s51, v232
	v_add_u32_e32 v32, s72, v232
	ds_read_b128 v[4:7], v16
	ds_read_b128 v[8:11], v16 offset:1024
	ds_read_b128 v[12:15], v16 offset:2048
	ds_read_b128 v[16:19], v16 offset:3072
	ds_read_b128 v[20:23], v32
	ds_read_b128 v[24:27], v32 offset:1024
	ds_read_b128 v[28:31], v32 offset:2048
	ds_read_b128 v[32:35], v32 offset:3072
	v_add_u32_e32 v233, 0, v231
	ds_read_b128 v[36:39], v233
	ds_read_b128 v[40:43], v233 offset:1024
	ds_read_b128 v[44:47], v233 offset:2048
	ds_read_b128 v[48:51], v233 offset:3072
	ds_read_b128 v[52:55], v233 offset:4096
	ds_read_b128 v[56:59], v233 offset:5120
	ds_read_b128 v[60:63], v233 offset:6144
	ds_read_b128 v[64:67], v233 offset:7168
	s_waitcnt vmcnt(8)
	s_waitcnt lgkmcnt(0)
	s_barrier
	s_setprio 1
	s_waitcnt lgkmcnt(0)
	v_mfma_f32_16x16x32_bf16 v[68:71], v[4:7], v[36:39], 0
	v_mfma_f32_16x16x32_bf16 v[68:71], v[8:11], v[40:43], v[68:71]
	v_mfma_f32_16x16x32_bf16 v[72:75], v[12:15], v[36:39], 0
	v_mfma_f32_16x16x32_bf16 v[72:75], v[16:19], v[40:43], v[72:75]
	v_mfma_f32_16x16x32_bf16 v[80:83], v[12:15], v[44:47], 0
	v_mfma_f32_16x16x32_bf16 v[80:83], v[16:19], v[48:51], v[80:83]
	v_mfma_f32_16x16x32_bf16 v[76:79], v[4:7], v[44:47], 0
	v_mfma_f32_16x16x32_bf16 v[76:79], v[8:11], v[48:51], v[76:79]
	v_mfma_f32_16x16x32_bf16 v[84:87], v[4:7], v[52:55], 0
	v_mfma_f32_16x16x32_bf16 v[84:87], v[8:11], v[56:59], v[84:87]
	v_mfma_f32_16x16x32_bf16 v[88:91], v[12:15], v[52:55], 0
	v_mfma_f32_16x16x32_bf16 v[88:91], v[16:19], v[56:59], v[88:91]
	v_mfma_f32_16x16x32_bf16 v[96:99], v[12:15], v[60:63], 0
	v_mfma_f32_16x16x32_bf16 v[96:99], v[16:19], v[64:67], v[96:99]
	v_mfma_f32_16x16x32_bf16 v[92:95], v[4:7], v[60:63], 0
	v_mfma_f32_16x16x32_bf16 v[92:95], v[8:11], v[64:67], v[92:95]
	s_setprio 0
	s_setprio 1
	v_mfma_f32_16x16x32_bf16 v[100:103], v[20:23], v[36:39], 0
	v_mfma_f32_16x16x32_bf16 v[36:39], v[28:31], v[36:39], 0
	v_mfma_f32_16x16x32_bf16 v[104:107], v[20:23], v[44:47], 0
	v_mfma_f32_16x16x32_bf16 v[44:47], v[28:31], v[44:47], 0
	v_mfma_f32_16x16x32_bf16 v[108:111], v[20:23], v[52:55], 0
	v_mfma_f32_16x16x32_bf16 v[52:55], v[28:31], v[52:55], 0
	v_mfma_f32_16x16x32_bf16 v[112:115], v[20:23], v[60:63], 0
	v_mfma_f32_16x16x32_bf16 v[60:63], v[28:31], v[60:63], 0
	v_mfma_f32_16x16x32_bf16 v[100:103], v[24:27], v[40:43], v[100:103]
	v_mfma_f32_16x16x32_bf16 v[40:43], v[32:35], v[40:43], v[36:39]
	v_mfma_f32_16x16x32_bf16 v[104:107], v[24:27], v[48:51], v[104:107]
	v_mfma_f32_16x16x32_bf16 v[48:51], v[32:35], v[48:51], v[44:47]
	s_setprio 2
	s_barrier
	v_mfma_f32_16x16x32_bf16 v[108:111], v[24:27], v[56:59], v[108:111]
	v_mfma_f32_16x16x32_bf16 v[56:59], v[32:35], v[56:59], v[52:55]
	v_mfma_f32_16x16x32_bf16 v[112:115], v[24:27], v[64:67], v[112:115]
	v_mfma_f32_16x16x32_bf16 v[64:67], v[32:35], v[64:67], v[60:63]
	s_setprio 0
	v_lshl_add_u64 v[186:187], s[12:13], 0, v[2:3]
	s_add_i32 s51, s51, s56
	v_mov_b32_e32 v191, v3
	v_lshl_add_u64 v[134:135], v[186:187], 0, s[74:75]
	s_mov_b32 m0, s51
	v_lshl_add_u64 v[246:247], s[12:13], 0, v[190:191]
	ds_read_b128 v[36:39], v233 offset:16384
	ds_read_b128 v[44:47], v233 offset:17408
	ds_read_b128 v[52:55], v233 offset:18432
	ds_read_b128 v[60:63], v233 offset:19456
	ds_read_b128 v[116:119], v233 offset:20480
	ds_read_b128 v[120:123], v233 offset:21504
	ds_read_b128 v[124:127], v233 offset:22528
	ds_read_b128 v[128:131], v233 offset:23552
	global_load_lds_dwordx4 v[134:135], off
	v_lshl_add_u64 v[134:135], v[246:247], 0, s[74:75]
	s_add_i32 m0, s51, 0x2000
	s_add_i32 s51, s72, s56
	global_load_lds_dwordx4 v[134:135], off
	s_mov_b32 m0, s51
	v_mov_b32_e32 v133, v3
	global_load_lds_dwordx4 v2, s[16:17]
	s_add_i32 m0, s51, 0x2000
	v_lshl_add_u64 v[248:249], s[14:15], 0, v[132:133]
	v_mov_b32_e32 v189, v3
	global_load_lds_dwordx4 v190, s[16:17]
	v_lshl_add_u64 v[134:135], v[248:249], 0, s[74:75]
	s_mov_b32 m0, s57
	v_lshl_add_u64 v[250:251], s[14:15], 0, v[188:189]
	global_load_lds_dwordx4 v[134:135], off
	v_lshl_add_u64 v[134:135], v[250:251], 0, s[74:75]
	s_mov_b32 m0, s58
	s_nop 0
	global_load_lds_dwordx4 v[134:135], off
	s_waitcnt vmcnt(8)
	s_waitcnt lgkmcnt(0)
	s_barrier
	s_setprio 1
	s_waitcnt lgkmcnt(0)
	v_mfma_f32_16x16x32_bf16 v[134:137], v[4:7], v[36:39], 0
	v_mfma_f32_16x16x32_bf16 v[138:141], v[12:15], v[36:39], 0
	v_mfma_f32_16x16x32_bf16 v[142:145], v[4:7], v[52:55], 0
	v_mfma_f32_16x16x32_bf16 v[146:149], v[12:15], v[52:55], 0
	v_mfma_f32_16x16x32_bf16 v[150:153], v[4:7], v[116:119], 0
	v_mfma_f32_16x16x32_bf16 v[154:157], v[12:15], v[116:119], 0
	v_mfma_f32_16x16x32_bf16 v[4:7], v[4:7], v[124:127], 0
	v_mfma_f32_16x16x32_bf16 v[12:15], v[12:15], v[124:127], 0
	v_mfma_f32_16x16x32_bf16 v[134:137], v[8:11], v[44:47], v[134:137]
	v_mfma_f32_16x16x32_bf16 v[138:141], v[16:19], v[44:47], v[138:141]
	v_mfma_f32_16x16x32_bf16 v[142:145], v[8:11], v[60:63], v[142:145]
	v_mfma_f32_16x16x32_bf16 v[146:149], v[16:19], v[60:63], v[146:149]
	v_mfma_f32_16x16x32_bf16 v[150:153], v[8:11], v[120:123], v[150:153]
	v_mfma_f32_16x16x32_bf16 v[154:157], v[16:19], v[120:123], v[154:157]
	v_mfma_f32_16x16x32_bf16 v[158:161], v[8:11], v[128:131], v[4:7]
	v_mfma_f32_16x16x32_bf16 v[162:165], v[16:19], v[128:131], v[12:15]
	s_setprio 0
	s_setprio 1
	v_mfma_f32_16x16x32_bf16 v[4:7], v[20:23], v[36:39], 0
	v_mfma_f32_16x16x32_bf16 v[8:11], v[28:31], v[36:39], 0
	v_mfma_f32_16x16x32_bf16 v[12:15], v[20:23], v[52:55], 0
	v_mfma_f32_16x16x32_bf16 v[16:19], v[28:31], v[52:55], 0
	v_mfma_f32_16x16x32_bf16 v[36:39], v[20:23], v[116:119], 0
	v_mfma_f32_16x16x32_bf16 v[52:55], v[28:31], v[116:119], 0
	v_mfma_f32_16x16x32_bf16 v[20:23], v[20:23], v[124:127], 0
	v_mfma_f32_16x16x32_bf16 v[28:31], v[28:31], v[124:127], 0
	v_mfma_f32_16x16x32_bf16 v[116:119], v[24:27], v[44:47], v[4:7]
	v_mfma_f32_16x16x32_bf16 v[124:127], v[32:35], v[44:47], v[8:11]
	v_mfma_f32_16x16x32_bf16 v[174:177], v[24:27], v[120:123], v[36:39]
	v_mfma_f32_16x16x32_bf16 v[120:123], v[32:35], v[120:123], v[52:55]
	s_setprio 2
	s_barrier
	v_mfma_f32_16x16x32_bf16 v[178:181], v[24:27], v[128:131], v[20:23]
	v_mfma_f32_16x16x32_bf16 v[128:131], v[32:35], v[128:131], v[28:31]
	v_mfma_f32_16x16x32_bf16 v[166:169], v[24:27], v[60:63], v[12:15]
	v_mfma_f32_16x16x32_bf16 v[170:173], v[32:35], v[60:63], v[16:19]
	s_setprio 0
	s_add_i32 s51, 0, 0x18000
	v_add_u32_e32 v4, s51, v232
	s_add_i32 s72, 0, 0x1c000
	ds_read_b128 v[182:185], v4
	ds_read_b128 v[192:195], v4 offset:1024
	ds_read_b128 v[196:199], v4 offset:2048
	ds_read_b128 v[200:203], v4 offset:3072
	v_add_u32_e32 v4, s72, v232
	ds_read_b128 v[204:207], v4
	ds_read_b128 v[208:211], v4 offset:1024
	ds_read_b128 v[212:215], v4 offset:2048
	ds_read_b128 v[216:219], v4 offset:3072
	s_mov_b32 m0, s59
	ds_read_b128 v[44:47], v233 offset:32768
	ds_read_b128 v[52:55], v233 offset:33792
	ds_read_b128 v[60:63], v233 offset:34816
	ds_read_b128 v[220:223], v233 offset:35840
	ds_read_b128 v[224:227], v233 offset:36864
	ds_read_b128 v[234:237], v233 offset:37888
	ds_read_b128 v[238:241], v233 offset:38912
	ds_read_b128 v[242:245], v233 offset:39936
	global_load_lds_dwordx4 v132, s[26:27]
	s_mov_b32 m0, s60
	s_nop 0
	global_load_lds_dwordx4 v188, s[26:27]
	s_waitcnt vmcnt(8)
	s_waitcnt lgkmcnt(0)
	s_barrier
	s_setprio 1
	s_waitcnt lgkmcnt(0)
	v_mfma_f32_16x16x32_bf16 v[4:7], v[182:185], v[44:47], v[68:71]
	v_mfma_f32_16x16x32_bf16 v[8:11], v[196:199], v[44:47], v[72:75]
	v_mfma_f32_16x16x32_bf16 v[12:15], v[182:185], v[60:63], v[76:79]
	v_mfma_f32_16x16x32_bf16 v[16:19], v[196:199], v[60:63], v[80:83]
	v_mfma_f32_16x16x32_bf16 v[20:23], v[182:185], v[224:227], v[84:87]
	v_mfma_f32_16x16x32_bf16 v[24:27], v[196:199], v[224:227], v[88:91]
	v_mfma_f32_16x16x32_bf16 v[28:31], v[182:185], v[238:241], v[92:95]
	v_mfma_f32_16x16x32_bf16 v[32:35], v[196:199], v[238:241], v[96:99]
	v_mfma_f32_16x16x32_bf16 v[4:7], v[192:195], v[52:55], v[4:7]
	v_mfma_f32_16x16x32_bf16 v[8:11], v[200:203], v[52:55], v[8:11]
	v_mfma_f32_16x16x32_bf16 v[12:15], v[192:195], v[220:223], v[12:15]
	v_mfma_f32_16x16x32_bf16 v[16:19], v[200:203], v[220:223], v[16:19]
	v_mfma_f32_16x16x32_bf16 v[20:23], v[192:195], v[234:237], v[20:23]
	v_mfma_f32_16x16x32_bf16 v[24:27], v[200:203], v[234:237], v[24:27]
	v_mfma_f32_16x16x32_bf16 v[28:31], v[192:195], v[242:245], v[28:31]
	v_mfma_f32_16x16x32_bf16 v[32:35], v[200:203], v[242:245], v[32:35]
	s_setprio 0
	s_setprio 1
	v_mfma_f32_16x16x32_bf16 v[36:39], v[204:207], v[44:47], v[100:103]
	v_mfma_f32_16x16x32_bf16 v[40:43], v[212:215], v[44:47], v[40:43]
	v_mfma_f32_16x16x32_bf16 v[36:39], v[208:211], v[52:55], v[36:39]
	v_mfma_f32_16x16x32_bf16 v[40:43], v[216:219], v[52:55], v[40:43]
	v_mfma_f32_16x16x32_bf16 v[44:47], v[204:207], v[60:63], v[104:107]
	v_mfma_f32_16x16x32_bf16 v[48:51], v[212:215], v[60:63], v[48:51]
	v_mfma_f32_16x16x32_bf16 v[52:55], v[204:207], v[224:227], v[108:111]
	v_mfma_f32_16x16x32_bf16 v[56:59], v[212:215], v[224:227], v[56:59]
	v_mfma_f32_16x16x32_bf16 v[60:63], v[204:207], v[238:241], v[112:115]
	v_mfma_f32_16x16x32_bf16 v[64:67], v[212:215], v[238:241], v[64:67]
	v_mfma_f32_16x16x32_bf16 v[44:47], v[208:211], v[220:223], v[44:47]
	v_mfma_f32_16x16x32_bf16 v[48:51], v[216:219], v[220:223], v[48:51]
	s_setprio 2
	s_barrier
	v_mfma_f32_16x16x32_bf16 v[52:55], v[208:211], v[234:237], v[52:55]
	v_mfma_f32_16x16x32_bf16 v[56:59], v[216:219], v[234:237], v[56:59]
	v_mfma_f32_16x16x32_bf16 v[60:63], v[208:211], v[242:245], v[60:63]
	v_mfma_f32_16x16x32_bf16 v[64:67], v[216:219], v[242:245], v[64:67]
	s_setprio 0
	s_add_i32 s51, s51, s56
	v_lshl_add_u64 v[68:69], v[186:187], 0, s[24:25]
	s_mov_b32 m0, s51
	ds_read_b128 v[104:107], v233 offset:49152
	ds_read_b128 v[108:111], v233 offset:50176
	ds_read_b128 v[112:115], v233 offset:51200
	ds_read_b128 v[220:223], v233 offset:52224
	ds_read_b128 v[224:227], v233 offset:53248
	ds_read_b128 v[234:237], v233 offset:54272
	ds_read_b128 v[238:241], v233 offset:55296
	ds_read_b128 v[242:245], v233 offset:56320
	global_load_lds_dwordx4 v[68:69], off
	v_lshl_add_u64 v[68:69], v[246:247], 0, s[24:25]
	s_add_i32 m0, s51, 0x2000
	s_add_i32 s51, s72, s56
	global_load_lds_dwordx4 v[68:69], off
	s_mov_b32 m0, s51
	v_lshl_add_u64 v[68:69], v[248:249], 0, s[24:25]
	global_load_lds_dwordx4 v2, s[28:29]
	s_add_i32 m0, s51, 0x2000
	s_nop 0
	global_load_lds_dwordx4 v190, s[28:29]
	s_mov_b32 m0, s64
	s_nop 0
	global_load_lds_dwordx4 v[68:69], off
	v_lshl_add_u64 v[68:69], v[250:251], 0, s[24:25]
	s_mov_b32 m0, s65
	s_nop 0
	global_load_lds_dwordx4 v[68:69], off
	s_waitcnt vmcnt(8)
	s_waitcnt lgkmcnt(0)
	s_barrier
	s_setprio 1
	s_waitcnt lgkmcnt(0)
	v_mfma_f32_16x16x32_bf16 v[68:71], v[182:185], v[104:107], v[134:137]
	v_mfma_f32_16x16x32_bf16 v[72:75], v[196:199], v[104:107], v[138:141]
	v_mfma_f32_16x16x32_bf16 v[76:79], v[182:185], v[112:115], v[142:145]
	v_mfma_f32_16x16x32_bf16 v[80:83], v[196:199], v[112:115], v[146:149]
	v_mfma_f32_16x16x32_bf16 v[84:87], v[182:185], v[224:227], v[150:153]
	v_mfma_f32_16x16x32_bf16 v[88:91], v[196:199], v[224:227], v[154:157]
	v_mfma_f32_16x16x32_bf16 v[92:95], v[182:185], v[238:241], v[158:161]
	v_mfma_f32_16x16x32_bf16 v[96:99], v[196:199], v[238:241], v[162:165]
	v_mfma_f32_16x16x32_bf16 v[68:71], v[192:195], v[108:111], v[68:71]
	v_mfma_f32_16x16x32_bf16 v[72:75], v[200:203], v[108:111], v[72:75]
	v_mfma_f32_16x16x32_bf16 v[76:79], v[192:195], v[220:223], v[76:79]
	v_mfma_f32_16x16x32_bf16 v[80:83], v[200:203], v[220:223], v[80:83]
	v_mfma_f32_16x16x32_bf16 v[84:87], v[192:195], v[234:237], v[84:87]
	v_mfma_f32_16x16x32_bf16 v[88:91], v[200:203], v[234:237], v[88:91]
	v_mfma_f32_16x16x32_bf16 v[92:95], v[192:195], v[242:245], v[92:95]
	v_mfma_f32_16x16x32_bf16 v[96:99], v[200:203], v[242:245], v[96:99]
	s_setprio 0
	s_setprio 1
	v_mfma_f32_16x16x32_bf16 v[100:103], v[204:207], v[104:107], v[116:119]
	v_mfma_f32_16x16x32_bf16 v[104:107], v[212:215], v[104:107], v[124:127]
	v_mfma_f32_16x16x32_bf16 v[100:103], v[208:211], v[108:111], v[100:103]
	v_mfma_f32_16x16x32_bf16 v[104:107], v[216:219], v[108:111], v[104:107]
	v_mfma_f32_16x16x32_bf16 v[108:111], v[204:207], v[112:115], v[166:169]
	v_mfma_f32_16x16x32_bf16 v[112:115], v[212:215], v[112:115], v[170:173]
	v_mfma_f32_16x16x32_bf16 v[116:119], v[204:207], v[224:227], v[174:177]
	v_mfma_f32_16x16x32_bf16 v[120:123], v[212:215], v[224:227], v[120:123]
	v_mfma_f32_16x16x32_bf16 v[124:127], v[204:207], v[238:241], v[178:181]
	v_mfma_f32_16x16x32_bf16 v[128:131], v[212:215], v[238:241], v[128:131]
	v_mfma_f32_16x16x32_bf16 v[108:111], v[208:211], v[220:223], v[108:111]
	v_mfma_f32_16x16x32_bf16 v[112:115], v[216:219], v[220:223], v[112:115]
	s_setprio 2
	s_barrier
	v_mfma_f32_16x16x32_bf16 v[116:119], v[208:211], v[234:237], v[116:119]
	v_mfma_f32_16x16x32_bf16 v[120:123], v[216:219], v[234:237], v[120:123]
	v_mfma_f32_16x16x32_bf16 v[124:127], v[208:211], v[242:245], v[124:127]
	v_mfma_f32_16x16x32_bf16 v[128:131], v[216:219], v[242:245], v[128:131]
	s_setprio 0
	s_add_i32 s43, s43, 2
	s_cmp_ge_i32 s43, s42
	s_cbranch_scc0 .LBB0_1625
	v_mov_b32_e32 v192, v2
	s_branch .LBB0_1628

.LBB0_1629:
	s_add_u32 s12, s14, 0xfff80080
	s_addc_u32 s13, s15, -1
	s_add_i32 s29, 0, 0x10000
	s_cmp_eq_u32 s28, 28
	s_cselect_b32 s17, s9, s13
	s_cselect_b32 s16, s8, s12
	s_cselect_b32 s13, s11, s27
	s_cselect_b32 s12, s10, s26
	s_add_i32 s51, 0, 0x14000
	v_add_u32_e32 v144, s29, v232
	v_add_u32_e32 v160, s51, v232
	s_waitcnt lgkmcnt(0)
	ds_read_b128 v[132:135], v144
	ds_read_b128 v[136:139], v144 offset:1024
	ds_read_b128 v[140:143], v144 offset:2048
	ds_read_b128 v[144:147], v144 offset:3072
	ds_read_b128 v[148:151], v160
	ds_read_b128 v[152:155], v160 offset:1024
	ds_read_b128 v[156:159], v160 offset:2048
	ds_read_b128 v[160:163], v160 offset:3072
	s_mov_b32 m0, s66
	v_add_u32_e32 v210, 0, v231
	ds_read_b128 v[164:167], v210
	ds_read_b128 v[168:171], v210 offset:1024
	ds_read_b128 v[172:175], v210 offset:2048
	ds_read_b128 v[176:179], v210 offset:3072
	ds_read_b128 v[180:183], v210 offset:4096
	ds_read_b128 v[184:187], v210 offset:5120
	ds_read_b128 v[194:197], v210 offset:6144
	ds_read_b128 v[198:201], v210 offset:7168
	global_load_lds_dwordx4 v2, s[14:15]
	s_mov_b32 m0, s67
	v_mov_b32_e32 v189, v3
	global_load_lds_dwordx4 v188, s[14:15]
	s_waitcnt vmcnt(8)
	s_waitcnt lgkmcnt(0)
	s_barrier
	s_setprio 1
	s_waitcnt lgkmcnt(0)
	v_mfma_f32_16x16x32_bf16 v[4:7], v[132:135], v[164:167], v[4:7]
	v_mfma_f32_16x16x32_bf16 v[4:7], v[136:139], v[168:171], v[4:7]
	v_mfma_f32_16x16x32_bf16 v[8:11], v[144:147], v[168:171], v[8:11]
	v_mfma_f32_16x16x32_bf16 v[8:11], v[140:143], v[164:167], v[8:11]
	v_mfma_f32_16x16x32_bf16 v[16:19], v[140:143], v[172:175], v[16:19]
	v_mfma_f32_16x16x32_bf16 v[16:19], v[144:147], v[176:179], v[16:19]
	v_mfma_f32_16x16x32_bf16 v[12:15], v[136:139], v[176:179], v[12:15]
	v_mfma_f32_16x16x32_bf16 v[12:15], v[132:135], v[172:175], v[12:15]
	v_mfma_f32_16x16x32_bf16 v[20:23], v[132:135], v[180:183], v[20:23]
	v_mfma_f32_16x16x32_bf16 v[20:23], v[136:139], v[184:187], v[20:23]
	v_mfma_f32_16x16x32_bf16 v[24:27], v[144:147], v[184:187], v[24:27]
	v_mfma_f32_16x16x32_bf16 v[24:27], v[140:143], v[180:183], v[24:27]
	v_mfma_f32_16x16x32_bf16 v[32:35], v[140:143], v[194:197], v[32:35]
	v_mfma_f32_16x16x32_bf16 v[32:35], v[144:147], v[198:201], v[32:35]
	v_mfma_f32_16x16x32_bf16 v[28:31], v[136:139], v[198:201], v[28:31]
	v_mfma_f32_16x16x32_bf16 v[28:31], v[132:135], v[194:197], v[28:31]
	s_setprio 0
	s_setprio 1
	v_mfma_f32_16x16x32_bf16 v[36:39], v[148:151], v[164:167], v[36:39]
	v_mfma_f32_16x16x32_bf16 v[36:39], v[152:155], v[168:171], v[36:39]
	v_mfma_f32_16x16x32_bf16 v[40:43], v[160:163], v[168:171], v[40:43]
	v_mfma_f32_16x16x32_bf16 v[40:43], v[156:159], v[164:167], v[40:43]
	v_mfma_f32_16x16x32_bf16 v[48:51], v[156:159], v[172:175], v[48:51]
	v_mfma_f32_16x16x32_bf16 v[48:51], v[160:163], v[176:179], v[48:51]
	v_mfma_f32_16x16x32_bf16 v[44:47], v[152:155], v[176:179], v[44:47]
	v_mfma_f32_16x16x32_bf16 v[44:47], v[148:151], v[172:175], v[44:47]
	v_mfma_f32_16x16x32_bf16 v[52:55], v[148:151], v[180:183], v[52:55]
	v_mfma_f32_16x16x32_bf16 v[52:55], v[152:155], v[184:187], v[52:55]
	v_mfma_f32_16x16x32_bf16 v[56:59], v[160:163], v[184:187], v[56:59]
	v_mfma_f32_16x16x32_bf16 v[56:59], v[156:159], v[180:183], v[56:59]
	s_setprio 2
	s_barrier
	v_mfma_f32_16x16x32_bf16 v[64:67], v[156:159], v[194:197], v[64:67]
	v_mfma_f32_16x16x32_bf16 v[64:67], v[160:163], v[198:201], v[64:67]
	v_mfma_f32_16x16x32_bf16 v[60:63], v[152:155], v[198:201], v[60:63]
	v_mfma_f32_16x16x32_bf16 v[60:63], v[148:151], v[194:197], v[60:63]
	s_setprio 0
	s_add_i32 s29, s29, s56
	s_mov_b32 m0, s29
	ds_read_b128 v[164:167], v210 offset:16384
	ds_read_b128 v[168:171], v210 offset:17408
	ds_read_b128 v[172:175], v210 offset:18432
	ds_read_b128 v[176:179], v210 offset:19456
	ds_read_b128 v[180:183], v210 offset:20480
	ds_read_b128 v[184:187], v210 offset:21504
	ds_read_b128 v[194:197], v210 offset:22528
	ds_read_b128 v[198:201], v210 offset:23552
	global_load_lds_dwordx4 v192, s[12:13]
	s_add_i32 m0, s29, 0x2000
	s_add_u32 s42, s12, 0x80000
	s_addc_u32 s43, s13, 0
	s_add_i32 s29, s51, s56
	global_load_lds_dwordx4 v190, s[12:13]
	s_mov_b32 m0, s29
	v_mov_b32_e32 v193, v3
	global_load_lds_dwordx4 v192, s[42:43]
	s_add_i32 m0, s29, 0x2000
	v_mov_b32_e32 v191, v3
	global_load_lds_dwordx4 v190, s[42:43]
	s_mov_b32 m0, s57
	v_lshl_add_u64 v[202:203], s[12:13], 0, v[192:193]
	global_load_lds_dwordx4 v2, s[16:17]
	s_mov_b32 m0, s58
	v_lshl_add_u64 v[204:205], s[12:13], 0, v[190:191]
	global_load_lds_dwordx4 v188, s[16:17]
	s_waitcnt vmcnt(8)
	s_waitcnt lgkmcnt(0)
	v_lshl_add_u64 v[206:207], s[16:17], 0, v[2:3]
	v_lshl_add_u64 v[208:209], s[16:17], 0, v[188:189]
	s_barrier
	s_setprio 1
	s_waitcnt lgkmcnt(0)
	v_mfma_f32_16x16x32_bf16 v[68:71], v[132:135], v[164:167], v[68:71]
	v_mfma_f32_16x16x32_bf16 v[68:71], v[136:139], v[168:171], v[68:71]
	v_mfma_f32_16x16x32_bf16 v[72:75], v[144:147], v[168:171], v[72:75]
	v_mfma_f32_16x16x32_bf16 v[72:75], v[140:143], v[164:167], v[72:75]
	v_mfma_f32_16x16x32_bf16 v[80:83], v[140:143], v[172:175], v[80:83]
	v_mfma_f32_16x16x32_bf16 v[80:83], v[144:147], v[176:179], v[80:83]
	v_mfma_f32_16x16x32_bf16 v[76:79], v[136:139], v[176:179], v[76:79]
	v_mfma_f32_16x16x32_bf16 v[76:79], v[132:135], v[172:175], v[76:79]
	v_mfma_f32_16x16x32_bf16 v[84:87], v[132:135], v[180:183], v[84:87]
	v_mfma_f32_16x16x32_bf16 v[84:87], v[136:139], v[184:187], v[84:87]
	v_mfma_f32_16x16x32_bf16 v[88:91], v[144:147], v[184:187], v[88:91]
	v_mfma_f32_16x16x32_bf16 v[88:91], v[140:143], v[180:183], v[88:91]
	v_mfma_f32_16x16x32_bf16 v[96:99], v[140:143], v[194:197], v[96:99]
	v_mfma_f32_16x16x32_bf16 v[96:99], v[144:147], v[198:201], v[96:99]
	v_mfma_f32_16x16x32_bf16 v[92:95], v[136:139], v[198:201], v[92:95]
	v_mfma_f32_16x16x32_bf16 v[92:95], v[132:135], v[194:197], v[92:95]
	s_setprio 0
	s_setprio 1
	v_mfma_f32_16x16x32_bf16 v[100:103], v[148:151], v[164:167], v[100:103]
	v_mfma_f32_16x16x32_bf16 v[100:103], v[152:155], v[168:171], v[100:103]
	v_mfma_f32_16x16x32_bf16 v[104:107], v[160:163], v[168:171], v[104:107]
	v_mfma_f32_16x16x32_bf16 v[104:107], v[156:159], v[164:167], v[104:107]
	v_mfma_f32_16x16x32_bf16 v[112:115], v[156:159], v[172:175], v[112:115]
	v_mfma_f32_16x16x32_bf16 v[112:115], v[160:163], v[176:179], v[112:115]
	v_mfma_f32_16x16x32_bf16 v[108:111], v[152:155], v[176:179], v[108:111]
	v_mfma_f32_16x16x32_bf16 v[108:111], v[148:151], v[172:175], v[108:111]
	v_mfma_f32_16x16x32_bf16 v[116:119], v[148:151], v[180:183], v[116:119]
	v_mfma_f32_16x16x32_bf16 v[116:119], v[152:155], v[184:187], v[116:119]
	v_mfma_f32_16x16x32_bf16 v[120:123], v[160:163], v[184:187], v[120:123]
	v_mfma_f32_16x16x32_bf16 v[120:123], v[156:159], v[180:183], v[120:123]
	s_setprio 2
	s_barrier
	v_mfma_f32_16x16x32_bf16 v[128:131], v[156:159], v[194:197], v[128:131]
	v_mfma_f32_16x16x32_bf16 v[128:131], v[160:163], v[198:201], v[128:131]
	v_mfma_f32_16x16x32_bf16 v[124:127], v[152:155], v[198:201], v[124:127]
	v_mfma_f32_16x16x32_bf16 v[124:127], v[148:151], v[194:197], v[124:127]
	s_setprio 0
	s_add_i32 s29, 0, 0x18000
	s_add_i32 s42, 0, 0x1c000
	v_add_u32_e32 v144, s29, v232
	v_add_u32_e32 v160, s42, v232
	ds_read_b128 v[132:135], v144
	ds_read_b128 v[136:139], v144 offset:1024
	ds_read_b128 v[140:143], v144 offset:2048
	ds_read_b128 v[144:147], v144 offset:3072
	ds_read_b128 v[148:151], v160
	ds_read_b128 v[152:155], v160 offset:1024
	ds_read_b128 v[156:159], v160 offset:2048
	ds_read_b128 v[160:163], v160 offset:3072
	s_add_u32 s16, s16, 0x80000
	s_addc_u32 s17, s17, 0
	s_mov_b32 m0, s59
	ds_read_b128 v[164:167], v210 offset:32768
	ds_read_b128 v[168:171], v210 offset:33792
	ds_read_b128 v[172:175], v210 offset:34816
	ds_read_b128 v[176:179], v210 offset:35840
	ds_read_b128 v[180:183], v210 offset:36864
	ds_read_b128 v[184:187], v210 offset:37888
	ds_read_b128 v[194:197], v210 offset:38912
	ds_read_b128 v[198:201], v210 offset:39936
	global_load_lds_dwordx4 v2, s[16:17]
	s_mov_b32 m0, s60
	s_nop 0
	global_load_lds_dwordx4 v188, s[16:17]
	s_waitcnt vmcnt(8)
	s_waitcnt lgkmcnt(0)
	s_barrier
	s_setprio 1
	s_waitcnt lgkmcnt(0)
	v_mfma_f32_16x16x32_bf16 v[4:7], v[132:135], v[164:167], v[4:7]
	v_mfma_f32_16x16x32_bf16 v[4:7], v[136:139], v[168:171], v[4:7]
	v_mfma_f32_16x16x32_bf16 v[8:11], v[144:147], v[168:171], v[8:11]
	v_mfma_f32_16x16x32_bf16 v[8:11], v[140:143], v[164:167], v[8:11]
	v_mfma_f32_16x16x32_bf16 v[16:19], v[140:143], v[172:175], v[16:19]
	v_mfma_f32_16x16x32_bf16 v[16:19], v[144:147], v[176:179], v[16:19]
	v_mfma_f32_16x16x32_bf16 v[12:15], v[136:139], v[176:179], v[12:15]
	v_mfma_f32_16x16x32_bf16 v[12:15], v[132:135], v[172:175], v[12:15]
	v_mfma_f32_16x16x32_bf16 v[20:23], v[132:135], v[180:183], v[20:23]
	v_mfma_f32_16x16x32_bf16 v[20:23], v[136:139], v[184:187], v[20:23]
	v_mfma_f32_16x16x32_bf16 v[24:27], v[144:147], v[184:187], v[24:27]
	v_mfma_f32_16x16x32_bf16 v[24:27], v[140:143], v[180:183], v[24:27]
	v_mfma_f32_16x16x32_bf16 v[32:35], v[140:143], v[194:197], v[32:35]
	v_mfma_f32_16x16x32_bf16 v[32:35], v[144:147], v[198:201], v[32:35]
	v_mfma_f32_16x16x32_bf16 v[28:31], v[136:139], v[198:201], v[28:31]
	v_mfma_f32_16x16x32_bf16 v[28:31], v[132:135], v[194:197], v[28:31]
	s_setprio 0
	s_setprio 1
	v_mfma_f32_16x16x32_bf16 v[36:39], v[148:151], v[164:167], v[36:39]
	v_mfma_f32_16x16x32_bf16 v[36:39], v[152:155], v[168:171], v[36:39]
	v_mfma_f32_16x16x32_bf16 v[40:43], v[160:163], v[168:171], v[40:43]
	v_mfma_f32_16x16x32_bf16 v[40:43], v[156:159], v[164:167], v[40:43]
	v_mfma_f32_16x16x32_bf16 v[48:51], v[156:159], v[172:175], v[48:51]
	v_mfma_f32_16x16x32_bf16 v[48:51], v[160:163], v[176:179], v[48:51]
	v_mfma_f32_16x16x32_bf16 v[44:47], v[152:155], v[176:179], v[44:47]
	v_mfma_f32_16x16x32_bf16 v[44:47], v[148:151], v[172:175], v[44:47]
	v_mfma_f32_16x16x32_bf16 v[52:55], v[148:151], v[180:183], v[52:55]
	v_mfma_f32_16x16x32_bf16 v[52:55], v[152:155], v[184:187], v[52:55]
	v_mfma_f32_16x16x32_bf16 v[56:59], v[160:163], v[184:187], v[56:59]
	v_mfma_f32_16x16x32_bf16 v[56:59], v[156:159], v[180:183], v[56:59]
	s_setprio 2
	s_barrier
	v_mfma_f32_16x16x32_bf16 v[64:67], v[156:159], v[194:197], v[64:67]
	v_mfma_f32_16x16x32_bf16 v[64:67], v[160:163], v[198:201], v[64:67]
	v_mfma_f32_16x16x32_bf16 v[60:63], v[152:155], v[198:201], v[60:63]
	v_mfma_f32_16x16x32_bf16 v[60:63], v[148:151], v[194:197], v[60:63]
	s_setprio 0
	s_add_i32 s16, s29, s56
	v_lshl_add_u64 v[202:203], v[202:203], 0, s[86:87]
	s_mov_b32 m0, s16
	ds_read_b128 v[164:167], v210 offset:49152
	ds_read_b128 v[168:171], v210 offset:50176
	ds_read_b128 v[172:175], v210 offset:51200
	ds_read_b128 v[176:179], v210 offset:52224
	ds_read_b128 v[180:183], v210 offset:53248
	ds_read_b128 v[184:187], v210 offset:54272
	ds_read_b128 v[194:197], v210 offset:55296
	ds_read_b128 v[198:201], v210 offset:56320
	global_load_lds_dwordx4 v[202:203], off
	s_add_i32 m0, s16, 0x2000
	s_add_u32 s12, s12, 0x80080
	v_lshl_add_u64 v[202:203], v[204:205], 0, s[86:87]
	s_addc_u32 s13, s13, 0
	s_add_i32 s16, s42, s56
	global_load_lds_dwordx4 v[202:203], off
	s_mov_b32 m0, s16
	v_lshl_add_u64 v[202:203], v[206:207], 0, s[86:87]
	global_load_lds_dwordx4 v192, s[12:13]
	s_add_i32 m0, s16, 0x2000
	s_nop 0
	global_load_lds_dwordx4 v190, s[12:13]
	s_mov_b32 m0, s64
	s_nop 0
	global_load_lds_dwordx4 v[202:203], off
	v_lshl_add_u64 v[202:203], v[208:209], 0, s[86:87]
	s_mov_b32 m0, s65
	s_nop 0
	global_load_lds_dwordx4 v[202:203], off
	s_waitcnt vmcnt(8)
	s_waitcnt lgkmcnt(0)
	s_barrier
	s_setprio 1
	s_waitcnt lgkmcnt(0)
	v_mfma_f32_16x16x32_bf16 v[68:71], v[132:135], v[164:167], v[68:71]
	v_mfma_f32_16x16x32_bf16 v[68:71], v[136:139], v[168:171], v[68:71]
	v_mfma_f32_16x16x32_bf16 v[72:75], v[144:147], v[168:171], v[72:75]
	v_mfma_f32_16x16x32_bf16 v[72:75], v[140:143], v[164:167], v[72:75]
	v_mfma_f32_16x16x32_bf16 v[80:83], v[140:143], v[172:175], v[80:83]
	v_mfma_f32_16x16x32_bf16 v[80:83], v[144:147], v[176:179], v[80:83]
	v_mfma_f32_16x16x32_bf16 v[76:79], v[136:139], v[176:179], v[76:79]
	v_mfma_f32_16x16x32_bf16 v[76:79], v[132:135], v[172:175], v[76:79]
	v_mfma_f32_16x16x32_bf16 v[84:87], v[132:135], v[180:183], v[84:87]
	v_mfma_f32_16x16x32_bf16 v[84:87], v[136:139], v[184:187], v[84:87]
	v_mfma_f32_16x16x32_bf16 v[88:91], v[144:147], v[184:187], v[88:91]
	v_mfma_f32_16x16x32_bf16 v[88:91], v[140:143], v[180:183], v[88:91]
	v_mfma_f32_16x16x32_bf16 v[96:99], v[140:143], v[194:197], v[96:99]
	v_mfma_f32_16x16x32_bf16 v[96:99], v[144:147], v[198:201], v[96:99]
	v_mfma_f32_16x16x32_bf16 v[92:95], v[136:139], v[198:201], v[92:95]
	v_mfma_f32_16x16x32_bf16 v[92:95], v[132:135], v[194:197], v[92:95]
	s_setprio 0
	s_setprio 1
	v_mfma_f32_16x16x32_bf16 v[100:103], v[148:151], v[164:167], v[100:103]
	v_mfma_f32_16x16x32_bf16 v[100:103], v[152:155], v[168:171], v[100:103]
	v_mfma_f32_16x16x32_bf16 v[104:107], v[160:163], v[168:171], v[104:107]
	v_mfma_f32_16x16x32_bf16 v[104:107], v[156:159], v[164:167], v[104:107]
	v_mfma_f32_16x16x32_bf16 v[112:115], v[156:159], v[172:175], v[112:115]
	v_mfma_f32_16x16x32_bf16 v[112:115], v[160:163], v[176:179], v[112:115]
	v_mfma_f32_16x16x32_bf16 v[108:111], v[152:155], v[176:179], v[108:111]
	v_mfma_f32_16x16x32_bf16 v[108:111], v[148:151], v[172:175], v[108:111]
	v_mfma_f32_16x16x32_bf16 v[116:119], v[148:151], v[180:183], v[116:119]
	v_mfma_f32_16x16x32_bf16 v[116:119], v[152:155], v[184:187], v[116:119]
	v_mfma_f32_16x16x32_bf16 v[120:123], v[160:163], v[184:187], v[120:123]
	v_mfma_f32_16x16x32_bf16 v[120:123], v[156:159], v[180:183], v[120:123]
	s_setprio 2
	s_barrier
	v_mfma_f32_16x16x32_bf16 v[128:131], v[156:159], v[194:197], v[128:131]
	v_mfma_f32_16x16x32_bf16 v[128:131], v[160:163], v[198:201], v[128:131]
	v_mfma_f32_16x16x32_bf16 v[124:127], v[152:155], v[198:201], v[124:127]
	v_mfma_f32_16x16x32_bf16 v[124:127], v[148:151], v[194:197], v[124:127]
	s_setprio 0
	s_add_i32 s28, s28, 2
	s_add_u32 s14, s14, 0x100
	s_addc_u32 s15, s15, 0
	s_add_u32 s26, s26, 0x100
	s_addc_u32 s27, s27, 0
	s_cmp_gt_u32 s28, 29
	s_cbranch_scc0 .LBB0_1629
	s_and_b64 vcc, exec, s[48:49]
	s_cbranch_vccz .LBB0_1632
	s_barrier

.LBB0_2065:
	s_add_i32 s51, 0, 0x10000
	s_add_i32 s71, 0, 0x14000
	v_add_u32_e32 v16, s51, v232
	v_add_u32_e32 v32, s71, v232
	ds_read_b128 v[4:7], v16
	ds_read_b128 v[8:11], v16 offset:1024
	ds_read_b128 v[12:15], v16 offset:2048
	ds_read_b128 v[16:19], v16 offset:3072
	ds_read_b128 v[20:23], v32
	ds_read_b128 v[24:27], v32 offset:1024
	ds_read_b128 v[28:31], v32 offset:2048
	ds_read_b128 v[32:35], v32 offset:3072
	v_add_u32_e32 v233, 0, v231
	ds_read_b128 v[36:39], v233
	ds_read_b128 v[40:43], v233 offset:1024
	ds_read_b128 v[44:47], v233 offset:2048
	ds_read_b128 v[48:51], v233 offset:3072
	ds_read_b128 v[52:55], v233 offset:4096
	ds_read_b128 v[56:59], v233 offset:5120
	ds_read_b128 v[60:63], v233 offset:6144
	ds_read_b128 v[64:67], v233 offset:7168
	s_waitcnt vmcnt(8)
	s_waitcnt lgkmcnt(0)
	s_barrier
	s_setprio 1
	s_waitcnt lgkmcnt(0)
	v_mfma_f32_16x16x32_bf16 v[68:71], v[4:7], v[36:39], 0
	v_mfma_f32_16x16x32_bf16 v[68:71], v[8:11], v[40:43], v[68:71]
	v_mfma_f32_16x16x32_bf16 v[72:75], v[12:15], v[36:39], 0
	v_mfma_f32_16x16x32_bf16 v[72:75], v[16:19], v[40:43], v[72:75]
	v_mfma_f32_16x16x32_bf16 v[80:83], v[12:15], v[44:47], 0
	v_mfma_f32_16x16x32_bf16 v[80:83], v[16:19], v[48:51], v[80:83]
	v_mfma_f32_16x16x32_bf16 v[76:79], v[4:7], v[44:47], 0
	v_mfma_f32_16x16x32_bf16 v[76:79], v[8:11], v[48:51], v[76:79]
	v_mfma_f32_16x16x32_bf16 v[84:87], v[4:7], v[52:55], 0
	v_mfma_f32_16x16x32_bf16 v[84:87], v[8:11], v[56:59], v[84:87]
	v_mfma_f32_16x16x32_bf16 v[88:91], v[12:15], v[52:55], 0
	v_mfma_f32_16x16x32_bf16 v[88:91], v[16:19], v[56:59], v[88:91]
	v_mfma_f32_16x16x32_bf16 v[96:99], v[12:15], v[60:63], 0
	v_mfma_f32_16x16x32_bf16 v[96:99], v[16:19], v[64:67], v[96:99]
	v_mfma_f32_16x16x32_bf16 v[92:95], v[4:7], v[60:63], 0
	v_mfma_f32_16x16x32_bf16 v[92:95], v[8:11], v[64:67], v[92:95]
	s_setprio 0
	s_setprio 1
	v_mfma_f32_16x16x32_bf16 v[100:103], v[20:23], v[36:39], 0
	v_mfma_f32_16x16x32_bf16 v[36:39], v[28:31], v[36:39], 0
	v_mfma_f32_16x16x32_bf16 v[104:107], v[20:23], v[44:47], 0
	v_mfma_f32_16x16x32_bf16 v[44:47], v[28:31], v[44:47], 0
	v_mfma_f32_16x16x32_bf16 v[108:111], v[20:23], v[52:55], 0
	v_mfma_f32_16x16x32_bf16 v[52:55], v[28:31], v[52:55], 0
	v_mfma_f32_16x16x32_bf16 v[112:115], v[20:23], v[60:63], 0
	v_mfma_f32_16x16x32_bf16 v[60:63], v[28:31], v[60:63], 0
	v_mfma_f32_16x16x32_bf16 v[100:103], v[24:27], v[40:43], v[100:103]
	v_mfma_f32_16x16x32_bf16 v[40:43], v[32:35], v[40:43], v[36:39]
	v_mfma_f32_16x16x32_bf16 v[104:107], v[24:27], v[48:51], v[104:107]
	v_mfma_f32_16x16x32_bf16 v[48:51], v[32:35], v[48:51], v[44:47]
	s_setprio 2
	s_barrier
	v_mfma_f32_16x16x32_bf16 v[108:111], v[24:27], v[56:59], v[108:111]
	v_mfma_f32_16x16x32_bf16 v[56:59], v[32:35], v[56:59], v[52:55]
	v_mfma_f32_16x16x32_bf16 v[112:115], v[24:27], v[64:67], v[112:115]
	v_mfma_f32_16x16x32_bf16 v[64:67], v[32:35], v[64:67], v[60:63]
	s_setprio 0
	v_lshl_add_u64 v[186:187], s[12:13], 0, v[2:3]
	s_add_i32 s51, s51, s38
	v_mov_b32_e32 v191, v3
	v_lshl_add_u64 v[134:135], v[186:187], 0, s[74:75]
	s_mov_b32 m0, s51
	v_lshl_add_u64 v[246:247], s[12:13], 0, v[190:191]
	ds_read_b128 v[36:39], v233 offset:16384
	ds_read_b128 v[44:47], v233 offset:17408
	ds_read_b128 v[52:55], v233 offset:18432
	ds_read_b128 v[60:63], v233 offset:19456
	ds_read_b128 v[116:119], v233 offset:20480
	ds_read_b128 v[120:123], v233 offset:21504
	ds_read_b128 v[124:127], v233 offset:22528
	ds_read_b128 v[128:131], v233 offset:23552
	global_load_lds_dwordx4 v[134:135], off
	v_lshl_add_u64 v[134:135], v[246:247], 0, s[74:75]
	s_add_i32 m0, s51, 0x2000
	s_add_i32 s51, s71, s38
	global_load_lds_dwordx4 v[134:135], off
	s_mov_b32 m0, s51
	v_mov_b32_e32 v133, v3
	global_load_lds_dwordx4 v2, s[16:17]
	s_add_i32 m0, s51, 0x2000
	v_lshl_add_u64 v[248:249], s[14:15], 0, v[132:133]
	v_mov_b32_e32 v189, v3
	global_load_lds_dwordx4 v190, s[16:17]
	v_lshl_add_u64 v[134:135], v[248:249], 0, s[74:75]
	s_mov_b32 m0, s56
	v_lshl_add_u64 v[250:251], s[14:15], 0, v[188:189]
	global_load_lds_dwordx4 v[134:135], off
	v_lshl_add_u64 v[134:135], v[250:251], 0, s[74:75]
	s_mov_b32 m0, s57
	s_nop 0
	global_load_lds_dwordx4 v[134:135], off
	s_waitcnt vmcnt(8)
	s_waitcnt lgkmcnt(0)
	s_barrier
	s_setprio 1
	s_waitcnt lgkmcnt(0)
	v_mfma_f32_16x16x32_bf16 v[134:137], v[4:7], v[36:39], 0
	v_mfma_f32_16x16x32_bf16 v[138:141], v[12:15], v[36:39], 0
	v_mfma_f32_16x16x32_bf16 v[142:145], v[4:7], v[52:55], 0
	v_mfma_f32_16x16x32_bf16 v[146:149], v[12:15], v[52:55], 0
	v_mfma_f32_16x16x32_bf16 v[150:153], v[4:7], v[116:119], 0
	v_mfma_f32_16x16x32_bf16 v[154:157], v[12:15], v[116:119], 0
	v_mfma_f32_16x16x32_bf16 v[4:7], v[4:7], v[124:127], 0
	v_mfma_f32_16x16x32_bf16 v[12:15], v[12:15], v[124:127], 0
	v_mfma_f32_16x16x32_bf16 v[134:137], v[8:11], v[44:47], v[134:137]
	v_mfma_f32_16x16x32_bf16 v[138:141], v[16:19], v[44:47], v[138:141]
	v_mfma_f32_16x16x32_bf16 v[142:145], v[8:11], v[60:63], v[142:145]
	v_mfma_f32_16x16x32_bf16 v[146:149], v[16:19], v[60:63], v[146:149]
	v_mfma_f32_16x16x32_bf16 v[150:153], v[8:11], v[120:123], v[150:153]
	v_mfma_f32_16x16x32_bf16 v[154:157], v[16:19], v[120:123], v[154:157]
	v_mfma_f32_16x16x32_bf16 v[158:161], v[8:11], v[128:131], v[4:7]
	v_mfma_f32_16x16x32_bf16 v[162:165], v[16:19], v[128:131], v[12:15]
	s_setprio 0
	s_setprio 1
	v_mfma_f32_16x16x32_bf16 v[4:7], v[20:23], v[36:39], 0
	v_mfma_f32_16x16x32_bf16 v[8:11], v[28:31], v[36:39], 0
	v_mfma_f32_16x16x32_bf16 v[12:15], v[20:23], v[52:55], 0
	v_mfma_f32_16x16x32_bf16 v[16:19], v[28:31], v[52:55], 0
	v_mfma_f32_16x16x32_bf16 v[36:39], v[20:23], v[116:119], 0
	v_mfma_f32_16x16x32_bf16 v[52:55], v[28:31], v[116:119], 0
	v_mfma_f32_16x16x32_bf16 v[20:23], v[20:23], v[124:127], 0
	v_mfma_f32_16x16x32_bf16 v[28:31], v[28:31], v[124:127], 0
	v_mfma_f32_16x16x32_bf16 v[116:119], v[24:27], v[44:47], v[4:7]
	v_mfma_f32_16x16x32_bf16 v[124:127], v[32:35], v[44:47], v[8:11]
	v_mfma_f32_16x16x32_bf16 v[174:177], v[24:27], v[120:123], v[36:39]
	v_mfma_f32_16x16x32_bf16 v[120:123], v[32:35], v[120:123], v[52:55]
	s_setprio 2
	s_barrier
	v_mfma_f32_16x16x32_bf16 v[178:181], v[24:27], v[128:131], v[20:23]
	v_mfma_f32_16x16x32_bf16 v[128:131], v[32:35], v[128:131], v[28:31]
	v_mfma_f32_16x16x32_bf16 v[166:169], v[24:27], v[60:63], v[12:15]
	v_mfma_f32_16x16x32_bf16 v[170:173], v[32:35], v[60:63], v[16:19]
	s_setprio 0
	s_add_i32 s51, 0, 0x18000
	v_add_u32_e32 v4, s51, v232
	s_add_i32 s71, 0, 0x1c000
	ds_read_b128 v[182:185], v4
	ds_read_b128 v[192:195], v4 offset:1024
	ds_read_b128 v[196:199], v4 offset:2048
	ds_read_b128 v[200:203], v4 offset:3072
	v_add_u32_e32 v4, s71, v232
	ds_read_b128 v[204:207], v4
	ds_read_b128 v[208:211], v4 offset:1024
	ds_read_b128 v[212:215], v4 offset:2048
	ds_read_b128 v[216:219], v4 offset:3072
	s_mov_b32 m0, s58
	ds_read_b128 v[44:47], v233 offset:32768
	ds_read_b128 v[52:55], v233 offset:33792
	ds_read_b128 v[60:63], v233 offset:34816
	ds_read_b128 v[220:223], v233 offset:35840
	ds_read_b128 v[224:227], v233 offset:36864
	ds_read_b128 v[234:237], v233 offset:37888
	ds_read_b128 v[238:241], v233 offset:38912
	ds_read_b128 v[242:245], v233 offset:39936
	global_load_lds_dwordx4 v132, s[26:27]
	s_mov_b32 m0, s59
	s_nop 0
	global_load_lds_dwordx4 v188, s[26:27]
	s_waitcnt vmcnt(8)
	s_waitcnt lgkmcnt(0)
	s_barrier
	s_setprio 1
	s_waitcnt lgkmcnt(0)
	v_mfma_f32_16x16x32_bf16 v[4:7], v[182:185], v[44:47], v[68:71]
	v_mfma_f32_16x16x32_bf16 v[8:11], v[196:199], v[44:47], v[72:75]
	v_mfma_f32_16x16x32_bf16 v[12:15], v[182:185], v[60:63], v[76:79]
	v_mfma_f32_16x16x32_bf16 v[16:19], v[196:199], v[60:63], v[80:83]
	v_mfma_f32_16x16x32_bf16 v[20:23], v[182:185], v[224:227], v[84:87]
	v_mfma_f32_16x16x32_bf16 v[24:27], v[196:199], v[224:227], v[88:91]
	v_mfma_f32_16x16x32_bf16 v[28:31], v[182:185], v[238:241], v[92:95]
	v_mfma_f32_16x16x32_bf16 v[32:35], v[196:199], v[238:241], v[96:99]
	v_mfma_f32_16x16x32_bf16 v[4:7], v[192:195], v[52:55], v[4:7]
	v_mfma_f32_16x16x32_bf16 v[8:11], v[200:203], v[52:55], v[8:11]
	v_mfma_f32_16x16x32_bf16 v[12:15], v[192:195], v[220:223], v[12:15]
	v_mfma_f32_16x16x32_bf16 v[16:19], v[200:203], v[220:223], v[16:19]
	v_mfma_f32_16x16x32_bf16 v[20:23], v[192:195], v[234:237], v[20:23]
	v_mfma_f32_16x16x32_bf16 v[24:27], v[200:203], v[234:237], v[24:27]
	v_mfma_f32_16x16x32_bf16 v[28:31], v[192:195], v[242:245], v[28:31]
	v_mfma_f32_16x16x32_bf16 v[32:35], v[200:203], v[242:245], v[32:35]
	s_setprio 0
	s_setprio 1
	v_mfma_f32_16x16x32_bf16 v[36:39], v[204:207], v[44:47], v[100:103]
	v_mfma_f32_16x16x32_bf16 v[40:43], v[212:215], v[44:47], v[40:43]
	v_mfma_f32_16x16x32_bf16 v[36:39], v[208:211], v[52:55], v[36:39]
	v_mfma_f32_16x16x32_bf16 v[40:43], v[216:219], v[52:55], v[40:43]
	v_mfma_f32_16x16x32_bf16 v[44:47], v[204:207], v[60:63], v[104:107]
	v_mfma_f32_16x16x32_bf16 v[48:51], v[212:215], v[60:63], v[48:51]
	v_mfma_f32_16x16x32_bf16 v[52:55], v[204:207], v[224:227], v[108:111]
	v_mfma_f32_16x16x32_bf16 v[56:59], v[212:215], v[224:227], v[56:59]
	v_mfma_f32_16x16x32_bf16 v[60:63], v[204:207], v[238:241], v[112:115]
	v_mfma_f32_16x16x32_bf16 v[64:67], v[212:215], v[238:241], v[64:67]
	v_mfma_f32_16x16x32_bf16 v[44:47], v[208:211], v[220:223], v[44:47]
	v_mfma_f32_16x16x32_bf16 v[48:51], v[216:219], v[220:223], v[48:51]
	s_setprio 2
	s_barrier
	v_mfma_f32_16x16x32_bf16 v[52:55], v[208:211], v[234:237], v[52:55]
	v_mfma_f32_16x16x32_bf16 v[56:59], v[216:219], v[234:237], v[56:59]
	v_mfma_f32_16x16x32_bf16 v[60:63], v[208:211], v[242:245], v[60:63]
	v_mfma_f32_16x16x32_bf16 v[64:67], v[216:219], v[242:245], v[64:67]
	s_setprio 0
	s_add_i32 s51, s51, s38
	v_lshl_add_u64 v[68:69], v[186:187], 0, s[24:25]
	s_mov_b32 m0, s51
	ds_read_b128 v[104:107], v233 offset:49152
	ds_read_b128 v[108:111], v233 offset:50176
	ds_read_b128 v[112:115], v233 offset:51200
	ds_read_b128 v[220:223], v233 offset:52224
	ds_read_b128 v[224:227], v233 offset:53248
	ds_read_b128 v[234:237], v233 offset:54272
	ds_read_b128 v[238:241], v233 offset:55296
	ds_read_b128 v[242:245], v233 offset:56320
	global_load_lds_dwordx4 v[68:69], off
	v_lshl_add_u64 v[68:69], v[246:247], 0, s[24:25]
	s_add_i32 m0, s51, 0x2000
	s_add_i32 s51, s71, s38
	global_load_lds_dwordx4 v[68:69], off
	s_mov_b32 m0, s51
	v_lshl_add_u64 v[68:69], v[248:249], 0, s[24:25]
	global_load_lds_dwordx4 v2, s[28:29]
	s_add_i32 m0, s51, 0x2000
	s_nop 0
	global_load_lds_dwordx4 v190, s[28:29]
	s_mov_b32 m0, s63
	s_nop 0
	global_load_lds_dwordx4 v[68:69], off
	v_lshl_add_u64 v[68:69], v[250:251], 0, s[24:25]
	s_mov_b32 m0, s64
	s_nop 0
	global_load_lds_dwordx4 v[68:69], off
	s_waitcnt vmcnt(8)
	s_waitcnt lgkmcnt(0)
	s_barrier
	s_setprio 1
	s_waitcnt lgkmcnt(0)
	v_mfma_f32_16x16x32_bf16 v[68:71], v[182:185], v[104:107], v[134:137]
	v_mfma_f32_16x16x32_bf16 v[72:75], v[196:199], v[104:107], v[138:141]
	v_mfma_f32_16x16x32_bf16 v[76:79], v[182:185], v[112:115], v[142:145]
	v_mfma_f32_16x16x32_bf16 v[80:83], v[196:199], v[112:115], v[146:149]
	v_mfma_f32_16x16x32_bf16 v[84:87], v[182:185], v[224:227], v[150:153]
	v_mfma_f32_16x16x32_bf16 v[88:91], v[196:199], v[224:227], v[154:157]
	v_mfma_f32_16x16x32_bf16 v[92:95], v[182:185], v[238:241], v[158:161]
	v_mfma_f32_16x16x32_bf16 v[96:99], v[196:199], v[238:241], v[162:165]
	v_mfma_f32_16x16x32_bf16 v[68:71], v[192:195], v[108:111], v[68:71]
	v_mfma_f32_16x16x32_bf16 v[72:75], v[200:203], v[108:111], v[72:75]
	v_mfma_f32_16x16x32_bf16 v[76:79], v[192:195], v[220:223], v[76:79]
	v_mfma_f32_16x16x32_bf16 v[80:83], v[200:203], v[220:223], v[80:83]
	v_mfma_f32_16x16x32_bf16 v[84:87], v[192:195], v[234:237], v[84:87]
	v_mfma_f32_16x16x32_bf16 v[88:91], v[200:203], v[234:237], v[88:91]
	v_mfma_f32_16x16x32_bf16 v[92:95], v[192:195], v[242:245], v[92:95]
	v_mfma_f32_16x16x32_bf16 v[96:99], v[200:203], v[242:245], v[96:99]
	s_setprio 0
	s_setprio 1
	v_mfma_f32_16x16x32_bf16 v[100:103], v[204:207], v[104:107], v[116:119]
	v_mfma_f32_16x16x32_bf16 v[104:107], v[212:215], v[104:107], v[124:127]
	v_mfma_f32_16x16x32_bf16 v[100:103], v[208:211], v[108:111], v[100:103]
	v_mfma_f32_16x16x32_bf16 v[104:107], v[216:219], v[108:111], v[104:107]
	v_mfma_f32_16x16x32_bf16 v[108:111], v[204:207], v[112:115], v[166:169]
	v_mfma_f32_16x16x32_bf16 v[112:115], v[212:215], v[112:115], v[170:173]
	v_mfma_f32_16x16x32_bf16 v[116:119], v[204:207], v[224:227], v[174:177]
	v_mfma_f32_16x16x32_bf16 v[120:123], v[212:215], v[224:227], v[120:123]
	v_mfma_f32_16x16x32_bf16 v[124:127], v[204:207], v[238:241], v[178:181]
	v_mfma_f32_16x16x32_bf16 v[128:131], v[212:215], v[238:241], v[128:131]
	v_mfma_f32_16x16x32_bf16 v[108:111], v[208:211], v[220:223], v[108:111]
	v_mfma_f32_16x16x32_bf16 v[112:115], v[216:219], v[220:223], v[112:115]
	s_setprio 2
	s_barrier
	v_mfma_f32_16x16x32_bf16 v[116:119], v[208:211], v[234:237], v[116:119]
	v_mfma_f32_16x16x32_bf16 v[120:123], v[216:219], v[234:237], v[120:123]
	v_mfma_f32_16x16x32_bf16 v[124:127], v[208:211], v[242:245], v[124:127]
	v_mfma_f32_16x16x32_bf16 v[128:131], v[216:219], v[242:245], v[128:131]
	s_setprio 0
	s_add_i32 s45, s45, 2
	s_cmp_ge_i32 s45, s44
	s_cbranch_scc0 .LBB0_2065
	v_mov_b32_e32 v192, v2
	s_branch .LBB0_2068

.LBB0_2069:
	s_add_u32 s12, s14, 0xfff80080
	s_addc_u32 s13, s15, -1
	s_add_i32 s29, 0, 0x10000
	s_cmp_eq_u32 s28, 4
	s_cselect_b32 s17, s9, s13
	s_cselect_b32 s16, s8, s12
	s_cselect_b32 s13, s11, s27
	s_cselect_b32 s12, s10, s26
	s_add_i32 s51, 0, 0x14000
	v_add_u32_e32 v144, s29, v232
	v_add_u32_e32 v160, s51, v232
	s_waitcnt lgkmcnt(0)
	ds_read_b128 v[132:135], v144
	ds_read_b128 v[136:139], v144 offset:1024
	ds_read_b128 v[140:143], v144 offset:2048
	ds_read_b128 v[144:147], v144 offset:3072
	ds_read_b128 v[148:151], v160
	ds_read_b128 v[152:155], v160 offset:1024
	ds_read_b128 v[156:159], v160 offset:2048
	ds_read_b128 v[160:163], v160 offset:3072
	s_mov_b32 m0, s65
	v_add_u32_e32 v210, 0, v231
	ds_read_b128 v[164:167], v210
	ds_read_b128 v[168:171], v210 offset:1024
	ds_read_b128 v[172:175], v210 offset:2048
	ds_read_b128 v[176:179], v210 offset:3072
	ds_read_b128 v[180:183], v210 offset:4096
	ds_read_b128 v[184:187], v210 offset:5120
	ds_read_b128 v[194:197], v210 offset:6144
	ds_read_b128 v[198:201], v210 offset:7168
	global_load_lds_dwordx4 v2, s[14:15]
	s_mov_b32 m0, s66
	v_mov_b32_e32 v189, v3
	global_load_lds_dwordx4 v188, s[14:15]
	s_waitcnt vmcnt(8)
	s_waitcnt lgkmcnt(0)
	s_barrier
	s_setprio 1
	s_waitcnt lgkmcnt(0)
	v_mfma_f32_16x16x32_bf16 v[4:7], v[132:135], v[164:167], v[4:7]
	v_mfma_f32_16x16x32_bf16 v[4:7], v[136:139], v[168:171], v[4:7]
	v_mfma_f32_16x16x32_bf16 v[8:11], v[144:147], v[168:171], v[8:11]
	v_mfma_f32_16x16x32_bf16 v[8:11], v[140:143], v[164:167], v[8:11]
	v_mfma_f32_16x16x32_bf16 v[16:19], v[140:143], v[172:175], v[16:19]
	v_mfma_f32_16x16x32_bf16 v[16:19], v[144:147], v[176:179], v[16:19]
	v_mfma_f32_16x16x32_bf16 v[12:15], v[136:139], v[176:179], v[12:15]
	v_mfma_f32_16x16x32_bf16 v[12:15], v[132:135], v[172:175], v[12:15]
	v_mfma_f32_16x16x32_bf16 v[20:23], v[132:135], v[180:183], v[20:23]
	v_mfma_f32_16x16x32_bf16 v[20:23], v[136:139], v[184:187], v[20:23]
	v_mfma_f32_16x16x32_bf16 v[24:27], v[144:147], v[184:187], v[24:27]
	v_mfma_f32_16x16x32_bf16 v[24:27], v[140:143], v[180:183], v[24:27]
	v_mfma_f32_16x16x32_bf16 v[32:35], v[140:143], v[194:197], v[32:35]
	v_mfma_f32_16x16x32_bf16 v[32:35], v[144:147], v[198:201], v[32:35]
	v_mfma_f32_16x16x32_bf16 v[28:31], v[136:139], v[198:201], v[28:31]
	v_mfma_f32_16x16x32_bf16 v[28:31], v[132:135], v[194:197], v[28:31]
	s_setprio 0
	s_setprio 1
	v_mfma_f32_16x16x32_bf16 v[36:39], v[148:151], v[164:167], v[36:39]
	v_mfma_f32_16x16x32_bf16 v[36:39], v[152:155], v[168:171], v[36:39]
	v_mfma_f32_16x16x32_bf16 v[40:43], v[160:163], v[168:171], v[40:43]
	v_mfma_f32_16x16x32_bf16 v[40:43], v[156:159], v[164:167], v[40:43]
	v_mfma_f32_16x16x32_bf16 v[48:51], v[156:159], v[172:175], v[48:51]
	v_mfma_f32_16x16x32_bf16 v[48:51], v[160:163], v[176:179], v[48:51]
	v_mfma_f32_16x16x32_bf16 v[44:47], v[152:155], v[176:179], v[44:47]
	v_mfma_f32_16x16x32_bf16 v[44:47], v[148:151], v[172:175], v[44:47]
	v_mfma_f32_16x16x32_bf16 v[52:55], v[148:151], v[180:183], v[52:55]
	v_mfma_f32_16x16x32_bf16 v[52:55], v[152:155], v[184:187], v[52:55]
	v_mfma_f32_16x16x32_bf16 v[56:59], v[160:163], v[184:187], v[56:59]
	v_mfma_f32_16x16x32_bf16 v[56:59], v[156:159], v[180:183], v[56:59]
	s_setprio 2
	s_barrier
	v_mfma_f32_16x16x32_bf16 v[64:67], v[156:159], v[194:197], v[64:67]
	v_mfma_f32_16x16x32_bf16 v[64:67], v[160:163], v[198:201], v[64:67]
	v_mfma_f32_16x16x32_bf16 v[60:63], v[152:155], v[198:201], v[60:63]
	v_mfma_f32_16x16x32_bf16 v[60:63], v[148:151], v[194:197], v[60:63]
	s_setprio 0
	s_add_i32 s29, s29, s38
	s_mov_b32 m0, s29
	ds_read_b128 v[164:167], v210 offset:16384
	ds_read_b128 v[168:171], v210 offset:17408
	ds_read_b128 v[172:175], v210 offset:18432
	ds_read_b128 v[176:179], v210 offset:19456
	ds_read_b128 v[180:183], v210 offset:20480
	ds_read_b128 v[184:187], v210 offset:21504
	ds_read_b128 v[194:197], v210 offset:22528
	ds_read_b128 v[198:201], v210 offset:23552
	global_load_lds_dwordx4 v192, s[12:13]
	s_add_i32 m0, s29, 0x2000
	s_add_u32 s44, s12, 0x20000
	s_addc_u32 s45, s13, 0
	s_add_i32 s29, s51, s38
	global_load_lds_dwordx4 v190, s[12:13]
	s_mov_b32 m0, s29
	v_mov_b32_e32 v193, v3
	global_load_lds_dwordx4 v192, s[44:45]
	s_add_i32 m0, s29, 0x2000
	v_mov_b32_e32 v191, v3
	global_load_lds_dwordx4 v190, s[44:45]
	s_mov_b32 m0, s56
	v_lshl_add_u64 v[202:203], s[12:13], 0, v[192:193]
	global_load_lds_dwordx4 v2, s[16:17]
	s_mov_b32 m0, s57
	v_lshl_add_u64 v[204:205], s[12:13], 0, v[190:191]
	global_load_lds_dwordx4 v188, s[16:17]
	s_waitcnt vmcnt(8)
	s_waitcnt lgkmcnt(0)
	v_lshl_add_u64 v[206:207], s[16:17], 0, v[2:3]
	v_lshl_add_u64 v[208:209], s[16:17], 0, v[188:189]
	s_barrier
	s_setprio 1
	s_waitcnt lgkmcnt(0)
	v_mfma_f32_16x16x32_bf16 v[68:71], v[132:135], v[164:167], v[68:71]
	v_mfma_f32_16x16x32_bf16 v[68:71], v[136:139], v[168:171], v[68:71]
	v_mfma_f32_16x16x32_bf16 v[72:75], v[144:147], v[168:171], v[72:75]
	v_mfma_f32_16x16x32_bf16 v[72:75], v[140:143], v[164:167], v[72:75]
	v_mfma_f32_16x16x32_bf16 v[80:83], v[140:143], v[172:175], v[80:83]
	v_mfma_f32_16x16x32_bf16 v[80:83], v[144:147], v[176:179], v[80:83]
	v_mfma_f32_16x16x32_bf16 v[76:79], v[136:139], v[176:179], v[76:79]
	v_mfma_f32_16x16x32_bf16 v[76:79], v[132:135], v[172:175], v[76:79]
	v_mfma_f32_16x16x32_bf16 v[84:87], v[132:135], v[180:183], v[84:87]
	v_mfma_f32_16x16x32_bf16 v[84:87], v[136:139], v[184:187], v[84:87]
	v_mfma_f32_16x16x32_bf16 v[88:91], v[144:147], v[184:187], v[88:91]
	v_mfma_f32_16x16x32_bf16 v[88:91], v[140:143], v[180:183], v[88:91]
	v_mfma_f32_16x16x32_bf16 v[96:99], v[140:143], v[194:197], v[96:99]
	v_mfma_f32_16x16x32_bf16 v[96:99], v[144:147], v[198:201], v[96:99]
	v_mfma_f32_16x16x32_bf16 v[92:95], v[136:139], v[198:201], v[92:95]
	v_mfma_f32_16x16x32_bf16 v[92:95], v[132:135], v[194:197], v[92:95]
	s_setprio 0
	s_setprio 1
	v_mfma_f32_16x16x32_bf16 v[100:103], v[148:151], v[164:167], v[100:103]
	v_mfma_f32_16x16x32_bf16 v[100:103], v[152:155], v[168:171], v[100:103]
	v_mfma_f32_16x16x32_bf16 v[104:107], v[160:163], v[168:171], v[104:107]
	v_mfma_f32_16x16x32_bf16 v[104:107], v[156:159], v[164:167], v[104:107]
	v_mfma_f32_16x16x32_bf16 v[112:115], v[156:159], v[172:175], v[112:115]
	v_mfma_f32_16x16x32_bf16 v[112:115], v[160:163], v[176:179], v[112:115]
	v_mfma_f32_16x16x32_bf16 v[108:111], v[152:155], v[176:179], v[108:111]
	v_mfma_f32_16x16x32_bf16 v[108:111], v[148:151], v[172:175], v[108:111]
	v_mfma_f32_16x16x32_bf16 v[116:119], v[148:151], v[180:183], v[116:119]
	v_mfma_f32_16x16x32_bf16 v[116:119], v[152:155], v[184:187], v[116:119]
	v_mfma_f32_16x16x32_bf16 v[120:123], v[160:163], v[184:187], v[120:123]
	v_mfma_f32_16x16x32_bf16 v[120:123], v[156:159], v[180:183], v[120:123]
	s_setprio 2
	s_barrier
	v_mfma_f32_16x16x32_bf16 v[128:131], v[156:159], v[194:197], v[128:131]
	v_mfma_f32_16x16x32_bf16 v[128:131], v[160:163], v[198:201], v[128:131]
	v_mfma_f32_16x16x32_bf16 v[124:127], v[152:155], v[198:201], v[124:127]
	v_mfma_f32_16x16x32_bf16 v[124:127], v[148:151], v[194:197], v[124:127]
	s_setprio 0
	s_add_i32 s29, 0, 0x18000
	s_add_i32 s44, 0, 0x1c000
	v_add_u32_e32 v144, s29, v232
	v_add_u32_e32 v160, s44, v232
	ds_read_b128 v[132:135], v144
	ds_read_b128 v[136:139], v144 offset:1024
	ds_read_b128 v[140:143], v144 offset:2048
	ds_read_b128 v[144:147], v144 offset:3072
	ds_read_b128 v[148:151], v160
	ds_read_b128 v[152:155], v160 offset:1024
	ds_read_b128 v[156:159], v160 offset:2048
	ds_read_b128 v[160:163], v160 offset:3072
	s_add_u32 s16, s16, 0x80000
	s_addc_u32 s17, s17, 0
	s_mov_b32 m0, s58
	ds_read_b128 v[164:167], v210 offset:32768
	ds_read_b128 v[168:171], v210 offset:33792
	ds_read_b128 v[172:175], v210 offset:34816
	ds_read_b128 v[176:179], v210 offset:35840
	ds_read_b128 v[180:183], v210 offset:36864
	ds_read_b128 v[184:187], v210 offset:37888
	ds_read_b128 v[194:197], v210 offset:38912
	ds_read_b128 v[198:201], v210 offset:39936
	global_load_lds_dwordx4 v2, s[16:17]
	s_mov_b32 m0, s59
	s_nop 0
	global_load_lds_dwordx4 v188, s[16:17]
	s_waitcnt vmcnt(8)
	s_waitcnt lgkmcnt(0)
	s_barrier
	s_setprio 1
	s_waitcnt lgkmcnt(0)
	v_mfma_f32_16x16x32_bf16 v[4:7], v[132:135], v[164:167], v[4:7]
	v_mfma_f32_16x16x32_bf16 v[4:7], v[136:139], v[168:171], v[4:7]
	v_mfma_f32_16x16x32_bf16 v[8:11], v[144:147], v[168:171], v[8:11]
	v_mfma_f32_16x16x32_bf16 v[8:11], v[140:143], v[164:167], v[8:11]
	v_mfma_f32_16x16x32_bf16 v[16:19], v[140:143], v[172:175], v[16:19]
	v_mfma_f32_16x16x32_bf16 v[16:19], v[144:147], v[176:179], v[16:19]
	v_mfma_f32_16x16x32_bf16 v[12:15], v[136:139], v[176:179], v[12:15]
	v_mfma_f32_16x16x32_bf16 v[12:15], v[132:135], v[172:175], v[12:15]
	v_mfma_f32_16x16x32_bf16 v[20:23], v[132:135], v[180:183], v[20:23]
	v_mfma_f32_16x16x32_bf16 v[20:23], v[136:139], v[184:187], v[20:23]
	v_mfma_f32_16x16x32_bf16 v[24:27], v[144:147], v[184:187], v[24:27]
	v_mfma_f32_16x16x32_bf16 v[24:27], v[140:143], v[180:183], v[24:27]
	v_mfma_f32_16x16x32_bf16 v[32:35], v[140:143], v[194:197], v[32:35]
	v_mfma_f32_16x16x32_bf16 v[32:35], v[144:147], v[198:201], v[32:35]
	v_mfma_f32_16x16x32_bf16 v[28:31], v[136:139], v[198:201], v[28:31]
	v_mfma_f32_16x16x32_bf16 v[28:31], v[132:135], v[194:197], v[28:31]
	s_setprio 0
	s_setprio 1
	v_mfma_f32_16x16x32_bf16 v[36:39], v[148:151], v[164:167], v[36:39]
	v_mfma_f32_16x16x32_bf16 v[36:39], v[152:155], v[168:171], v[36:39]
	v_mfma_f32_16x16x32_bf16 v[40:43], v[160:163], v[168:171], v[40:43]
	v_mfma_f32_16x16x32_bf16 v[40:43], v[156:159], v[164:167], v[40:43]
	v_mfma_f32_16x16x32_bf16 v[48:51], v[156:159], v[172:175], v[48:51]
	v_mfma_f32_16x16x32_bf16 v[48:51], v[160:163], v[176:179], v[48:51]
	v_mfma_f32_16x16x32_bf16 v[44:47], v[152:155], v[176:179], v[44:47]
	v_mfma_f32_16x16x32_bf16 v[44:47], v[148:151], v[172:175], v[44:47]
	v_mfma_f32_16x16x32_bf16 v[52:55], v[148:151], v[180:183], v[52:55]
	v_mfma_f32_16x16x32_bf16 v[52:55], v[152:155], v[184:187], v[52:55]
	v_mfma_f32_16x16x32_bf16 v[56:59], v[160:163], v[184:187], v[56:59]
	v_mfma_f32_16x16x32_bf16 v[56:59], v[156:159], v[180:183], v[56:59]
	s_setprio 2
	s_barrier
	v_mfma_f32_16x16x32_bf16 v[64:67], v[156:159], v[194:197], v[64:67]
	v_mfma_f32_16x16x32_bf16 v[64:67], v[160:163], v[198:201], v[64:67]
	v_mfma_f32_16x16x32_bf16 v[60:63], v[152:155], v[198:201], v[60:63]
	v_mfma_f32_16x16x32_bf16 v[60:63], v[148:151], v[194:197], v[60:63]
	s_setprio 0
	s_add_i32 s16, s29, s38
	v_lshl_add_u64 v[202:203], v[202:203], 0, s[86:87]
	s_mov_b32 m0, s16
	ds_read_b128 v[164:167], v210 offset:49152
	ds_read_b128 v[168:171], v210 offset:50176
	ds_read_b128 v[172:175], v210 offset:51200
	ds_read_b128 v[176:179], v210 offset:52224
	ds_read_b128 v[180:183], v210 offset:53248
	ds_read_b128 v[184:187], v210 offset:54272
	ds_read_b128 v[194:197], v210 offset:55296
	ds_read_b128 v[198:201], v210 offset:56320
	global_load_lds_dwordx4 v[202:203], off
	s_add_i32 m0, s16, 0x2000
	s_add_u32 s12, s12, 0x20080
	v_lshl_add_u64 v[202:203], v[204:205], 0, s[86:87]
	s_addc_u32 s13, s13, 0
	s_add_i32 s16, s44, s38
	global_load_lds_dwordx4 v[202:203], off
	s_mov_b32 m0, s16
	v_lshl_add_u64 v[202:203], v[206:207], 0, s[86:87]
	global_load_lds_dwordx4 v192, s[12:13]
	s_add_i32 m0, s16, 0x2000
	s_nop 0
	global_load_lds_dwordx4 v190, s[12:13]
	s_mov_b32 m0, s63
	s_nop 0
	global_load_lds_dwordx4 v[202:203], off
	v_lshl_add_u64 v[202:203], v[208:209], 0, s[86:87]
	s_mov_b32 m0, s64
	s_nop 0
	global_load_lds_dwordx4 v[202:203], off
	s_waitcnt vmcnt(8)
	s_waitcnt lgkmcnt(0)
	s_barrier
	s_setprio 1
	s_waitcnt lgkmcnt(0)
	v_mfma_f32_16x16x32_bf16 v[68:71], v[132:135], v[164:167], v[68:71]
	v_mfma_f32_16x16x32_bf16 v[68:71], v[136:139], v[168:171], v[68:71]
	v_mfma_f32_16x16x32_bf16 v[72:75], v[144:147], v[168:171], v[72:75]
	v_mfma_f32_16x16x32_bf16 v[72:75], v[140:143], v[164:167], v[72:75]
	v_mfma_f32_16x16x32_bf16 v[80:83], v[140:143], v[172:175], v[80:83]
	v_mfma_f32_16x16x32_bf16 v[80:83], v[144:147], v[176:179], v[80:83]
	v_mfma_f32_16x16x32_bf16 v[76:79], v[136:139], v[176:179], v[76:79]
	v_mfma_f32_16x16x32_bf16 v[76:79], v[132:135], v[172:175], v[76:79]
	v_mfma_f32_16x16x32_bf16 v[84:87], v[132:135], v[180:183], v[84:87]
	v_mfma_f32_16x16x32_bf16 v[84:87], v[136:139], v[184:187], v[84:87]
	v_mfma_f32_16x16x32_bf16 v[88:91], v[144:147], v[184:187], v[88:91]
	v_mfma_f32_16x16x32_bf16 v[88:91], v[140:143], v[180:183], v[88:91]
	v_mfma_f32_16x16x32_bf16 v[96:99], v[140:143], v[194:197], v[96:99]
	v_mfma_f32_16x16x32_bf16 v[96:99], v[144:147], v[198:201], v[96:99]
	v_mfma_f32_16x16x32_bf16 v[92:95], v[136:139], v[198:201], v[92:95]
	v_mfma_f32_16x16x32_bf16 v[92:95], v[132:135], v[194:197], v[92:95]
	s_setprio 0
	s_setprio 1
	v_mfma_f32_16x16x32_bf16 v[100:103], v[148:151], v[164:167], v[100:103]
	v_mfma_f32_16x16x32_bf16 v[100:103], v[152:155], v[168:171], v[100:103]
	v_mfma_f32_16x16x32_bf16 v[104:107], v[160:163], v[168:171], v[104:107]
	v_mfma_f32_16x16x32_bf16 v[104:107], v[156:159], v[164:167], v[104:107]
	v_mfma_f32_16x16x32_bf16 v[112:115], v[156:159], v[172:175], v[112:115]
	v_mfma_f32_16x16x32_bf16 v[112:115], v[160:163], v[176:179], v[112:115]
	v_mfma_f32_16x16x32_bf16 v[108:111], v[152:155], v[176:179], v[108:111]
	v_mfma_f32_16x16x32_bf16 v[108:111], v[148:151], v[172:175], v[108:111]
	v_mfma_f32_16x16x32_bf16 v[116:119], v[148:151], v[180:183], v[116:119]
	v_mfma_f32_16x16x32_bf16 v[116:119], v[152:155], v[184:187], v[116:119]
	v_mfma_f32_16x16x32_bf16 v[120:123], v[160:163], v[184:187], v[120:123]
	v_mfma_f32_16x16x32_bf16 v[120:123], v[156:159], v[180:183], v[120:123]
	s_setprio 2
	s_barrier
	v_mfma_f32_16x16x32_bf16 v[128:131], v[156:159], v[194:197], v[128:131]
	v_mfma_f32_16x16x32_bf16 v[128:131], v[160:163], v[198:201], v[128:131]
	v_mfma_f32_16x16x32_bf16 v[124:127], v[152:155], v[198:201], v[124:127]
	v_mfma_f32_16x16x32_bf16 v[124:127], v[148:151], v[194:197], v[124:127]
	s_setprio 0
	s_add_i32 s28, s28, 2
	s_add_u32 s14, s14, 0x100
	s_addc_u32 s15, s15, 0
	s_add_u32 s26, s26, 0x100
	s_addc_u32 s27, s27, 0
	s_cmp_gt_u32 s28, 5
	s_cbranch_scc0 .LBB0_2069
	s_and_b64 vcc, exec, s[48:49]
	s_cbranch_vccz .LBB0_2072
	s_barrier

.LBB0_2159:
	s_add_i32 s68, 0, 0x10000
	s_add_i32 s69, 0, 0x14000
	v_add_u32_e32 v16, s68, v143
	v_add_u32_e32 v32, s69, v143
	ds_read_b128 v[4:7], v16
	ds_read_b128 v[8:11], v16 offset:1024
	ds_read_b128 v[12:15], v16 offset:2048
	ds_read_b128 v[16:19], v16 offset:3072
	ds_read_b128 v[20:23], v32
	ds_read_b128 v[24:27], v32 offset:1024
	ds_read_b128 v[28:31], v32 offset:2048
	ds_read_b128 v[32:35], v32 offset:3072
	v_add_u32_e32 v231, 0, v142
	ds_read_b128 v[36:39], v231
	ds_read_b128 v[40:43], v231 offset:1024
	ds_read_b128 v[44:47], v231 offset:2048
	ds_read_b128 v[48:51], v231 offset:3072
	ds_read_b128 v[52:55], v231 offset:4096
	ds_read_b128 v[56:59], v231 offset:5120
	ds_read_b128 v[60:63], v231 offset:6144
	ds_read_b128 v[64:67], v231 offset:7168
	s_waitcnt vmcnt(8)
	s_waitcnt lgkmcnt(0)
	s_barrier
	s_setprio 1
	s_waitcnt lgkmcnt(0)
	v_mfma_f32_16x16x32_f16 v[68:71], v[4:7], v[36:39], 0
	v_mfma_f32_16x16x32_f16 v[72:75], v[12:15], v[36:39], 0
	v_mfma_f32_16x16x32_f16 v[76:79], v[4:7], v[44:47], 0
	v_mfma_f32_16x16x32_f16 v[80:83], v[12:15], v[44:47], 0
	v_mfma_f32_16x16x32_f16 v[84:87], v[4:7], v[52:55], 0
	v_mfma_f32_16x16x32_f16 v[88:91], v[12:15], v[52:55], 0
	v_mfma_f32_16x16x32_f16 v[92:95], v[4:7], v[60:63], 0
	v_mfma_f32_16x16x32_f16 v[96:99], v[12:15], v[60:63], 0
	v_mfma_f32_16x16x32_f16 v[68:71], v[8:11], v[40:43], v[68:71]
	v_mfma_f32_16x16x32_f16 v[72:75], v[16:19], v[40:43], v[72:75]
	v_mfma_f32_16x16x32_f16 v[76:79], v[8:11], v[48:51], v[76:79]
	v_mfma_f32_16x16x32_f16 v[80:83], v[16:19], v[48:51], v[80:83]
	v_mfma_f32_16x16x32_f16 v[84:87], v[8:11], v[56:59], v[84:87]
	v_mfma_f32_16x16x32_f16 v[88:91], v[16:19], v[56:59], v[88:91]
	v_mfma_f32_16x16x32_f16 v[92:95], v[8:11], v[64:67], v[92:95]
	v_mfma_f32_16x16x32_f16 v[100:103], v[16:19], v[64:67], v[96:99]
	s_setprio 0
	s_setprio 1
	v_mfma_f32_16x16x32_f16 v[96:99], v[20:23], v[36:39], 0
	v_mfma_f32_16x16x32_f16 v[36:39], v[28:31], v[36:39], 0
	v_mfma_f32_16x16x32_f16 v[104:107], v[20:23], v[44:47], 0
	v_mfma_f32_16x16x32_f16 v[44:47], v[28:31], v[44:47], 0
	v_mfma_f32_16x16x32_f16 v[108:111], v[20:23], v[52:55], 0
	v_mfma_f32_16x16x32_f16 v[52:55], v[28:31], v[52:55], 0
	v_mfma_f32_16x16x32_f16 v[112:115], v[20:23], v[60:63], 0
	v_mfma_f32_16x16x32_f16 v[60:63], v[28:31], v[60:63], 0
	v_mfma_f32_16x16x32_f16 v[116:119], v[24:27], v[40:43], v[96:99]
	v_mfma_f32_16x16x32_f16 v[36:39], v[32:35], v[40:43], v[36:39]
	v_mfma_f32_16x16x32_f16 v[40:43], v[24:27], v[48:51], v[104:107]
	v_mfma_f32_16x16x32_f16 v[44:47], v[32:35], v[48:51], v[44:47]
	s_setprio 2
	s_barrier
	v_mfma_f32_16x16x32_f16 v[48:51], v[24:27], v[56:59], v[108:111]
	v_mfma_f32_16x16x32_f16 v[52:55], v[32:35], v[56:59], v[52:55]
	v_mfma_f32_16x16x32_f16 v[56:59], v[24:27], v[64:67], v[112:115]
	v_mfma_f32_16x16x32_f16 v[60:63], v[32:35], v[64:67], v[60:63]
	s_setprio 0
	v_lshl_add_u64 v[138:139], s[8:9], 0, v[2:3]
	s_add_i32 s68, s68, s53
	v_mov_b32_e32 v135, v3
	v_lshl_add_u64 v[144:145], v[138:139], 0, s[74:75]
	s_mov_b32 m0, s68
	v_lshl_add_u64 v[192:193], s[8:9], 0, v[134:135]
	ds_read_b128 v[64:67], v231 offset:16384
	ds_read_b128 v[96:99], v231 offset:17408
	ds_read_b128 v[104:107], v231 offset:18432
	ds_read_b128 v[108:111], v231 offset:19456
	ds_read_b128 v[112:115], v231 offset:20480
	ds_read_b128 v[120:123], v231 offset:21504
	ds_read_b128 v[124:127], v231 offset:22528
	ds_read_b128 v[128:131], v231 offset:23552
	global_load_lds_dwordx4 v[144:145], off
	v_lshl_add_u64 v[144:145], v[192:193], 0, s[74:75]
	s_add_i32 m0, s68, 0x2000
	s_add_i32 s68, s69, s53
	global_load_lds_dwordx4 v[144:145], off
	s_mov_b32 m0, s68
	v_mov_b32_e32 v137, v3
	global_load_lds_dwordx4 v2, s[40:41]
	s_add_i32 m0, s68, 0x2000
	v_lshl_add_u64 v[248:249], s[6:7], 0, v[136:137]
	v_mov_b32_e32 v133, v3
	global_load_lds_dwordx4 v134, s[40:41]
	v_lshl_add_u64 v[144:145], v[248:249], 0, s[74:75]
	s_mov_b32 m0, s54
	v_lshl_add_u64 v[250:251], s[6:7], 0, v[132:133]
	global_load_lds_dwordx4 v[144:145], off
	v_lshl_add_u64 v[144:145], v[250:251], 0, s[74:75]
	s_mov_b32 m0, s55
	s_nop 0
	global_load_lds_dwordx4 v[144:145], off
	s_waitcnt vmcnt(8)
	s_waitcnt lgkmcnt(0)
	s_barrier
	s_setprio 1
	s_waitcnt lgkmcnt(0)
	v_mfma_f32_16x16x32_f16 v[144:147], v[4:7], v[64:67], 0
	v_mfma_f32_16x16x32_f16 v[148:151], v[12:15], v[64:67], 0
	v_mfma_f32_16x16x32_f16 v[152:155], v[4:7], v[104:107], 0
	v_mfma_f32_16x16x32_f16 v[156:159], v[12:15], v[104:107], 0
	v_mfma_f32_16x16x32_f16 v[160:163], v[4:7], v[112:115], 0
	v_mfma_f32_16x16x32_f16 v[164:167], v[12:15], v[112:115], 0
	v_mfma_f32_16x16x32_f16 v[4:7], v[4:7], v[124:127], 0
	v_mfma_f32_16x16x32_f16 v[12:15], v[12:15], v[124:127], 0
	v_mfma_f32_16x16x32_f16 v[144:147], v[8:11], v[96:99], v[144:147]
	v_mfma_f32_16x16x32_f16 v[152:155], v[8:11], v[108:111], v[152:155]
	v_mfma_f32_16x16x32_f16 v[160:163], v[8:11], v[120:123], v[160:163]
	v_mfma_f32_16x16x32_f16 v[4:7], v[8:11], v[128:131], v[4:7]
	v_mfma_f32_16x16x32_f16 v[8:11], v[16:19], v[128:131], v[12:15]
	v_mfma_f32_16x16x32_f16 v[148:151], v[16:19], v[96:99], v[148:151]
	v_mfma_f32_16x16x32_f16 v[156:159], v[16:19], v[108:111], v[156:159]
	v_mfma_f32_16x16x32_f16 v[164:167], v[16:19], v[120:123], v[164:167]
	s_setprio 0
	s_setprio 1
	v_mfma_f32_16x16x32_f16 v[12:15], v[20:23], v[64:67], 0
	v_mfma_f32_16x16x32_f16 v[16:19], v[28:31], v[64:67], 0
	v_mfma_f32_16x16x32_f16 v[64:67], v[20:23], v[104:107], 0
	v_mfma_f32_16x16x32_f16 v[104:107], v[28:31], v[104:107], 0
	v_mfma_f32_16x16x32_f16 v[168:171], v[20:23], v[112:115], 0
	v_mfma_f32_16x16x32_f16 v[112:115], v[28:31], v[112:115], 0
	v_mfma_f32_16x16x32_f16 v[20:23], v[20:23], v[124:127], 0
	v_mfma_f32_16x16x32_f16 v[28:31], v[28:31], v[124:127], 0
	v_mfma_f32_16x16x32_f16 v[12:15], v[24:27], v[96:99], v[12:15]
	v_mfma_f32_16x16x32_f16 v[172:175], v[32:35], v[96:99], v[16:19]
	v_mfma_f32_16x16x32_f16 v[176:179], v[24:27], v[108:111], v[64:67]
	v_mfma_f32_16x16x32_f16 v[180:183], v[32:35], v[108:111], v[104:107]
	s_setprio 2
	s_barrier
	v_mfma_f32_16x16x32_f16 v[168:171], v[24:27], v[120:123], v[168:171]
	v_mfma_f32_16x16x32_f16 v[184:187], v[32:35], v[120:123], v[112:115]
	v_mfma_f32_16x16x32_f16 v[188:191], v[24:27], v[128:131], v[20:23]
	v_mfma_f32_16x16x32_f16 v[196:199], v[32:35], v[128:131], v[28:31]
	s_setprio 0
	s_add_i32 s68, 0, 0x18000
	v_add_u32_e32 v24, s68, v143
	s_add_i32 s69, 0, 0x1c000
	ds_read_b128 v[16:19], v24
	ds_read_b128 v[20:23], v24 offset:1024
	ds_read_b128 v[28:31], v24 offset:2048
	ds_read_b128 v[200:203], v24 offset:3072
	v_add_u32_e32 v24, s69, v143
	ds_read_b128 v[204:207], v24
	ds_read_b128 v[208:211], v24 offset:1024
	ds_read_b128 v[212:215], v24 offset:2048
	ds_read_b128 v[216:219], v24 offset:3072
	s_mov_b32 m0, s56
	ds_read_b128 v[24:27], v231 offset:32768
	ds_read_b128 v[32:35], v231 offset:33792
	ds_read_b128 v[64:67], v231 offset:34816
	ds_read_b128 v[220:223], v231 offset:35840
	ds_read_b128 v[224:227], v231 offset:36864
	ds_read_b128 v[232:235], v231 offset:37888
	ds_read_b128 v[236:239], v231 offset:38912
	ds_read_b128 v[240:243], v231 offset:39936
	global_load_lds_dwordx4 v136, s[42:43]
	s_mov_b32 m0, s57
	s_nop 0
	global_load_lds_dwordx4 v132, s[42:43]
	s_waitcnt vmcnt(8)
	s_waitcnt lgkmcnt(0)
	s_barrier
	s_setprio 1
	s_waitcnt lgkmcnt(0)
	v_mfma_f32_16x16x32_f16 v[68:71], v[16:19], v[24:27], v[68:71]
	v_mfma_f32_16x16x32_f16 v[128:131], v[20:23], v[32:35], v[68:71]
	v_mfma_f32_16x16x32_f16 v[68:71], v[28:31], v[24:27], v[72:75]
	v_mfma_f32_16x16x32_f16 v[120:123], v[200:203], v[32:35], v[68:71]
	v_mfma_f32_16x16x32_f16 v[68:71], v[16:19], v[64:67], v[76:79]
	v_mfma_f32_16x16x32_f16 v[112:115], v[20:23], v[220:223], v[68:71]
	v_mfma_f32_16x16x32_f16 v[68:71], v[28:31], v[64:67], v[80:83]
	v_mfma_f32_16x16x32_f16 v[104:107], v[200:203], v[220:223], v[68:71]
	v_mfma_f32_16x16x32_f16 v[68:71], v[16:19], v[224:227], v[84:87]
	v_mfma_f32_16x16x32_f16 v[96:99], v[20:23], v[232:235], v[68:71]
	v_mfma_f32_16x16x32_f16 v[68:71], v[28:31], v[224:227], v[88:91]
	v_mfma_f32_16x16x32_f16 v[88:91], v[200:203], v[232:235], v[68:71]
	v_mfma_f32_16x16x32_f16 v[68:71], v[16:19], v[236:239], v[92:95]
	v_mfma_f32_16x16x32_f16 v[80:83], v[20:23], v[240:243], v[68:71]
	v_mfma_f32_16x16x32_f16 v[68:71], v[28:31], v[236:239], v[100:103]
	v_mfma_f32_16x16x32_f16 v[72:75], v[200:203], v[240:243], v[68:71]
	s_setprio 0
	s_setprio 1
	v_mfma_f32_16x16x32_f16 v[68:71], v[204:207], v[24:27], v[116:119]
	v_mfma_f32_16x16x32_f16 v[24:27], v[212:215], v[24:27], v[36:39]
	v_mfma_f32_16x16x32_f16 v[116:119], v[216:219], v[32:35], v[24:27]
	v_mfma_f32_16x16x32_f16 v[24:27], v[204:207], v[64:67], v[40:43]
	v_mfma_f32_16x16x32_f16 v[108:111], v[208:211], v[220:223], v[24:27]
	v_mfma_f32_16x16x32_f16 v[24:27], v[212:215], v[64:67], v[44:47]
	v_mfma_f32_16x16x32_f16 v[100:103], v[216:219], v[220:223], v[24:27]
	v_mfma_f32_16x16x32_f16 v[24:27], v[204:207], v[224:227], v[48:51]
	v_mfma_f32_16x16x32_f16 v[92:95], v[208:211], v[232:235], v[24:27]
	v_mfma_f32_16x16x32_f16 v[24:27], v[212:215], v[224:227], v[52:55]
	v_mfma_f32_16x16x32_f16 v[84:87], v[216:219], v[232:235], v[24:27]
	v_mfma_f32_16x16x32_f16 v[24:27], v[204:207], v[236:239], v[56:59]
	s_setprio 2
	s_barrier
	v_mfma_f32_16x16x32_f16 v[76:79], v[208:211], v[240:243], v[24:27]
	v_mfma_f32_16x16x32_f16 v[24:27], v[212:215], v[236:239], v[60:63]
	v_mfma_f32_16x16x32_f16 v[124:127], v[208:211], v[32:35], v[68:71]
	v_mfma_f32_16x16x32_f16 v[68:71], v[216:219], v[240:243], v[24:27]
	s_setprio 0
	s_add_i32 s68, s68, s53
	s_nop 2
	v_lshl_add_u64 v[24:25], v[138:139], 0, s[24:25]
	s_mov_b32 m0, s68
	ds_read_b128 v[36:39], v231 offset:49152
	ds_read_b128 v[44:47], v231 offset:50176
	ds_read_b128 v[220:223], v231 offset:51200
	ds_read_b128 v[224:227], v231 offset:52224
	ds_read_b128 v[232:235], v231 offset:53248
	ds_read_b128 v[236:239], v231 offset:54272
	ds_read_b128 v[240:243], v231 offset:55296
	ds_read_b128 v[244:247], v231 offset:56320
	global_load_lds_dwordx4 v[24:25], off
	v_lshl_add_u64 v[24:25], v[192:193], 0, s[24:25]
	s_add_i32 m0, s68, 0x2000
	s_add_i32 s68, s69, s53
	global_load_lds_dwordx4 v[24:25], off
	s_mov_b32 m0, s68
	v_lshl_add_u64 v[24:25], v[248:249], 0, s[24:25]
	global_load_lds_dwordx4 v2, s[44:45]
	s_add_i32 m0, s68, 0x2000
	s_nop 0
	global_load_lds_dwordx4 v134, s[44:45]
	s_mov_b32 m0, s59
	s_nop 0
	global_load_lds_dwordx4 v[24:25], off
	v_lshl_add_u64 v[24:25], v[250:251], 0, s[24:25]
	s_mov_b32 m0, s60
	s_nop 0
	global_load_lds_dwordx4 v[24:25], off
	s_waitcnt vmcnt(8)
	s_waitcnt lgkmcnt(0)
	s_barrier
	s_setprio 1
	s_waitcnt lgkmcnt(0)
	v_mfma_f32_16x16x32_f16 v[24:27], v[16:19], v[36:39], v[144:147]
	v_mfma_f32_16x16x32_f16 v[64:67], v[20:23], v[44:47], v[24:27]
	v_mfma_f32_16x16x32_f16 v[24:27], v[28:31], v[36:39], v[148:151]
	v_mfma_f32_16x16x32_f16 v[56:59], v[200:203], v[44:47], v[24:27]
	v_mfma_f32_16x16x32_f16 v[24:27], v[16:19], v[220:223], v[152:155]
	v_mfma_f32_16x16x32_f16 v[48:51], v[20:23], v[224:227], v[24:27]
	v_mfma_f32_16x16x32_f16 v[24:27], v[28:31], v[220:223], v[156:159]
	v_mfma_f32_16x16x32_f16 v[40:43], v[200:203], v[224:227], v[24:27]
	v_mfma_f32_16x16x32_f16 v[24:27], v[16:19], v[232:235], v[160:163]
	v_mfma_f32_16x16x32_f16 v[4:7], v[16:19], v[240:243], v[4:7]
	v_mfma_f32_16x16x32_f16 v[32:35], v[20:23], v[236:239], v[24:27]
	v_mfma_f32_16x16x32_f16 v[24:27], v[28:31], v[232:235], v[164:167]
	v_mfma_f32_16x16x32_f16 v[16:19], v[20:23], v[244:247], v[4:7]
	v_mfma_f32_16x16x32_f16 v[4:7], v[28:31], v[240:243], v[8:11]
	v_mfma_f32_16x16x32_f16 v[24:27], v[200:203], v[236:239], v[24:27]
	v_mfma_f32_16x16x32_f16 v[8:11], v[200:203], v[244:247], v[4:7]
	s_setprio 0
	s_setprio 1
	v_mfma_f32_16x16x32_f16 v[4:7], v[204:207], v[36:39], v[12:15]
	v_mfma_f32_16x16x32_f16 v[60:63], v[208:211], v[44:47], v[4:7]
	v_mfma_f32_16x16x32_f16 v[4:7], v[212:215], v[36:39], v[172:175]
	v_mfma_f32_16x16x32_f16 v[52:55], v[216:219], v[44:47], v[4:7]
	v_mfma_f32_16x16x32_f16 v[4:7], v[204:207], v[220:223], v[176:179]
	v_mfma_f32_16x16x32_f16 v[44:47], v[208:211], v[224:227], v[4:7]
	v_mfma_f32_16x16x32_f16 v[4:7], v[212:215], v[220:223], v[180:183]
	v_mfma_f32_16x16x32_f16 v[36:39], v[216:219], v[224:227], v[4:7]
	v_mfma_f32_16x16x32_f16 v[4:7], v[204:207], v[232:235], v[168:171]
	v_mfma_f32_16x16x32_f16 v[28:31], v[208:211], v[236:239], v[4:7]
	v_mfma_f32_16x16x32_f16 v[4:7], v[212:215], v[232:235], v[184:187]
	v_mfma_f32_16x16x32_f16 v[20:23], v[216:219], v[236:239], v[4:7]
	s_setprio 2
	s_barrier
	v_mfma_f32_16x16x32_f16 v[4:7], v[204:207], v[240:243], v[188:191]
	v_mfma_f32_16x16x32_f16 v[12:15], v[208:211], v[244:247], v[4:7]
	v_mfma_f32_16x16x32_f16 v[4:7], v[212:215], v[240:243], v[196:199]
	v_mfma_f32_16x16x32_f16 v[4:7], v[216:219], v[244:247], v[4:7]
	s_setprio 0
	s_add_i32 s67, s67, 2
	s_cmp_ge_i32 s67, s11
	s_cbranch_scc0 .LBB0_2159

.LBB0_2161:
	s_add_u32 s68, s6, s40
	s_addc_u32 s69, s7, s41
	s_add_u32 s42, s68, 0x200
	s_addc_u32 s43, s69, 0
	s_add_u32 s44, s8, s40
	s_addc_u32 s45, s9, s41
	s_add_u32 s67, s44, 0x200
	s_addc_u32 s70, s45, 0
	s_add_i32 s71, 0, 0x10000
	s_cmp_eq_u32 s11, 28
	s_cselect_b32 s45, s29, s43
	s_cselect_b32 s44, s28, s42
	v_add_u32_e32 v133, s71, v143
	s_cselect_b32 s43, s37, s70
	s_cselect_b32 s42, s36, s67
	s_add_i32 s67, 0, 0x14000
	ds_read_b128 v[144:147], v133
	ds_read_b128 v[148:151], v133 offset:1024
	ds_read_b128 v[152:155], v133 offset:2048
	ds_read_b128 v[156:159], v133 offset:3072
	v_add_u32_e32 v133, s67, v143
	ds_read_b128 v[160:163], v133
	ds_read_b128 v[164:167], v133 offset:1024
	ds_read_b128 v[168:171], v133 offset:2048
	ds_read_b128 v[172:175], v133 offset:3072
	v_lshl_add_u64 v[136:137], s[68:69], 0, v[2:3]
	s_mov_b32 m0, s61
	v_add_u32_e32 v216, 0, v142
	v_lshl_add_u64 v[136:137], v[136:137], 0, s[34:35]
	v_mov_b32_e32 v133, v3
	ds_read_b128 v[176:179], v216
	ds_read_b128 v[180:183], v216 offset:1024
	ds_read_b128 v[184:187], v216 offset:2048
	ds_read_b128 v[188:191], v216 offset:3072
	ds_read_b128 v[196:199], v216 offset:4096
	ds_read_b128 v[200:203], v216 offset:5120
	ds_read_b128 v[204:207], v216 offset:6144
	ds_read_b128 v[208:211], v216 offset:7168
	global_load_lds_dwordx4 v[136:137], off
	v_lshl_add_u64 v[136:137], s[68:69], 0, v[132:133]
	v_lshl_add_u64 v[136:137], v[136:137], 0, s[34:35]
	s_mov_b32 m0, s62
	s_nop 0
	global_load_lds_dwordx4 v[136:137], off
	s_waitcnt vmcnt(8)
	s_waitcnt lgkmcnt(0)
	s_barrier
	s_setprio 1
	s_waitcnt lgkmcnt(0)
	v_mfma_f32_16x16x32_f16 v[128:131], v[144:147], v[176:179], v[128:131]
	v_mfma_f32_16x16x32_f16 v[128:131], v[148:151], v[180:183], v[128:131]
	v_mfma_f32_16x16x32_f16 v[120:123], v[156:159], v[180:183], v[120:123]
	v_mfma_f32_16x16x32_f16 v[120:123], v[152:155], v[176:179], v[120:123]
	v_mfma_f32_16x16x32_f16 v[104:107], v[152:155], v[184:187], v[104:107]
	v_mfma_f32_16x16x32_f16 v[104:107], v[156:159], v[188:191], v[104:107]
	v_mfma_f32_16x16x32_f16 v[112:115], v[148:151], v[188:191], v[112:115]
	v_mfma_f32_16x16x32_f16 v[112:115], v[144:147], v[184:187], v[112:115]
	v_mfma_f32_16x16x32_f16 v[96:99], v[144:147], v[196:199], v[96:99]
	v_mfma_f32_16x16x32_f16 v[96:99], v[148:151], v[200:203], v[96:99]
	v_mfma_f32_16x16x32_f16 v[88:91], v[156:159], v[200:203], v[88:91]
	v_mfma_f32_16x16x32_f16 v[88:91], v[152:155], v[196:199], v[88:91]
	v_mfma_f32_16x16x32_f16 v[72:75], v[152:155], v[204:207], v[72:75]
	v_mfma_f32_16x16x32_f16 v[72:75], v[156:159], v[208:211], v[72:75]
	v_mfma_f32_16x16x32_f16 v[80:83], v[148:151], v[208:211], v[80:83]
	v_mfma_f32_16x16x32_f16 v[80:83], v[144:147], v[204:207], v[80:83]
	s_setprio 0
	s_setprio 1
	v_mfma_f32_16x16x32_f16 v[124:127], v[160:163], v[176:179], v[124:127]
	v_mfma_f32_16x16x32_f16 v[124:127], v[164:167], v[180:183], v[124:127]
	v_mfma_f32_16x16x32_f16 v[116:119], v[172:175], v[180:183], v[116:119]
	v_mfma_f32_16x16x32_f16 v[116:119], v[168:171], v[176:179], v[116:119]
	v_mfma_f32_16x16x32_f16 v[100:103], v[168:171], v[184:187], v[100:103]
	v_mfma_f32_16x16x32_f16 v[100:103], v[172:175], v[188:191], v[100:103]
	v_mfma_f32_16x16x32_f16 v[108:111], v[164:167], v[188:191], v[108:111]
	v_mfma_f32_16x16x32_f16 v[108:111], v[160:163], v[184:187], v[108:111]
	v_mfma_f32_16x16x32_f16 v[92:95], v[160:163], v[196:199], v[92:95]
	v_mfma_f32_16x16x32_f16 v[92:95], v[164:167], v[200:203], v[92:95]
	v_mfma_f32_16x16x32_f16 v[84:87], v[172:175], v[200:203], v[84:87]
	v_mfma_f32_16x16x32_f16 v[84:87], v[168:171], v[196:199], v[84:87]
	s_setprio 2
	s_barrier
	v_mfma_f32_16x16x32_f16 v[68:71], v[168:171], v[204:207], v[68:71]
	v_mfma_f32_16x16x32_f16 v[68:71], v[172:175], v[208:211], v[68:71]
	v_mfma_f32_16x16x32_f16 v[76:79], v[164:167], v[208:211], v[76:79]
	v_mfma_f32_16x16x32_f16 v[76:79], v[160:163], v[204:207], v[76:79]
	s_setprio 0
	s_add_i32 s68, s71, s53
	s_mov_b32 m0, s68
	ds_read_b128 v[176:179], v216 offset:16384
	ds_read_b128 v[180:183], v216 offset:17408
	ds_read_b128 v[184:187], v216 offset:18432
	ds_read_b128 v[188:191], v216 offset:19456
	ds_read_b128 v[196:199], v216 offset:20480
	ds_read_b128 v[200:203], v216 offset:21504
	ds_read_b128 v[204:207], v216 offset:22528
	ds_read_b128 v[208:211], v216 offset:23552
	global_load_lds_dwordx4 v138, s[42:43]
	s_add_i32 m0, s68, 0x2000
	s_add_u32 s68, s42, 0x80000
	s_addc_u32 s69, s43, 0
	s_add_i32 s67, s67, s53
	global_load_lds_dwordx4 v134, s[42:43]
	s_mov_b32 m0, s67
	v_mov_b32_e32 v139, v3
	global_load_lds_dwordx4 v138, s[68:69]
	s_add_i32 m0, s67, 0x2000
	v_mov_b32_e32 v135, v3
	global_load_lds_dwordx4 v134, s[68:69]
	s_mov_b32 m0, s54
	v_lshl_add_u64 v[136:137], s[42:43], 0, v[138:139]
	global_load_lds_dwordx4 v2, s[44:45]
	s_mov_b32 m0, s55
	v_lshl_add_u64 v[192:193], s[42:43], 0, v[134:135]
	global_load_lds_dwordx4 v132, s[44:45]
	s_waitcnt vmcnt(8)
	s_waitcnt lgkmcnt(0)
	v_lshl_add_u64 v[212:213], s[44:45], 0, v[2:3]
	v_lshl_add_u64 v[214:215], s[44:45], 0, v[132:133]
	s_barrier
	s_setprio 1
	s_waitcnt lgkmcnt(0)
	v_mfma_f32_16x16x32_f16 v[64:67], v[144:147], v[176:179], v[64:67]
	v_mfma_f32_16x16x32_f16 v[64:67], v[148:151], v[180:183], v[64:67]
	v_mfma_f32_16x16x32_f16 v[56:59], v[156:159], v[180:183], v[56:59]
	v_mfma_f32_16x16x32_f16 v[56:59], v[152:155], v[176:179], v[56:59]
	v_mfma_f32_16x16x32_f16 v[40:43], v[152:155], v[184:187], v[40:43]
	v_mfma_f32_16x16x32_f16 v[40:43], v[156:159], v[188:191], v[40:43]
	v_mfma_f32_16x16x32_f16 v[48:51], v[148:151], v[188:191], v[48:51]
	v_mfma_f32_16x16x32_f16 v[48:51], v[144:147], v[184:187], v[48:51]
	v_mfma_f32_16x16x32_f16 v[32:35], v[144:147], v[196:199], v[32:35]
	v_mfma_f32_16x16x32_f16 v[32:35], v[148:151], v[200:203], v[32:35]
	v_mfma_f32_16x16x32_f16 v[24:27], v[156:159], v[200:203], v[24:27]
	v_mfma_f32_16x16x32_f16 v[24:27], v[152:155], v[196:199], v[24:27]
	v_mfma_f32_16x16x32_f16 v[8:11], v[152:155], v[204:207], v[8:11]
	v_mfma_f32_16x16x32_f16 v[8:11], v[156:159], v[208:211], v[8:11]
	v_mfma_f32_16x16x32_f16 v[16:19], v[148:151], v[208:211], v[16:19]
	v_mfma_f32_16x16x32_f16 v[16:19], v[144:147], v[204:207], v[16:19]
	s_setprio 0
	s_setprio 1
	v_mfma_f32_16x16x32_f16 v[60:63], v[160:163], v[176:179], v[60:63]
	v_mfma_f32_16x16x32_f16 v[60:63], v[164:167], v[180:183], v[60:63]
	v_mfma_f32_16x16x32_f16 v[52:55], v[172:175], v[180:183], v[52:55]
	v_mfma_f32_16x16x32_f16 v[52:55], v[168:171], v[176:179], v[52:55]
	v_mfma_f32_16x16x32_f16 v[36:39], v[168:171], v[184:187], v[36:39]
	v_mfma_f32_16x16x32_f16 v[36:39], v[172:175], v[188:191], v[36:39]
	v_mfma_f32_16x16x32_f16 v[44:47], v[164:167], v[188:191], v[44:47]
	v_mfma_f32_16x16x32_f16 v[44:47], v[160:163], v[184:187], v[44:47]
	v_mfma_f32_16x16x32_f16 v[28:31], v[160:163], v[196:199], v[28:31]
	v_mfma_f32_16x16x32_f16 v[28:31], v[164:167], v[200:203], v[28:31]
	v_mfma_f32_16x16x32_f16 v[20:23], v[172:175], v[200:203], v[20:23]
	v_mfma_f32_16x16x32_f16 v[20:23], v[168:171], v[196:199], v[20:23]
	s_setprio 2
	s_barrier
	v_mfma_f32_16x16x32_f16 v[4:7], v[168:171], v[204:207], v[4:7]
	v_mfma_f32_16x16x32_f16 v[4:7], v[172:175], v[208:211], v[4:7]
	v_mfma_f32_16x16x32_f16 v[12:15], v[164:167], v[208:211], v[12:15]
	v_mfma_f32_16x16x32_f16 v[12:15], v[160:163], v[204:207], v[12:15]
	s_setprio 0
	s_add_i32 s67, 0, 0x18000
	v_add_u32_e32 v135, s67, v143
	s_add_i32 s68, 0, 0x1c000
	ds_read_b128 v[144:147], v135
	ds_read_b128 v[148:151], v135 offset:1024
	ds_read_b128 v[152:155], v135 offset:2048
	ds_read_b128 v[156:159], v135 offset:3072
	v_add_u32_e32 v135, s68, v143
	ds_read_b128 v[160:163], v135
	ds_read_b128 v[164:167], v135 offset:1024
	ds_read_b128 v[168:171], v135 offset:2048
	ds_read_b128 v[172:175], v135 offset:3072
	s_add_u32 s44, s44, 0x80000
	s_addc_u32 s45, s45, 0
	s_mov_b32 m0, s56
	ds_read_b128 v[176:179], v216 offset:32768
	ds_read_b128 v[180:183], v216 offset:33792
	ds_read_b128 v[184:187], v216 offset:34816
	ds_read_b128 v[188:191], v216 offset:35840
	ds_read_b128 v[196:199], v216 offset:36864
	ds_read_b128 v[200:203], v216 offset:37888
	ds_read_b128 v[204:207], v216 offset:38912
	ds_read_b128 v[208:211], v216 offset:39936
	global_load_lds_dwordx4 v2, s[44:45]
	s_mov_b32 m0, s57
	s_nop 0
	global_load_lds_dwordx4 v132, s[44:45]
	s_waitcnt vmcnt(8)
	s_waitcnt lgkmcnt(0)
	s_barrier
	s_setprio 1
	s_waitcnt lgkmcnt(0)
	v_mfma_f32_16x16x32_f16 v[128:131], v[144:147], v[176:179], v[128:131]
	v_mfma_f32_16x16x32_f16 v[128:131], v[148:151], v[180:183], v[128:131]
	v_mfma_f32_16x16x32_f16 v[120:123], v[156:159], v[180:183], v[120:123]
	v_mfma_f32_16x16x32_f16 v[120:123], v[152:155], v[176:179], v[120:123]
	v_mfma_f32_16x16x32_f16 v[104:107], v[152:155], v[184:187], v[104:107]
	v_mfma_f32_16x16x32_f16 v[104:107], v[156:159], v[188:191], v[104:107]
	v_mfma_f32_16x16x32_f16 v[112:115], v[148:151], v[188:191], v[112:115]
	v_mfma_f32_16x16x32_f16 v[112:115], v[144:147], v[184:187], v[112:115]
	v_mfma_f32_16x16x32_f16 v[96:99], v[144:147], v[196:199], v[96:99]
	v_mfma_f32_16x16x32_f16 v[96:99], v[148:151], v[200:203], v[96:99]
	v_mfma_f32_16x16x32_f16 v[88:91], v[156:159], v[200:203], v[88:91]
	v_mfma_f32_16x16x32_f16 v[88:91], v[152:155], v[196:199], v[88:91]
	v_mfma_f32_16x16x32_f16 v[72:75], v[152:155], v[204:207], v[72:75]
	v_mfma_f32_16x16x32_f16 v[72:75], v[156:159], v[208:211], v[72:75]
	v_mfma_f32_16x16x32_f16 v[80:83], v[148:151], v[208:211], v[80:83]
	v_mfma_f32_16x16x32_f16 v[80:83], v[144:147], v[204:207], v[80:83]
	s_setprio 0
	s_setprio 1
	v_mfma_f32_16x16x32_f16 v[124:127], v[160:163], v[176:179], v[124:127]
	v_mfma_f32_16x16x32_f16 v[124:127], v[164:167], v[180:183], v[124:127]
	v_mfma_f32_16x16x32_f16 v[116:119], v[172:175], v[180:183], v[116:119]
	v_mfma_f32_16x16x32_f16 v[116:119], v[168:171], v[176:179], v[116:119]
	v_mfma_f32_16x16x32_f16 v[100:103], v[168:171], v[184:187], v[100:103]
	v_mfma_f32_16x16x32_f16 v[100:103], v[172:175], v[188:191], v[100:103]
	v_mfma_f32_16x16x32_f16 v[108:111], v[164:167], v[188:191], v[108:111]
	v_mfma_f32_16x16x32_f16 v[108:111], v[160:163], v[184:187], v[108:111]
	v_mfma_f32_16x16x32_f16 v[92:95], v[160:163], v[196:199], v[92:95]
	v_mfma_f32_16x16x32_f16 v[92:95], v[164:167], v[200:203], v[92:95]
	v_mfma_f32_16x16x32_f16 v[84:87], v[172:175], v[200:203], v[84:87]
	v_mfma_f32_16x16x32_f16 v[84:87], v[168:171], v[196:199], v[84:87]
	s_setprio 2
	s_barrier
	v_mfma_f32_16x16x32_f16 v[68:71], v[168:171], v[204:207], v[68:71]
	v_mfma_f32_16x16x32_f16 v[68:71], v[172:175], v[208:211], v[68:71]
	v_mfma_f32_16x16x32_f16 v[76:79], v[164:167], v[208:211], v[76:79]
	v_mfma_f32_16x16x32_f16 v[76:79], v[160:163], v[204:207], v[76:79]
	s_setprio 0
	s_add_i32 s44, s67, s53
	v_lshl_add_u64 v[136:137], v[136:137], 0, s[86:87]
	s_mov_b32 m0, s44
	ds_read_b128 v[176:179], v216 offset:49152
	ds_read_b128 v[180:183], v216 offset:50176
	ds_read_b128 v[184:187], v216 offset:51200
	ds_read_b128 v[188:191], v216 offset:52224
	ds_read_b128 v[196:199], v216 offset:53248
	ds_read_b128 v[200:203], v216 offset:54272
	ds_read_b128 v[204:207], v216 offset:55296
	ds_read_b128 v[208:211], v216 offset:56320
	global_load_lds_dwordx4 v[136:137], off
	s_add_i32 m0, s44, 0x2000
	s_add_u32 s42, s42, 0x80080
	v_lshl_add_u64 v[136:137], v[192:193], 0, s[86:87]
	s_addc_u32 s43, s43, 0
	s_add_i32 s44, s68, s53
	global_load_lds_dwordx4 v[136:137], off
	s_mov_b32 m0, s44
	v_lshl_add_u64 v[136:137], v[212:213], 0, s[86:87]
	global_load_lds_dwordx4 v138, s[42:43]
	s_add_i32 m0, s44, 0x2000
	s_nop 0
	global_load_lds_dwordx4 v134, s[42:43]
	s_mov_b32 m0, s59
	s_nop 0
	global_load_lds_dwordx4 v[136:137], off
	v_lshl_add_u64 v[136:137], v[214:215], 0, s[86:87]
	s_mov_b32 m0, s60
	s_nop 0
	global_load_lds_dwordx4 v[136:137], off
	s_waitcnt vmcnt(8)
	s_waitcnt lgkmcnt(0)
	s_barrier
	s_setprio 1
	s_waitcnt lgkmcnt(0)
	v_mfma_f32_16x16x32_f16 v[64:67], v[144:147], v[176:179], v[64:67]
	v_mfma_f32_16x16x32_f16 v[64:67], v[148:151], v[180:183], v[64:67]
	v_mfma_f32_16x16x32_f16 v[56:59], v[156:159], v[180:183], v[56:59]
	v_mfma_f32_16x16x32_f16 v[56:59], v[152:155], v[176:179], v[56:59]
	v_mfma_f32_16x16x32_f16 v[40:43], v[152:155], v[184:187], v[40:43]
	v_mfma_f32_16x16x32_f16 v[40:43], v[156:159], v[188:191], v[40:43]
	v_mfma_f32_16x16x32_f16 v[48:51], v[148:151], v[188:191], v[48:51]
	v_mfma_f32_16x16x32_f16 v[48:51], v[144:147], v[184:187], v[48:51]
	v_mfma_f32_16x16x32_f16 v[32:35], v[144:147], v[196:199], v[32:35]
	v_mfma_f32_16x16x32_f16 v[32:35], v[148:151], v[200:203], v[32:35]
	v_mfma_f32_16x16x32_f16 v[24:27], v[156:159], v[200:203], v[24:27]
	v_mfma_f32_16x16x32_f16 v[24:27], v[152:155], v[196:199], v[24:27]
	v_mfma_f32_16x16x32_f16 v[8:11], v[152:155], v[204:207], v[8:11]
	v_mfma_f32_16x16x32_f16 v[8:11], v[156:159], v[208:211], v[8:11]
	v_mfma_f32_16x16x32_f16 v[16:19], v[148:151], v[208:211], v[16:19]
	v_mfma_f32_16x16x32_f16 v[16:19], v[144:147], v[204:207], v[16:19]
	s_setprio 0
	s_setprio 1
	v_mfma_f32_16x16x32_f16 v[60:63], v[160:163], v[176:179], v[60:63]
	v_mfma_f32_16x16x32_f16 v[60:63], v[164:167], v[180:183], v[60:63]
	v_mfma_f32_16x16x32_f16 v[52:55], v[172:175], v[180:183], v[52:55]
	v_mfma_f32_16x16x32_f16 v[52:55], v[168:171], v[176:179], v[52:55]
	v_mfma_f32_16x16x32_f16 v[36:39], v[168:171], v[184:187], v[36:39]
	v_mfma_f32_16x16x32_f16 v[36:39], v[172:175], v[188:191], v[36:39]
	v_mfma_f32_16x16x32_f16 v[44:47], v[164:167], v[188:191], v[44:47]
	v_mfma_f32_16x16x32_f16 v[44:47], v[160:163], v[184:187], v[44:47]
	v_mfma_f32_16x16x32_f16 v[28:31], v[160:163], v[196:199], v[28:31]
	v_mfma_f32_16x16x32_f16 v[28:31], v[164:167], v[200:203], v[28:31]
	v_mfma_f32_16x16x32_f16 v[20:23], v[172:175], v[200:203], v[20:23]
	v_mfma_f32_16x16x32_f16 v[20:23], v[168:171], v[196:199], v[20:23]
	s_setprio 2
	s_barrier
	v_mfma_f32_16x16x32_f16 v[4:7], v[168:171], v[204:207], v[4:7]
	v_mfma_f32_16x16x32_f16 v[4:7], v[172:175], v[208:211], v[4:7]
	v_mfma_f32_16x16x32_f16 v[12:15], v[164:167], v[208:211], v[12:15]
	v_mfma_f32_16x16x32_f16 v[12:15], v[160:163], v[204:207], v[12:15]
	s_setprio 0
	s_add_i32 s11, s11, 2
	s_add_u32 s40, s40, 0x100
	s_addc_u32 s41, s41, 0
	s_cmp_gt_u32 s11, 29
	s_cbranch_scc0 .LBB0_2161
	s_andn2_b64 vcc, exec, s[26:27]
	s_cbranch_vccnz .LBB0_2164
	s_add_u32 s6, s28, 0x80080
	s_addc_u32 s7, s29, 0
	s_mov_b32 m0, s61
	v_lshl_add_u64 v[144:145], s[6:7], 0, v[2:3]
	v_lshl_add_u64 v[136:137], s[6:7], 0, v[132:133]
	global_load_lds_dwordx4 v[144:145], off
	s_mov_b32 m0, s62
	s_mov_b32 s47, s65
	global_load_lds_dwordx4 v[136:137], off
	s_mov_b32 s64, s10
	s_mov_b64 s[8:9], s[14:15]
	s_mov_b64 s[6:7], s[12:13]
	s_mov_b32 s63, s66

.LBB0_2269:
	s_add_i32 s51, 0, 0x10000
	s_add_i32 s71, 0, 0x14000
	v_add_u32_e32 v16, s51, v232
	v_add_u32_e32 v32, s71, v232
	ds_read_b128 v[4:7], v16
	ds_read_b128 v[8:11], v16 offset:1024
	ds_read_b128 v[12:15], v16 offset:2048
	ds_read_b128 v[16:19], v16 offset:3072
	ds_read_b128 v[20:23], v32
	ds_read_b128 v[24:27], v32 offset:1024
	ds_read_b128 v[28:31], v32 offset:2048
	ds_read_b128 v[32:35], v32 offset:3072
	v_add_u32_e32 v233, 0, v231
	ds_read_b128 v[36:39], v233
	ds_read_b128 v[40:43], v233 offset:1024
	ds_read_b128 v[44:47], v233 offset:2048
	ds_read_b128 v[48:51], v233 offset:3072
	ds_read_b128 v[52:55], v233 offset:4096
	ds_read_b128 v[56:59], v233 offset:5120
	ds_read_b128 v[60:63], v233 offset:6144
	ds_read_b128 v[64:67], v233 offset:7168
	s_waitcnt vmcnt(8)
	s_waitcnt lgkmcnt(0)
	s_barrier
	s_setprio 1
	s_waitcnt lgkmcnt(0)
	v_mfma_f32_16x16x32_bf16 v[68:71], v[4:7], v[36:39], 0
	v_mfma_f32_16x16x32_bf16 v[68:71], v[8:11], v[40:43], v[68:71]
	v_mfma_f32_16x16x32_bf16 v[72:75], v[12:15], v[36:39], 0
	v_mfma_f32_16x16x32_bf16 v[72:75], v[16:19], v[40:43], v[72:75]
	v_mfma_f32_16x16x32_bf16 v[80:83], v[12:15], v[44:47], 0
	v_mfma_f32_16x16x32_bf16 v[80:83], v[16:19], v[48:51], v[80:83]
	v_mfma_f32_16x16x32_bf16 v[76:79], v[4:7], v[44:47], 0
	v_mfma_f32_16x16x32_bf16 v[76:79], v[8:11], v[48:51], v[76:79]
	v_mfma_f32_16x16x32_bf16 v[84:87], v[4:7], v[52:55], 0
	v_mfma_f32_16x16x32_bf16 v[84:87], v[8:11], v[56:59], v[84:87]
	v_mfma_f32_16x16x32_bf16 v[88:91], v[12:15], v[52:55], 0
	v_mfma_f32_16x16x32_bf16 v[88:91], v[16:19], v[56:59], v[88:91]
	v_mfma_f32_16x16x32_bf16 v[96:99], v[12:15], v[60:63], 0
	v_mfma_f32_16x16x32_bf16 v[96:99], v[16:19], v[64:67], v[96:99]
	v_mfma_f32_16x16x32_bf16 v[92:95], v[4:7], v[60:63], 0
	v_mfma_f32_16x16x32_bf16 v[92:95], v[8:11], v[64:67], v[92:95]
	s_setprio 0
	s_setprio 1
	v_mfma_f32_16x16x32_bf16 v[100:103], v[20:23], v[36:39], 0
	v_mfma_f32_16x16x32_bf16 v[36:39], v[28:31], v[36:39], 0
	v_mfma_f32_16x16x32_bf16 v[104:107], v[20:23], v[44:47], 0
	v_mfma_f32_16x16x32_bf16 v[44:47], v[28:31], v[44:47], 0
	v_mfma_f32_16x16x32_bf16 v[108:111], v[20:23], v[52:55], 0
	v_mfma_f32_16x16x32_bf16 v[52:55], v[28:31], v[52:55], 0
	v_mfma_f32_16x16x32_bf16 v[112:115], v[20:23], v[60:63], 0
	v_mfma_f32_16x16x32_bf16 v[60:63], v[28:31], v[60:63], 0
	v_mfma_f32_16x16x32_bf16 v[100:103], v[24:27], v[40:43], v[100:103]
	v_mfma_f32_16x16x32_bf16 v[40:43], v[32:35], v[40:43], v[36:39]
	v_mfma_f32_16x16x32_bf16 v[104:107], v[24:27], v[48:51], v[104:107]
	v_mfma_f32_16x16x32_bf16 v[48:51], v[32:35], v[48:51], v[44:47]
	s_setprio 2
	s_barrier
	v_mfma_f32_16x16x32_bf16 v[108:111], v[24:27], v[56:59], v[108:111]
	v_mfma_f32_16x16x32_bf16 v[56:59], v[32:35], v[56:59], v[52:55]
	v_mfma_f32_16x16x32_bf16 v[112:115], v[24:27], v[64:67], v[112:115]
	v_mfma_f32_16x16x32_bf16 v[64:67], v[32:35], v[64:67], v[60:63]
	s_setprio 0
	v_lshl_add_u64 v[186:187], s[12:13], 0, v[2:3]
	s_add_i32 s51, s51, s38
	v_mov_b32_e32 v191, v3
	v_lshl_add_u64 v[134:135], v[186:187], 0, s[74:75]
	s_mov_b32 m0, s51
	v_lshl_add_u64 v[246:247], s[12:13], 0, v[190:191]
	ds_read_b128 v[36:39], v233 offset:16384
	ds_read_b128 v[44:47], v233 offset:17408
	ds_read_b128 v[52:55], v233 offset:18432
	ds_read_b128 v[60:63], v233 offset:19456
	ds_read_b128 v[116:119], v233 offset:20480
	ds_read_b128 v[120:123], v233 offset:21504
	ds_read_b128 v[124:127], v233 offset:22528
	ds_read_b128 v[128:131], v233 offset:23552
	global_load_lds_dwordx4 v[134:135], off
	v_lshl_add_u64 v[134:135], v[246:247], 0, s[74:75]
	s_add_i32 m0, s51, 0x2000
	s_add_i32 s51, s71, s38
	global_load_lds_dwordx4 v[134:135], off
	s_mov_b32 m0, s51
	v_mov_b32_e32 v133, v3
	global_load_lds_dwordx4 v2, s[16:17]
	s_add_i32 m0, s51, 0x2000
	v_lshl_add_u64 v[248:249], s[14:15], 0, v[132:133]
	v_mov_b32_e32 v189, v3
	global_load_lds_dwordx4 v190, s[16:17]
	v_lshl_add_u64 v[134:135], v[248:249], 0, s[74:75]
	s_mov_b32 m0, s56
	v_lshl_add_u64 v[250:251], s[14:15], 0, v[188:189]
	global_load_lds_dwordx4 v[134:135], off
	v_lshl_add_u64 v[134:135], v[250:251], 0, s[74:75]
	s_mov_b32 m0, s57
	s_nop 0
	global_load_lds_dwordx4 v[134:135], off
	s_waitcnt vmcnt(8)
	s_waitcnt lgkmcnt(0)
	s_barrier
	s_setprio 1
	s_waitcnt lgkmcnt(0)
	v_mfma_f32_16x16x32_bf16 v[134:137], v[4:7], v[36:39], 0
	v_mfma_f32_16x16x32_bf16 v[138:141], v[12:15], v[36:39], 0
	v_mfma_f32_16x16x32_bf16 v[142:145], v[4:7], v[52:55], 0
	v_mfma_f32_16x16x32_bf16 v[146:149], v[12:15], v[52:55], 0
	v_mfma_f32_16x16x32_bf16 v[150:153], v[4:7], v[116:119], 0
	v_mfma_f32_16x16x32_bf16 v[154:157], v[12:15], v[116:119], 0
	v_mfma_f32_16x16x32_bf16 v[4:7], v[4:7], v[124:127], 0
	v_mfma_f32_16x16x32_bf16 v[12:15], v[12:15], v[124:127], 0
	v_mfma_f32_16x16x32_bf16 v[134:137], v[8:11], v[44:47], v[134:137]
	v_mfma_f32_16x16x32_bf16 v[138:141], v[16:19], v[44:47], v[138:141]
	v_mfma_f32_16x16x32_bf16 v[142:145], v[8:11], v[60:63], v[142:145]
	v_mfma_f32_16x16x32_bf16 v[146:149], v[16:19], v[60:63], v[146:149]
	v_mfma_f32_16x16x32_bf16 v[150:153], v[8:11], v[120:123], v[150:153]
	v_mfma_f32_16x16x32_bf16 v[154:157], v[16:19], v[120:123], v[154:157]
	v_mfma_f32_16x16x32_bf16 v[158:161], v[8:11], v[128:131], v[4:7]
	v_mfma_f32_16x16x32_bf16 v[162:165], v[16:19], v[128:131], v[12:15]
	s_setprio 0
	s_setprio 1
	v_mfma_f32_16x16x32_bf16 v[4:7], v[20:23], v[36:39], 0
	v_mfma_f32_16x16x32_bf16 v[8:11], v[28:31], v[36:39], 0
	v_mfma_f32_16x16x32_bf16 v[12:15], v[20:23], v[52:55], 0
	v_mfma_f32_16x16x32_bf16 v[16:19], v[28:31], v[52:55], 0
	v_mfma_f32_16x16x32_bf16 v[36:39], v[20:23], v[116:119], 0
	v_mfma_f32_16x16x32_bf16 v[52:55], v[28:31], v[116:119], 0
	v_mfma_f32_16x16x32_bf16 v[20:23], v[20:23], v[124:127], 0
	v_mfma_f32_16x16x32_bf16 v[28:31], v[28:31], v[124:127], 0
	v_mfma_f32_16x16x32_bf16 v[116:119], v[24:27], v[44:47], v[4:7]
	v_mfma_f32_16x16x32_bf16 v[124:127], v[32:35], v[44:47], v[8:11]
	v_mfma_f32_16x16x32_bf16 v[174:177], v[24:27], v[120:123], v[36:39]
	v_mfma_f32_16x16x32_bf16 v[120:123], v[32:35], v[120:123], v[52:55]
	s_setprio 2
	s_barrier
	v_mfma_f32_16x16x32_bf16 v[178:181], v[24:27], v[128:131], v[20:23]
	v_mfma_f32_16x16x32_bf16 v[128:131], v[32:35], v[128:131], v[28:31]
	v_mfma_f32_16x16x32_bf16 v[166:169], v[24:27], v[60:63], v[12:15]
	v_mfma_f32_16x16x32_bf16 v[170:173], v[32:35], v[60:63], v[16:19]
	s_setprio 0
	s_add_i32 s51, 0, 0x18000
	v_add_u32_e32 v4, s51, v232
	s_add_i32 s71, 0, 0x1c000
	ds_read_b128 v[182:185], v4
	ds_read_b128 v[192:195], v4 offset:1024
	ds_read_b128 v[196:199], v4 offset:2048
	ds_read_b128 v[200:203], v4 offset:3072
	v_add_u32_e32 v4, s71, v232
	ds_read_b128 v[204:207], v4
	ds_read_b128 v[208:211], v4 offset:1024
	ds_read_b128 v[212:215], v4 offset:2048
	ds_read_b128 v[216:219], v4 offset:3072
	s_mov_b32 m0, s58
	ds_read_b128 v[44:47], v233 offset:32768
	ds_read_b128 v[52:55], v233 offset:33792
	ds_read_b128 v[60:63], v233 offset:34816
	ds_read_b128 v[220:223], v233 offset:35840
	ds_read_b128 v[224:227], v233 offset:36864
	ds_read_b128 v[234:237], v233 offset:37888
	ds_read_b128 v[238:241], v233 offset:38912
	ds_read_b128 v[242:245], v233 offset:39936
	global_load_lds_dwordx4 v132, s[26:27]
	s_mov_b32 m0, s59
	s_nop 0
	global_load_lds_dwordx4 v188, s[26:27]
	s_waitcnt vmcnt(8)
	s_waitcnt lgkmcnt(0)
	s_barrier
	s_setprio 1
	s_waitcnt lgkmcnt(0)
	v_mfma_f32_16x16x32_bf16 v[4:7], v[182:185], v[44:47], v[68:71]
	v_mfma_f32_16x16x32_bf16 v[8:11], v[196:199], v[44:47], v[72:75]
	v_mfma_f32_16x16x32_bf16 v[12:15], v[182:185], v[60:63], v[76:79]
	v_mfma_f32_16x16x32_bf16 v[16:19], v[196:199], v[60:63], v[80:83]
	v_mfma_f32_16x16x32_bf16 v[20:23], v[182:185], v[224:227], v[84:87]
	v_mfma_f32_16x16x32_bf16 v[24:27], v[196:199], v[224:227], v[88:91]
	v_mfma_f32_16x16x32_bf16 v[28:31], v[182:185], v[238:241], v[92:95]
	v_mfma_f32_16x16x32_bf16 v[32:35], v[196:199], v[238:241], v[96:99]
	v_mfma_f32_16x16x32_bf16 v[4:7], v[192:195], v[52:55], v[4:7]
	v_mfma_f32_16x16x32_bf16 v[8:11], v[200:203], v[52:55], v[8:11]
	v_mfma_f32_16x16x32_bf16 v[12:15], v[192:195], v[220:223], v[12:15]
	v_mfma_f32_16x16x32_bf16 v[16:19], v[200:203], v[220:223], v[16:19]
	v_mfma_f32_16x16x32_bf16 v[20:23], v[192:195], v[234:237], v[20:23]
	v_mfma_f32_16x16x32_bf16 v[24:27], v[200:203], v[234:237], v[24:27]
	v_mfma_f32_16x16x32_bf16 v[28:31], v[192:195], v[242:245], v[28:31]
	v_mfma_f32_16x16x32_bf16 v[32:35], v[200:203], v[242:245], v[32:35]
	s_setprio 0
	s_setprio 1
	v_mfma_f32_16x16x32_bf16 v[36:39], v[204:207], v[44:47], v[100:103]
	v_mfma_f32_16x16x32_bf16 v[40:43], v[212:215], v[44:47], v[40:43]
	v_mfma_f32_16x16x32_bf16 v[36:39], v[208:211], v[52:55], v[36:39]
	v_mfma_f32_16x16x32_bf16 v[40:43], v[216:219], v[52:55], v[40:43]
	v_mfma_f32_16x16x32_bf16 v[44:47], v[204:207], v[60:63], v[104:107]
	v_mfma_f32_16x16x32_bf16 v[48:51], v[212:215], v[60:63], v[48:51]
	v_mfma_f32_16x16x32_bf16 v[52:55], v[204:207], v[224:227], v[108:111]
	v_mfma_f32_16x16x32_bf16 v[56:59], v[212:215], v[224:227], v[56:59]
	v_mfma_f32_16x16x32_bf16 v[60:63], v[204:207], v[238:241], v[112:115]
	v_mfma_f32_16x16x32_bf16 v[64:67], v[212:215], v[238:241], v[64:67]
	v_mfma_f32_16x16x32_bf16 v[44:47], v[208:211], v[220:223], v[44:47]
	v_mfma_f32_16x16x32_bf16 v[48:51], v[216:219], v[220:223], v[48:51]
	s_setprio 2
	s_barrier
	v_mfma_f32_16x16x32_bf16 v[52:55], v[208:211], v[234:237], v[52:55]
	v_mfma_f32_16x16x32_bf16 v[56:59], v[216:219], v[234:237], v[56:59]
	v_mfma_f32_16x16x32_bf16 v[60:63], v[208:211], v[242:245], v[60:63]
	v_mfma_f32_16x16x32_bf16 v[64:67], v[216:219], v[242:245], v[64:67]
	s_setprio 0
	s_add_i32 s51, s51, s38
	v_lshl_add_u64 v[68:69], v[186:187], 0, s[24:25]
	s_mov_b32 m0, s51
	ds_read_b128 v[104:107], v233 offset:49152
	ds_read_b128 v[108:111], v233 offset:50176
	ds_read_b128 v[112:115], v233 offset:51200
	ds_read_b128 v[220:223], v233 offset:52224
	ds_read_b128 v[224:227], v233 offset:53248
	ds_read_b128 v[234:237], v233 offset:54272
	ds_read_b128 v[238:241], v233 offset:55296
	ds_read_b128 v[242:245], v233 offset:56320
	global_load_lds_dwordx4 v[68:69], off
	v_lshl_add_u64 v[68:69], v[246:247], 0, s[24:25]
	s_add_i32 m0, s51, 0x2000
	s_add_i32 s51, s71, s38
	global_load_lds_dwordx4 v[68:69], off
	s_mov_b32 m0, s51
	v_lshl_add_u64 v[68:69], v[248:249], 0, s[24:25]
	global_load_lds_dwordx4 v2, s[28:29]
	s_add_i32 m0, s51, 0x2000
	s_nop 0
	global_load_lds_dwordx4 v190, s[28:29]
	s_mov_b32 m0, s63
	s_nop 0
	global_load_lds_dwordx4 v[68:69], off
	v_lshl_add_u64 v[68:69], v[250:251], 0, s[24:25]
	s_mov_b32 m0, s64
	s_nop 0
	global_load_lds_dwordx4 v[68:69], off
	s_waitcnt vmcnt(8)
	s_waitcnt lgkmcnt(0)
	s_barrier
	s_setprio 1
	s_waitcnt lgkmcnt(0)
	v_mfma_f32_16x16x32_bf16 v[68:71], v[182:185], v[104:107], v[134:137]
	v_mfma_f32_16x16x32_bf16 v[72:75], v[196:199], v[104:107], v[138:141]
	v_mfma_f32_16x16x32_bf16 v[76:79], v[182:185], v[112:115], v[142:145]
	v_mfma_f32_16x16x32_bf16 v[80:83], v[196:199], v[112:115], v[146:149]
	v_mfma_f32_16x16x32_bf16 v[84:87], v[182:185], v[224:227], v[150:153]
	v_mfma_f32_16x16x32_bf16 v[88:91], v[196:199], v[224:227], v[154:157]
	v_mfma_f32_16x16x32_bf16 v[92:95], v[182:185], v[238:241], v[158:161]
	v_mfma_f32_16x16x32_bf16 v[96:99], v[196:199], v[238:241], v[162:165]
	v_mfma_f32_16x16x32_bf16 v[68:71], v[192:195], v[108:111], v[68:71]
	v_mfma_f32_16x16x32_bf16 v[72:75], v[200:203], v[108:111], v[72:75]
	v_mfma_f32_16x16x32_bf16 v[76:79], v[192:195], v[220:223], v[76:79]
	v_mfma_f32_16x16x32_bf16 v[80:83], v[200:203], v[220:223], v[80:83]
	v_mfma_f32_16x16x32_bf16 v[84:87], v[192:195], v[234:237], v[84:87]
	v_mfma_f32_16x16x32_bf16 v[88:91], v[200:203], v[234:237], v[88:91]
	v_mfma_f32_16x16x32_bf16 v[92:95], v[192:195], v[242:245], v[92:95]
	v_mfma_f32_16x16x32_bf16 v[96:99], v[200:203], v[242:245], v[96:99]
	s_setprio 0
	s_setprio 1
	v_mfma_f32_16x16x32_bf16 v[100:103], v[204:207], v[104:107], v[116:119]
	v_mfma_f32_16x16x32_bf16 v[104:107], v[212:215], v[104:107], v[124:127]
	v_mfma_f32_16x16x32_bf16 v[100:103], v[208:211], v[108:111], v[100:103]
	v_mfma_f32_16x16x32_bf16 v[104:107], v[216:219], v[108:111], v[104:107]
	v_mfma_f32_16x16x32_bf16 v[108:111], v[204:207], v[112:115], v[166:169]
	v_mfma_f32_16x16x32_bf16 v[112:115], v[212:215], v[112:115], v[170:173]
	v_mfma_f32_16x16x32_bf16 v[116:119], v[204:207], v[224:227], v[174:177]
	v_mfma_f32_16x16x32_bf16 v[120:123], v[212:215], v[224:227], v[120:123]
	v_mfma_f32_16x16x32_bf16 v[124:127], v[204:207], v[238:241], v[178:181]
	v_mfma_f32_16x16x32_bf16 v[128:131], v[212:215], v[238:241], v[128:131]
	v_mfma_f32_16x16x32_bf16 v[108:111], v[208:211], v[220:223], v[108:111]
	v_mfma_f32_16x16x32_bf16 v[112:115], v[216:219], v[220:223], v[112:115]
	s_setprio 2
	s_barrier
	v_mfma_f32_16x16x32_bf16 v[116:119], v[208:211], v[234:237], v[116:119]
	v_mfma_f32_16x16x32_bf16 v[120:123], v[216:219], v[234:237], v[120:123]
	v_mfma_f32_16x16x32_bf16 v[124:127], v[208:211], v[242:245], v[124:127]
	v_mfma_f32_16x16x32_bf16 v[128:131], v[216:219], v[242:245], v[128:131]
	s_setprio 0
	s_add_i32 s41, s41, 2
	s_cmp_ge_i32 s41, s40
	s_cbranch_scc0 .LBB0_2269
	v_mov_b32_e32 v192, v2
	s_branch .LBB0_2272

.LBB0_2273:
	s_add_u32 s12, s14, 0xfffc0080
	s_addc_u32 s13, s15, -1
	s_add_i32 s29, 0, 0x10000
	s_cmp_eq_u32 s28, 12
	s_cselect_b32 s17, s9, s13
	s_cselect_b32 s16, s8, s12
	s_cselect_b32 s13, s11, s27
	s_cselect_b32 s12, s10, s26
	s_add_i32 s51, 0, 0x14000
	v_add_u32_e32 v144, s29, v232
	v_add_u32_e32 v160, s51, v232
	s_waitcnt lgkmcnt(0)
	ds_read_b128 v[132:135], v144
	ds_read_b128 v[136:139], v144 offset:1024
	ds_read_b128 v[140:143], v144 offset:2048
	ds_read_b128 v[144:147], v144 offset:3072
	ds_read_b128 v[148:151], v160
	ds_read_b128 v[152:155], v160 offset:1024
	ds_read_b128 v[156:159], v160 offset:2048
	ds_read_b128 v[160:163], v160 offset:3072
	s_mov_b32 m0, s65
	v_add_u32_e32 v210, 0, v231
	ds_read_b128 v[164:167], v210
	ds_read_b128 v[168:171], v210 offset:1024
	ds_read_b128 v[172:175], v210 offset:2048
	ds_read_b128 v[176:179], v210 offset:3072
	ds_read_b128 v[180:183], v210 offset:4096
	ds_read_b128 v[184:187], v210 offset:5120
	ds_read_b128 v[194:197], v210 offset:6144
	ds_read_b128 v[198:201], v210 offset:7168
	global_load_lds_dwordx4 v2, s[14:15]
	s_mov_b32 m0, s66
	v_mov_b32_e32 v189, v3
	global_load_lds_dwordx4 v188, s[14:15]
	s_waitcnt vmcnt(8)
	s_waitcnt lgkmcnt(0)
	s_barrier
	s_setprio 1
	s_waitcnt lgkmcnt(0)
	v_mfma_f32_16x16x32_bf16 v[4:7], v[132:135], v[164:167], v[4:7]
	v_mfma_f32_16x16x32_bf16 v[4:7], v[136:139], v[168:171], v[4:7]
	v_mfma_f32_16x16x32_bf16 v[8:11], v[144:147], v[168:171], v[8:11]
	v_mfma_f32_16x16x32_bf16 v[8:11], v[140:143], v[164:167], v[8:11]
	v_mfma_f32_16x16x32_bf16 v[16:19], v[140:143], v[172:175], v[16:19]
	v_mfma_f32_16x16x32_bf16 v[16:19], v[144:147], v[176:179], v[16:19]
	v_mfma_f32_16x16x32_bf16 v[12:15], v[136:139], v[176:179], v[12:15]
	v_mfma_f32_16x16x32_bf16 v[12:15], v[132:135], v[172:175], v[12:15]
	v_mfma_f32_16x16x32_bf16 v[20:23], v[132:135], v[180:183], v[20:23]
	v_mfma_f32_16x16x32_bf16 v[20:23], v[136:139], v[184:187], v[20:23]
	v_mfma_f32_16x16x32_bf16 v[24:27], v[144:147], v[184:187], v[24:27]
	v_mfma_f32_16x16x32_bf16 v[24:27], v[140:143], v[180:183], v[24:27]
	v_mfma_f32_16x16x32_bf16 v[32:35], v[140:143], v[194:197], v[32:35]
	v_mfma_f32_16x16x32_bf16 v[32:35], v[144:147], v[198:201], v[32:35]
	v_mfma_f32_16x16x32_bf16 v[28:31], v[136:139], v[198:201], v[28:31]
	v_mfma_f32_16x16x32_bf16 v[28:31], v[132:135], v[194:197], v[28:31]
	s_setprio 0
	s_setprio 1
	v_mfma_f32_16x16x32_bf16 v[36:39], v[148:151], v[164:167], v[36:39]
	v_mfma_f32_16x16x32_bf16 v[36:39], v[152:155], v[168:171], v[36:39]
	v_mfma_f32_16x16x32_bf16 v[40:43], v[160:163], v[168:171], v[40:43]
	v_mfma_f32_16x16x32_bf16 v[40:43], v[156:159], v[164:167], v[40:43]
	v_mfma_f32_16x16x32_bf16 v[48:51], v[156:159], v[172:175], v[48:51]
	v_mfma_f32_16x16x32_bf16 v[48:51], v[160:163], v[176:179], v[48:51]
	v_mfma_f32_16x16x32_bf16 v[44:47], v[152:155], v[176:179], v[44:47]
	v_mfma_f32_16x16x32_bf16 v[44:47], v[148:151], v[172:175], v[44:47]
	v_mfma_f32_16x16x32_bf16 v[52:55], v[148:151], v[180:183], v[52:55]
	v_mfma_f32_16x16x32_bf16 v[52:55], v[152:155], v[184:187], v[52:55]
	v_mfma_f32_16x16x32_bf16 v[56:59], v[160:163], v[184:187], v[56:59]
	v_mfma_f32_16x16x32_bf16 v[56:59], v[156:159], v[180:183], v[56:59]
	s_setprio 2
	s_barrier
	v_mfma_f32_16x16x32_bf16 v[64:67], v[156:159], v[194:197], v[64:67]
	v_mfma_f32_16x16x32_bf16 v[64:67], v[160:163], v[198:201], v[64:67]
	v_mfma_f32_16x16x32_bf16 v[60:63], v[152:155], v[198:201], v[60:63]
	v_mfma_f32_16x16x32_bf16 v[60:63], v[148:151], v[194:197], v[60:63]
	s_setprio 0
	s_add_i32 s29, s29, s38
	s_mov_b32 m0, s29
	ds_read_b128 v[164:167], v210 offset:16384
	ds_read_b128 v[168:171], v210 offset:17408
	ds_read_b128 v[172:175], v210 offset:18432
	ds_read_b128 v[176:179], v210 offset:19456
	ds_read_b128 v[180:183], v210 offset:20480
	ds_read_b128 v[184:187], v210 offset:21504
	ds_read_b128 v[194:197], v210 offset:22528
	ds_read_b128 v[198:201], v210 offset:23552
	global_load_lds_dwordx4 v192, s[12:13]
	s_add_i32 m0, s29, 0x2000
	s_add_u32 s40, s12, 0x100000
	s_addc_u32 s41, s13, 0
	s_add_i32 s29, s51, s38
	global_load_lds_dwordx4 v190, s[12:13]
	s_mov_b32 m0, s29
	v_mov_b32_e32 v193, v3
	global_load_lds_dwordx4 v192, s[40:41]
	s_add_i32 m0, s29, 0x2000
	v_mov_b32_e32 v191, v3
	global_load_lds_dwordx4 v190, s[40:41]
	s_mov_b32 m0, s56
	v_lshl_add_u64 v[202:203], s[12:13], 0, v[192:193]
	global_load_lds_dwordx4 v2, s[16:17]
	s_mov_b32 m0, s57
	v_lshl_add_u64 v[204:205], s[12:13], 0, v[190:191]
	global_load_lds_dwordx4 v188, s[16:17]
	s_waitcnt vmcnt(8)
	s_waitcnt lgkmcnt(0)
	v_lshl_add_u64 v[206:207], s[16:17], 0, v[2:3]
	v_lshl_add_u64 v[208:209], s[16:17], 0, v[188:189]
	s_barrier
	s_setprio 1
	s_waitcnt lgkmcnt(0)
	v_mfma_f32_16x16x32_bf16 v[68:71], v[132:135], v[164:167], v[68:71]
	v_mfma_f32_16x16x32_bf16 v[68:71], v[136:139], v[168:171], v[68:71]
	v_mfma_f32_16x16x32_bf16 v[72:75], v[144:147], v[168:171], v[72:75]
	v_mfma_f32_16x16x32_bf16 v[72:75], v[140:143], v[164:167], v[72:75]
	v_mfma_f32_16x16x32_bf16 v[80:83], v[140:143], v[172:175], v[80:83]
	v_mfma_f32_16x16x32_bf16 v[80:83], v[144:147], v[176:179], v[80:83]
	v_mfma_f32_16x16x32_bf16 v[76:79], v[136:139], v[176:179], v[76:79]
	v_mfma_f32_16x16x32_bf16 v[76:79], v[132:135], v[172:175], v[76:79]
	v_mfma_f32_16x16x32_bf16 v[84:87], v[132:135], v[180:183], v[84:87]
	v_mfma_f32_16x16x32_bf16 v[84:87], v[136:139], v[184:187], v[84:87]
	v_mfma_f32_16x16x32_bf16 v[88:91], v[144:147], v[184:187], v[88:91]
	v_mfma_f32_16x16x32_bf16 v[88:91], v[140:143], v[180:183], v[88:91]
	v_mfma_f32_16x16x32_bf16 v[96:99], v[140:143], v[194:197], v[96:99]
	v_mfma_f32_16x16x32_bf16 v[96:99], v[144:147], v[198:201], v[96:99]
	v_mfma_f32_16x16x32_bf16 v[92:95], v[136:139], v[198:201], v[92:95]
	v_mfma_f32_16x16x32_bf16 v[92:95], v[132:135], v[194:197], v[92:95]
	s_setprio 0
	s_setprio 1
	v_mfma_f32_16x16x32_bf16 v[100:103], v[148:151], v[164:167], v[100:103]
	v_mfma_f32_16x16x32_bf16 v[100:103], v[152:155], v[168:171], v[100:103]
	v_mfma_f32_16x16x32_bf16 v[104:107], v[160:163], v[168:171], v[104:107]
	v_mfma_f32_16x16x32_bf16 v[104:107], v[156:159], v[164:167], v[104:107]
	v_mfma_f32_16x16x32_bf16 v[112:115], v[156:159], v[172:175], v[112:115]
	v_mfma_f32_16x16x32_bf16 v[112:115], v[160:163], v[176:179], v[112:115]
	v_mfma_f32_16x16x32_bf16 v[108:111], v[152:155], v[176:179], v[108:111]
	v_mfma_f32_16x16x32_bf16 v[108:111], v[148:151], v[172:175], v[108:111]
	v_mfma_f32_16x16x32_bf16 v[116:119], v[148:151], v[180:183], v[116:119]
	v_mfma_f32_16x16x32_bf16 v[116:119], v[152:155], v[184:187], v[116:119]
	v_mfma_f32_16x16x32_bf16 v[120:123], v[160:163], v[184:187], v[120:123]
	v_mfma_f32_16x16x32_bf16 v[120:123], v[156:159], v[180:183], v[120:123]
	s_setprio 2
	s_barrier
	v_mfma_f32_16x16x32_bf16 v[128:131], v[156:159], v[194:197], v[128:131]
	v_mfma_f32_16x16x32_bf16 v[128:131], v[160:163], v[198:201], v[128:131]
	v_mfma_f32_16x16x32_bf16 v[124:127], v[152:155], v[198:201], v[124:127]
	v_mfma_f32_16x16x32_bf16 v[124:127], v[148:151], v[194:197], v[124:127]
	s_setprio 0
	s_add_i32 s29, 0, 0x18000
	s_add_i32 s40, 0, 0x1c000
	v_add_u32_e32 v144, s29, v232
	v_add_u32_e32 v160, s40, v232
	ds_read_b128 v[132:135], v144
	ds_read_b128 v[136:139], v144 offset:1024
	ds_read_b128 v[140:143], v144 offset:2048
	ds_read_b128 v[144:147], v144 offset:3072
	ds_read_b128 v[148:151], v160
	ds_read_b128 v[152:155], v160 offset:1024
	ds_read_b128 v[156:159], v160 offset:2048
	ds_read_b128 v[160:163], v160 offset:3072
	s_add_u32 s16, s16, 0x40000
	s_addc_u32 s17, s17, 0
	s_mov_b32 m0, s58
	ds_read_b128 v[164:167], v210 offset:32768
	ds_read_b128 v[168:171], v210 offset:33792
	ds_read_b128 v[172:175], v210 offset:34816
	ds_read_b128 v[176:179], v210 offset:35840
	ds_read_b128 v[180:183], v210 offset:36864
	ds_read_b128 v[184:187], v210 offset:37888
	ds_read_b128 v[194:197], v210 offset:38912
	ds_read_b128 v[198:201], v210 offset:39936
	global_load_lds_dwordx4 v2, s[16:17]
	s_mov_b32 m0, s59
	s_nop 0
	global_load_lds_dwordx4 v188, s[16:17]
	s_waitcnt vmcnt(8)
	s_waitcnt lgkmcnt(0)
	s_barrier
	s_setprio 1
	s_waitcnt lgkmcnt(0)
	v_mfma_f32_16x16x32_bf16 v[4:7], v[132:135], v[164:167], v[4:7]
	v_mfma_f32_16x16x32_bf16 v[4:7], v[136:139], v[168:171], v[4:7]
	v_mfma_f32_16x16x32_bf16 v[8:11], v[144:147], v[168:171], v[8:11]
	v_mfma_f32_16x16x32_bf16 v[8:11], v[140:143], v[164:167], v[8:11]
	v_mfma_f32_16x16x32_bf16 v[16:19], v[140:143], v[172:175], v[16:19]
	v_mfma_f32_16x16x32_bf16 v[16:19], v[144:147], v[176:179], v[16:19]
	v_mfma_f32_16x16x32_bf16 v[12:15], v[136:139], v[176:179], v[12:15]
	v_mfma_f32_16x16x32_bf16 v[12:15], v[132:135], v[172:175], v[12:15]
	v_mfma_f32_16x16x32_bf16 v[20:23], v[132:135], v[180:183], v[20:23]
	v_mfma_f32_16x16x32_bf16 v[20:23], v[136:139], v[184:187], v[20:23]
	v_mfma_f32_16x16x32_bf16 v[24:27], v[144:147], v[184:187], v[24:27]
	v_mfma_f32_16x16x32_bf16 v[24:27], v[140:143], v[180:183], v[24:27]
	v_mfma_f32_16x16x32_bf16 v[32:35], v[140:143], v[194:197], v[32:35]
	v_mfma_f32_16x16x32_bf16 v[32:35], v[144:147], v[198:201], v[32:35]
	v_mfma_f32_16x16x32_bf16 v[28:31], v[136:139], v[198:201], v[28:31]
	v_mfma_f32_16x16x32_bf16 v[28:31], v[132:135], v[194:197], v[28:31]
	s_setprio 0
	s_setprio 1
	v_mfma_f32_16x16x32_bf16 v[36:39], v[148:151], v[164:167], v[36:39]
	v_mfma_f32_16x16x32_bf16 v[36:39], v[152:155], v[168:171], v[36:39]
	v_mfma_f32_16x16x32_bf16 v[40:43], v[160:163], v[168:171], v[40:43]
	v_mfma_f32_16x16x32_bf16 v[40:43], v[156:159], v[164:167], v[40:43]
	v_mfma_f32_16x16x32_bf16 v[48:51], v[156:159], v[172:175], v[48:51]
	v_mfma_f32_16x16x32_bf16 v[48:51], v[160:163], v[176:179], v[48:51]
	v_mfma_f32_16x16x32_bf16 v[44:47], v[152:155], v[176:179], v[44:47]
	v_mfma_f32_16x16x32_bf16 v[44:47], v[148:151], v[172:175], v[44:47]
	v_mfma_f32_16x16x32_bf16 v[52:55], v[148:151], v[180:183], v[52:55]
	v_mfma_f32_16x16x32_bf16 v[52:55], v[152:155], v[184:187], v[52:55]
	v_mfma_f32_16x16x32_bf16 v[56:59], v[160:163], v[184:187], v[56:59]
	v_mfma_f32_16x16x32_bf16 v[56:59], v[156:159], v[180:183], v[56:59]
	s_setprio 2
	s_barrier
	v_mfma_f32_16x16x32_bf16 v[64:67], v[156:159], v[194:197], v[64:67]
	v_mfma_f32_16x16x32_bf16 v[64:67], v[160:163], v[198:201], v[64:67]
	v_mfma_f32_16x16x32_bf16 v[60:63], v[152:155], v[198:201], v[60:63]
	v_mfma_f32_16x16x32_bf16 v[60:63], v[148:151], v[194:197], v[60:63]
	s_setprio 0
	s_add_i32 s16, s29, s38
	v_lshl_add_u64 v[202:203], v[202:203], 0, s[86:87]
	s_mov_b32 m0, s16
	ds_read_b128 v[164:167], v210 offset:49152
	ds_read_b128 v[168:171], v210 offset:50176
	ds_read_b128 v[172:175], v210 offset:51200
	ds_read_b128 v[176:179], v210 offset:52224
	ds_read_b128 v[180:183], v210 offset:53248
	ds_read_b128 v[184:187], v210 offset:54272
	ds_read_b128 v[194:197], v210 offset:55296
	ds_read_b128 v[198:201], v210 offset:56320
	global_load_lds_dwordx4 v[202:203], off
	s_add_i32 m0, s16, 0x2000
	s_add_u32 s12, s12, 0x100080
	v_lshl_add_u64 v[202:203], v[204:205], 0, s[86:87]
	s_addc_u32 s13, s13, 0
	s_add_i32 s16, s40, s38
	global_load_lds_dwordx4 v[202:203], off
	s_mov_b32 m0, s16
	v_lshl_add_u64 v[202:203], v[206:207], 0, s[86:87]
	global_load_lds_dwordx4 v192, s[12:13]
	s_add_i32 m0, s16, 0x2000
	s_nop 0
	global_load_lds_dwordx4 v190, s[12:13]
	s_mov_b32 m0, s63
	s_nop 0
	global_load_lds_dwordx4 v[202:203], off
	v_lshl_add_u64 v[202:203], v[208:209], 0, s[86:87]
	s_mov_b32 m0, s64
	s_nop 0
	global_load_lds_dwordx4 v[202:203], off
	s_waitcnt vmcnt(8)
	s_waitcnt lgkmcnt(0)
	s_barrier
	s_setprio 1
	s_waitcnt lgkmcnt(0)
	v_mfma_f32_16x16x32_bf16 v[68:71], v[132:135], v[164:167], v[68:71]
	v_mfma_f32_16x16x32_bf16 v[68:71], v[136:139], v[168:171], v[68:71]
	v_mfma_f32_16x16x32_bf16 v[72:75], v[144:147], v[168:171], v[72:75]
	v_mfma_f32_16x16x32_bf16 v[72:75], v[140:143], v[164:167], v[72:75]
	v_mfma_f32_16x16x32_bf16 v[80:83], v[140:143], v[172:175], v[80:83]
	v_mfma_f32_16x16x32_bf16 v[80:83], v[144:147], v[176:179], v[80:83]
	v_mfma_f32_16x16x32_bf16 v[76:79], v[136:139], v[176:179], v[76:79]
	v_mfma_f32_16x16x32_bf16 v[76:79], v[132:135], v[172:175], v[76:79]
	v_mfma_f32_16x16x32_bf16 v[84:87], v[132:135], v[180:183], v[84:87]
	v_mfma_f32_16x16x32_bf16 v[84:87], v[136:139], v[184:187], v[84:87]
	v_mfma_f32_16x16x32_bf16 v[88:91], v[144:147], v[184:187], v[88:91]
	v_mfma_f32_16x16x32_bf16 v[88:91], v[140:143], v[180:183], v[88:91]
	v_mfma_f32_16x16x32_bf16 v[96:99], v[140:143], v[194:197], v[96:99]
	v_mfma_f32_16x16x32_bf16 v[96:99], v[144:147], v[198:201], v[96:99]
	v_mfma_f32_16x16x32_bf16 v[92:95], v[136:139], v[198:201], v[92:95]
	v_mfma_f32_16x16x32_bf16 v[92:95], v[132:135], v[194:197], v[92:95]
	s_setprio 0
	s_setprio 1
	v_mfma_f32_16x16x32_bf16 v[100:103], v[148:151], v[164:167], v[100:103]
	v_mfma_f32_16x16x32_bf16 v[100:103], v[152:155], v[168:171], v[100:103]
	v_mfma_f32_16x16x32_bf16 v[104:107], v[160:163], v[168:171], v[104:107]
	v_mfma_f32_16x16x32_bf16 v[104:107], v[156:159], v[164:167], v[104:107]
	v_mfma_f32_16x16x32_bf16 v[112:115], v[156:159], v[172:175], v[112:115]
	v_mfma_f32_16x16x32_bf16 v[112:115], v[160:163], v[176:179], v[112:115]
	v_mfma_f32_16x16x32_bf16 v[108:111], v[152:155], v[176:179], v[108:111]
	v_mfma_f32_16x16x32_bf16 v[108:111], v[148:151], v[172:175], v[108:111]
	v_mfma_f32_16x16x32_bf16 v[116:119], v[148:151], v[180:183], v[116:119]
	v_mfma_f32_16x16x32_bf16 v[116:119], v[152:155], v[184:187], v[116:119]
	v_mfma_f32_16x16x32_bf16 v[120:123], v[160:163], v[184:187], v[120:123]
	v_mfma_f32_16x16x32_bf16 v[120:123], v[156:159], v[180:183], v[120:123]
	s_setprio 2
	s_barrier
	v_mfma_f32_16x16x32_bf16 v[128:131], v[156:159], v[194:197], v[128:131]
	v_mfma_f32_16x16x32_bf16 v[128:131], v[160:163], v[198:201], v[128:131]
	v_mfma_f32_16x16x32_bf16 v[124:127], v[152:155], v[198:201], v[124:127]
	v_mfma_f32_16x16x32_bf16 v[124:127], v[148:151], v[194:197], v[124:127]
	s_setprio 0
	s_add_i32 s28, s28, 2
	s_add_u32 s14, s14, 0x100
	s_addc_u32 s15, s15, 0
	s_add_u32 s26, s26, 0x100
	s_addc_u32 s27, s27, 0
	s_cmp_gt_u32 s28, 13
	s_cbranch_scc0 .LBB0_2273
	s_and_b64 vcc, exec, s[48:49]
	s_cbranch_vccz .LBB0_2276
	s_barrier
